# v33
# speedup vs baseline: 1.0087x; 1.0087x over previous
.LBB0_189:
	s_add_u32 s36, s34, 0xfffc0080
	s_addc_u32 s37, s35, -1
	s_add_i32 s75, 0, 0x10000
	v_add_u32_e32 v140, s75, v161
	ds_read_b128 v[164:167], v140
	ds_read_b128 v[168:171], v140 offset:1024
	ds_read_b128 v[172:175], v140 offset:2048
	ds_read_b128 v[176:179], v140 offset:3072
	s_cmp_eq_u32 s74, 12
	s_cselect_b32 s39, s25, s37
	s_cselect_b32 s38, s69, s36
	s_cselect_b32 s37, s23, s73
	s_cselect_b32 s36, s70, s71
	v_lshl_add_u64 v[140:141], s[34:35], 0, v[136:137]
	s_add_i32 m0, s31, 0xc000
	ds_read_b128 v[180:183], v163
	ds_read_b128 v[184:187], v163 offset:1024
	ds_read_b128 v[188:191], v163 offset:2048
	ds_read_b128 v[192:195], v163 offset:3072
	ds_read_b128 v[196:199], v163 offset:4096
	ds_read_b128 v[200:203], v163 offset:5120
	ds_read_b128 v[204:207], v163 offset:6144
	ds_read_b128 v[208:211], v163 offset:7168
	global_load_lds_dwordx4 v[140:141], off
	v_lshl_add_u64 v[140:141], s[34:35], 0, v[138:139]
	s_add_i32 m0, s31, 0xe000
	s_nop 0
	global_load_lds_dwordx4 v[140:141], off
	s_waitcnt lgkmcnt(8)
	s_barrier
	s_waitcnt lgkmcnt(0)
	s_setprio 1
	v_mfma_f32_16x16x32_bf16 v[124:127], v[164:167], v[180:183], v[124:127]
	v_mfma_f32_16x16x32_bf16 v[120:123], v[172:175], v[180:183], v[120:123]
	v_mfma_f32_16x16x32_bf16 v[116:119], v[164:167], v[188:191], v[116:119]
	v_mfma_f32_16x16x32_bf16 v[108:111], v[172:175], v[188:191], v[108:111]
	v_mfma_f32_16x16x32_bf16 v[100:103], v[164:167], v[196:199], v[100:103]
	v_mfma_f32_16x16x32_bf16 v[92:95], v[172:175], v[196:199], v[92:95]
	v_mfma_f32_16x16x32_bf16 v[84:87], v[164:167], v[204:207], v[84:87]
	v_mfma_f32_16x16x32_bf16 v[76:79], v[172:175], v[204:207], v[76:79]
	v_mfma_f32_16x16x32_bf16 v[124:127], v[168:171], v[184:187], v[124:127]
	v_mfma_f32_16x16x32_bf16 v[120:123], v[176:179], v[184:187], v[120:123]
	v_mfma_f32_16x16x32_bf16 v[116:119], v[168:171], v[192:195], v[116:119]
	v_mfma_f32_16x16x32_bf16 v[108:111], v[176:179], v[192:195], v[108:111]
	v_mfma_f32_16x16x32_bf16 v[100:103], v[168:171], v[200:203], v[100:103]
	v_mfma_f32_16x16x32_bf16 v[92:95], v[176:179], v[200:203], v[92:95]
	v_mfma_f32_16x16x32_bf16 v[84:87], v[168:171], v[208:211], v[84:87]
	v_mfma_f32_16x16x32_bf16 v[76:79], v[176:179], v[208:211], v[76:79]
	s_setprio 0
	s_barrier
	s_add_i32 s78, 0, 0x14000
	v_add_u32_e32 v140, s78, v161
	s_add_i32 s75, s75, s57
	ds_read_b128 v[212:215], v140
	ds_read_b128 v[216:219], v140 offset:1024
	ds_read_b128 v[220:223], v140 offset:2048
	ds_read_b128 v[224:227], v140 offset:3072
	v_lshl_add_u64 v[140:141], s[36:37], 0, v[128:129]
	s_mov_b32 m0, s75
	v_lshl_add_u64 v[228:229], s[36:37], 0, v[130:131]
	global_load_lds_dwordx4 v[140:141], off
	s_add_i32 m0, s75, 0x2000
	s_nop 0
	global_load_lds_dwordx4 v[228:229], off
	s_barrier
	s_waitcnt lgkmcnt(0)
	s_setprio 1
	v_mfma_f32_16x16x32_bf16 v[112:115], v[212:215], v[180:183], v[112:115]
	v_mfma_f32_16x16x32_bf16 v[104:107], v[220:223], v[180:183], v[104:107]
	v_mfma_f32_16x16x32_bf16 v[96:99], v[212:215], v[188:191], v[96:99]
	v_mfma_f32_16x16x32_bf16 v[88:91], v[220:223], v[188:191], v[88:91]
	v_mfma_f32_16x16x32_bf16 v[80:83], v[212:215], v[196:199], v[80:83]
	v_mfma_f32_16x16x32_bf16 v[72:75], v[220:223], v[196:199], v[72:75]
	v_mfma_f32_16x16x32_bf16 v[68:71], v[212:215], v[204:207], v[68:71]
	v_mfma_f32_16x16x32_bf16 v[64:67], v[220:223], v[204:207], v[64:67]
	v_mfma_f32_16x16x32_bf16 v[112:115], v[216:219], v[184:187], v[112:115]
	v_mfma_f32_16x16x32_bf16 v[104:107], v[224:227], v[184:187], v[104:107]
	v_mfma_f32_16x16x32_bf16 v[96:99], v[216:219], v[192:195], v[96:99]
	v_mfma_f32_16x16x32_bf16 v[88:91], v[224:227], v[192:195], v[88:91]
	v_mfma_f32_16x16x32_bf16 v[80:83], v[216:219], v[200:203], v[80:83]
	v_mfma_f32_16x16x32_bf16 v[72:75], v[224:227], v[200:203], v[72:75]
	v_mfma_f32_16x16x32_bf16 v[68:71], v[216:219], v[208:211], v[68:71]
	v_mfma_f32_16x16x32_bf16 v[64:67], v[224:227], v[208:211], v[64:67]
	s_setprio 0
	s_mov_b32 m0, s31
	v_lshl_add_u64 v[230:231], s[38:39], 0, v[134:135]
	s_barrier
	ds_read_b128 v[180:183], v163 offset:16384
	ds_read_b128 v[184:187], v163 offset:17408
	ds_read_b128 v[188:191], v163 offset:18432
	ds_read_b128 v[192:195], v163 offset:19456
	ds_read_b128 v[196:199], v163 offset:20480
	ds_read_b128 v[200:203], v163 offset:21504
	ds_read_b128 v[204:207], v163 offset:22528
	ds_read_b128 v[208:211], v163 offset:23552
	global_load_lds_dwordx4 v[230:231], off
	v_lshl_add_u64 v[232:233], s[38:39], 0, v[132:133]
	s_mov_b32 m0, s60
	s_nop 0
	global_load_lds_dwordx4 v[232:233], off
	s_barrier
	s_waitcnt lgkmcnt(0)
	s_setprio 1
	v_mfma_f32_16x16x32_bf16 v[60:63], v[164:167], v[180:183], v[60:63]
	v_mfma_f32_16x16x32_bf16 v[56:59], v[172:175], v[180:183], v[56:59]
	v_mfma_f32_16x16x32_bf16 v[52:55], v[164:167], v[188:191], v[52:55]
	v_mfma_f32_16x16x32_bf16 v[44:47], v[172:175], v[188:191], v[44:47]
	v_mfma_f32_16x16x32_bf16 v[36:39], v[164:167], v[196:199], v[36:39]
	v_mfma_f32_16x16x32_bf16 v[28:31], v[172:175], v[196:199], v[28:31]
	v_mfma_f32_16x16x32_bf16 v[20:23], v[164:167], v[204:207], v[20:23]
	v_mfma_f32_16x16x32_bf16 v[12:15], v[172:175], v[204:207], v[12:15]
	v_mfma_f32_16x16x32_bf16 v[60:63], v[168:171], v[184:187], v[60:63]
	v_mfma_f32_16x16x32_bf16 v[56:59], v[176:179], v[184:187], v[56:59]
	v_mfma_f32_16x16x32_bf16 v[52:55], v[168:171], v[192:195], v[52:55]
	v_mfma_f32_16x16x32_bf16 v[44:47], v[176:179], v[192:195], v[44:47]
	v_mfma_f32_16x16x32_bf16 v[36:39], v[168:171], v[200:203], v[36:39]
	v_mfma_f32_16x16x32_bf16 v[28:31], v[176:179], v[200:203], v[28:31]
	v_mfma_f32_16x16x32_bf16 v[20:23], v[168:171], v[208:211], v[20:23]
	v_mfma_f32_16x16x32_bf16 v[12:15], v[176:179], v[208:211], v[12:15]
	s_setprio 0
	s_barrier
	s_add_u32 s76, s36, 0x40000
	s_addc_u32 s77, s37, 0
	s_add_i32 s75, s78, s57
	v_lshl_add_u64 v[164:165], s[76:77], 0, v[128:129]
	s_mov_b32 m0, s75
	s_nop 0
	global_load_lds_dwordx4 v[164:165], off
	v_lshl_add_u64 v[164:165], s[76:77], 0, v[130:131]
	s_add_i32 m0, s75, 0x2000
	s_nop 0
	global_load_lds_dwordx4 v[164:165], off
	s_waitcnt vmcnt(6)
	s_barrier
	s_setprio 1
	v_mfma_f32_16x16x32_bf16 v[48:51], v[212:215], v[180:183], v[48:51]
	v_mfma_f32_16x16x32_bf16 v[40:43], v[220:223], v[180:183], v[40:43]
	v_mfma_f32_16x16x32_bf16 v[32:35], v[212:215], v[188:191], v[32:35]
	v_mfma_f32_16x16x32_bf16 v[24:27], v[220:223], v[188:191], v[24:27]
	v_mfma_f32_16x16x32_bf16 v[16:19], v[212:215], v[196:199], v[16:19]
	v_mfma_f32_16x16x32_bf16 v[8:11], v[220:223], v[196:199], v[8:11]
	v_mfma_f32_16x16x32_bf16 v[4:7], v[212:215], v[204:207], v[4:7]
	v_mfma_f32_16x16x32_bf16 v[0:3], v[220:223], v[204:207], v[0:3]
	v_mfma_f32_16x16x32_bf16 v[48:51], v[216:219], v[184:187], v[48:51]
	v_mfma_f32_16x16x32_bf16 v[40:43], v[224:227], v[184:187], v[40:43]
	v_mfma_f32_16x16x32_bf16 v[32:35], v[216:219], v[192:195], v[32:35]
	v_mfma_f32_16x16x32_bf16 v[24:27], v[224:227], v[192:195], v[24:27]
	v_mfma_f32_16x16x32_bf16 v[16:19], v[216:219], v[200:203], v[16:19]
	v_mfma_f32_16x16x32_bf16 v[8:11], v[224:227], v[200:203], v[8:11]
	v_mfma_f32_16x16x32_bf16 v[4:7], v[216:219], v[208:211], v[4:7]
	v_mfma_f32_16x16x32_bf16 v[0:3], v[224:227], v[208:211], v[0:3]
	s_setprio 0
	s_add_i32 s75, 0, 0x18000
	v_add_u32_e32 v176, s75, v161
	s_barrier
	ds_read_b128 v[164:167], v176
	ds_read_b128 v[168:171], v176 offset:1024
	ds_read_b128 v[172:175], v176 offset:2048
	ds_read_b128 v[176:179], v176 offset:3072
	s_add_u32 s38, s38, 0x40000
	s_addc_u32 s39, s39, 0
	s_mov_b32 m0, s61
	v_lshl_add_u64 v[212:213], s[38:39], 0, v[134:135]
	ds_read_b128 v[180:183], v163 offset:32768
	ds_read_b128 v[184:187], v163 offset:33792
	ds_read_b128 v[188:191], v163 offset:34816
	ds_read_b128 v[192:195], v163 offset:35840
	ds_read_b128 v[196:199], v163 offset:36864
	ds_read_b128 v[200:203], v163 offset:37888
	ds_read_b128 v[204:207], v163 offset:38912
	ds_read_b128 v[208:211], v163 offset:39936
	global_load_lds_dwordx4 v[212:213], off
	v_lshl_add_u64 v[212:213], s[38:39], 0, v[132:133]
	s_mov_b32 m0, s62
	s_nop 0
	global_load_lds_dwordx4 v[212:213], off
	s_waitcnt lgkmcnt(8)
	s_barrier
	s_waitcnt lgkmcnt(0)
	s_setprio 1
	v_mfma_f32_16x16x32_bf16 v[124:127], v[164:167], v[180:183], v[124:127]
	v_mfma_f32_16x16x32_bf16 v[120:123], v[172:175], v[180:183], v[120:123]
	v_mfma_f32_16x16x32_bf16 v[116:119], v[164:167], v[188:191], v[116:119]
	v_mfma_f32_16x16x32_bf16 v[108:111], v[172:175], v[188:191], v[108:111]
	v_mfma_f32_16x16x32_bf16 v[100:103], v[164:167], v[196:199], v[100:103]
	v_mfma_f32_16x16x32_bf16 v[92:95], v[172:175], v[196:199], v[92:95]
	v_mfma_f32_16x16x32_bf16 v[84:87], v[164:167], v[204:207], v[84:87]
	v_mfma_f32_16x16x32_bf16 v[76:79], v[172:175], v[204:207], v[76:79]
	v_mfma_f32_16x16x32_bf16 v[124:127], v[168:171], v[184:187], v[124:127]
	v_mfma_f32_16x16x32_bf16 v[120:123], v[176:179], v[184:187], v[120:123]
	v_mfma_f32_16x16x32_bf16 v[116:119], v[168:171], v[192:195], v[116:119]
	v_mfma_f32_16x16x32_bf16 v[108:111], v[176:179], v[192:195], v[108:111]
	v_mfma_f32_16x16x32_bf16 v[100:103], v[168:171], v[200:203], v[100:103]
	v_mfma_f32_16x16x32_bf16 v[92:95], v[176:179], v[200:203], v[92:95]
	v_mfma_f32_16x16x32_bf16 v[84:87], v[168:171], v[208:211], v[84:87]
	v_mfma_f32_16x16x32_bf16 v[76:79], v[176:179], v[208:211], v[76:79]
	s_setprio 0
	s_barrier
	s_add_i32 s38, 0, 0x1c000
	s_add_i32 s39, s75, s57
	v_add_u32_e32 v224, s38, v161
	v_lshl_add_u64 v[140:141], v[140:141], 0, s[14:15]
	s_mov_b32 m0, s39
	ds_read_b128 v[212:215], v224
	ds_read_b128 v[216:219], v224 offset:1024
	ds_read_b128 v[220:223], v224 offset:2048
	ds_read_b128 v[224:227], v224 offset:3072
	global_load_lds_dwordx4 v[140:141], off
	v_lshl_add_u64 v[140:141], v[228:229], 0, s[14:15]
	s_add_i32 m0, s39, 0x2000
	s_nop 0
	global_load_lds_dwordx4 v[140:141], off
	s_barrier
	s_waitcnt lgkmcnt(0)
	s_setprio 1
	v_mfma_f32_16x16x32_bf16 v[112:115], v[212:215], v[180:183], v[112:115]
	v_mfma_f32_16x16x32_bf16 v[104:107], v[220:223], v[180:183], v[104:107]
	v_mfma_f32_16x16x32_bf16 v[96:99], v[212:215], v[188:191], v[96:99]
	v_mfma_f32_16x16x32_bf16 v[88:91], v[220:223], v[188:191], v[88:91]
	v_mfma_f32_16x16x32_bf16 v[80:83], v[212:215], v[196:199], v[80:83]
	v_mfma_f32_16x16x32_bf16 v[72:75], v[220:223], v[196:199], v[72:75]
	v_mfma_f32_16x16x32_bf16 v[68:71], v[212:215], v[204:207], v[68:71]
	v_mfma_f32_16x16x32_bf16 v[64:67], v[220:223], v[204:207], v[64:67]
	v_mfma_f32_16x16x32_bf16 v[112:115], v[216:219], v[184:187], v[112:115]
	v_mfma_f32_16x16x32_bf16 v[104:107], v[224:227], v[184:187], v[104:107]
	v_mfma_f32_16x16x32_bf16 v[96:99], v[216:219], v[192:195], v[96:99]
	v_mfma_f32_16x16x32_bf16 v[88:91], v[224:227], v[192:195], v[88:91]
	v_mfma_f32_16x16x32_bf16 v[80:83], v[216:219], v[200:203], v[80:83]
	v_mfma_f32_16x16x32_bf16 v[72:75], v[224:227], v[200:203], v[72:75]
	v_mfma_f32_16x16x32_bf16 v[68:71], v[216:219], v[208:211], v[68:71]
	v_mfma_f32_16x16x32_bf16 v[64:67], v[224:227], v[208:211], v[64:67]
	s_setprio 0
	s_mov_b32 m0, s63
	v_lshl_add_u64 v[140:141], v[230:231], 0, s[14:15]
	s_barrier
	ds_read_b128 v[180:183], v163 offset:49152
	ds_read_b128 v[184:187], v163 offset:50176
	ds_read_b128 v[188:191], v163 offset:51200
	ds_read_b128 v[192:195], v163 offset:52224
	ds_read_b128 v[196:199], v163 offset:53248
	ds_read_b128 v[200:203], v163 offset:54272
	ds_read_b128 v[204:207], v163 offset:55296
	ds_read_b128 v[208:211], v163 offset:56320
	global_load_lds_dwordx4 v[140:141], off
	v_lshl_add_u64 v[140:141], v[232:233], 0, s[14:15]
	s_mov_b32 m0, s64
	s_nop 0
	global_load_lds_dwordx4 v[140:141], off
	s_barrier
	s_waitcnt lgkmcnt(0)
	s_setprio 1
	v_mfma_f32_16x16x32_bf16 v[60:63], v[164:167], v[180:183], v[60:63]
	v_mfma_f32_16x16x32_bf16 v[56:59], v[172:175], v[180:183], v[56:59]
	v_mfma_f32_16x16x32_bf16 v[52:55], v[164:167], v[188:191], v[52:55]
	v_mfma_f32_16x16x32_bf16 v[44:47], v[172:175], v[188:191], v[44:47]
	v_mfma_f32_16x16x32_bf16 v[36:39], v[164:167], v[196:199], v[36:39]
	v_mfma_f32_16x16x32_bf16 v[28:31], v[172:175], v[196:199], v[28:31]
	v_mfma_f32_16x16x32_bf16 v[20:23], v[164:167], v[204:207], v[20:23]
	v_mfma_f32_16x16x32_bf16 v[12:15], v[172:175], v[204:207], v[12:15]
	v_mfma_f32_16x16x32_bf16 v[60:63], v[168:171], v[184:187], v[60:63]
	v_mfma_f32_16x16x32_bf16 v[56:59], v[176:179], v[184:187], v[56:59]
	v_mfma_f32_16x16x32_bf16 v[52:55], v[168:171], v[192:195], v[52:55]
	v_mfma_f32_16x16x32_bf16 v[44:47], v[176:179], v[192:195], v[44:47]
	v_mfma_f32_16x16x32_bf16 v[36:39], v[168:171], v[200:203], v[36:39]
	v_mfma_f32_16x16x32_bf16 v[28:31], v[176:179], v[200:203], v[28:31]
	v_mfma_f32_16x16x32_bf16 v[20:23], v[168:171], v[208:211], v[20:23]
	v_mfma_f32_16x16x32_bf16 v[12:15], v[176:179], v[208:211], v[12:15]
	s_setprio 0
	s_barrier
	s_add_u32 s36, s36, 0x40080
	s_addc_u32 s37, s37, 0
	s_add_i32 s38, s38, s57
	v_lshl_add_u64 v[140:141], s[36:37], 0, v[128:129]
	s_mov_b32 m0, s38
	s_nop 0
	global_load_lds_dwordx4 v[140:141], off
	v_lshl_add_u64 v[140:141], s[36:37], 0, v[130:131]
	s_add_i32 m0, s38, 0x2000
	s_nop 0
	global_load_lds_dwordx4 v[140:141], off
	s_waitcnt vmcnt(6)
	s_barrier
	s_setprio 1
	v_mfma_f32_16x16x32_bf16 v[48:51], v[212:215], v[180:183], v[48:51]
	v_mfma_f32_16x16x32_bf16 v[40:43], v[220:223], v[180:183], v[40:43]
	v_mfma_f32_16x16x32_bf16 v[32:35], v[212:215], v[188:191], v[32:35]
	v_mfma_f32_16x16x32_bf16 v[24:27], v[220:223], v[188:191], v[24:27]
	v_mfma_f32_16x16x32_bf16 v[16:19], v[212:215], v[196:199], v[16:19]
	v_mfma_f32_16x16x32_bf16 v[8:11], v[220:223], v[196:199], v[8:11]
	v_mfma_f32_16x16x32_bf16 v[4:7], v[212:215], v[204:207], v[4:7]
	v_mfma_f32_16x16x32_bf16 v[0:3], v[220:223], v[204:207], v[0:3]
	v_mfma_f32_16x16x32_bf16 v[48:51], v[216:219], v[184:187], v[48:51]
	v_mfma_f32_16x16x32_bf16 v[40:43], v[224:227], v[184:187], v[40:43]
	v_mfma_f32_16x16x32_bf16 v[32:35], v[216:219], v[192:195], v[32:35]
	v_mfma_f32_16x16x32_bf16 v[24:27], v[224:227], v[192:195], v[24:27]
	v_mfma_f32_16x16x32_bf16 v[16:19], v[216:219], v[200:203], v[16:19]
	v_mfma_f32_16x16x32_bf16 v[8:11], v[224:227], v[200:203], v[8:11]
	v_mfma_f32_16x16x32_bf16 v[4:7], v[216:219], v[208:211], v[4:7]
	v_mfma_f32_16x16x32_bf16 v[0:3], v[224:227], v[208:211], v[0:3]
	s_setprio 0
	s_add_i32 s74, s74, 2
	s_add_u32 s34, s34, 0x100
	s_addc_u32 s35, s35, 0
	s_add_u32 s71, s71, 0x100
	s_addc_u32 s73, s73, 0
	s_cmp_gt_u32 s74, 13
	s_barrier
	s_cbranch_scc0 .LBB0_189
	v_lshl_or_b32 v140, s68, 8, v162
	v_lshl_add_u32 v166, s30, 8, v159
	v_ashrrev_i32_e32 v141, 31, v140
	v_lshl_add_u64 v[140:141], v[140:141], 1, s[20:21]
	v_mad_i64_i32 v[164:165], s[34:35], v166, s52, 0
	v_lshl_add_u64 v[164:165], v[164:165], 1, v[140:141]
	v_cvt_pk_bf16_f32 v124, v124, v125
	v_cvt_pk_bf16_f32 v125, v126, v127
	v_cvt_pk_bf16_f32 v126, v120, v121
	v_cvt_pk_bf16_f32 v127, v122, v123
	global_store_dwordx4 v[164:165], v[124:127], off
	v_cvt_pk_bf16_f32 v112, v112, v113
	v_cvt_pk_bf16_f32 v113, v114, v115
	v_cvt_pk_bf16_f32 v114, v104, v105
	v_or_b32_e32 v104, 16, v166
	v_mad_i64_i32 v[104:105], s[34:35], v104, s52, 0
	v_cvt_pk_bf16_f32 v115, v106, v107
	global_store_dwordx4 v[164:165], v[112:115], off offset:256
	s_and_b64 vcc, exec, s[4:5]
	s_mov_b32 s68, s22
	v_lshl_add_u64 v[112:113], v[104:105], 1, v[140:141]
	v_cvt_pk_bf16_f32 v104, v116, v117
	v_cvt_pk_bf16_f32 v105, v118, v119
	v_cvt_pk_bf16_f32 v106, v108, v109
	v_cvt_pk_bf16_f32 v107, v110, v111
	global_store_dwordx4 v[112:113], v[104:107], off
	v_cvt_pk_bf16_f32 v96, v96, v97
	v_cvt_pk_bf16_f32 v97, v98, v99
	v_cvt_pk_bf16_f32 v98, v88, v89
	v_or_b32_e32 v88, 32, v166
	v_mad_i64_i32 v[88:89], s[34:35], v88, s52, 0
	v_cvt_pk_bf16_f32 v99, v90, v91
	global_store_dwordx4 v[112:113], v[96:99], off offset:256
	s_mov_b32 s30, s24
	s_mov_b64 s[36:37], s[28:29]
	v_lshl_add_u64 v[96:97], v[88:89], 1, v[140:141]
	v_cvt_pk_bf16_f32 v88, v100, v101
	v_cvt_pk_bf16_f32 v89, v102, v103
	v_cvt_pk_bf16_f32 v90, v92, v93
	v_cvt_pk_bf16_f32 v91, v94, v95
	global_store_dwordx4 v[96:97], v[88:91], off
	v_cvt_pk_bf16_f32 v80, v80, v81
	v_cvt_pk_bf16_f32 v81, v82, v83
	v_cvt_pk_bf16_f32 v82, v72, v73
	v_or_b32_e32 v72, 48, v166
	v_mad_i64_i32 v[72:73], s[34:35], v72, s52, 0
	v_cvt_pk_bf16_f32 v83, v74, v75
	global_store_dwordx4 v[96:97], v[80:83], off offset:256
	s_nop 1
	v_lshl_add_u64 v[80:81], v[72:73], 1, v[140:141]
	v_cvt_pk_bf16_f32 v72, v84, v85
	v_cvt_pk_bf16_f32 v73, v86, v87
	v_cvt_pk_bf16_f32 v74, v76, v77
	v_cvt_pk_bf16_f32 v75, v78, v79
	global_store_dwordx4 v[80:81], v[72:75], off
	v_cvt_pk_bf16_f32 v68, v68, v69
	v_cvt_pk_bf16_f32 v69, v70, v71
	v_cvt_pk_bf16_f32 v70, v64, v65
	v_add_u32_e32 v64, 0x80, v166
	v_mad_i64_i32 v[64:65], s[34:35], v64, s52, 0
	v_lshl_add_u64 v[64:65], v[64:65], 1, v[140:141]
	v_cvt_pk_bf16_f32 v71, v66, v67
	global_store_dwordx4 v[80:81], v[68:71], off offset:256
	v_cvt_pk_bf16_f32 v60, v60, v61
	v_cvt_pk_bf16_f32 v61, v62, v63
	v_cvt_pk_bf16_f32 v62, v56, v57
	v_cvt_pk_bf16_f32 v63, v58, v59
	global_store_dwordx4 v[64:65], v[60:63], off
	v_cvt_pk_bf16_f32 v48, v48, v49
	v_cvt_pk_bf16_f32 v49, v50, v51
	v_cvt_pk_bf16_f32 v50, v40, v41
	v_add_u32_e32 v40, 0x90, v166
	v_mad_i64_i32 v[40:41], s[34:35], v40, s52, 0
	v_cvt_pk_bf16_f32 v51, v42, v43
	global_store_dwordx4 v[64:65], v[48:51], off offset:256
	s_nop 1
	v_lshl_add_u64 v[48:49], v[40:41], 1, v[140:141]
	v_cvt_pk_bf16_f32 v40, v52, v53
	v_cvt_pk_bf16_f32 v41, v54, v55
	v_cvt_pk_bf16_f32 v42, v44, v45
	v_cvt_pk_bf16_f32 v43, v46, v47
	global_store_dwordx4 v[48:49], v[40:43], off
	v_cvt_pk_bf16_f32 v32, v32, v33
	v_cvt_pk_bf16_f32 v33, v34, v35
	v_cvt_pk_bf16_f32 v34, v24, v25
	v_add_u32_e32 v24, 0xa0, v166
	v_mad_i64_i32 v[24:25], s[34:35], v24, s52, 0
	v_cvt_pk_bf16_f32 v35, v26, v27
	global_store_dwordx4 v[48:49], v[32:35], off offset:256
	s_nop 1
	v_lshl_add_u64 v[32:33], v[24:25], 1, v[140:141]
	v_cvt_pk_bf16_f32 v24, v36, v37
	v_cvt_pk_bf16_f32 v25, v38, v39
	v_cvt_pk_bf16_f32 v26, v28, v29
	v_cvt_pk_bf16_f32 v27, v30, v31
	global_store_dwordx4 v[32:33], v[24:27], off
	v_cvt_pk_bf16_f32 v16, v16, v17
	v_cvt_pk_bf16_f32 v17, v18, v19
	v_cvt_pk_bf16_f32 v18, v8, v9
	v_add_u32_e32 v8, 0xb0, v166
	v_mad_i64_i32 v[8:9], s[34:35], v8, s52, 0
	v_cvt_pk_bf16_f32 v19, v10, v11
	global_store_dwordx4 v[32:33], v[16:19], off offset:256
	s_mov_b64 s[34:35], s[26:27]
	s_nop 0
	v_lshl_add_u64 v[16:17], v[8:9], 1, v[140:141]
	v_cvt_pk_bf16_f32 v8, v20, v21
	v_cvt_pk_bf16_f32 v9, v22, v23
	v_cvt_pk_bf16_f32 v10, v12, v13
	v_cvt_pk_bf16_f32 v11, v14, v15
	global_store_dwordx4 v[16:17], v[8:11], off
	v_cvt_pk_bf16_f32 v4, v4, v5
	v_cvt_pk_bf16_f32 v5, v6, v7
	v_cvt_pk_bf16_f32 v6, v0, v1
	v_cvt_pk_bf16_f32 v7, v2, v3
	global_store_dwordx4 v[16:17], v[4:7], off offset:256
	s_cbranch_vccz .LBB0_186
	s_waitcnt vmcnt(0)
	s_cmpk_gt_u32 s56, 0xff
	s_cbranch_scc1 .LBB0_174
	s_barrier
	s_branch .LBB0_174

.LBB0_203:
	ds_read_b128 v[144:147], v153
	ds_read_b128 v[156:159], v153 offset:1024
	ds_read_b128 v[162:165], v153 offset:2048
	ds_read_b128 v[166:169], v153 offset:3072
	s_add_u32 s26, s24, 0xfffc0080
	s_addc_u32 s27, s25, -1
	s_cmp_eq_u32 s54, 12
	s_cselect_b32 s29, s5, s27
	s_cselect_b32 s28, s17, s26
	s_cselect_b32 s27, s15, s53
	s_cselect_b32 s26, s23, s52
	v_lshl_add_u64 v[148:149], s[24:25], 0, v[136:137]
	s_add_i32 m0, s36, 0xc000
	ds_read_b128 v[170:173], v154
	ds_read_b128 v[174:177], v154 offset:1024
	ds_read_b128 v[178:181], v154 offset:2048
	ds_read_b128 v[182:185], v154 offset:3072
	ds_read_b128 v[186:189], v154 offset:4096
	ds_read_b128 v[190:193], v154 offset:5120
	ds_read_b128 v[194:197], v154 offset:6144
	ds_read_b128 v[198:201], v154 offset:7168
	global_load_lds_dwordx4 v[148:149], off
	v_lshl_add_u64 v[148:149], s[24:25], 0, v[138:139]
	s_add_i32 m0, s36, 0xe000
	s_nop 0
	global_load_lds_dwordx4 v[148:149], off
	s_waitcnt lgkmcnt(8)
	s_barrier
	s_waitcnt lgkmcnt(0)
	s_setprio 1
	v_mfma_f32_16x16x32_bf16 v[124:127], v[144:147], v[170:173], v[124:127]
	v_mfma_f32_16x16x32_bf16 v[120:123], v[162:165], v[170:173], v[120:123]
	v_mfma_f32_16x16x32_bf16 v[108:111], v[144:147], v[178:181], v[108:111]
	v_mfma_f32_16x16x32_bf16 v[104:107], v[162:165], v[178:181], v[104:107]
	v_mfma_f32_16x16x32_bf16 v[92:95], v[144:147], v[186:189], v[92:95]
	v_mfma_f32_16x16x32_bf16 v[88:91], v[162:165], v[186:189], v[88:91]
	v_mfma_f32_16x16x32_bf16 v[76:79], v[144:147], v[194:197], v[76:79]
	v_mfma_f32_16x16x32_bf16 v[72:75], v[162:165], v[194:197], v[72:75]
	v_mfma_f32_16x16x32_bf16 v[124:127], v[156:159], v[174:177], v[124:127]
	v_mfma_f32_16x16x32_bf16 v[120:123], v[166:169], v[174:177], v[120:123]
	v_mfma_f32_16x16x32_bf16 v[108:111], v[156:159], v[182:185], v[108:111]
	v_mfma_f32_16x16x32_bf16 v[104:107], v[166:169], v[182:185], v[104:107]
	v_mfma_f32_16x16x32_bf16 v[92:95], v[156:159], v[190:193], v[92:95]
	v_mfma_f32_16x16x32_bf16 v[88:91], v[166:169], v[190:193], v[88:91]
	v_mfma_f32_16x16x32_bf16 v[76:79], v[156:159], v[198:201], v[76:79]
	v_mfma_f32_16x16x32_bf16 v[72:75], v[166:169], v[198:201], v[72:75]
	s_setprio 0
	s_barrier
	s_add_i32 s55, s48, s35
	v_lshl_add_u64 v[148:149], s[26:27], 0, v[130:131]
	s_mov_b32 m0, s55
	ds_read_b128 v[202:205], v155
	ds_read_b128 v[206:209], v155 offset:1024
	ds_read_b128 v[210:213], v155 offset:2048
	ds_read_b128 v[214:217], v155 offset:3072
	global_load_lds_dwordx4 v[148:149], off
	v_lshl_add_u64 v[218:219], s[26:27], 0, v[134:135]
	s_add_i32 m0, s55, 0x2000
	s_nop 0
	global_load_lds_dwordx4 v[218:219], off
	s_barrier
	s_waitcnt lgkmcnt(0)
	s_setprio 1
	v_mfma_f32_16x16x32_bf16 v[116:119], v[202:205], v[170:173], v[116:119]
	v_mfma_f32_16x16x32_bf16 v[112:115], v[210:213], v[170:173], v[112:115]
	v_mfma_f32_16x16x32_bf16 v[100:103], v[202:205], v[178:181], v[100:103]
	v_mfma_f32_16x16x32_bf16 v[96:99], v[210:213], v[178:181], v[96:99]
	v_mfma_f32_16x16x32_bf16 v[84:87], v[202:205], v[186:189], v[84:87]
	v_mfma_f32_16x16x32_bf16 v[80:83], v[210:213], v[186:189], v[80:83]
	v_mfma_f32_16x16x32_bf16 v[68:71], v[202:205], v[194:197], v[68:71]
	v_mfma_f32_16x16x32_bf16 v[64:67], v[210:213], v[194:197], v[64:67]
	v_mfma_f32_16x16x32_bf16 v[116:119], v[206:209], v[174:177], v[116:119]
	v_mfma_f32_16x16x32_bf16 v[112:115], v[214:217], v[174:177], v[112:115]
	v_mfma_f32_16x16x32_bf16 v[100:103], v[206:209], v[182:185], v[100:103]
	v_mfma_f32_16x16x32_bf16 v[96:99], v[214:217], v[182:185], v[96:99]
	v_mfma_f32_16x16x32_bf16 v[84:87], v[206:209], v[190:193], v[84:87]
	v_mfma_f32_16x16x32_bf16 v[80:83], v[214:217], v[190:193], v[80:83]
	v_mfma_f32_16x16x32_bf16 v[68:71], v[206:209], v[198:201], v[68:71]
	v_mfma_f32_16x16x32_bf16 v[64:67], v[214:217], v[198:201], v[64:67]
	s_setprio 0
	s_mov_b32 m0, s36
	v_lshl_add_u64 v[220:221], s[28:29], 0, v[128:129]
	s_barrier
	ds_read_b128 v[170:173], v154 offset:16384
	ds_read_b128 v[174:177], v154 offset:17408
	ds_read_b128 v[178:181], v154 offset:18432
	ds_read_b128 v[182:185], v154 offset:19456
	ds_read_b128 v[186:189], v154 offset:20480
	ds_read_b128 v[190:193], v154 offset:21504
	ds_read_b128 v[194:197], v154 offset:22528
	ds_read_b128 v[198:201], v154 offset:23552
	global_load_lds_dwordx4 v[220:221], off
	v_lshl_add_u64 v[222:223], s[28:29], 0, v[132:133]
	s_mov_b32 m0, s37
	s_nop 0
	global_load_lds_dwordx4 v[222:223], off
	s_barrier
	s_waitcnt lgkmcnt(0)
	s_setprio 1
	v_mfma_f32_16x16x32_bf16 v[60:63], v[144:147], v[170:173], v[60:63]
	v_mfma_f32_16x16x32_bf16 v[56:59], v[162:165], v[170:173], v[56:59]
	v_mfma_f32_16x16x32_bf16 v[44:47], v[144:147], v[178:181], v[44:47]
	v_mfma_f32_16x16x32_bf16 v[40:43], v[162:165], v[178:181], v[40:43]
	v_mfma_f32_16x16x32_bf16 v[28:31], v[144:147], v[186:189], v[28:31]
	v_mfma_f32_16x16x32_bf16 v[24:27], v[162:165], v[186:189], v[24:27]
	v_mfma_f32_16x16x32_bf16 v[12:15], v[144:147], v[194:197], v[12:15]
	v_mfma_f32_16x16x32_bf16 v[8:11], v[162:165], v[194:197], v[8:11]
	v_mfma_f32_16x16x32_bf16 v[60:63], v[156:159], v[174:177], v[60:63]
	v_mfma_f32_16x16x32_bf16 v[56:59], v[166:169], v[174:177], v[56:59]
	v_mfma_f32_16x16x32_bf16 v[44:47], v[156:159], v[182:185], v[44:47]
	v_mfma_f32_16x16x32_bf16 v[40:43], v[166:169], v[182:185], v[40:43]
	v_mfma_f32_16x16x32_bf16 v[28:31], v[156:159], v[190:193], v[28:31]
	v_mfma_f32_16x16x32_bf16 v[24:27], v[166:169], v[190:193], v[24:27]
	v_mfma_f32_16x16x32_bf16 v[12:15], v[156:159], v[198:201], v[12:15]
	v_mfma_f32_16x16x32_bf16 v[8:11], v[166:169], v[198:201], v[8:11]
	s_setprio 0
	s_barrier
	s_add_u32 s56, s26, 0x40000
	s_addc_u32 s57, s27, 0
	s_add_i32 s55, s49, s35
	v_lshl_add_u64 v[144:145], s[56:57], 0, v[130:131]
	s_mov_b32 m0, s55
	s_nop 0
	global_load_lds_dwordx4 v[144:145], off
	v_lshl_add_u64 v[144:145], s[56:57], 0, v[134:135]
	s_add_i32 m0, s55, 0x2000
	s_nop 0
	global_load_lds_dwordx4 v[144:145], off
	s_waitcnt vmcnt(6)
	s_barrier
	s_setprio 1
	v_mfma_f32_16x16x32_bf16 v[52:55], v[202:205], v[170:173], v[52:55]
	v_mfma_f32_16x16x32_bf16 v[48:51], v[210:213], v[170:173], v[48:51]
	v_mfma_f32_16x16x32_bf16 v[36:39], v[202:205], v[178:181], v[36:39]
	v_mfma_f32_16x16x32_bf16 v[32:35], v[210:213], v[178:181], v[32:35]
	v_mfma_f32_16x16x32_bf16 v[20:23], v[202:205], v[186:189], v[20:23]
	v_mfma_f32_16x16x32_bf16 v[16:19], v[210:213], v[186:189], v[16:19]
	v_mfma_f32_16x16x32_bf16 v[4:7], v[202:205], v[194:197], v[4:7]
	v_mfma_f32_16x16x32_bf16 v[0:3], v[210:213], v[194:197], v[0:3]
	v_mfma_f32_16x16x32_bf16 v[52:55], v[206:209], v[174:177], v[52:55]
	v_mfma_f32_16x16x32_bf16 v[48:51], v[214:217], v[174:177], v[48:51]
	v_mfma_f32_16x16x32_bf16 v[36:39], v[206:209], v[182:185], v[36:39]
	v_mfma_f32_16x16x32_bf16 v[32:35], v[214:217], v[182:185], v[32:35]
	v_mfma_f32_16x16x32_bf16 v[20:23], v[206:209], v[190:193], v[20:23]
	v_mfma_f32_16x16x32_bf16 v[16:19], v[214:217], v[190:193], v[16:19]
	v_mfma_f32_16x16x32_bf16 v[4:7], v[206:209], v[198:201], v[4:7]
	v_mfma_f32_16x16x32_bf16 v[0:3], v[214:217], v[198:201], v[0:3]
	s_setprio 0
	s_add_i32 s55, 0, 0x18000
	v_add_u32_e32 v161, s55, v151
	s_barrier
	ds_read_b128 v[144:147], v161
	ds_read_b128 v[156:159], v161 offset:1024
	ds_read_b128 v[162:165], v161 offset:2048
	ds_read_b128 v[166:169], v161 offset:3072
	s_add_u32 s28, s28, 0x40000
	s_addc_u32 s29, s29, 0
	s_mov_b32 m0, s38
	v_lshl_add_u64 v[202:203], s[28:29], 0, v[128:129]
	ds_read_b128 v[170:173], v154 offset:32768
	ds_read_b128 v[174:177], v154 offset:33792
	ds_read_b128 v[178:181], v154 offset:34816
	ds_read_b128 v[182:185], v154 offset:35840
	ds_read_b128 v[186:189], v154 offset:36864
	ds_read_b128 v[190:193], v154 offset:37888
	ds_read_b128 v[194:197], v154 offset:38912
	ds_read_b128 v[198:201], v154 offset:39936
	global_load_lds_dwordx4 v[202:203], off
	v_lshl_add_u64 v[202:203], s[28:29], 0, v[132:133]
	s_mov_b32 m0, s39
	s_nop 0
	global_load_lds_dwordx4 v[202:203], off
	s_waitcnt lgkmcnt(8)
	s_barrier
	s_waitcnt lgkmcnt(0)
	s_setprio 1
	v_mfma_f32_16x16x32_bf16 v[124:127], v[144:147], v[170:173], v[124:127]
	v_mfma_f32_16x16x32_bf16 v[120:123], v[162:165], v[170:173], v[120:123]
	v_mfma_f32_16x16x32_bf16 v[108:111], v[144:147], v[178:181], v[108:111]
	v_mfma_f32_16x16x32_bf16 v[104:107], v[162:165], v[178:181], v[104:107]
	v_mfma_f32_16x16x32_bf16 v[92:95], v[144:147], v[186:189], v[92:95]
	v_mfma_f32_16x16x32_bf16 v[88:91], v[162:165], v[186:189], v[88:91]
	v_mfma_f32_16x16x32_bf16 v[76:79], v[144:147], v[194:197], v[76:79]
	v_mfma_f32_16x16x32_bf16 v[72:75], v[162:165], v[194:197], v[72:75]
	v_mfma_f32_16x16x32_bf16 v[124:127], v[156:159], v[174:177], v[124:127]
	v_mfma_f32_16x16x32_bf16 v[120:123], v[166:169], v[174:177], v[120:123]
	v_mfma_f32_16x16x32_bf16 v[108:111], v[156:159], v[182:185], v[108:111]
	v_mfma_f32_16x16x32_bf16 v[104:107], v[166:169], v[182:185], v[104:107]
	v_mfma_f32_16x16x32_bf16 v[92:95], v[156:159], v[190:193], v[92:95]
	v_mfma_f32_16x16x32_bf16 v[88:91], v[166:169], v[190:193], v[88:91]
	v_mfma_f32_16x16x32_bf16 v[76:79], v[156:159], v[198:201], v[76:79]
	v_mfma_f32_16x16x32_bf16 v[72:75], v[166:169], v[198:201], v[72:75]
	s_setprio 0
	s_barrier
	s_add_i32 s28, 0, 0x1c000
	s_add_i32 s29, s55, s35
	v_add_u32_e32 v161, s28, v151
	v_lshl_add_u64 v[148:149], v[148:149], 0, s[12:13]
	s_mov_b32 m0, s29
	ds_read_b128 v[202:205], v161
	ds_read_b128 v[206:209], v161 offset:1024
	ds_read_b128 v[210:213], v161 offset:2048
	ds_read_b128 v[214:217], v161 offset:3072
	global_load_lds_dwordx4 v[148:149], off
	v_lshl_add_u64 v[148:149], v[218:219], 0, s[12:13]
	s_add_i32 m0, s29, 0x2000
	s_nop 0
	global_load_lds_dwordx4 v[148:149], off
	s_barrier
	s_waitcnt lgkmcnt(0)
	s_setprio 1
	v_mfma_f32_16x16x32_bf16 v[116:119], v[202:205], v[170:173], v[116:119]
	v_mfma_f32_16x16x32_bf16 v[112:115], v[210:213], v[170:173], v[112:115]
	v_mfma_f32_16x16x32_bf16 v[100:103], v[202:205], v[178:181], v[100:103]
	v_mfma_f32_16x16x32_bf16 v[96:99], v[210:213], v[178:181], v[96:99]
	v_mfma_f32_16x16x32_bf16 v[84:87], v[202:205], v[186:189], v[84:87]
	v_mfma_f32_16x16x32_bf16 v[80:83], v[210:213], v[186:189], v[80:83]
	v_mfma_f32_16x16x32_bf16 v[68:71], v[202:205], v[194:197], v[68:71]
	v_mfma_f32_16x16x32_bf16 v[64:67], v[210:213], v[194:197], v[64:67]
	v_mfma_f32_16x16x32_bf16 v[116:119], v[206:209], v[174:177], v[116:119]
	v_mfma_f32_16x16x32_bf16 v[112:115], v[214:217], v[174:177], v[112:115]
	v_mfma_f32_16x16x32_bf16 v[100:103], v[206:209], v[182:185], v[100:103]
	v_mfma_f32_16x16x32_bf16 v[96:99], v[214:217], v[182:185], v[96:99]
	v_mfma_f32_16x16x32_bf16 v[84:87], v[206:209], v[190:193], v[84:87]
	v_mfma_f32_16x16x32_bf16 v[80:83], v[214:217], v[190:193], v[80:83]
	v_mfma_f32_16x16x32_bf16 v[68:71], v[206:209], v[198:201], v[68:71]
	v_mfma_f32_16x16x32_bf16 v[64:67], v[214:217], v[198:201], v[64:67]
	s_setprio 0
	s_mov_b32 m0, s44
	v_lshl_add_u64 v[148:149], v[220:221], 0, s[12:13]
	s_barrier
	ds_read_b128 v[170:173], v154 offset:49152
	ds_read_b128 v[174:177], v154 offset:50176
	ds_read_b128 v[178:181], v154 offset:51200
	ds_read_b128 v[182:185], v154 offset:52224
	ds_read_b128 v[186:189], v154 offset:53248
	ds_read_b128 v[190:193], v154 offset:54272
	ds_read_b128 v[194:197], v154 offset:55296
	ds_read_b128 v[198:201], v154 offset:56320
	global_load_lds_dwordx4 v[148:149], off
	v_lshl_add_u64 v[148:149], v[222:223], 0, s[12:13]
	s_mov_b32 m0, s46
	s_nop 0
	global_load_lds_dwordx4 v[148:149], off
	s_barrier
	s_waitcnt lgkmcnt(0)
	s_setprio 1
	v_mfma_f32_16x16x32_bf16 v[60:63], v[144:147], v[170:173], v[60:63]
	v_mfma_f32_16x16x32_bf16 v[56:59], v[162:165], v[170:173], v[56:59]
	v_mfma_f32_16x16x32_bf16 v[44:47], v[144:147], v[178:181], v[44:47]
	v_mfma_f32_16x16x32_bf16 v[40:43], v[162:165], v[178:181], v[40:43]
	v_mfma_f32_16x16x32_bf16 v[28:31], v[144:147], v[186:189], v[28:31]
	v_mfma_f32_16x16x32_bf16 v[24:27], v[162:165], v[186:189], v[24:27]
	v_mfma_f32_16x16x32_bf16 v[12:15], v[144:147], v[194:197], v[12:15]
	v_mfma_f32_16x16x32_bf16 v[8:11], v[162:165], v[194:197], v[8:11]
	v_mfma_f32_16x16x32_bf16 v[60:63], v[156:159], v[174:177], v[60:63]
	v_mfma_f32_16x16x32_bf16 v[56:59], v[166:169], v[174:177], v[56:59]
	v_mfma_f32_16x16x32_bf16 v[44:47], v[156:159], v[182:185], v[44:47]
	v_mfma_f32_16x16x32_bf16 v[40:43], v[166:169], v[182:185], v[40:43]
	v_mfma_f32_16x16x32_bf16 v[28:31], v[156:159], v[190:193], v[28:31]
	v_mfma_f32_16x16x32_bf16 v[24:27], v[166:169], v[190:193], v[24:27]
	v_mfma_f32_16x16x32_bf16 v[12:15], v[156:159], v[198:201], v[12:15]
	v_mfma_f32_16x16x32_bf16 v[8:11], v[166:169], v[198:201], v[8:11]
	s_setprio 0
	s_barrier
	s_add_u32 s26, s26, 0x40080
	s_addc_u32 s27, s27, 0
	s_add_i32 s28, s28, s35
	v_lshl_add_u64 v[144:145], s[26:27], 0, v[130:131]
	s_mov_b32 m0, s28
	s_nop 0
	global_load_lds_dwordx4 v[144:145], off
	v_lshl_add_u64 v[144:145], s[26:27], 0, v[134:135]
	s_add_i32 m0, s28, 0x2000
	s_nop 0
	global_load_lds_dwordx4 v[144:145], off
	s_waitcnt vmcnt(6)
	s_barrier
	s_setprio 1
	v_mfma_f32_16x16x32_bf16 v[52:55], v[202:205], v[170:173], v[52:55]
	v_mfma_f32_16x16x32_bf16 v[48:51], v[210:213], v[170:173], v[48:51]
	v_mfma_f32_16x16x32_bf16 v[36:39], v[202:205], v[178:181], v[36:39]
	v_mfma_f32_16x16x32_bf16 v[32:35], v[210:213], v[178:181], v[32:35]
	v_mfma_f32_16x16x32_bf16 v[20:23], v[202:205], v[186:189], v[20:23]
	v_mfma_f32_16x16x32_bf16 v[16:19], v[210:213], v[186:189], v[16:19]
	v_mfma_f32_16x16x32_bf16 v[4:7], v[202:205], v[194:197], v[4:7]
	v_mfma_f32_16x16x32_bf16 v[0:3], v[210:213], v[194:197], v[0:3]
	v_mfma_f32_16x16x32_bf16 v[52:55], v[206:209], v[174:177], v[52:55]
	v_mfma_f32_16x16x32_bf16 v[48:51], v[214:217], v[174:177], v[48:51]
	v_mfma_f32_16x16x32_bf16 v[36:39], v[206:209], v[182:185], v[36:39]
	v_mfma_f32_16x16x32_bf16 v[32:35], v[214:217], v[182:185], v[32:35]
	v_mfma_f32_16x16x32_bf16 v[20:23], v[206:209], v[190:193], v[20:23]
	v_mfma_f32_16x16x32_bf16 v[16:19], v[214:217], v[190:193], v[16:19]
	v_mfma_f32_16x16x32_bf16 v[4:7], v[206:209], v[198:201], v[4:7]
	v_mfma_f32_16x16x32_bf16 v[0:3], v[214:217], v[198:201], v[0:3]
	s_setprio 0
	s_add_i32 s54, s54, 2
	s_add_u32 s24, s24, 0x100
	s_addc_u32 s25, s25, 0
	s_add_u32 s52, s52, 0x100
	s_addc_u32 s53, s53, 0
	s_cmp_gt_u32 s54, 13
	s_barrier
	s_cbranch_scc0 .LBB0_203
	v_lshl_or_b32 v148, s22, 8, v152
	v_cmp_lt_i32_e32 vcc, s50, v148
	s_and_saveexec_b64 s[22:23], vcc
	s_cbranch_execz .LBB0_206
	v_mul_f32_e32 v149, 0x3d372713, v126
	v_mul_f32_e32 v145, 0x3d372713, v120
	v_mul_f32_e32 v149, v126, v149
	v_mul_f32_e32 v156, 0x3d372713, v122
	v_mul_f32_e32 v145, v120, v145
	v_mul_f32_e32 v146, 0x3d372713, v125
	v_fma_f32 v149, v126, v149, v126
	v_mul_f32_e32 v156, v122, v156
	v_fma_f32 v145, v120, v145, v120
	v_mul_f32_e32 v146, v125, v146
	v_mul_f32_e32 v149, 0xc0135761, v149
	v_fma_f32 v156, v122, v156, v122
	v_mul_f32_e32 v145, 0xc0135761, v145
	v_fma_f32 v146, v125, v146, v125
	v_exp_f32_e32 v149, v149
	v_mul_f32_e32 v156, 0xc0135761, v156
	v_exp_f32_e32 v145, v145
	v_mul_f32_e32 v146, 0xc0135761, v146
	v_exp_f32_e32 v157, v156
	v_exp_f32_e32 v147, v146
	v_add_f32_e32 v149, 1.0, v149
	v_add_f32_e32 v145, 1.0, v145
	v_rcp_f32_e32 v156, v149
	v_add_f32_e32 v149, 1.0, v157
	v_mul_f32_e32 v157, 0x3d372713, v127
	v_mul_f32_e32 v144, 0x3d372713, v124
	v_rcp_f32_e32 v146, v145
	v_add_f32_e32 v145, 1.0, v147
	v_mul_f32_e32 v147, 0x3d372713, v121
	v_mul_f32_e32 v157, v127, v157
	v_mul_f32_e32 v158, 0x3d372713, v123
	v_mul_f32_e32 v144, v124, v144
	v_mul_f32_e32 v147, v121, v147
	v_fma_f32 v157, v127, v157, v127
	v_mul_f32_e32 v158, v123, v158
	v_fma_f32 v144, v124, v144, v124
	v_fma_f32 v147, v121, v147, v121
	v_mul_f32_e32 v157, 0xc0135761, v157
	v_fma_f32 v158, v123, v158, v123
	v_mul_f32_e32 v144, 0xc0135761, v144
	v_mul_f32_e32 v147, 0xc0135761, v147
	v_exp_f32_e32 v157, v157
	v_mul_f32_e32 v158, 0xc0135761, v158
	v_exp_f32_e32 v144, v144
	v_exp_f32_e32 v147, v147
	v_exp_f32_e32 v159, v158
	v_rcp_f32_e32 v158, v149
	v_add_f32_e32 v149, 1.0, v157
	v_add_f32_e32 v144, 1.0, v144
	v_add_f32_e32 v147, 1.0, v147
	v_rcp_f32_e32 v157, v149
	v_add_f32_e32 v149, 1.0, v159
	v_rcp_f32_e32 v144, v144
	v_rcp_f32_e32 v145, v145
	v_rcp_f32_e32 v159, v149
	v_rcp_f32_e32 v147, v147
	v_pk_mul_f32 v[126:127], v[126:127], v[156:157]
	v_pk_mul_f32 v[124:125], v[124:125], v[144:145]
	v_pk_mul_f32 v[122:123], v[122:123], v[158:159]
	v_pk_mul_f32 v[120:121], v[120:121], v[146:147]

.LBB0_321:
	ds_read_b128 v[144:147], v157
	ds_read_b128 v[148:151], v157 offset:1024
	ds_read_b128 v[164:167], v157 offset:2048
	ds_read_b128 v[168:171], v157 offset:3072
	s_add_u32 s4, s8, 0x100
	s_addc_u32 s5, s9, 0
	s_cmp_eq_u32 s60, 2
	s_cselect_b32 s11, s29, s5
	s_cselect_b32 s10, s28, s4
	s_cselect_b32 s7, s31, s37
	s_cselect_b32 s6, s30, s35
	v_lshl_add_u64 v[152:153], s[8:9], 0, v[136:137]
	s_add_i32 m0, s46, 0xc000
	ds_read_b128 v[172:175], v158
	ds_read_b128 v[176:179], v158 offset:1024
	ds_read_b128 v[180:183], v158 offset:2048
	ds_read_b128 v[184:187], v158 offset:3072
	ds_read_b128 v[188:191], v158 offset:4096
	ds_read_b128 v[192:195], v158 offset:5120
	ds_read_b128 v[196:199], v158 offset:6144
	ds_read_b128 v[200:203], v158 offset:7168
	global_load_lds_dwordx4 v[152:153], off
	v_lshl_add_u64 v[152:153], s[8:9], 0, v[138:139]
	s_add_i32 m0, s46, 0xe000
	s_nop 0
	global_load_lds_dwordx4 v[152:153], off
	s_waitcnt lgkmcnt(8)
	s_barrier
	s_waitcnt lgkmcnt(0)
	s_setprio 1
	v_mfma_f32_16x16x32_bf16 v[124:127], v[144:147], v[172:175], v[124:127]
	v_mfma_f32_16x16x32_bf16 v[120:123], v[164:167], v[172:175], v[120:123]
	v_mfma_f32_16x16x32_bf16 v[116:119], v[144:147], v[180:183], v[116:119]
	v_mfma_f32_16x16x32_bf16 v[112:115], v[164:167], v[180:183], v[112:115]
	v_mfma_f32_16x16x32_bf16 v[108:111], v[144:147], v[188:191], v[108:111]
	v_mfma_f32_16x16x32_bf16 v[104:107], v[164:167], v[188:191], v[104:107]
	v_mfma_f32_16x16x32_bf16 v[100:103], v[144:147], v[196:199], v[100:103]
	v_mfma_f32_16x16x32_bf16 v[96:99], v[164:167], v[196:199], v[96:99]
	v_mfma_f32_16x16x32_bf16 v[124:127], v[148:151], v[176:179], v[124:127]
	v_mfma_f32_16x16x32_bf16 v[120:123], v[168:171], v[176:179], v[120:123]
	v_mfma_f32_16x16x32_bf16 v[116:119], v[148:151], v[184:187], v[116:119]
	v_mfma_f32_16x16x32_bf16 v[112:115], v[168:171], v[184:187], v[112:115]
	v_mfma_f32_16x16x32_bf16 v[108:111], v[148:151], v[192:195], v[108:111]
	v_mfma_f32_16x16x32_bf16 v[104:107], v[168:171], v[192:195], v[104:107]
	v_mfma_f32_16x16x32_bf16 v[100:103], v[148:151], v[200:203], v[100:103]
	v_mfma_f32_16x16x32_bf16 v[96:99], v[168:171], v[200:203], v[96:99]
	s_setprio 0
	s_barrier
	s_add_i32 s8, s54, s44
	v_lshl_add_u64 v[152:153], s[6:7], 0, v[130:131]
	s_mov_b32 m0, s8
	ds_read_b128 v[204:207], v159
	ds_read_b128 v[208:211], v159 offset:1024
	ds_read_b128 v[212:215], v159 offset:2048
	ds_read_b128 v[216:219], v159 offset:3072
	global_load_lds_dwordx4 v[152:153], off
	v_lshl_add_u64 v[220:221], s[6:7], 0, v[134:135]
	s_add_i32 m0, s8, 0x2000
	s_nop 0
	global_load_lds_dwordx4 v[220:221], off
	s_barrier
	s_waitcnt lgkmcnt(0)
	s_setprio 1
	v_mfma_f32_16x16x32_bf16 v[60:63], v[204:207], v[172:175], v[60:63]
	v_mfma_f32_16x16x32_bf16 v[56:59], v[212:215], v[172:175], v[56:59]
	v_mfma_f32_16x16x32_bf16 v[52:55], v[204:207], v[180:183], v[52:55]
	v_mfma_f32_16x16x32_bf16 v[48:51], v[212:215], v[180:183], v[48:51]
	v_mfma_f32_16x16x32_bf16 v[44:47], v[204:207], v[188:191], v[44:47]
	v_mfma_f32_16x16x32_bf16 v[40:43], v[212:215], v[188:191], v[40:43]
	v_mfma_f32_16x16x32_bf16 v[36:39], v[204:207], v[196:199], v[36:39]
	v_mfma_f32_16x16x32_bf16 v[32:35], v[212:215], v[196:199], v[32:35]
	v_mfma_f32_16x16x32_bf16 v[60:63], v[208:211], v[176:179], v[60:63]
	v_mfma_f32_16x16x32_bf16 v[56:59], v[216:219], v[176:179], v[56:59]
	v_mfma_f32_16x16x32_bf16 v[52:55], v[208:211], v[184:187], v[52:55]
	v_mfma_f32_16x16x32_bf16 v[48:51], v[216:219], v[184:187], v[48:51]
	v_mfma_f32_16x16x32_bf16 v[44:47], v[208:211], v[192:195], v[44:47]
	v_mfma_f32_16x16x32_bf16 v[40:43], v[216:219], v[192:195], v[40:43]
	v_mfma_f32_16x16x32_bf16 v[36:39], v[208:211], v[200:203], v[36:39]
	v_mfma_f32_16x16x32_bf16 v[32:35], v[216:219], v[200:203], v[32:35]
	s_setprio 0
	s_mov_b32 m0, s46
	v_lshl_add_u64 v[222:223], s[10:11], 0, v[128:129]
	s_barrier
	ds_read_b128 v[172:175], v158 offset:16384
	ds_read_b128 v[176:179], v158 offset:17408
	ds_read_b128 v[180:183], v158 offset:18432
	ds_read_b128 v[184:187], v158 offset:19456
	ds_read_b128 v[188:191], v158 offset:20480
	ds_read_b128 v[192:195], v158 offset:21504
	ds_read_b128 v[196:199], v158 offset:22528
	ds_read_b128 v[200:203], v158 offset:23552
	global_load_lds_dwordx4 v[222:223], off
	v_lshl_add_u64 v[224:225], s[10:11], 0, v[132:133]
	s_mov_b32 m0, s47
	s_nop 0
	global_load_lds_dwordx4 v[224:225], off
	s_barrier
	s_waitcnt lgkmcnt(0)
	s_setprio 1
	v_mfma_f32_16x16x32_bf16 v[92:95], v[144:147], v[172:175], v[92:95]
	v_mfma_f32_16x16x32_bf16 v[88:91], v[164:167], v[172:175], v[88:91]
	v_mfma_f32_16x16x32_bf16 v[84:87], v[144:147], v[180:183], v[84:87]
	v_mfma_f32_16x16x32_bf16 v[80:83], v[164:167], v[180:183], v[80:83]
	v_mfma_f32_16x16x32_bf16 v[76:79], v[144:147], v[188:191], v[76:79]
	v_mfma_f32_16x16x32_bf16 v[72:75], v[164:167], v[188:191], v[72:75]
	v_mfma_f32_16x16x32_bf16 v[68:71], v[144:147], v[196:199], v[68:71]
	v_mfma_f32_16x16x32_bf16 v[64:67], v[164:167], v[196:199], v[64:67]
	v_mfma_f32_16x16x32_bf16 v[92:95], v[148:151], v[176:179], v[92:95]
	v_mfma_f32_16x16x32_bf16 v[88:91], v[168:171], v[176:179], v[88:91]
	v_mfma_f32_16x16x32_bf16 v[84:87], v[148:151], v[184:187], v[84:87]
	v_mfma_f32_16x16x32_bf16 v[80:83], v[168:171], v[184:187], v[80:83]
	v_mfma_f32_16x16x32_bf16 v[76:79], v[148:151], v[192:195], v[76:79]
	v_mfma_f32_16x16x32_bf16 v[72:75], v[168:171], v[192:195], v[72:75]
	v_mfma_f32_16x16x32_bf16 v[68:71], v[148:151], v[200:203], v[68:71]
	v_mfma_f32_16x16x32_bf16 v[64:67], v[168:171], v[200:203], v[64:67]
	s_setprio 0
	s_barrier
	s_add_u32 s8, s6, 0x18000
	s_addc_u32 s9, s7, 0
	s_add_i32 s61, s55, s44
	v_lshl_add_u64 v[144:145], s[8:9], 0, v[130:131]
	s_mov_b32 m0, s61
	s_nop 0
	global_load_lds_dwordx4 v[144:145], off
	v_lshl_add_u64 v[144:145], s[8:9], 0, v[134:135]
	s_add_i32 m0, s61, 0x2000
	s_nop 0
	global_load_lds_dwordx4 v[144:145], off
	s_waitcnt vmcnt(6)
	s_barrier
	s_setprio 1
	v_mfma_f32_16x16x32_bf16 v[28:31], v[204:207], v[172:175], v[28:31]
	v_mfma_f32_16x16x32_bf16 v[24:27], v[212:215], v[172:175], v[24:27]
	v_mfma_f32_16x16x32_bf16 v[20:23], v[204:207], v[180:183], v[20:23]
	v_mfma_f32_16x16x32_bf16 v[16:19], v[212:215], v[180:183], v[16:19]
	v_mfma_f32_16x16x32_bf16 v[12:15], v[204:207], v[188:191], v[12:15]
	v_mfma_f32_16x16x32_bf16 v[8:11], v[212:215], v[188:191], v[8:11]
	v_mfma_f32_16x16x32_bf16 v[4:7], v[204:207], v[196:199], v[4:7]
	v_mfma_f32_16x16x32_bf16 v[0:3], v[212:215], v[196:199], v[0:3]
	v_mfma_f32_16x16x32_bf16 v[28:31], v[208:211], v[176:179], v[28:31]
	v_mfma_f32_16x16x32_bf16 v[24:27], v[216:219], v[176:179], v[24:27]
	v_mfma_f32_16x16x32_bf16 v[20:23], v[208:211], v[184:187], v[20:23]
	v_mfma_f32_16x16x32_bf16 v[16:19], v[216:219], v[184:187], v[16:19]
	v_mfma_f32_16x16x32_bf16 v[12:15], v[208:211], v[192:195], v[12:15]
	v_mfma_f32_16x16x32_bf16 v[8:11], v[216:219], v[192:195], v[8:11]
	v_mfma_f32_16x16x32_bf16 v[4:7], v[208:211], v[200:203], v[4:7]
	v_mfma_f32_16x16x32_bf16 v[0:3], v[216:219], v[200:203], v[0:3]
	s_setprio 0
	s_add_i32 s61, 0, 0x18000
	v_add_u32_e32 v163, s61, v155
	s_barrier
	ds_read_b128 v[144:147], v163
	ds_read_b128 v[148:151], v163 offset:1024
	ds_read_b128 v[164:167], v163 offset:2048
	ds_read_b128 v[168:171], v163 offset:3072
	s_add_u32 s8, s10, 0x18000
	s_addc_u32 s9, s11, 0
	s_mov_b32 m0, s48
	v_lshl_add_u64 v[204:205], s[8:9], 0, v[128:129]
	ds_read_b128 v[172:175], v158 offset:32768
	ds_read_b128 v[176:179], v158 offset:33792
	ds_read_b128 v[180:183], v158 offset:34816
	ds_read_b128 v[184:187], v158 offset:35840
	ds_read_b128 v[188:191], v158 offset:36864
	ds_read_b128 v[192:195], v158 offset:37888
	ds_read_b128 v[196:199], v158 offset:38912
	ds_read_b128 v[200:203], v158 offset:39936
	global_load_lds_dwordx4 v[204:205], off
	v_lshl_add_u64 v[204:205], s[8:9], 0, v[132:133]
	s_mov_b32 m0, s49
	s_nop 0
	global_load_lds_dwordx4 v[204:205], off
	s_waitcnt lgkmcnt(8)
	s_barrier
	s_waitcnt lgkmcnt(0)
	s_setprio 1
	v_mfma_f32_16x16x32_bf16 v[124:127], v[144:147], v[172:175], v[124:127]
	v_mfma_f32_16x16x32_bf16 v[120:123], v[164:167], v[172:175], v[120:123]
	v_mfma_f32_16x16x32_bf16 v[116:119], v[144:147], v[180:183], v[116:119]
	v_mfma_f32_16x16x32_bf16 v[112:115], v[164:167], v[180:183], v[112:115]
	v_mfma_f32_16x16x32_bf16 v[108:111], v[144:147], v[188:191], v[108:111]
	v_mfma_f32_16x16x32_bf16 v[104:107], v[164:167], v[188:191], v[104:107]
	v_mfma_f32_16x16x32_bf16 v[100:103], v[144:147], v[196:199], v[100:103]
	v_mfma_f32_16x16x32_bf16 v[96:99], v[164:167], v[196:199], v[96:99]
	v_mfma_f32_16x16x32_bf16 v[124:127], v[148:151], v[176:179], v[124:127]
	v_mfma_f32_16x16x32_bf16 v[120:123], v[168:171], v[176:179], v[120:123]
	v_mfma_f32_16x16x32_bf16 v[116:119], v[148:151], v[184:187], v[116:119]
	v_mfma_f32_16x16x32_bf16 v[112:115], v[168:171], v[184:187], v[112:115]
	v_mfma_f32_16x16x32_bf16 v[108:111], v[148:151], v[192:195], v[108:111]
	v_mfma_f32_16x16x32_bf16 v[104:107], v[168:171], v[192:195], v[104:107]
	v_mfma_f32_16x16x32_bf16 v[100:103], v[148:151], v[200:203], v[100:103]
	v_mfma_f32_16x16x32_bf16 v[96:99], v[168:171], v[200:203], v[96:99]
	s_setprio 0
	s_barrier
	s_add_i32 s8, 0, 0x1c000
	s_add_i32 s9, s61, s44
	v_add_u32_e32 v163, s8, v155
	v_lshl_add_u64 v[152:153], v[152:153], 0, s[26:27]
	s_mov_b32 m0, s9
	ds_read_b128 v[204:207], v163
	ds_read_b128 v[208:211], v163 offset:1024
	ds_read_b128 v[212:215], v163 offset:2048
	ds_read_b128 v[216:219], v163 offset:3072
	global_load_lds_dwordx4 v[152:153], off
	v_lshl_add_u64 v[152:153], v[220:221], 0, s[26:27]
	s_add_i32 m0, s9, 0x2000
	s_nop 0
	global_load_lds_dwordx4 v[152:153], off
	s_barrier
	s_waitcnt lgkmcnt(0)
	s_setprio 1
	v_mfma_f32_16x16x32_bf16 v[60:63], v[204:207], v[172:175], v[60:63]
	v_mfma_f32_16x16x32_bf16 v[56:59], v[212:215], v[172:175], v[56:59]
	v_mfma_f32_16x16x32_bf16 v[52:55], v[204:207], v[180:183], v[52:55]
	v_mfma_f32_16x16x32_bf16 v[48:51], v[212:215], v[180:183], v[48:51]
	v_mfma_f32_16x16x32_bf16 v[44:47], v[204:207], v[188:191], v[44:47]
	v_mfma_f32_16x16x32_bf16 v[40:43], v[212:215], v[188:191], v[40:43]
	v_mfma_f32_16x16x32_bf16 v[36:39], v[204:207], v[196:199], v[36:39]
	v_mfma_f32_16x16x32_bf16 v[32:35], v[212:215], v[196:199], v[32:35]
	v_mfma_f32_16x16x32_bf16 v[60:63], v[208:211], v[176:179], v[60:63]
	v_mfma_f32_16x16x32_bf16 v[56:59], v[216:219], v[176:179], v[56:59]
	v_mfma_f32_16x16x32_bf16 v[52:55], v[208:211], v[184:187], v[52:55]
	v_mfma_f32_16x16x32_bf16 v[48:51], v[216:219], v[184:187], v[48:51]
	v_mfma_f32_16x16x32_bf16 v[44:47], v[208:211], v[192:195], v[44:47]
	v_mfma_f32_16x16x32_bf16 v[40:43], v[216:219], v[192:195], v[40:43]
	v_mfma_f32_16x16x32_bf16 v[36:39], v[208:211], v[200:203], v[36:39]
	v_mfma_f32_16x16x32_bf16 v[32:35], v[216:219], v[200:203], v[32:35]
	s_setprio 0
	s_mov_b32 m0, s51
	v_lshl_add_u64 v[152:153], v[222:223], 0, s[26:27]
	s_barrier
	ds_read_b128 v[172:175], v158 offset:49152
	ds_read_b128 v[176:179], v158 offset:50176
	ds_read_b128 v[180:183], v158 offset:51200
	ds_read_b128 v[184:187], v158 offset:52224
	ds_read_b128 v[188:191], v158 offset:53248
	ds_read_b128 v[192:195], v158 offset:54272
	ds_read_b128 v[196:199], v158 offset:55296
	ds_read_b128 v[200:203], v158 offset:56320
	global_load_lds_dwordx4 v[152:153], off
	v_lshl_add_u64 v[152:153], v[224:225], 0, s[26:27]
	s_mov_b32 m0, s52
	s_nop 0
	global_load_lds_dwordx4 v[152:153], off
	s_barrier
	s_waitcnt lgkmcnt(0)
	s_setprio 1
	v_mfma_f32_16x16x32_bf16 v[92:95], v[144:147], v[172:175], v[92:95]
	v_mfma_f32_16x16x32_bf16 v[88:91], v[164:167], v[172:175], v[88:91]
	v_mfma_f32_16x16x32_bf16 v[84:87], v[144:147], v[180:183], v[84:87]
	v_mfma_f32_16x16x32_bf16 v[80:83], v[164:167], v[180:183], v[80:83]
	v_mfma_f32_16x16x32_bf16 v[76:79], v[144:147], v[188:191], v[76:79]
	v_mfma_f32_16x16x32_bf16 v[72:75], v[164:167], v[188:191], v[72:75]
	v_mfma_f32_16x16x32_bf16 v[68:71], v[144:147], v[196:199], v[68:71]
	v_mfma_f32_16x16x32_bf16 v[64:67], v[164:167], v[196:199], v[64:67]
	v_mfma_f32_16x16x32_bf16 v[92:95], v[148:151], v[176:179], v[92:95]
	v_mfma_f32_16x16x32_bf16 v[88:91], v[168:171], v[176:179], v[88:91]
	v_mfma_f32_16x16x32_bf16 v[84:87], v[148:151], v[184:187], v[84:87]
	v_mfma_f32_16x16x32_bf16 v[80:83], v[168:171], v[184:187], v[80:83]
	v_mfma_f32_16x16x32_bf16 v[76:79], v[148:151], v[192:195], v[76:79]
	v_mfma_f32_16x16x32_bf16 v[72:75], v[168:171], v[192:195], v[72:75]
	v_mfma_f32_16x16x32_bf16 v[68:71], v[148:151], v[200:203], v[68:71]
	v_mfma_f32_16x16x32_bf16 v[64:67], v[168:171], v[200:203], v[64:67]
	s_setprio 0
	s_barrier
	s_add_u32 s6, s6, 0x18080
	s_addc_u32 s7, s7, 0
	s_add_i32 s8, s8, s44
	v_lshl_add_u64 v[144:145], s[6:7], 0, v[130:131]
	s_mov_b32 m0, s8
	s_nop 0
	global_load_lds_dwordx4 v[144:145], off
	v_lshl_add_u64 v[144:145], s[6:7], 0, v[134:135]
	s_add_i32 m0, s8, 0x2000
	s_nop 0
	global_load_lds_dwordx4 v[144:145], off
	s_waitcnt vmcnt(6)
	s_barrier
	s_setprio 1
	v_mfma_f32_16x16x32_bf16 v[28:31], v[204:207], v[172:175], v[28:31]
	v_mfma_f32_16x16x32_bf16 v[24:27], v[212:215], v[172:175], v[24:27]
	v_mfma_f32_16x16x32_bf16 v[20:23], v[204:207], v[180:183], v[20:23]
	v_mfma_f32_16x16x32_bf16 v[16:19], v[212:215], v[180:183], v[16:19]
	v_mfma_f32_16x16x32_bf16 v[12:15], v[204:207], v[188:191], v[12:15]
	v_mfma_f32_16x16x32_bf16 v[8:11], v[212:215], v[188:191], v[8:11]
	v_mfma_f32_16x16x32_bf16 v[4:7], v[204:207], v[196:199], v[4:7]
	v_mfma_f32_16x16x32_bf16 v[0:3], v[212:215], v[196:199], v[0:3]
	v_mfma_f32_16x16x32_bf16 v[28:31], v[208:211], v[176:179], v[28:31]
	v_mfma_f32_16x16x32_bf16 v[24:27], v[216:219], v[176:179], v[24:27]
	v_mfma_f32_16x16x32_bf16 v[20:23], v[208:211], v[184:187], v[20:23]
	v_mfma_f32_16x16x32_bf16 v[16:19], v[216:219], v[184:187], v[16:19]
	v_mfma_f32_16x16x32_bf16 v[12:15], v[208:211], v[192:195], v[12:15]
	v_mfma_f32_16x16x32_bf16 v[8:11], v[216:219], v[192:195], v[8:11]
	v_mfma_f32_16x16x32_bf16 v[4:7], v[208:211], v[200:203], v[4:7]
	v_mfma_f32_16x16x32_bf16 v[0:3], v[216:219], v[200:203], v[0:3]
	s_setprio 0
	s_add_i32 s60, s60, 2
	s_add_u32 s35, s35, 0x100
	s_addc_u32 s37, s37, 0
	s_cmp_gt_u32 s60, 3
	s_mov_b64 s[8:9], s[4:5]
	s_barrier
	s_cbranch_scc0 .LBB0_321
	s_lshl_b32 s37, s34, 8
	s_ashr_i32 s6, s34, 1
	s_cmp_lt_i32 s6, 2
	s_cselect_b64 s[8:9], -1, 0
	s_cmp_gt_i32 s6, 1
	s_cselect_b64 s[34:35], -1, 0
	s_lshl_b32 s60, s6, 9
	s_add_i32 s61, s60, 0xfffffc00
	v_bitop3_b32 v144, s37, v161, v156 bitop3:0xc8
	v_or_b32_e32 v146, s61, v144
	v_or_b32_e32 v144, s60, v144
	v_mov_b32_e32 v145, 0
	s_cmp_lt_i32 s6, 4
	v_cndmask_b32_e64 v152, v146, v144, s[8:9]
	s_cselect_b64 s[4:5], -1, 0
	s_cmp_gt_i32 s6, 3
	v_ashrrev_i32_e32 v153, 31, v152
	v_mov_b32_e32 v144, v145
	s_cbranch_scc1 .LBB0_330
	s_and_b64 s[10:11], s[8:9], exec
	s_cselect_b32 s7, s21, s23
	s_cselect_b32 s10, s20, s22
	v_mov_b32_e32 v146, s10
	v_mov_b32_e32 v147, s7
	v_lshl_add_u64 v[146:147], v[152:153], 2, v[146:147]
	global_load_dword v144, v[146:147], off
	v_cndmask_b32_e64 v146, 0, 1, s[4:5]
	v_cmp_ne_u32_e64 s[10:11], 1, v146
	s_andn2_b64 vcc, exec, s[4:5]
	s_cbranch_vccz .LBB0_331

.LBB0_583:
	ds_read_b128 v[128:131], v164
	ds_read_b128 v[132:135], v164 offset:1024
	ds_read_b128 v[152:155], v164 offset:2048
	ds_read_b128 v[156:159], v164 offset:3072
	s_add_u32 s38, s36, 0xfffc0080
	s_addc_u32 s39, s37, -1
	s_cmp_eq_u32 s63, 12
	s_cselect_b32 s41, s9, s39
	s_cselect_b32 s40, s29, s38
	s_cselect_b32 s39, s27, s62
	s_cselect_b32 s38, s60, s61
	v_lshl_add_u64 v[200:201], s[36:37], 0, v[144:145]
	s_add_i32 m0, s50, 0xc000
	ds_read_b128 v[168:171], v165
	ds_read_b128 v[172:175], v165 offset:1024
	ds_read_b128 v[176:179], v165 offset:2048
	ds_read_b128 v[180:183], v165 offset:3072
	ds_read_b128 v[184:187], v165 offset:4096
	ds_read_b128 v[188:191], v165 offset:5120
	ds_read_b128 v[192:195], v165 offset:6144
	ds_read_b128 v[196:199], v165 offset:7168
	global_load_lds_dwordx4 v[200:201], off
	v_lshl_add_u64 v[200:201], s[36:37], 0, v[146:147]
	s_add_i32 m0, s50, 0xe000
	s_nop 0
	global_load_lds_dwordx4 v[200:201], off
	s_waitcnt lgkmcnt(8)
	s_barrier
	s_waitcnt lgkmcnt(0)
	s_setprio 1
	v_mfma_f32_16x16x32_bf16 v[120:123], v[128:131], v[168:171], v[120:123]
	v_mfma_f32_16x16x32_bf16 v[124:127], v[152:155], v[168:171], v[124:127]
	v_mfma_f32_16x16x32_bf16 v[104:107], v[128:131], v[176:179], v[104:107]
	v_mfma_f32_16x16x32_bf16 v[108:111], v[152:155], v[176:179], v[108:111]
	v_mfma_f32_16x16x32_bf16 v[88:91], v[128:131], v[184:187], v[88:91]
	v_mfma_f32_16x16x32_bf16 v[92:95], v[152:155], v[184:187], v[92:95]
	v_mfma_f32_16x16x32_bf16 v[72:75], v[128:131], v[192:195], v[72:75]
	v_mfma_f32_16x16x32_bf16 v[76:79], v[152:155], v[192:195], v[76:79]
	v_mfma_f32_16x16x32_bf16 v[120:123], v[132:135], v[172:175], v[120:123]
	v_mfma_f32_16x16x32_bf16 v[124:127], v[156:159], v[172:175], v[124:127]
	v_mfma_f32_16x16x32_bf16 v[104:107], v[132:135], v[180:183], v[104:107]
	v_mfma_f32_16x16x32_bf16 v[108:111], v[156:159], v[180:183], v[108:111]
	v_mfma_f32_16x16x32_bf16 v[88:91], v[132:135], v[188:191], v[88:91]
	v_mfma_f32_16x16x32_bf16 v[92:95], v[156:159], v[188:191], v[92:95]
	v_mfma_f32_16x16x32_bf16 v[72:75], v[132:135], v[196:199], v[72:75]
	v_mfma_f32_16x16x32_bf16 v[76:79], v[156:159], v[196:199], v[76:79]
	s_setprio 0
	s_barrier
	s_add_i32 s64, s57, s49
	v_lshl_add_u64 v[216:217], s[38:39], 0, v[138:139]
	s_mov_b32 m0, s64
	ds_read_b128 v[200:203], v166
	ds_read_b128 v[204:207], v166 offset:1024
	ds_read_b128 v[208:211], v166 offset:2048
	ds_read_b128 v[212:215], v166 offset:3072
	global_load_lds_dwordx4 v[216:217], off
	v_lshl_add_u64 v[218:219], s[38:39], 0, v[142:143]
	s_add_i32 m0, s64, 0x2000
	s_nop 0
	global_load_lds_dwordx4 v[218:219], off
	s_barrier
	s_waitcnt lgkmcnt(0)
	s_setprio 1
	v_mfma_f32_16x16x32_bf16 v[112:115], v[200:203], v[168:171], v[112:115]
	v_mfma_f32_16x16x32_bf16 v[116:119], v[208:211], v[168:171], v[116:119]
	v_mfma_f32_16x16x32_bf16 v[96:99], v[200:203], v[176:179], v[96:99]
	v_mfma_f32_16x16x32_bf16 v[100:103], v[208:211], v[176:179], v[100:103]
	v_mfma_f32_16x16x32_bf16 v[80:83], v[200:203], v[184:187], v[80:83]
	v_mfma_f32_16x16x32_bf16 v[84:87], v[208:211], v[184:187], v[84:87]
	v_mfma_f32_16x16x32_bf16 v[64:67], v[200:203], v[192:195], v[64:67]
	v_mfma_f32_16x16x32_bf16 v[68:71], v[208:211], v[192:195], v[68:71]
	v_mfma_f32_16x16x32_bf16 v[112:115], v[204:207], v[172:175], v[112:115]
	v_mfma_f32_16x16x32_bf16 v[116:119], v[212:215], v[172:175], v[116:119]
	v_mfma_f32_16x16x32_bf16 v[96:99], v[204:207], v[180:183], v[96:99]
	v_mfma_f32_16x16x32_bf16 v[100:103], v[212:215], v[180:183], v[100:103]
	v_mfma_f32_16x16x32_bf16 v[80:83], v[204:207], v[188:191], v[80:83]
	v_mfma_f32_16x16x32_bf16 v[84:87], v[212:215], v[188:191], v[84:87]
	v_mfma_f32_16x16x32_bf16 v[64:67], v[204:207], v[196:199], v[64:67]
	v_mfma_f32_16x16x32_bf16 v[68:71], v[212:215], v[196:199], v[68:71]
	s_setprio 0
	s_mov_b32 m0, s50
	v_lshl_add_u64 v[220:221], s[40:41], 0, v[136:137]
	s_barrier
	ds_read_b128 v[168:171], v165 offset:16384
	ds_read_b128 v[172:175], v165 offset:17408
	ds_read_b128 v[176:179], v165 offset:18432
	ds_read_b128 v[180:183], v165 offset:19456
	ds_read_b128 v[184:187], v165 offset:20480
	ds_read_b128 v[188:191], v165 offset:21504
	ds_read_b128 v[192:195], v165 offset:22528
	ds_read_b128 v[196:199], v165 offset:23552
	global_load_lds_dwordx4 v[220:221], off
	v_lshl_add_u64 v[222:223], s[40:41], 0, v[140:141]
	s_mov_b32 m0, s51
	s_nop 0
	global_load_lds_dwordx4 v[222:223], off
	s_barrier
	s_waitcnt lgkmcnt(0)
	s_setprio 1
	v_mfma_f32_16x16x32_bf16 v[56:59], v[128:131], v[168:171], v[56:59]
	v_mfma_f32_16x16x32_bf16 v[60:63], v[152:155], v[168:171], v[60:63]
	v_mfma_f32_16x16x32_bf16 v[40:43], v[128:131], v[176:179], v[40:43]
	v_mfma_f32_16x16x32_bf16 v[44:47], v[152:155], v[176:179], v[44:47]
	v_mfma_f32_16x16x32_bf16 v[24:27], v[128:131], v[184:187], v[24:27]
	v_mfma_f32_16x16x32_bf16 v[28:31], v[152:155], v[184:187], v[28:31]
	v_mfma_f32_16x16x32_bf16 v[8:11], v[128:131], v[192:195], v[8:11]
	v_mfma_f32_16x16x32_bf16 v[12:15], v[152:155], v[192:195], v[12:15]
	v_mfma_f32_16x16x32_bf16 v[56:59], v[132:135], v[172:175], v[56:59]
	v_mfma_f32_16x16x32_bf16 v[60:63], v[156:159], v[172:175], v[60:63]
	v_mfma_f32_16x16x32_bf16 v[40:43], v[132:135], v[180:183], v[40:43]
	v_mfma_f32_16x16x32_bf16 v[44:47], v[156:159], v[180:183], v[44:47]
	v_mfma_f32_16x16x32_bf16 v[24:27], v[132:135], v[188:191], v[24:27]
	v_mfma_f32_16x16x32_bf16 v[28:31], v[156:159], v[188:191], v[28:31]
	v_mfma_f32_16x16x32_bf16 v[8:11], v[132:135], v[196:199], v[8:11]
	v_mfma_f32_16x16x32_bf16 v[12:15], v[156:159], v[196:199], v[12:15]
	s_setprio 0
	s_barrier
	s_add_u32 s64, s38, 0x40000
	s_addc_u32 s65, s39, 0
	s_add_i32 s66, s58, s49
	v_lshl_add_u64 v[128:129], s[64:65], 0, v[138:139]
	s_mov_b32 m0, s66
	s_nop 0
	global_load_lds_dwordx4 v[128:129], off
	v_lshl_add_u64 v[128:129], s[64:65], 0, v[142:143]
	s_add_i32 m0, s66, 0x2000
	s_nop 0
	global_load_lds_dwordx4 v[128:129], off
	s_waitcnt vmcnt(6)
	s_barrier
	s_setprio 1
	v_mfma_f32_16x16x32_bf16 v[48:51], v[200:203], v[168:171], v[48:51]
	v_mfma_f32_16x16x32_bf16 v[52:55], v[208:211], v[168:171], v[52:55]
	v_mfma_f32_16x16x32_bf16 v[32:35], v[200:203], v[176:179], v[32:35]
	v_mfma_f32_16x16x32_bf16 v[36:39], v[208:211], v[176:179], v[36:39]
	v_mfma_f32_16x16x32_bf16 v[16:19], v[200:203], v[184:187], v[16:19]
	v_mfma_f32_16x16x32_bf16 v[20:23], v[208:211], v[184:187], v[20:23]
	v_mfma_f32_16x16x32_bf16 v[4:7], v[200:203], v[192:195], v[4:7]
	v_mfma_f32_16x16x32_bf16 v[0:3], v[208:211], v[192:195], v[0:3]
	v_mfma_f32_16x16x32_bf16 v[48:51], v[204:207], v[172:175], v[48:51]
	v_mfma_f32_16x16x32_bf16 v[52:55], v[212:215], v[172:175], v[52:55]
	v_mfma_f32_16x16x32_bf16 v[32:35], v[204:207], v[180:183], v[32:35]
	v_mfma_f32_16x16x32_bf16 v[36:39], v[212:215], v[180:183], v[36:39]
	v_mfma_f32_16x16x32_bf16 v[16:19], v[204:207], v[188:191], v[16:19]
	v_mfma_f32_16x16x32_bf16 v[20:23], v[212:215], v[188:191], v[20:23]
	v_mfma_f32_16x16x32_bf16 v[4:7], v[204:207], v[196:199], v[4:7]
	v_mfma_f32_16x16x32_bf16 v[0:3], v[212:215], v[196:199], v[0:3]
	s_setprio 0
	s_add_i32 s64, 0, 0x18000
	v_add_u32_e32 v156, s64, v162
	s_barrier
	ds_read_b128 v[128:131], v156
	ds_read_b128 v[132:135], v156 offset:1024
	ds_read_b128 v[152:155], v156 offset:2048
	ds_read_b128 v[156:159], v156 offset:3072
	s_add_u32 s40, s40, 0x40000
	s_addc_u32 s41, s41, 0
	s_mov_b32 m0, s52
	v_lshl_add_u64 v[200:201], s[40:41], 0, v[136:137]
	ds_read_b128 v[168:171], v165 offset:32768
	ds_read_b128 v[172:175], v165 offset:33792
	ds_read_b128 v[176:179], v165 offset:34816
	ds_read_b128 v[180:183], v165 offset:35840
	ds_read_b128 v[184:187], v165 offset:36864
	ds_read_b128 v[188:191], v165 offset:37888
	ds_read_b128 v[192:195], v165 offset:38912
	ds_read_b128 v[196:199], v165 offset:39936
	global_load_lds_dwordx4 v[200:201], off
	v_lshl_add_u64 v[200:201], s[40:41], 0, v[140:141]
	s_mov_b32 m0, s53
	s_nop 0
	global_load_lds_dwordx4 v[200:201], off
	s_waitcnt lgkmcnt(8)
	s_barrier
	s_waitcnt lgkmcnt(0)
	s_setprio 1
	v_mfma_f32_16x16x32_bf16 v[120:123], v[128:131], v[168:171], v[120:123]
	v_mfma_f32_16x16x32_bf16 v[124:127], v[152:155], v[168:171], v[124:127]
	v_mfma_f32_16x16x32_bf16 v[104:107], v[128:131], v[176:179], v[104:107]
	v_mfma_f32_16x16x32_bf16 v[108:111], v[152:155], v[176:179], v[108:111]
	v_mfma_f32_16x16x32_bf16 v[88:91], v[128:131], v[184:187], v[88:91]
	v_mfma_f32_16x16x32_bf16 v[92:95], v[152:155], v[184:187], v[92:95]
	v_mfma_f32_16x16x32_bf16 v[72:75], v[128:131], v[192:195], v[72:75]
	v_mfma_f32_16x16x32_bf16 v[76:79], v[152:155], v[192:195], v[76:79]
	v_mfma_f32_16x16x32_bf16 v[120:123], v[132:135], v[172:175], v[120:123]
	v_mfma_f32_16x16x32_bf16 v[124:127], v[156:159], v[172:175], v[124:127]
	v_mfma_f32_16x16x32_bf16 v[104:107], v[132:135], v[180:183], v[104:107]
	v_mfma_f32_16x16x32_bf16 v[108:111], v[156:159], v[180:183], v[108:111]
	v_mfma_f32_16x16x32_bf16 v[88:91], v[132:135], v[188:191], v[88:91]
	v_mfma_f32_16x16x32_bf16 v[92:95], v[156:159], v[188:191], v[92:95]
	v_mfma_f32_16x16x32_bf16 v[72:75], v[132:135], v[196:199], v[72:75]
	v_mfma_f32_16x16x32_bf16 v[76:79], v[156:159], v[196:199], v[76:79]
	s_setprio 0
	s_barrier
	s_add_i32 s40, 0, 0x1c000
	s_add_i32 s41, s64, s49
	v_add_u32_e32 v212, s40, v162
	v_lshl_add_u64 v[216:217], v[216:217], 0, s[22:23]
	s_mov_b32 m0, s41
	ds_read_b128 v[200:203], v212
	ds_read_b128 v[204:207], v212 offset:1024
	ds_read_b128 v[208:211], v212 offset:2048
	ds_read_b128 v[212:215], v212 offset:3072
	global_load_lds_dwordx4 v[216:217], off
	v_lshl_add_u64 v[216:217], v[218:219], 0, s[22:23]
	s_add_i32 m0, s41, 0x2000
	s_nop 0
	global_load_lds_dwordx4 v[216:217], off
	s_barrier
	s_waitcnt lgkmcnt(0)
	s_setprio 1
	v_mfma_f32_16x16x32_bf16 v[112:115], v[200:203], v[168:171], v[112:115]
	v_mfma_f32_16x16x32_bf16 v[116:119], v[208:211], v[168:171], v[116:119]
	v_mfma_f32_16x16x32_bf16 v[96:99], v[200:203], v[176:179], v[96:99]
	v_mfma_f32_16x16x32_bf16 v[100:103], v[208:211], v[176:179], v[100:103]
	v_mfma_f32_16x16x32_bf16 v[80:83], v[200:203], v[184:187], v[80:83]
	v_mfma_f32_16x16x32_bf16 v[84:87], v[208:211], v[184:187], v[84:87]
	v_mfma_f32_16x16x32_bf16 v[64:67], v[200:203], v[192:195], v[64:67]
	v_mfma_f32_16x16x32_bf16 v[68:71], v[208:211], v[192:195], v[68:71]
	v_mfma_f32_16x16x32_bf16 v[112:115], v[204:207], v[172:175], v[112:115]
	v_mfma_f32_16x16x32_bf16 v[116:119], v[212:215], v[172:175], v[116:119]
	v_mfma_f32_16x16x32_bf16 v[96:99], v[204:207], v[180:183], v[96:99]
	v_mfma_f32_16x16x32_bf16 v[100:103], v[212:215], v[180:183], v[100:103]
	v_mfma_f32_16x16x32_bf16 v[80:83], v[204:207], v[188:191], v[80:83]
	v_mfma_f32_16x16x32_bf16 v[84:87], v[212:215], v[188:191], v[84:87]
	v_mfma_f32_16x16x32_bf16 v[64:67], v[204:207], v[196:199], v[64:67]
	v_mfma_f32_16x16x32_bf16 v[68:71], v[212:215], v[196:199], v[68:71]
	s_setprio 0
	s_mov_b32 m0, s55
	v_lshl_add_u64 v[216:217], v[220:221], 0, s[22:23]
	s_barrier
	ds_read_b128 v[168:171], v165 offset:49152
	ds_read_b128 v[172:175], v165 offset:50176
	ds_read_b128 v[176:179], v165 offset:51200
	ds_read_b128 v[180:183], v165 offset:52224
	ds_read_b128 v[184:187], v165 offset:53248
	ds_read_b128 v[188:191], v165 offset:54272
	ds_read_b128 v[192:195], v165 offset:55296
	ds_read_b128 v[196:199], v165 offset:56320
	global_load_lds_dwordx4 v[216:217], off
	v_lshl_add_u64 v[216:217], v[222:223], 0, s[22:23]
	s_mov_b32 m0, s56
	s_nop 0
	global_load_lds_dwordx4 v[216:217], off
	s_barrier
	s_waitcnt lgkmcnt(0)
	s_setprio 1
	v_mfma_f32_16x16x32_bf16 v[56:59], v[128:131], v[168:171], v[56:59]
	v_mfma_f32_16x16x32_bf16 v[60:63], v[152:155], v[168:171], v[60:63]
	v_mfma_f32_16x16x32_bf16 v[40:43], v[128:131], v[176:179], v[40:43]
	v_mfma_f32_16x16x32_bf16 v[44:47], v[152:155], v[176:179], v[44:47]
	v_mfma_f32_16x16x32_bf16 v[24:27], v[128:131], v[184:187], v[24:27]
	v_mfma_f32_16x16x32_bf16 v[28:31], v[152:155], v[184:187], v[28:31]
	v_mfma_f32_16x16x32_bf16 v[8:11], v[128:131], v[192:195], v[8:11]
	v_mfma_f32_16x16x32_bf16 v[12:15], v[152:155], v[192:195], v[12:15]
	v_mfma_f32_16x16x32_bf16 v[56:59], v[132:135], v[172:175], v[56:59]
	v_mfma_f32_16x16x32_bf16 v[60:63], v[156:159], v[172:175], v[60:63]
	v_mfma_f32_16x16x32_bf16 v[40:43], v[132:135], v[180:183], v[40:43]
	v_mfma_f32_16x16x32_bf16 v[44:47], v[156:159], v[180:183], v[44:47]
	v_mfma_f32_16x16x32_bf16 v[24:27], v[132:135], v[188:191], v[24:27]
	v_mfma_f32_16x16x32_bf16 v[28:31], v[156:159], v[188:191], v[28:31]
	v_mfma_f32_16x16x32_bf16 v[8:11], v[132:135], v[196:199], v[8:11]
	v_mfma_f32_16x16x32_bf16 v[12:15], v[156:159], v[196:199], v[12:15]
	s_setprio 0
	s_barrier
	s_add_u32 s38, s38, 0x40080
	s_addc_u32 s39, s39, 0
	s_add_i32 s40, s40, s49
	v_lshl_add_u64 v[128:129], s[38:39], 0, v[138:139]
	s_mov_b32 m0, s40
	s_nop 0
	global_load_lds_dwordx4 v[128:129], off
	v_lshl_add_u64 v[128:129], s[38:39], 0, v[142:143]
	s_add_i32 m0, s40, 0x2000
	s_nop 0
	global_load_lds_dwordx4 v[128:129], off
	s_waitcnt vmcnt(6)
	s_barrier
	s_setprio 1
	v_mfma_f32_16x16x32_bf16 v[48:51], v[200:203], v[168:171], v[48:51]
	v_mfma_f32_16x16x32_bf16 v[52:55], v[208:211], v[168:171], v[52:55]
	v_mfma_f32_16x16x32_bf16 v[32:35], v[200:203], v[176:179], v[32:35]
	v_mfma_f32_16x16x32_bf16 v[36:39], v[208:211], v[176:179], v[36:39]
	v_mfma_f32_16x16x32_bf16 v[16:19], v[200:203], v[184:187], v[16:19]
	v_mfma_f32_16x16x32_bf16 v[20:23], v[208:211], v[184:187], v[20:23]
	v_mfma_f32_16x16x32_bf16 v[4:7], v[200:203], v[192:195], v[4:7]
	v_mfma_f32_16x16x32_bf16 v[0:3], v[208:211], v[192:195], v[0:3]
	v_mfma_f32_16x16x32_bf16 v[48:51], v[204:207], v[172:175], v[48:51]
	v_mfma_f32_16x16x32_bf16 v[52:55], v[212:215], v[172:175], v[52:55]
	v_mfma_f32_16x16x32_bf16 v[32:35], v[204:207], v[180:183], v[32:35]
	v_mfma_f32_16x16x32_bf16 v[36:39], v[212:215], v[180:183], v[36:39]
	v_mfma_f32_16x16x32_bf16 v[16:19], v[204:207], v[188:191], v[16:19]
	v_mfma_f32_16x16x32_bf16 v[20:23], v[212:215], v[188:191], v[20:23]
	v_mfma_f32_16x16x32_bf16 v[4:7], v[204:207], v[196:199], v[4:7]
	v_mfma_f32_16x16x32_bf16 v[0:3], v[212:215], v[196:199], v[0:3]
	s_setprio 0
	s_add_i32 s63, s63, 2
	s_add_u32 s36, s36, 0x100
	s_addc_u32 s37, s37, 0
	s_add_u32 s61, s61, 0x100
	s_addc_u32 s62, s62, 0
	s_cmp_gt_u32 s63, 13
	s_barrier
	s_cbranch_scc0 .LBB0_583
	v_lshl_add_u32 v152, s8, 8, v161
	v_lshl_or_b32 v153, s16, 8, v163
	s_lshl_b32 s36, s16, 2
	s_ashr_i32 s37, s36, 31
	s_lshl_b32 s16, s54, 2
	v_lshl_add_u32 v154, v152, 10, v153
	v_lshl_add_u32 v156, v152, 6, s16
	v_lshl_add_u32 v156, s36, 2, v156
	v_lshlrev_b32_e32 v155, 1, v154
	v_lshlrev_b32_e32 v154, 2, v154
	global_load_dwordx4 v[168:171], v154, s[14:15]
	global_load_dwordx4 v[172:175], v154, s[14:15] offset:16
	global_load_dwordx4 v[176:179], v154, s[14:15] offset:512
	global_load_dwordx4 v[180:183], v154, s[14:15] offset:528
	v_add_u32_e32 v154, 0x10000, v154
	global_load_dwordx4 v[184:187], v154, s[14:15]
	global_load_dwordx4 v[188:191], v154, s[14:15] offset:16
	global_load_dwordx4 v[192:195], v154, s[14:15] offset:512
	global_load_dwordx4 v[196:199], v154, s[14:15] offset:528
	v_add_u32_e32 v154, 0x10000, v154
	global_load_dwordx4 v[200:203], v154, s[14:15]
	global_load_dwordx4 v[204:207], v154, s[14:15] offset:16
	global_load_dwordx4 v[208:211], v154, s[14:15] offset:512
	global_load_dwordx4 v[212:215], v154, s[14:15] offset:528
	v_add_u32_e32 v154, 0x10000, v154
	global_load_dwordx4 v[216:219], v154, s[14:15]
	global_load_dwordx4 v[220:223], v154, s[14:15] offset:16
	global_load_dwordx4 v[128:131], v154, s[14:15] offset:512
	global_load_dwordx4 v[132:135], v154, s[14:15] offset:528
	v_add_u32_e32 v154, 0x50000, v154
	s_waitcnt vmcnt(12)
	v_pk_add_f32 v[120:121], v[120:121], v[168:169]
	v_pk_add_f32 v[122:123], v[122:123], v[170:171]
	v_pk_add_f32 v[124:125], v[124:125], v[172:173]
	v_pk_add_f32 v[126:127], v[126:127], v[174:175]
	v_cvt_pk_bf16_f32 v168, v120, v121
	v_cvt_pk_bf16_f32 v169, v122, v123
	v_cvt_pk_bf16_f32 v170, v124, v125
	v_cvt_pk_bf16_f32 v171, v126, v127
	v_pk_mul_f32 v[172:173], v[120:121], v[120:121]
	global_store_dwordx4 v155, v[168:171], s[18:19]
	v_pk_fma_f32 v[172:173], v[122:123], v[122:123], v[172:173]
	v_pk_fma_f32 v[172:173], v[124:125], v[124:125], v[172:173]
	v_pk_fma_f32 v[172:173], v[126:127], v[126:127], v[172:173]
	v_pk_add_f32 v[112:113], v[112:113], v[176:177]
	v_pk_add_f32 v[114:115], v[114:115], v[178:179]
	v_pk_add_f32 v[116:117], v[116:117], v[180:181]
	v_pk_add_f32 v[118:119], v[118:119], v[182:183]
	v_cvt_pk_bf16_f32 v176, v112, v113
	v_cvt_pk_bf16_f32 v177, v114, v115
	v_cvt_pk_bf16_f32 v178, v116, v117
	v_cvt_pk_bf16_f32 v179, v118, v119
	v_pk_fma_f32 v[172:173], v[112:113], v[112:113], v[172:173]
	global_store_dwordx4 v155, v[176:179], s[18:19] offset:256
	v_pk_fma_f32 v[172:173], v[114:115], v[114:115], v[172:173]
	v_pk_fma_f32 v[172:173], v[116:117], v[116:117], v[172:173]
	v_pk_fma_f32 v[172:173], v[118:119], v[118:119], v[172:173]
	v_add_f32_e32 v157, v172, v173
	v_add_u32_e32 v155, 0x8000, v155
	v_mov_b32_e32 v158, v157
	s_nop 1
	v_permlane16_swap_b32_e32 v157, v158
	s_nop 0
	v_add_f32_e32 v157, v157, v158
	v_mov_b32_e32 v158, v157
	s_nop 1
	v_permlane32_swap_b32_e32 v157, v158
	s_nop 0
	v_add_f32_e32 v157, v157, v158
	s_and_saveexec_b64 s[38:39], s[4:5]
	global_store_dword v156, v157, s[20:21]
	s_mov_b64 exec, s[38:39]
	global_load_dwordx4 v[168:171], v154, s[14:15]
	global_load_dwordx4 v[172:175], v154, s[14:15] offset:16
	global_load_dwordx4 v[176:179], v154, s[14:15] offset:512
	global_load_dwordx4 v[180:183], v154, s[14:15] offset:528
	v_add_u32_e32 v154, 0x10000, v154
	s_waitcnt vmcnt(15)
	v_pk_add_f32 v[104:105], v[104:105], v[184:185]
	v_pk_add_f32 v[106:107], v[106:107], v[186:187]
	v_pk_add_f32 v[108:109], v[108:109], v[188:189]
	v_pk_add_f32 v[110:111], v[110:111], v[190:191]
	v_cvt_pk_bf16_f32 v184, v104, v105
	v_cvt_pk_bf16_f32 v185, v106, v107
	v_cvt_pk_bf16_f32 v186, v108, v109
	v_cvt_pk_bf16_f32 v187, v110, v111
	v_pk_mul_f32 v[188:189], v[104:105], v[104:105]
	global_store_dwordx4 v155, v[184:187], s[18:19]
	v_pk_fma_f32 v[188:189], v[106:107], v[106:107], v[188:189]
	v_pk_fma_f32 v[188:189], v[108:109], v[108:109], v[188:189]
	v_pk_fma_f32 v[188:189], v[110:111], v[110:111], v[188:189]
	v_pk_add_f32 v[96:97], v[96:97], v[192:193]
	v_pk_add_f32 v[98:99], v[98:99], v[194:195]
	v_pk_add_f32 v[100:101], v[100:101], v[196:197]
	v_pk_add_f32 v[102:103], v[102:103], v[198:199]
	v_cvt_pk_bf16_f32 v192, v96, v97
	v_cvt_pk_bf16_f32 v193, v98, v99
	v_cvt_pk_bf16_f32 v194, v100, v101
	v_cvt_pk_bf16_f32 v195, v102, v103
	v_pk_fma_f32 v[188:189], v[96:97], v[96:97], v[188:189]
	global_store_dwordx4 v155, v[192:195], s[18:19] offset:256
	v_pk_fma_f32 v[188:189], v[98:99], v[98:99], v[188:189]
	v_pk_fma_f32 v[188:189], v[100:101], v[100:101], v[188:189]
	v_pk_fma_f32 v[188:189], v[102:103], v[102:103], v[188:189]
	v_add_f32_e32 v157, v188, v189
	v_add_u32_e32 v155, 0x8000, v155
	v_mov_b32_e32 v158, v157
	s_nop 1
	v_permlane16_swap_b32_e32 v157, v158
	s_nop 0
	v_add_f32_e32 v157, v157, v158
	v_mov_b32_e32 v158, v157
	s_nop 1
	v_permlane32_swap_b32_e32 v157, v158
	s_nop 0
	v_add_f32_e32 v157, v157, v158
	s_and_saveexec_b64 s[38:39], s[4:5]
	global_store_dword v156, v157, s[20:21] offset:1024
	s_mov_b64 exec, s[38:39]
	global_load_dwordx4 v[184:187], v154, s[14:15]
	global_load_dwordx4 v[188:191], v154, s[14:15] offset:16
	global_load_dwordx4 v[192:195], v154, s[14:15] offset:512
	global_load_dwordx4 v[196:199], v154, s[14:15] offset:528
	v_add_u32_e32 v154, 0x10000, v154
	s_waitcnt vmcnt(18)
	v_pk_add_f32 v[88:89], v[88:89], v[200:201]
	v_pk_add_f32 v[90:91], v[90:91], v[202:203]
	v_pk_add_f32 v[92:93], v[92:93], v[204:205]
	v_pk_add_f32 v[94:95], v[94:95], v[206:207]
	v_cvt_pk_bf16_f32 v200, v88, v89
	v_cvt_pk_bf16_f32 v201, v90, v91
	v_cvt_pk_bf16_f32 v202, v92, v93
	v_cvt_pk_bf16_f32 v203, v94, v95
	v_pk_mul_f32 v[204:205], v[88:89], v[88:89]
	global_store_dwordx4 v155, v[200:203], s[18:19]
	v_pk_fma_f32 v[204:205], v[90:91], v[90:91], v[204:205]
	v_pk_fma_f32 v[204:205], v[92:93], v[92:93], v[204:205]
	v_pk_fma_f32 v[204:205], v[94:95], v[94:95], v[204:205]
	v_pk_add_f32 v[80:81], v[80:81], v[208:209]
	v_pk_add_f32 v[82:83], v[82:83], v[210:211]
	v_pk_add_f32 v[84:85], v[84:85], v[212:213]
	v_pk_add_f32 v[86:87], v[86:87], v[214:215]
	v_cvt_pk_bf16_f32 v208, v80, v81
	v_cvt_pk_bf16_f32 v209, v82, v83
	v_cvt_pk_bf16_f32 v210, v84, v85
	v_cvt_pk_bf16_f32 v211, v86, v87
	v_pk_fma_f32 v[204:205], v[80:81], v[80:81], v[204:205]
	global_store_dwordx4 v155, v[208:211], s[18:19] offset:256
	v_pk_fma_f32 v[204:205], v[82:83], v[82:83], v[204:205]
	v_pk_fma_f32 v[204:205], v[84:85], v[84:85], v[204:205]
	v_pk_fma_f32 v[204:205], v[86:87], v[86:87], v[204:205]
	v_add_f32_e32 v157, v204, v205
	v_add_u32_e32 v155, 0x8000, v155
	v_mov_b32_e32 v158, v157
	s_nop 1
	v_permlane16_swap_b32_e32 v157, v158
	s_nop 0
	v_add_f32_e32 v157, v157, v158
	v_mov_b32_e32 v158, v157
	s_nop 1
	v_permlane32_swap_b32_e32 v157, v158
	s_nop 0
	v_add_f32_e32 v157, v157, v158
	s_and_saveexec_b64 s[38:39], s[4:5]
	global_store_dword v156, v157, s[20:21] offset:2048
	s_mov_b64 exec, s[38:39]
	global_load_dwordx4 v[200:203], v154, s[14:15]
	global_load_dwordx4 v[204:207], v154, s[14:15] offset:16
	global_load_dwordx4 v[208:211], v154, s[14:15] offset:512
	global_load_dwordx4 v[212:215], v154, s[14:15] offset:528
	v_add_u32_e32 v154, 0x10000, v154
	s_waitcnt vmcnt(21)
	v_pk_add_f32 v[72:73], v[72:73], v[216:217]
	v_pk_add_f32 v[74:75], v[74:75], v[218:219]
	v_pk_add_f32 v[76:77], v[76:77], v[220:221]
	v_pk_add_f32 v[78:79], v[78:79], v[222:223]
	v_cvt_pk_bf16_f32 v216, v72, v73
	v_cvt_pk_bf16_f32 v217, v74, v75
	v_cvt_pk_bf16_f32 v218, v76, v77
	v_cvt_pk_bf16_f32 v219, v78, v79
	v_pk_mul_f32 v[220:221], v[72:73], v[72:73]
	global_store_dwordx4 v155, v[216:219], s[18:19]
	v_pk_fma_f32 v[220:221], v[74:75], v[74:75], v[220:221]
	v_pk_fma_f32 v[220:221], v[76:77], v[76:77], v[220:221]
	v_pk_fma_f32 v[220:221], v[78:79], v[78:79], v[220:221]
	v_pk_add_f32 v[64:65], v[64:65], v[128:129]
	v_pk_add_f32 v[66:67], v[66:67], v[130:131]
	v_pk_add_f32 v[68:69], v[68:69], v[132:133]
	v_pk_add_f32 v[70:71], v[70:71], v[134:135]
	v_cvt_pk_bf16_f32 v128, v64, v65
	v_cvt_pk_bf16_f32 v129, v66, v67
	v_cvt_pk_bf16_f32 v130, v68, v69
	v_cvt_pk_bf16_f32 v131, v70, v71
	v_pk_fma_f32 v[220:221], v[64:65], v[64:65], v[220:221]
	global_store_dwordx4 v155, v[128:131], s[18:19] offset:256
	v_pk_fma_f32 v[220:221], v[66:67], v[66:67], v[220:221]
	v_pk_fma_f32 v[220:221], v[68:69], v[68:69], v[220:221]
	v_pk_fma_f32 v[220:221], v[70:71], v[70:71], v[220:221]
	v_add_f32_e32 v157, v220, v221
	v_add_u32_e32 v155, 0x28000, v155
	v_mov_b32_e32 v158, v157
	s_nop 1
	v_permlane16_swap_b32_e32 v157, v158
	s_nop 0
	v_add_f32_e32 v157, v157, v158
	v_mov_b32_e32 v158, v157
	s_nop 1
	v_permlane32_swap_b32_e32 v157, v158
	s_nop 0
	v_add_f32_e32 v157, v157, v158
	s_and_saveexec_b64 s[38:39], s[4:5]
	global_store_dword v156, v157, s[20:21] offset:3072
	s_mov_b64 exec, s[38:39]
	v_add_u32_e32 v156, 0x2000, v156
	global_load_dwordx4 v[216:219], v154, s[14:15]
	global_load_dwordx4 v[220:223], v154, s[14:15] offset:16
	global_load_dwordx4 v[128:131], v154, s[14:15] offset:512
	global_load_dwordx4 v[132:135], v154, s[14:15] offset:528
	s_waitcnt vmcnt(21)
	v_pk_add_f32 v[56:57], v[56:57], v[168:169]
	v_pk_add_f32 v[58:59], v[58:59], v[170:171]
	v_pk_add_f32 v[60:61], v[60:61], v[172:173]
	v_pk_add_f32 v[62:63], v[62:63], v[174:175]
	v_cvt_pk_bf16_f32 v168, v56, v57
	v_cvt_pk_bf16_f32 v169, v58, v59
	v_cvt_pk_bf16_f32 v170, v60, v61
	v_cvt_pk_bf16_f32 v171, v62, v63
	v_pk_mul_f32 v[172:173], v[56:57], v[56:57]
	global_store_dwordx4 v155, v[168:171], s[18:19]
	v_pk_fma_f32 v[172:173], v[58:59], v[58:59], v[172:173]
	v_pk_fma_f32 v[172:173], v[60:61], v[60:61], v[172:173]
	v_pk_fma_f32 v[172:173], v[62:63], v[62:63], v[172:173]
	v_pk_add_f32 v[48:49], v[48:49], v[176:177]
	v_pk_add_f32 v[50:51], v[50:51], v[178:179]
	v_pk_add_f32 v[52:53], v[52:53], v[180:181]
	v_pk_add_f32 v[54:55], v[54:55], v[182:183]
	v_cvt_pk_bf16_f32 v176, v48, v49
	v_cvt_pk_bf16_f32 v177, v50, v51
	v_cvt_pk_bf16_f32 v178, v52, v53
	v_cvt_pk_bf16_f32 v179, v54, v55
	v_pk_fma_f32 v[172:173], v[48:49], v[48:49], v[172:173]
	global_store_dwordx4 v155, v[176:179], s[18:19] offset:256
	v_pk_fma_f32 v[172:173], v[50:51], v[50:51], v[172:173]
	v_pk_fma_f32 v[172:173], v[52:53], v[52:53], v[172:173]
	v_pk_fma_f32 v[172:173], v[54:55], v[54:55], v[172:173]
	v_add_f32_e32 v157, v172, v173
	v_add_u32_e32 v155, 0x8000, v155
	v_mov_b32_e32 v158, v157
	s_nop 1
	v_permlane16_swap_b32_e32 v157, v158
	s_nop 0
	v_add_f32_e32 v157, v157, v158
	v_mov_b32_e32 v158, v157
	s_nop 1
	v_permlane32_swap_b32_e32 v157, v158
	s_nop 0
	v_add_f32_e32 v157, v157, v158
	s_and_saveexec_b64 s[38:39], s[4:5]
	global_store_dword v156, v157, s[20:21]
	s_mov_b64 exec, s[38:39]
	s_waitcnt vmcnt(17)
	v_pk_add_f32 v[40:41], v[40:41], v[184:185]
	v_pk_add_f32 v[42:43], v[42:43], v[186:187]
	v_pk_add_f32 v[44:45], v[44:45], v[188:189]
	v_pk_add_f32 v[46:47], v[46:47], v[190:191]
	v_cvt_pk_bf16_f32 v184, v40, v41
	v_cvt_pk_bf16_f32 v185, v42, v43
	v_cvt_pk_bf16_f32 v186, v44, v45
	v_cvt_pk_bf16_f32 v187, v46, v47
	v_pk_mul_f32 v[188:189], v[40:41], v[40:41]
	global_store_dwordx4 v155, v[184:187], s[18:19]
	v_pk_fma_f32 v[188:189], v[42:43], v[42:43], v[188:189]
	v_pk_fma_f32 v[188:189], v[44:45], v[44:45], v[188:189]
	v_pk_fma_f32 v[188:189], v[46:47], v[46:47], v[188:189]
	v_pk_add_f32 v[32:33], v[32:33], v[192:193]
	v_pk_add_f32 v[34:35], v[34:35], v[194:195]
	v_pk_add_f32 v[36:37], v[36:37], v[196:197]
	v_pk_add_f32 v[38:39], v[38:39], v[198:199]
	v_cvt_pk_bf16_f32 v192, v32, v33
	v_cvt_pk_bf16_f32 v193, v34, v35
	v_cvt_pk_bf16_f32 v194, v36, v37
	v_cvt_pk_bf16_f32 v195, v38, v39
	v_pk_fma_f32 v[188:189], v[32:33], v[32:33], v[188:189]
	global_store_dwordx4 v155, v[192:195], s[18:19] offset:256
	v_pk_fma_f32 v[188:189], v[34:35], v[34:35], v[188:189]
	v_pk_fma_f32 v[188:189], v[36:37], v[36:37], v[188:189]
	v_pk_fma_f32 v[188:189], v[38:39], v[38:39], v[188:189]
	v_add_f32_e32 v157, v188, v189
	v_add_u32_e32 v155, 0x8000, v155
	v_mov_b32_e32 v158, v157
	s_nop 1
	v_permlane16_swap_b32_e32 v157, v158
	s_nop 0
	v_add_f32_e32 v157, v157, v158
	v_mov_b32_e32 v158, v157
	s_nop 1
	v_permlane32_swap_b32_e32 v157, v158
	s_nop 0
	v_add_f32_e32 v157, v157, v158
	s_and_saveexec_b64 s[38:39], s[4:5]
	global_store_dword v156, v157, s[20:21] offset:1024
	s_mov_b64 exec, s[38:39]
	s_waitcnt vmcnt(13)
	v_pk_add_f32 v[24:25], v[24:25], v[200:201]
	v_pk_add_f32 v[26:27], v[26:27], v[202:203]
	v_pk_add_f32 v[28:29], v[28:29], v[204:205]
	v_pk_add_f32 v[30:31], v[30:31], v[206:207]
	v_cvt_pk_bf16_f32 v200, v24, v25
	v_cvt_pk_bf16_f32 v201, v26, v27
	v_cvt_pk_bf16_f32 v202, v28, v29
	v_cvt_pk_bf16_f32 v203, v30, v31
	v_pk_mul_f32 v[204:205], v[24:25], v[24:25]
	global_store_dwordx4 v155, v[200:203], s[18:19]
	v_pk_fma_f32 v[204:205], v[26:27], v[26:27], v[204:205]
	v_pk_fma_f32 v[204:205], v[28:29], v[28:29], v[204:205]
	v_pk_fma_f32 v[204:205], v[30:31], v[30:31], v[204:205]
	v_pk_add_f32 v[16:17], v[16:17], v[208:209]
	v_pk_add_f32 v[18:19], v[18:19], v[210:211]
	v_pk_add_f32 v[20:21], v[20:21], v[212:213]
	v_pk_add_f32 v[22:23], v[22:23], v[214:215]
	v_cvt_pk_bf16_f32 v208, v16, v17
	v_cvt_pk_bf16_f32 v209, v18, v19
	v_cvt_pk_bf16_f32 v210, v20, v21
	v_cvt_pk_bf16_f32 v211, v22, v23
	v_pk_fma_f32 v[204:205], v[16:17], v[16:17], v[204:205]
	global_store_dwordx4 v155, v[208:211], s[18:19] offset:256
	v_pk_fma_f32 v[204:205], v[18:19], v[18:19], v[204:205]
	v_pk_fma_f32 v[204:205], v[20:21], v[20:21], v[204:205]
	v_pk_fma_f32 v[204:205], v[22:23], v[22:23], v[204:205]
	v_add_f32_e32 v157, v204, v205
	v_add_u32_e32 v155, 0x8000, v155
	v_mov_b32_e32 v158, v157
	s_nop 1
	v_permlane16_swap_b32_e32 v157, v158
	s_nop 0
	v_add_f32_e32 v157, v157, v158
	v_mov_b32_e32 v158, v157
	s_nop 1
	v_permlane32_swap_b32_e32 v157, v158
	s_nop 0
	v_add_f32_e32 v157, v157, v158
	s_and_saveexec_b64 s[38:39], s[4:5]
	global_store_dword v156, v157, s[20:21] offset:2048
	s_mov_b64 exec, s[38:39]
	s_waitcnt vmcnt(9)
	v_pk_add_f32 v[8:9], v[8:9], v[216:217]
	v_pk_add_f32 v[10:11], v[10:11], v[218:219]
	v_pk_add_f32 v[12:13], v[12:13], v[220:221]
	v_pk_add_f32 v[14:15], v[14:15], v[222:223]
	v_cvt_pk_bf16_f32 v216, v8, v9
	v_cvt_pk_bf16_f32 v217, v10, v11
	v_cvt_pk_bf16_f32 v218, v12, v13
	v_cvt_pk_bf16_f32 v219, v14, v15
	v_pk_mul_f32 v[220:221], v[8:9], v[8:9]
	global_store_dwordx4 v155, v[216:219], s[18:19]
	v_pk_fma_f32 v[220:221], v[10:11], v[10:11], v[220:221]
	v_pk_fma_f32 v[220:221], v[12:13], v[12:13], v[220:221]
	v_pk_fma_f32 v[220:221], v[14:15], v[14:15], v[220:221]
	v_pk_add_f32 v[4:5], v[4:5], v[128:129]
	v_pk_add_f32 v[6:7], v[6:7], v[130:131]
	v_pk_add_f32 v[0:1], v[0:1], v[132:133]
	v_pk_add_f32 v[2:3], v[2:3], v[134:135]
	v_cvt_pk_bf16_f32 v128, v4, v5
	v_cvt_pk_bf16_f32 v129, v6, v7
	v_cvt_pk_bf16_f32 v130, v0, v1
	v_cvt_pk_bf16_f32 v131, v2, v3
	v_pk_fma_f32 v[220:221], v[4:5], v[4:5], v[220:221]
	global_store_dwordx4 v155, v[128:131], s[18:19] offset:256
	v_pk_fma_f32 v[220:221], v[6:7], v[6:7], v[220:221]
	v_pk_fma_f32 v[220:221], v[0:1], v[0:1], v[220:221]
	v_pk_fma_f32 v[220:221], v[2:3], v[2:3], v[220:221]
	v_add_f32_e32 v157, v220, v221
	v_add_u32_e32 v155, 0x8000, v155
	v_mov_b32_e32 v158, v157
	s_nop 1
	v_permlane16_swap_b32_e32 v157, v158
	s_nop 0
	v_add_f32_e32 v157, v157, v158
	v_mov_b32_e32 v158, v157
	s_nop 1
	v_permlane32_swap_b32_e32 v157, v158
	s_nop 0
	v_add_f32_e32 v157, v157, v158
	s_and_saveexec_b64 s[38:39], s[4:5]
	global_store_dword v156, v157, s[20:21] offset:3072
	s_mov_b64 exec, s[38:39]
	s_branch .LBB0_575

.LBB0_698:
	s_add_u32 s28, s26, 0xfffc0080
	s_addc_u32 s29, s27, -1
	s_add_i32 s68, 0, 0x10000
	v_add_u32_e32 v155, s68, v153
	ds_read_b128 v[138:141], v155
	ds_read_b128 v[142:145], v155 offset:1024
	ds_read_b128 v[146:149], v155 offset:2048
	ds_read_b128 v[156:159], v155 offset:3072
	s_cmp_eq_u32 s51, 12
	s_cselect_b32 s31, s21, s29
	s_cselect_b32 s30, s38, s28
	s_cselect_b32 s29, s7, s50
	s_cselect_b32 s28, s39, s46
	v_lshl_add_u64 v[192:193], s[26:27], 0, v[134:135]
	s_add_i32 m0, s58, 0xc000
	ds_read_b128 v[160:163], v154
	ds_read_b128 v[164:167], v154 offset:1024
	ds_read_b128 v[168:171], v154 offset:2048
	ds_read_b128 v[172:175], v154 offset:3072
	ds_read_b128 v[176:179], v154 offset:4096
	ds_read_b128 v[180:183], v154 offset:5120
	ds_read_b128 v[184:187], v154 offset:6144
	ds_read_b128 v[188:191], v154 offset:7168
	global_load_lds_dwordx4 v[192:193], off
	v_lshl_add_u64 v[192:193], s[26:27], 0, v[136:137]
	s_add_i32 m0, s58, 0xe000
	s_nop 0
	global_load_lds_dwordx4 v[192:193], off
	s_waitcnt lgkmcnt(8)
	s_barrier
	s_waitcnt lgkmcnt(0)
	s_setprio 1
	v_mfma_f32_16x16x32_bf16 v[124:127], v[138:141], v[160:163], v[124:127]
	v_mfma_f32_16x16x32_bf16 v[120:123], v[146:149], v[160:163], v[120:123]
	v_mfma_f32_16x16x32_bf16 v[108:111], v[138:141], v[168:171], v[108:111]
	v_mfma_f32_16x16x32_bf16 v[104:107], v[146:149], v[168:171], v[104:107]
	v_mfma_f32_16x16x32_bf16 v[92:95], v[138:141], v[176:179], v[92:95]
	v_mfma_f32_16x16x32_bf16 v[88:91], v[146:149], v[176:179], v[88:91]
	v_mfma_f32_16x16x32_bf16 v[76:79], v[138:141], v[184:187], v[76:79]
	v_mfma_f32_16x16x32_bf16 v[72:75], v[146:149], v[184:187], v[72:75]
	v_mfma_f32_16x16x32_bf16 v[124:127], v[142:145], v[164:167], v[124:127]
	v_mfma_f32_16x16x32_bf16 v[120:123], v[156:159], v[164:167], v[120:123]
	v_mfma_f32_16x16x32_bf16 v[108:111], v[142:145], v[172:175], v[108:111]
	v_mfma_f32_16x16x32_bf16 v[104:107], v[156:159], v[172:175], v[104:107]
	v_mfma_f32_16x16x32_bf16 v[92:95], v[142:145], v[180:183], v[92:95]
	v_mfma_f32_16x16x32_bf16 v[88:91], v[156:159], v[180:183], v[88:91]
	v_mfma_f32_16x16x32_bf16 v[76:79], v[142:145], v[188:191], v[76:79]
	v_mfma_f32_16x16x32_bf16 v[72:75], v[156:159], v[188:191], v[72:75]
	s_setprio 0
	s_barrier
	s_add_i32 s70, 0, 0x14000
	s_add_i32 s68, s68, s57
	v_add_u32_e32 v155, s70, v153
	v_lshl_add_u64 v[210:211], s[28:29], 0, v[208:209]
	s_mov_b32 m0, s68
	ds_read_b128 v[192:195], v155
	ds_read_b128 v[196:199], v155 offset:1024
	ds_read_b128 v[200:203], v155 offset:2048
	ds_read_b128 v[204:207], v155 offset:3072
	global_load_lds_dwordx4 v[210:211], off
	v_lshl_add_u64 v[214:215], s[28:29], 0, v[128:129]
	s_add_i32 m0, s68, 0x2000
	s_nop 0
	global_load_lds_dwordx4 v[214:215], off
	s_barrier
	s_waitcnt lgkmcnt(0)
	s_setprio 1
	v_mfma_f32_16x16x32_bf16 v[116:119], v[192:195], v[160:163], v[116:119]
	v_mfma_f32_16x16x32_bf16 v[112:115], v[200:203], v[160:163], v[112:115]
	v_mfma_f32_16x16x32_bf16 v[100:103], v[192:195], v[168:171], v[100:103]
	v_mfma_f32_16x16x32_bf16 v[96:99], v[200:203], v[168:171], v[96:99]
	v_mfma_f32_16x16x32_bf16 v[84:87], v[192:195], v[176:179], v[84:87]
	v_mfma_f32_16x16x32_bf16 v[80:83], v[200:203], v[176:179], v[80:83]
	v_mfma_f32_16x16x32_bf16 v[68:71], v[192:195], v[184:187], v[68:71]
	v_mfma_f32_16x16x32_bf16 v[64:67], v[200:203], v[184:187], v[64:67]
	v_mfma_f32_16x16x32_bf16 v[116:119], v[196:199], v[164:167], v[116:119]
	v_mfma_f32_16x16x32_bf16 v[112:115], v[204:207], v[164:167], v[112:115]
	v_mfma_f32_16x16x32_bf16 v[100:103], v[196:199], v[172:175], v[100:103]
	v_mfma_f32_16x16x32_bf16 v[96:99], v[204:207], v[172:175], v[96:99]
	v_mfma_f32_16x16x32_bf16 v[84:87], v[196:199], v[180:183], v[84:87]
	v_mfma_f32_16x16x32_bf16 v[80:83], v[204:207], v[180:183], v[80:83]
	v_mfma_f32_16x16x32_bf16 v[68:71], v[196:199], v[188:191], v[68:71]
	v_mfma_f32_16x16x32_bf16 v[64:67], v[204:207], v[188:191], v[64:67]
	s_setprio 0
	s_mov_b32 m0, s58
	v_lshl_add_u64 v[216:217], s[30:31], 0, v[132:133]
	s_barrier
	ds_read_b128 v[160:163], v154 offset:16384
	ds_read_b128 v[164:167], v154 offset:17408
	ds_read_b128 v[168:171], v154 offset:18432
	ds_read_b128 v[172:175], v154 offset:19456
	ds_read_b128 v[176:179], v154 offset:20480
	ds_read_b128 v[180:183], v154 offset:21504
	ds_read_b128 v[184:187], v154 offset:22528
	ds_read_b128 v[188:191], v154 offset:23552
	global_load_lds_dwordx4 v[216:217], off
	v_lshl_add_u64 v[218:219], s[30:31], 0, v[130:131]
	s_mov_b32 m0, s59
	s_nop 0
	global_load_lds_dwordx4 v[218:219], off
	s_barrier
	s_waitcnt lgkmcnt(0)
	s_setprio 1
	v_mfma_f32_16x16x32_bf16 v[60:63], v[138:141], v[160:163], v[60:63]
	v_mfma_f32_16x16x32_bf16 v[56:59], v[146:149], v[160:163], v[56:59]
	v_mfma_f32_16x16x32_bf16 v[44:47], v[138:141], v[168:171], v[44:47]
	v_mfma_f32_16x16x32_bf16 v[40:43], v[146:149], v[168:171], v[40:43]
	v_mfma_f32_16x16x32_bf16 v[28:31], v[138:141], v[176:179], v[28:31]
	v_mfma_f32_16x16x32_bf16 v[24:27], v[146:149], v[176:179], v[24:27]
	v_mfma_f32_16x16x32_bf16 v[12:15], v[138:141], v[184:187], v[12:15]
	v_mfma_f32_16x16x32_bf16 v[8:11], v[146:149], v[184:187], v[8:11]
	v_mfma_f32_16x16x32_bf16 v[60:63], v[142:145], v[164:167], v[60:63]
	v_mfma_f32_16x16x32_bf16 v[56:59], v[156:159], v[164:167], v[56:59]
	v_mfma_f32_16x16x32_bf16 v[44:47], v[142:145], v[172:175], v[44:47]
	v_mfma_f32_16x16x32_bf16 v[40:43], v[156:159], v[172:175], v[40:43]
	v_mfma_f32_16x16x32_bf16 v[28:31], v[142:145], v[180:183], v[28:31]
	v_mfma_f32_16x16x32_bf16 v[24:27], v[156:159], v[180:183], v[24:27]
	v_mfma_f32_16x16x32_bf16 v[12:15], v[142:145], v[188:191], v[12:15]
	v_mfma_f32_16x16x32_bf16 v[8:11], v[156:159], v[188:191], v[8:11]
	s_setprio 0
	s_barrier
	s_add_u32 s68, s28, 0x40000
	s_addc_u32 s69, s29, 0
	s_add_i32 s70, s70, s57
	v_lshl_add_u64 v[138:139], s[68:69], 0, v[208:209]
	s_mov_b32 m0, s70
	s_nop 0
	global_load_lds_dwordx4 v[138:139], off
	v_lshl_add_u64 v[138:139], s[68:69], 0, v[128:129]
	s_add_i32 m0, s70, 0x2000
	s_nop 0
	global_load_lds_dwordx4 v[138:139], off
	s_waitcnt vmcnt(6)
	s_barrier
	s_setprio 1
	v_mfma_f32_16x16x32_bf16 v[52:55], v[192:195], v[160:163], v[52:55]
	v_mfma_f32_16x16x32_bf16 v[48:51], v[200:203], v[160:163], v[48:51]
	v_mfma_f32_16x16x32_bf16 v[36:39], v[192:195], v[168:171], v[36:39]
	v_mfma_f32_16x16x32_bf16 v[32:35], v[200:203], v[168:171], v[32:35]
	v_mfma_f32_16x16x32_bf16 v[20:23], v[192:195], v[176:179], v[20:23]
	v_mfma_f32_16x16x32_bf16 v[16:19], v[200:203], v[176:179], v[16:19]
	v_mfma_f32_16x16x32_bf16 v[4:7], v[192:195], v[184:187], v[4:7]
	v_mfma_f32_16x16x32_bf16 v[0:3], v[200:203], v[184:187], v[0:3]
	v_mfma_f32_16x16x32_bf16 v[52:55], v[196:199], v[164:167], v[52:55]
	v_mfma_f32_16x16x32_bf16 v[48:51], v[204:207], v[164:167], v[48:51]
	v_mfma_f32_16x16x32_bf16 v[36:39], v[196:199], v[172:175], v[36:39]
	v_mfma_f32_16x16x32_bf16 v[32:35], v[204:207], v[172:175], v[32:35]
	v_mfma_f32_16x16x32_bf16 v[20:23], v[196:199], v[180:183], v[20:23]
	v_mfma_f32_16x16x32_bf16 v[16:19], v[204:207], v[180:183], v[16:19]
	v_mfma_f32_16x16x32_bf16 v[4:7], v[196:199], v[188:191], v[4:7]
	v_mfma_f32_16x16x32_bf16 v[0:3], v[204:207], v[188:191], v[0:3]
	s_setprio 0
	s_add_i32 s68, 0, 0x18000
	v_add_u32_e32 v155, s68, v153
	s_barrier
	ds_read_b128 v[138:141], v155
	ds_read_b128 v[142:145], v155 offset:1024
	ds_read_b128 v[146:149], v155 offset:2048
	ds_read_b128 v[156:159], v155 offset:3072
	s_add_u32 s30, s30, 0x40000
	s_addc_u32 s31, s31, 0
	s_mov_b32 m0, s60
	v_lshl_add_u64 v[192:193], s[30:31], 0, v[132:133]
	ds_read_b128 v[160:163], v154 offset:32768
	ds_read_b128 v[164:167], v154 offset:33792
	ds_read_b128 v[168:171], v154 offset:34816
	ds_read_b128 v[172:175], v154 offset:35840
	ds_read_b128 v[176:179], v154 offset:36864
	ds_read_b128 v[180:183], v154 offset:37888
	ds_read_b128 v[184:187], v154 offset:38912
	ds_read_b128 v[188:191], v154 offset:39936
	global_load_lds_dwordx4 v[192:193], off
	v_lshl_add_u64 v[192:193], s[30:31], 0, v[130:131]
	s_mov_b32 m0, s61
	s_nop 0
	global_load_lds_dwordx4 v[192:193], off
	s_waitcnt lgkmcnt(8)
	s_barrier
	s_waitcnt lgkmcnt(0)
	s_setprio 1
	v_mfma_f32_16x16x32_bf16 v[124:127], v[138:141], v[160:163], v[124:127]
	v_mfma_f32_16x16x32_bf16 v[120:123], v[146:149], v[160:163], v[120:123]
	v_mfma_f32_16x16x32_bf16 v[108:111], v[138:141], v[168:171], v[108:111]
	v_mfma_f32_16x16x32_bf16 v[104:107], v[146:149], v[168:171], v[104:107]
	v_mfma_f32_16x16x32_bf16 v[92:95], v[138:141], v[176:179], v[92:95]
	v_mfma_f32_16x16x32_bf16 v[88:91], v[146:149], v[176:179], v[88:91]
	v_mfma_f32_16x16x32_bf16 v[76:79], v[138:141], v[184:187], v[76:79]
	v_mfma_f32_16x16x32_bf16 v[72:75], v[146:149], v[184:187], v[72:75]
	v_mfma_f32_16x16x32_bf16 v[124:127], v[142:145], v[164:167], v[124:127]
	v_mfma_f32_16x16x32_bf16 v[120:123], v[156:159], v[164:167], v[120:123]
	v_mfma_f32_16x16x32_bf16 v[108:111], v[142:145], v[172:175], v[108:111]
	v_mfma_f32_16x16x32_bf16 v[104:107], v[156:159], v[172:175], v[104:107]
	v_mfma_f32_16x16x32_bf16 v[92:95], v[142:145], v[180:183], v[92:95]
	v_mfma_f32_16x16x32_bf16 v[88:91], v[156:159], v[180:183], v[88:91]
	v_mfma_f32_16x16x32_bf16 v[76:79], v[142:145], v[188:191], v[76:79]
	v_mfma_f32_16x16x32_bf16 v[72:75], v[156:159], v[188:191], v[72:75]
	s_setprio 0
	s_barrier
	s_add_i32 s30, 0, 0x1c000
	s_add_i32 s31, s68, s57
	v_add_u32_e32 v155, s30, v153
	v_lshl_add_u64 v[210:211], v[210:211], 0, s[40:41]
	s_mov_b32 m0, s31
	ds_read_b128 v[192:195], v155
	ds_read_b128 v[196:199], v155 offset:1024
	ds_read_b128 v[200:203], v155 offset:2048
	ds_read_b128 v[204:207], v155 offset:3072
	global_load_lds_dwordx4 v[210:211], off
	v_lshl_add_u64 v[210:211], v[214:215], 0, s[40:41]
	s_add_i32 m0, s31, 0x2000
	s_nop 0
	global_load_lds_dwordx4 v[210:211], off
	s_barrier
	s_waitcnt lgkmcnt(0)
	s_setprio 1
	v_mfma_f32_16x16x32_bf16 v[116:119], v[192:195], v[160:163], v[116:119]
	v_mfma_f32_16x16x32_bf16 v[112:115], v[200:203], v[160:163], v[112:115]
	v_mfma_f32_16x16x32_bf16 v[100:103], v[192:195], v[168:171], v[100:103]
	v_mfma_f32_16x16x32_bf16 v[96:99], v[200:203], v[168:171], v[96:99]
	v_mfma_f32_16x16x32_bf16 v[84:87], v[192:195], v[176:179], v[84:87]
	v_mfma_f32_16x16x32_bf16 v[80:83], v[200:203], v[176:179], v[80:83]
	v_mfma_f32_16x16x32_bf16 v[68:71], v[192:195], v[184:187], v[68:71]
	v_mfma_f32_16x16x32_bf16 v[64:67], v[200:203], v[184:187], v[64:67]
	v_mfma_f32_16x16x32_bf16 v[116:119], v[196:199], v[164:167], v[116:119]
	v_mfma_f32_16x16x32_bf16 v[112:115], v[204:207], v[164:167], v[112:115]
	v_mfma_f32_16x16x32_bf16 v[100:103], v[196:199], v[172:175], v[100:103]
	v_mfma_f32_16x16x32_bf16 v[96:99], v[204:207], v[172:175], v[96:99]
	v_mfma_f32_16x16x32_bf16 v[84:87], v[196:199], v[180:183], v[84:87]
	v_mfma_f32_16x16x32_bf16 v[80:83], v[204:207], v[180:183], v[80:83]
	v_mfma_f32_16x16x32_bf16 v[68:71], v[196:199], v[188:191], v[68:71]
	v_mfma_f32_16x16x32_bf16 v[64:67], v[204:207], v[188:191], v[64:67]
	s_setprio 0
	s_mov_b32 m0, s64
	v_lshl_add_u64 v[210:211], v[216:217], 0, s[40:41]
	s_barrier
	ds_read_b128 v[160:163], v154 offset:49152
	ds_read_b128 v[164:167], v154 offset:50176
	ds_read_b128 v[168:171], v154 offset:51200
	ds_read_b128 v[172:175], v154 offset:52224
	ds_read_b128 v[176:179], v154 offset:53248
	ds_read_b128 v[180:183], v154 offset:54272
	ds_read_b128 v[184:187], v154 offset:55296
	ds_read_b128 v[188:191], v154 offset:56320
	global_load_lds_dwordx4 v[210:211], off
	v_lshl_add_u64 v[210:211], v[218:219], 0, s[40:41]
	s_mov_b32 m0, s65
	s_nop 0
	global_load_lds_dwordx4 v[210:211], off
	s_barrier
	s_waitcnt lgkmcnt(0)
	s_setprio 1
	v_mfma_f32_16x16x32_bf16 v[60:63], v[138:141], v[160:163], v[60:63]
	v_mfma_f32_16x16x32_bf16 v[56:59], v[146:149], v[160:163], v[56:59]
	v_mfma_f32_16x16x32_bf16 v[44:47], v[138:141], v[168:171], v[44:47]
	v_mfma_f32_16x16x32_bf16 v[40:43], v[146:149], v[168:171], v[40:43]
	v_mfma_f32_16x16x32_bf16 v[28:31], v[138:141], v[176:179], v[28:31]
	v_mfma_f32_16x16x32_bf16 v[24:27], v[146:149], v[176:179], v[24:27]
	v_mfma_f32_16x16x32_bf16 v[12:15], v[138:141], v[184:187], v[12:15]
	v_mfma_f32_16x16x32_bf16 v[8:11], v[146:149], v[184:187], v[8:11]
	v_mfma_f32_16x16x32_bf16 v[60:63], v[142:145], v[164:167], v[60:63]
	v_mfma_f32_16x16x32_bf16 v[56:59], v[156:159], v[164:167], v[56:59]
	v_mfma_f32_16x16x32_bf16 v[44:47], v[142:145], v[172:175], v[44:47]
	v_mfma_f32_16x16x32_bf16 v[40:43], v[156:159], v[172:175], v[40:43]
	v_mfma_f32_16x16x32_bf16 v[28:31], v[142:145], v[180:183], v[28:31]
	v_mfma_f32_16x16x32_bf16 v[24:27], v[156:159], v[180:183], v[24:27]
	v_mfma_f32_16x16x32_bf16 v[12:15], v[142:145], v[188:191], v[12:15]
	v_mfma_f32_16x16x32_bf16 v[8:11], v[156:159], v[188:191], v[8:11]
	s_setprio 0
	s_barrier
	s_add_u32 s28, s28, 0x40080
	s_addc_u32 s29, s29, 0
	s_add_i32 s30, s30, s57
	v_lshl_add_u64 v[138:139], s[28:29], 0, v[208:209]
	s_mov_b32 m0, s30
	s_nop 0
	global_load_lds_dwordx4 v[138:139], off
	v_lshl_add_u64 v[138:139], s[28:29], 0, v[128:129]
	s_add_i32 m0, s30, 0x2000
	s_nop 0
	global_load_lds_dwordx4 v[138:139], off
	s_waitcnt vmcnt(6)
	s_barrier
	s_setprio 1
	v_mfma_f32_16x16x32_bf16 v[52:55], v[192:195], v[160:163], v[52:55]
	v_mfma_f32_16x16x32_bf16 v[48:51], v[200:203], v[160:163], v[48:51]
	v_mfma_f32_16x16x32_bf16 v[36:39], v[192:195], v[168:171], v[36:39]
	v_mfma_f32_16x16x32_bf16 v[32:35], v[200:203], v[168:171], v[32:35]
	v_mfma_f32_16x16x32_bf16 v[20:23], v[192:195], v[176:179], v[20:23]
	v_mfma_f32_16x16x32_bf16 v[16:19], v[200:203], v[176:179], v[16:19]
	v_mfma_f32_16x16x32_bf16 v[4:7], v[192:195], v[184:187], v[4:7]
	v_mfma_f32_16x16x32_bf16 v[0:3], v[200:203], v[184:187], v[0:3]
	v_mfma_f32_16x16x32_bf16 v[52:55], v[196:199], v[164:167], v[52:55]
	v_mfma_f32_16x16x32_bf16 v[48:51], v[204:207], v[164:167], v[48:51]
	v_mfma_f32_16x16x32_bf16 v[36:39], v[196:199], v[172:175], v[36:39]
	v_mfma_f32_16x16x32_bf16 v[32:35], v[204:207], v[172:175], v[32:35]
	v_mfma_f32_16x16x32_bf16 v[20:23], v[196:199], v[180:183], v[20:23]
	v_mfma_f32_16x16x32_bf16 v[16:19], v[204:207], v[180:183], v[16:19]
	v_mfma_f32_16x16x32_bf16 v[4:7], v[196:199], v[188:191], v[4:7]
	v_mfma_f32_16x16x32_bf16 v[0:3], v[204:207], v[188:191], v[0:3]
	s_setprio 0
	s_add_i32 s51, s51, 2
	s_add_u32 s26, s26, 0x100
	s_addc_u32 s27, s27, 0
	s_add_u32 s46, s46, 0x100
	s_addc_u32 s50, s50, 0
	s_cmp_gt_u32 s51, 13
	s_barrier
	s_cbranch_scc0 .LBB0_698
	s_cmp_lt_i32 s34, 4
	s_cselect_b64 vcc, -1, 0
	v_mov_b32_e32 v138, 0x3e38aa3b
	s_nop 0
	v_cndmask_b32_e32 v155, 1.0, v138, vcc
	s_and_b64 s[26:27], vcc, exec
	v_lshl_add_u32 v140, s35, 8, v152
	s_cselect_b32 s7, s9, s11
	s_cselect_b32 s21, s8, s10
	v_mov_b32_e32 v138, s21
	v_mov_b32_e32 v139, s7
	v_lshlrev_b32_e32 v142, 3, v151
	v_mov_b32_e32 v143, 0
	v_lshl_add_u64 v[138:139], v[142:143], 2, v[138:139]
	global_load_dwordx4 v[188:191], v[138:139], off
	global_load_dwordx4 v[192:195], v[138:139], off offset:16
	global_load_dwordx4 v[196:199], v[138:139], off offset:128
	global_load_dwordx4 v[200:203], v[138:139], off offset:144
	s_lshl_b32 s7, s34, 8
	s_or_b32 s26, s7, s66
	s_ashr_i32 s27, s26, 31
	s_lshl_b64 s[26:27], s[26:27], 1
	s_add_u32 s26, s62, s26
	s_addc_u32 s27, s63, s27
	s_mov_b32 s34, s6
	s_mov_b32 s35, s20
	s_mov_b64 s[28:29], s[24:25]
	v_mbcnt_lo_u32_b32 v210, -1, 0
	v_mbcnt_hi_u32_b32 v210, -1, v210
	v_and_b32_e32 v210, 48, v210
	v_lshl_add_u32 v210, v140, 6, v210
	v_lshlrev_b32_e32 v211, 12, v140
	v_lshl_add_u32 v211, v151, 4, v211
	global_load_dwordx4 v[156:159], v210, s[18:19]
	global_load_dwordx4 v[160:163], v210, s[18:19] offset:1024
	global_load_dwordx4 v[164:167], v210, s[18:19] offset:2048
	global_load_dwordx4 v[168:171], v210, s[18:19] offset:3072
	v_add_u32_e32 v210, 0x2000, v210
	global_load_dwordx4 v[172:175], v210, s[18:19]
	global_load_dwordx4 v[176:179], v210, s[18:19] offset:1024
	global_load_dwordx4 v[180:183], v210, s[18:19] offset:2048
	global_load_dwordx4 v[184:187], v210, s[18:19] offset:3072
	s_waitcnt vmcnt(7)
	v_pk_add_f32 v[156:157], v[156:157], v[158:159]
	s_nop 0
	v_add_f32_e32 v214, v156, v157
	v_mov_b32_e32 v215, v214
	s_nop 1
	v_permlane16_swap_b32_e32 v214, v215
	s_nop 0
	v_add_f32_e32 v214, v214, v215
	v_mov_b32_e32 v215, v214
	s_nop 1
	v_permlane32_swap_b32_e32 v214, v215
	s_nop 0
	v_add_f32_e32 v214, v214, v215
	v_fmamk_f32 v214, v214, 0x3a800000, v248
	v_rsq_f32_e32 v216, v214
	s_nop 0
	v_pk_mul_f32 v[124:125], v[124:125], v[216:217] op_sel_hi:[1,0]
	v_pk_mul_f32 v[126:127], v[126:127], v[216:217] op_sel_hi:[1,0]
	v_pk_mul_f32 v[120:121], v[120:121], v[216:217] op_sel_hi:[1,0]
	v_pk_mul_f32 v[122:123], v[122:123], v[216:217] op_sel_hi:[1,0]
	v_pk_mul_f32 v[116:117], v[116:117], v[216:217] op_sel_hi:[1,0]
	v_pk_mul_f32 v[118:119], v[118:119], v[216:217] op_sel_hi:[1,0]
	v_pk_mul_f32 v[112:113], v[112:113], v[216:217] op_sel_hi:[1,0]
	v_pk_mul_f32 v[114:115], v[114:115], v[216:217] op_sel_hi:[1,0]
	v_pk_mul_f32 v[148:149], v[124:125], v[124:125]
	v_pk_fma_f32 v[148:149], v[126:127], v[126:127], v[148:149]
	v_pk_fma_f32 v[148:149], v[120:121], v[120:121], v[148:149]
	v_pk_fma_f32 v[148:149], v[122:123], v[122:123], v[148:149]
	v_pk_fma_f32 v[148:149], v[116:117], v[116:117], v[148:149]
	v_pk_fma_f32 v[148:149], v[118:119], v[118:119], v[148:149]
	v_pk_fma_f32 v[148:149], v[112:113], v[112:113], v[148:149]
	v_pk_fma_f32 v[148:149], v[114:115], v[114:115], v[148:149]
	v_add_f32_e32 v214, v148, v149
	v_mov_b32_e32 v215, v214
	s_nop 1
	v_permlane16_swap_b32_e32 v214, v215
	s_nop 0
	v_add_f32_e32 v214, v214, v215
	v_mov_b32_e32 v215, v214
	s_nop 1
	v_permlane32_swap_b32_e32 v214, v215
	s_nop 0
	v_add_f32_e32 v214, v214, v215
	v_fmamk_f32 v214, v214, 0x3c800000, v248
	v_rsq_f32_e32 v214, v214
	s_nop 0
	v_mul_f32_e32 v218, v155, v214
	v_pk_mul_f32 v[156:157], v[188:189], v[218:219] op_sel_hi:[1,0]
	v_pk_mul_f32 v[124:125], v[124:125], v[156:157]
	v_pk_mul_f32 v[156:157], v[190:191], v[218:219] op_sel_hi:[1,0]
	v_pk_mul_f32 v[126:127], v[126:127], v[156:157]
	v_pk_mul_f32 v[156:157], v[192:193], v[218:219] op_sel_hi:[1,0]
	v_pk_mul_f32 v[120:121], v[120:121], v[156:157]
	v_pk_mul_f32 v[156:157], v[194:195], v[218:219] op_sel_hi:[1,0]
	v_pk_mul_f32 v[122:123], v[122:123], v[156:157]
	v_cvt_pk_bf16_f32 v204, v124, v125
	v_cvt_pk_bf16_f32 v205, v126, v127
	v_cvt_pk_bf16_f32 v206, v120, v121
	v_cvt_pk_bf16_f32 v207, v122, v123
	global_store_dwordx4 v211, v[204:207], s[26:27]
	v_pk_mul_f32 v[156:157], v[196:197], v[218:219] op_sel_hi:[1,0]
	v_pk_mul_f32 v[116:117], v[116:117], v[156:157]
	v_pk_mul_f32 v[156:157], v[198:199], v[218:219] op_sel_hi:[1,0]
	v_pk_mul_f32 v[118:119], v[118:119], v[156:157]
	v_pk_mul_f32 v[156:157], v[200:201], v[218:219] op_sel_hi:[1,0]
	v_pk_mul_f32 v[112:113], v[112:113], v[156:157]
	v_pk_mul_f32 v[156:157], v[202:203], v[218:219] op_sel_hi:[1,0]
	v_pk_mul_f32 v[114:115], v[114:115], v[156:157]
	v_cvt_pk_bf16_f32 v144, v116, v117
	v_cvt_pk_bf16_f32 v145, v118, v119
	v_cvt_pk_bf16_f32 v146, v112, v113
	v_cvt_pk_bf16_f32 v147, v114, v115
	global_store_dwordx4 v211, v[144:147], s[26:27] offset:64
	v_add_u32_e32 v211, 0x10000, v211
	s_waitcnt vmcnt(8)
	v_pk_add_f32 v[160:161], v[160:161], v[162:163]
	s_nop 0
	v_add_f32_e32 v214, v160, v161
	v_mov_b32_e32 v215, v214
	s_nop 1
	v_permlane16_swap_b32_e32 v214, v215
	s_nop 0
	v_add_f32_e32 v214, v214, v215
	v_mov_b32_e32 v215, v214
	s_nop 1
	v_permlane32_swap_b32_e32 v214, v215
	s_nop 0
	v_add_f32_e32 v214, v214, v215
	v_fmamk_f32 v214, v214, 0x3a800000, v248
	v_rsq_f32_e32 v216, v214
	s_nop 0
	v_pk_mul_f32 v[108:109], v[108:109], v[216:217] op_sel_hi:[1,0]
	v_pk_mul_f32 v[110:111], v[110:111], v[216:217] op_sel_hi:[1,0]
	v_pk_mul_f32 v[104:105], v[104:105], v[216:217] op_sel_hi:[1,0]
	v_pk_mul_f32 v[106:107], v[106:107], v[216:217] op_sel_hi:[1,0]
	v_pk_mul_f32 v[100:101], v[100:101], v[216:217] op_sel_hi:[1,0]
	v_pk_mul_f32 v[102:103], v[102:103], v[216:217] op_sel_hi:[1,0]
	v_pk_mul_f32 v[96:97], v[96:97], v[216:217] op_sel_hi:[1,0]
	v_pk_mul_f32 v[98:99], v[98:99], v[216:217] op_sel_hi:[1,0]
	v_pk_mul_f32 v[148:149], v[108:109], v[108:109]
	v_pk_fma_f32 v[148:149], v[110:111], v[110:111], v[148:149]
	v_pk_fma_f32 v[148:149], v[104:105], v[104:105], v[148:149]
	v_pk_fma_f32 v[148:149], v[106:107], v[106:107], v[148:149]
	v_pk_fma_f32 v[148:149], v[100:101], v[100:101], v[148:149]
	v_pk_fma_f32 v[148:149], v[102:103], v[102:103], v[148:149]
	v_pk_fma_f32 v[148:149], v[96:97], v[96:97], v[148:149]
	v_pk_fma_f32 v[148:149], v[98:99], v[98:99], v[148:149]
	v_add_f32_e32 v214, v148, v149
	v_mov_b32_e32 v215, v214
	s_nop 1
	v_permlane16_swap_b32_e32 v214, v215
	s_nop 0
	v_add_f32_e32 v214, v214, v215
	v_mov_b32_e32 v215, v214
	s_nop 1
	v_permlane32_swap_b32_e32 v214, v215
	s_nop 0
	v_add_f32_e32 v214, v214, v215
	v_fmamk_f32 v214, v214, 0x3c800000, v248
	v_rsq_f32_e32 v214, v214
	s_nop 0
	v_mul_f32_e32 v218, v155, v214
	v_pk_mul_f32 v[160:161], v[188:189], v[218:219] op_sel_hi:[1,0]
	v_pk_mul_f32 v[108:109], v[108:109], v[160:161]
	v_pk_mul_f32 v[160:161], v[190:191], v[218:219] op_sel_hi:[1,0]
	v_pk_mul_f32 v[110:111], v[110:111], v[160:161]
	v_pk_mul_f32 v[160:161], v[192:193], v[218:219] op_sel_hi:[1,0]
	v_pk_mul_f32 v[104:105], v[104:105], v[160:161]
	v_pk_mul_f32 v[160:161], v[194:195], v[218:219] op_sel_hi:[1,0]
	v_pk_mul_f32 v[106:107], v[106:107], v[160:161]
	v_cvt_pk_bf16_f32 v204, v108, v109
	v_cvt_pk_bf16_f32 v205, v110, v111
	v_cvt_pk_bf16_f32 v206, v104, v105
	v_cvt_pk_bf16_f32 v207, v106, v107
	global_store_dwordx4 v211, v[204:207], s[26:27]
	v_pk_mul_f32 v[160:161], v[196:197], v[218:219] op_sel_hi:[1,0]
	v_pk_mul_f32 v[100:101], v[100:101], v[160:161]
	v_pk_mul_f32 v[160:161], v[198:199], v[218:219] op_sel_hi:[1,0]
	v_pk_mul_f32 v[102:103], v[102:103], v[160:161]
	v_pk_mul_f32 v[160:161], v[200:201], v[218:219] op_sel_hi:[1,0]
	v_pk_mul_f32 v[96:97], v[96:97], v[160:161]
	v_pk_mul_f32 v[160:161], v[202:203], v[218:219] op_sel_hi:[1,0]
	v_pk_mul_f32 v[98:99], v[98:99], v[160:161]
	v_cvt_pk_bf16_f32 v144, v100, v101
	v_cvt_pk_bf16_f32 v145, v102, v103
	v_cvt_pk_bf16_f32 v146, v96, v97
	v_cvt_pk_bf16_f32 v147, v98, v99
	global_store_dwordx4 v211, v[144:147], s[26:27] offset:64
	v_add_u32_e32 v211, 0x10000, v211
	s_waitcnt vmcnt(9)
	v_pk_add_f32 v[164:165], v[164:165], v[166:167]
	s_nop 0
	v_add_f32_e32 v214, v164, v165
	v_mov_b32_e32 v215, v214
	s_nop 1
	v_permlane16_swap_b32_e32 v214, v215
	s_nop 0
	v_add_f32_e32 v214, v214, v215
	v_mov_b32_e32 v215, v214
	s_nop 1
	v_permlane32_swap_b32_e32 v214, v215
	s_nop 0
	v_add_f32_e32 v214, v214, v215
	v_fmamk_f32 v214, v214, 0x3a800000, v248
	v_rsq_f32_e32 v216, v214
	s_nop 0
	v_pk_mul_f32 v[92:93], v[92:93], v[216:217] op_sel_hi:[1,0]
	v_pk_mul_f32 v[94:95], v[94:95], v[216:217] op_sel_hi:[1,0]
	v_pk_mul_f32 v[88:89], v[88:89], v[216:217] op_sel_hi:[1,0]
	v_pk_mul_f32 v[90:91], v[90:91], v[216:217] op_sel_hi:[1,0]
	v_pk_mul_f32 v[84:85], v[84:85], v[216:217] op_sel_hi:[1,0]
	v_pk_mul_f32 v[86:87], v[86:87], v[216:217] op_sel_hi:[1,0]
	v_pk_mul_f32 v[80:81], v[80:81], v[216:217] op_sel_hi:[1,0]
	v_pk_mul_f32 v[82:83], v[82:83], v[216:217] op_sel_hi:[1,0]
	v_pk_mul_f32 v[148:149], v[92:93], v[92:93]
	v_pk_fma_f32 v[148:149], v[94:95], v[94:95], v[148:149]
	v_pk_fma_f32 v[148:149], v[88:89], v[88:89], v[148:149]
	v_pk_fma_f32 v[148:149], v[90:91], v[90:91], v[148:149]
	v_pk_fma_f32 v[148:149], v[84:85], v[84:85], v[148:149]
	v_pk_fma_f32 v[148:149], v[86:87], v[86:87], v[148:149]
	v_pk_fma_f32 v[148:149], v[80:81], v[80:81], v[148:149]
	v_pk_fma_f32 v[148:149], v[82:83], v[82:83], v[148:149]
	v_add_f32_e32 v214, v148, v149
	v_mov_b32_e32 v215, v214
	s_nop 1
	v_permlane16_swap_b32_e32 v214, v215
	s_nop 0
	v_add_f32_e32 v214, v214, v215
	v_mov_b32_e32 v215, v214
	s_nop 1
	v_permlane32_swap_b32_e32 v214, v215
	s_nop 0
	v_add_f32_e32 v214, v214, v215
	v_fmamk_f32 v214, v214, 0x3c800000, v248
	v_rsq_f32_e32 v214, v214
	s_nop 0
	v_mul_f32_e32 v218, v155, v214
	v_pk_mul_f32 v[164:165], v[188:189], v[218:219] op_sel_hi:[1,0]
	v_pk_mul_f32 v[92:93], v[92:93], v[164:165]
	v_pk_mul_f32 v[164:165], v[190:191], v[218:219] op_sel_hi:[1,0]
	v_pk_mul_f32 v[94:95], v[94:95], v[164:165]
	v_pk_mul_f32 v[164:165], v[192:193], v[218:219] op_sel_hi:[1,0]
	v_pk_mul_f32 v[88:89], v[88:89], v[164:165]
	v_pk_mul_f32 v[164:165], v[194:195], v[218:219] op_sel_hi:[1,0]
	v_pk_mul_f32 v[90:91], v[90:91], v[164:165]
	v_cvt_pk_bf16_f32 v204, v92, v93
	v_cvt_pk_bf16_f32 v205, v94, v95
	v_cvt_pk_bf16_f32 v206, v88, v89
	v_cvt_pk_bf16_f32 v207, v90, v91
	global_store_dwordx4 v211, v[204:207], s[26:27]
	v_pk_mul_f32 v[164:165], v[196:197], v[218:219] op_sel_hi:[1,0]
	v_pk_mul_f32 v[84:85], v[84:85], v[164:165]
	v_pk_mul_f32 v[164:165], v[198:199], v[218:219] op_sel_hi:[1,0]
	v_pk_mul_f32 v[86:87], v[86:87], v[164:165]
	v_pk_mul_f32 v[164:165], v[200:201], v[218:219] op_sel_hi:[1,0]
	v_pk_mul_f32 v[80:81], v[80:81], v[164:165]
	v_pk_mul_f32 v[164:165], v[202:203], v[218:219] op_sel_hi:[1,0]
	v_pk_mul_f32 v[82:83], v[82:83], v[164:165]
	v_cvt_pk_bf16_f32 v144, v84, v85
	v_cvt_pk_bf16_f32 v145, v86, v87
	v_cvt_pk_bf16_f32 v146, v80, v81
	v_cvt_pk_bf16_f32 v147, v82, v83
	global_store_dwordx4 v211, v[144:147], s[26:27] offset:64
	v_add_u32_e32 v211, 0x10000, v211
	s_waitcnt vmcnt(10)
	v_pk_add_f32 v[168:169], v[168:169], v[170:171]
	s_nop 0
	v_add_f32_e32 v214, v168, v169
	v_mov_b32_e32 v215, v214
	s_nop 1
	v_permlane16_swap_b32_e32 v214, v215
	s_nop 0
	v_add_f32_e32 v214, v214, v215
	v_mov_b32_e32 v215, v214
	s_nop 1
	v_permlane32_swap_b32_e32 v214, v215
	s_nop 0
	v_add_f32_e32 v214, v214, v215
	v_fmamk_f32 v214, v214, 0x3a800000, v248
	v_rsq_f32_e32 v216, v214
	s_nop 0
	v_pk_mul_f32 v[76:77], v[76:77], v[216:217] op_sel_hi:[1,0]
	v_pk_mul_f32 v[78:79], v[78:79], v[216:217] op_sel_hi:[1,0]
	v_pk_mul_f32 v[72:73], v[72:73], v[216:217] op_sel_hi:[1,0]
	v_pk_mul_f32 v[74:75], v[74:75], v[216:217] op_sel_hi:[1,0]
	v_pk_mul_f32 v[68:69], v[68:69], v[216:217] op_sel_hi:[1,0]
	v_pk_mul_f32 v[70:71], v[70:71], v[216:217] op_sel_hi:[1,0]
	v_pk_mul_f32 v[64:65], v[64:65], v[216:217] op_sel_hi:[1,0]
	v_pk_mul_f32 v[66:67], v[66:67], v[216:217] op_sel_hi:[1,0]
	v_pk_mul_f32 v[148:149], v[76:77], v[76:77]
	v_pk_fma_f32 v[148:149], v[78:79], v[78:79], v[148:149]
	v_pk_fma_f32 v[148:149], v[72:73], v[72:73], v[148:149]
	v_pk_fma_f32 v[148:149], v[74:75], v[74:75], v[148:149]
	v_pk_fma_f32 v[148:149], v[68:69], v[68:69], v[148:149]
	v_pk_fma_f32 v[148:149], v[70:71], v[70:71], v[148:149]
	v_pk_fma_f32 v[148:149], v[64:65], v[64:65], v[148:149]
	v_pk_fma_f32 v[148:149], v[66:67], v[66:67], v[148:149]
	v_add_f32_e32 v214, v148, v149
	v_mov_b32_e32 v215, v214
	s_nop 1
	v_permlane16_swap_b32_e32 v214, v215
	s_nop 0
	v_add_f32_e32 v214, v214, v215
	v_mov_b32_e32 v215, v214
	s_nop 1
	v_permlane32_swap_b32_e32 v214, v215
	s_nop 0
	v_add_f32_e32 v214, v214, v215
	v_fmamk_f32 v214, v214, 0x3c800000, v248
	v_rsq_f32_e32 v214, v214
	s_nop 0
	v_mul_f32_e32 v218, v155, v214
	v_pk_mul_f32 v[168:169], v[188:189], v[218:219] op_sel_hi:[1,0]
	v_pk_mul_f32 v[76:77], v[76:77], v[168:169]
	v_pk_mul_f32 v[168:169], v[190:191], v[218:219] op_sel_hi:[1,0]
	v_pk_mul_f32 v[78:79], v[78:79], v[168:169]
	v_pk_mul_f32 v[168:169], v[192:193], v[218:219] op_sel_hi:[1,0]
	v_pk_mul_f32 v[72:73], v[72:73], v[168:169]
	v_pk_mul_f32 v[168:169], v[194:195], v[218:219] op_sel_hi:[1,0]
	v_pk_mul_f32 v[74:75], v[74:75], v[168:169]
	v_cvt_pk_bf16_f32 v204, v76, v77
	v_cvt_pk_bf16_f32 v205, v78, v79
	v_cvt_pk_bf16_f32 v206, v72, v73
	v_cvt_pk_bf16_f32 v207, v74, v75
	global_store_dwordx4 v211, v[204:207], s[26:27]
	v_pk_mul_f32 v[168:169], v[196:197], v[218:219] op_sel_hi:[1,0]
	v_pk_mul_f32 v[68:69], v[68:69], v[168:169]
	v_pk_mul_f32 v[168:169], v[198:199], v[218:219] op_sel_hi:[1,0]
	v_pk_mul_f32 v[70:71], v[70:71], v[168:169]
	v_pk_mul_f32 v[168:169], v[200:201], v[218:219] op_sel_hi:[1,0]
	v_pk_mul_f32 v[64:65], v[64:65], v[168:169]
	v_pk_mul_f32 v[168:169], v[202:203], v[218:219] op_sel_hi:[1,0]
	v_pk_mul_f32 v[66:67], v[66:67], v[168:169]
	v_cvt_pk_bf16_f32 v144, v68, v69
	v_cvt_pk_bf16_f32 v145, v70, v71
	v_cvt_pk_bf16_f32 v146, v64, v65
	v_cvt_pk_bf16_f32 v147, v66, v67
	global_store_dwordx4 v211, v[144:147], s[26:27] offset:64
	v_add_u32_e32 v211, 0x50000, v211
	s_waitcnt vmcnt(11)
	v_pk_add_f32 v[172:173], v[172:173], v[174:175]
	s_nop 0
	v_add_f32_e32 v214, v172, v173
	v_mov_b32_e32 v215, v214
	s_nop 1
	v_permlane16_swap_b32_e32 v214, v215
	s_nop 0
	v_add_f32_e32 v214, v214, v215
	v_mov_b32_e32 v215, v214
	s_nop 1
	v_permlane32_swap_b32_e32 v214, v215
	s_nop 0
	v_add_f32_e32 v214, v214, v215
	v_fmamk_f32 v214, v214, 0x3a800000, v248
	v_rsq_f32_e32 v216, v214
	s_nop 0
	v_pk_mul_f32 v[60:61], v[60:61], v[216:217] op_sel_hi:[1,0]
	v_pk_mul_f32 v[62:63], v[62:63], v[216:217] op_sel_hi:[1,0]
	v_pk_mul_f32 v[56:57], v[56:57], v[216:217] op_sel_hi:[1,0]
	v_pk_mul_f32 v[58:59], v[58:59], v[216:217] op_sel_hi:[1,0]
	v_pk_mul_f32 v[52:53], v[52:53], v[216:217] op_sel_hi:[1,0]
	v_pk_mul_f32 v[54:55], v[54:55], v[216:217] op_sel_hi:[1,0]
	v_pk_mul_f32 v[48:49], v[48:49], v[216:217] op_sel_hi:[1,0]
	v_pk_mul_f32 v[50:51], v[50:51], v[216:217] op_sel_hi:[1,0]
	v_pk_mul_f32 v[148:149], v[60:61], v[60:61]
	v_pk_fma_f32 v[148:149], v[62:63], v[62:63], v[148:149]
	v_pk_fma_f32 v[148:149], v[56:57], v[56:57], v[148:149]
	v_pk_fma_f32 v[148:149], v[58:59], v[58:59], v[148:149]
	v_pk_fma_f32 v[148:149], v[52:53], v[52:53], v[148:149]
	v_pk_fma_f32 v[148:149], v[54:55], v[54:55], v[148:149]
	v_pk_fma_f32 v[148:149], v[48:49], v[48:49], v[148:149]
	v_pk_fma_f32 v[148:149], v[50:51], v[50:51], v[148:149]
	v_add_f32_e32 v214, v148, v149
	v_mov_b32_e32 v215, v214
	s_nop 1
	v_permlane16_swap_b32_e32 v214, v215
	s_nop 0
	v_add_f32_e32 v214, v214, v215
	v_mov_b32_e32 v215, v214
	s_nop 1
	v_permlane32_swap_b32_e32 v214, v215
	s_nop 0
	v_add_f32_e32 v214, v214, v215
	v_fmamk_f32 v214, v214, 0x3c800000, v248
	v_rsq_f32_e32 v214, v214
	s_nop 0
	v_mul_f32_e32 v218, v155, v214
	v_pk_mul_f32 v[172:173], v[188:189], v[218:219] op_sel_hi:[1,0]
	v_pk_mul_f32 v[60:61], v[60:61], v[172:173]
	v_pk_mul_f32 v[172:173], v[190:191], v[218:219] op_sel_hi:[1,0]
	v_pk_mul_f32 v[62:63], v[62:63], v[172:173]
	v_pk_mul_f32 v[172:173], v[192:193], v[218:219] op_sel_hi:[1,0]
	v_pk_mul_f32 v[56:57], v[56:57], v[172:173]
	v_pk_mul_f32 v[172:173], v[194:195], v[218:219] op_sel_hi:[1,0]
	v_pk_mul_f32 v[58:59], v[58:59], v[172:173]
	v_cvt_pk_bf16_f32 v204, v60, v61
	v_cvt_pk_bf16_f32 v205, v62, v63
	v_cvt_pk_bf16_f32 v206, v56, v57
	v_cvt_pk_bf16_f32 v207, v58, v59
	global_store_dwordx4 v211, v[204:207], s[26:27]
	v_pk_mul_f32 v[172:173], v[196:197], v[218:219] op_sel_hi:[1,0]
	v_pk_mul_f32 v[52:53], v[52:53], v[172:173]
	v_pk_mul_f32 v[172:173], v[198:199], v[218:219] op_sel_hi:[1,0]
	v_pk_mul_f32 v[54:55], v[54:55], v[172:173]
	v_pk_mul_f32 v[172:173], v[200:201], v[218:219] op_sel_hi:[1,0]
	v_pk_mul_f32 v[48:49], v[48:49], v[172:173]
	v_pk_mul_f32 v[172:173], v[202:203], v[218:219] op_sel_hi:[1,0]
	v_pk_mul_f32 v[50:51], v[50:51], v[172:173]
	v_cvt_pk_bf16_f32 v144, v52, v53
	v_cvt_pk_bf16_f32 v145, v54, v55
	v_cvt_pk_bf16_f32 v146, v48, v49
	v_cvt_pk_bf16_f32 v147, v50, v51
	global_store_dwordx4 v211, v[144:147], s[26:27] offset:64
	v_add_u32_e32 v211, 0x10000, v211
	s_waitcnt vmcnt(12)
	v_pk_add_f32 v[176:177], v[176:177], v[178:179]
	s_nop 0
	v_add_f32_e32 v214, v176, v177
	v_mov_b32_e32 v215, v214
	s_nop 1
	v_permlane16_swap_b32_e32 v214, v215
	s_nop 0
	v_add_f32_e32 v214, v214, v215
	v_mov_b32_e32 v215, v214
	s_nop 1
	v_permlane32_swap_b32_e32 v214, v215
	s_nop 0
	v_add_f32_e32 v214, v214, v215
	v_fmamk_f32 v214, v214, 0x3a800000, v248
	v_rsq_f32_e32 v216, v214
	s_nop 0
	v_pk_mul_f32 v[44:45], v[44:45], v[216:217] op_sel_hi:[1,0]
	v_pk_mul_f32 v[46:47], v[46:47], v[216:217] op_sel_hi:[1,0]
	v_pk_mul_f32 v[40:41], v[40:41], v[216:217] op_sel_hi:[1,0]
	v_pk_mul_f32 v[42:43], v[42:43], v[216:217] op_sel_hi:[1,0]
	v_pk_mul_f32 v[36:37], v[36:37], v[216:217] op_sel_hi:[1,0]
	v_pk_mul_f32 v[38:39], v[38:39], v[216:217] op_sel_hi:[1,0]
	v_pk_mul_f32 v[32:33], v[32:33], v[216:217] op_sel_hi:[1,0]
	v_pk_mul_f32 v[34:35], v[34:35], v[216:217] op_sel_hi:[1,0]
	v_pk_mul_f32 v[148:149], v[44:45], v[44:45]
	v_pk_fma_f32 v[148:149], v[46:47], v[46:47], v[148:149]
	v_pk_fma_f32 v[148:149], v[40:41], v[40:41], v[148:149]
	v_pk_fma_f32 v[148:149], v[42:43], v[42:43], v[148:149]
	v_pk_fma_f32 v[148:149], v[36:37], v[36:37], v[148:149]
	v_pk_fma_f32 v[148:149], v[38:39], v[38:39], v[148:149]
	v_pk_fma_f32 v[148:149], v[32:33], v[32:33], v[148:149]
	v_pk_fma_f32 v[148:149], v[34:35], v[34:35], v[148:149]
	v_add_f32_e32 v214, v148, v149
	v_mov_b32_e32 v215, v214
	s_nop 1
	v_permlane16_swap_b32_e32 v214, v215
	s_nop 0
	v_add_f32_e32 v214, v214, v215
	v_mov_b32_e32 v215, v214
	s_nop 1
	v_permlane32_swap_b32_e32 v214, v215
	s_nop 0
	v_add_f32_e32 v214, v214, v215
	v_fmamk_f32 v214, v214, 0x3c800000, v248
	v_rsq_f32_e32 v214, v214
	s_nop 0
	v_mul_f32_e32 v218, v155, v214
	v_pk_mul_f32 v[176:177], v[188:189], v[218:219] op_sel_hi:[1,0]
	v_pk_mul_f32 v[44:45], v[44:45], v[176:177]
	v_pk_mul_f32 v[176:177], v[190:191], v[218:219] op_sel_hi:[1,0]
	v_pk_mul_f32 v[46:47], v[46:47], v[176:177]
	v_pk_mul_f32 v[176:177], v[192:193], v[218:219] op_sel_hi:[1,0]
	v_pk_mul_f32 v[40:41], v[40:41], v[176:177]
	v_pk_mul_f32 v[176:177], v[194:195], v[218:219] op_sel_hi:[1,0]
	v_pk_mul_f32 v[42:43], v[42:43], v[176:177]
	v_cvt_pk_bf16_f32 v204, v44, v45
	v_cvt_pk_bf16_f32 v205, v46, v47
	v_cvt_pk_bf16_f32 v206, v40, v41
	v_cvt_pk_bf16_f32 v207, v42, v43
	global_store_dwordx4 v211, v[204:207], s[26:27]
	v_pk_mul_f32 v[176:177], v[196:197], v[218:219] op_sel_hi:[1,0]
	v_pk_mul_f32 v[36:37], v[36:37], v[176:177]
	v_pk_mul_f32 v[176:177], v[198:199], v[218:219] op_sel_hi:[1,0]
	v_pk_mul_f32 v[38:39], v[38:39], v[176:177]
	v_pk_mul_f32 v[176:177], v[200:201], v[218:219] op_sel_hi:[1,0]
	v_pk_mul_f32 v[32:33], v[32:33], v[176:177]
	v_pk_mul_f32 v[176:177], v[202:203], v[218:219] op_sel_hi:[1,0]
	v_pk_mul_f32 v[34:35], v[34:35], v[176:177]
	v_cvt_pk_bf16_f32 v144, v36, v37
	v_cvt_pk_bf16_f32 v145, v38, v39
	v_cvt_pk_bf16_f32 v146, v32, v33
	v_cvt_pk_bf16_f32 v147, v34, v35
	global_store_dwordx4 v211, v[144:147], s[26:27] offset:64
	v_add_u32_e32 v211, 0x10000, v211
	s_waitcnt vmcnt(13)
	v_pk_add_f32 v[180:181], v[180:181], v[182:183]
	s_nop 0
	v_add_f32_e32 v214, v180, v181
	v_mov_b32_e32 v215, v214
	s_nop 1
	v_permlane16_swap_b32_e32 v214, v215
	s_nop 0
	v_add_f32_e32 v214, v214, v215
	v_mov_b32_e32 v215, v214
	s_nop 1
	v_permlane32_swap_b32_e32 v214, v215
	s_nop 0
	v_add_f32_e32 v214, v214, v215
	v_fmamk_f32 v214, v214, 0x3a800000, v248
	v_rsq_f32_e32 v216, v214
	s_nop 0
	v_pk_mul_f32 v[28:29], v[28:29], v[216:217] op_sel_hi:[1,0]
	v_pk_mul_f32 v[30:31], v[30:31], v[216:217] op_sel_hi:[1,0]
	v_pk_mul_f32 v[24:25], v[24:25], v[216:217] op_sel_hi:[1,0]
	v_pk_mul_f32 v[26:27], v[26:27], v[216:217] op_sel_hi:[1,0]
	v_pk_mul_f32 v[20:21], v[20:21], v[216:217] op_sel_hi:[1,0]
	v_pk_mul_f32 v[22:23], v[22:23], v[216:217] op_sel_hi:[1,0]
	v_pk_mul_f32 v[16:17], v[16:17], v[216:217] op_sel_hi:[1,0]
	v_pk_mul_f32 v[18:19], v[18:19], v[216:217] op_sel_hi:[1,0]
	v_pk_mul_f32 v[148:149], v[28:29], v[28:29]
	v_pk_fma_f32 v[148:149], v[30:31], v[30:31], v[148:149]
	v_pk_fma_f32 v[148:149], v[24:25], v[24:25], v[148:149]
	v_pk_fma_f32 v[148:149], v[26:27], v[26:27], v[148:149]
	v_pk_fma_f32 v[148:149], v[20:21], v[20:21], v[148:149]
	v_pk_fma_f32 v[148:149], v[22:23], v[22:23], v[148:149]
	v_pk_fma_f32 v[148:149], v[16:17], v[16:17], v[148:149]
	v_pk_fma_f32 v[148:149], v[18:19], v[18:19], v[148:149]
	v_add_f32_e32 v214, v148, v149
	v_mov_b32_e32 v215, v214
	s_nop 1
	v_permlane16_swap_b32_e32 v214, v215
	s_nop 0
	v_add_f32_e32 v214, v214, v215
	v_mov_b32_e32 v215, v214
	s_nop 1
	v_permlane32_swap_b32_e32 v214, v215
	s_nop 0
	v_add_f32_e32 v214, v214, v215
	v_fmamk_f32 v214, v214, 0x3c800000, v248
	v_rsq_f32_e32 v214, v214
	s_nop 0
	v_mul_f32_e32 v218, v155, v214
	v_pk_mul_f32 v[180:181], v[188:189], v[218:219] op_sel_hi:[1,0]
	v_pk_mul_f32 v[28:29], v[28:29], v[180:181]
	v_pk_mul_f32 v[180:181], v[190:191], v[218:219] op_sel_hi:[1,0]
	v_pk_mul_f32 v[30:31], v[30:31], v[180:181]
	v_pk_mul_f32 v[180:181], v[192:193], v[218:219] op_sel_hi:[1,0]
	v_pk_mul_f32 v[24:25], v[24:25], v[180:181]
	v_pk_mul_f32 v[180:181], v[194:195], v[218:219] op_sel_hi:[1,0]
	v_pk_mul_f32 v[26:27], v[26:27], v[180:181]
	v_cvt_pk_bf16_f32 v204, v28, v29
	v_cvt_pk_bf16_f32 v205, v30, v31
	v_cvt_pk_bf16_f32 v206, v24, v25
	v_cvt_pk_bf16_f32 v207, v26, v27
	global_store_dwordx4 v211, v[204:207], s[26:27]
	v_pk_mul_f32 v[180:181], v[196:197], v[218:219] op_sel_hi:[1,0]
	v_pk_mul_f32 v[20:21], v[20:21], v[180:181]
	v_pk_mul_f32 v[180:181], v[198:199], v[218:219] op_sel_hi:[1,0]
	v_pk_mul_f32 v[22:23], v[22:23], v[180:181]
	v_pk_mul_f32 v[180:181], v[200:201], v[218:219] op_sel_hi:[1,0]
	v_pk_mul_f32 v[16:17], v[16:17], v[180:181]
	v_pk_mul_f32 v[180:181], v[202:203], v[218:219] op_sel_hi:[1,0]
	v_pk_mul_f32 v[18:19], v[18:19], v[180:181]
	v_cvt_pk_bf16_f32 v144, v20, v21
	v_cvt_pk_bf16_f32 v145, v22, v23
	v_cvt_pk_bf16_f32 v146, v16, v17
	v_cvt_pk_bf16_f32 v147, v18, v19
	global_store_dwordx4 v211, v[144:147], s[26:27] offset:64
	v_add_u32_e32 v211, 0x10000, v211
	s_waitcnt vmcnt(14)
	v_pk_add_f32 v[184:185], v[184:185], v[186:187]
	s_nop 0
	v_add_f32_e32 v214, v184, v185
	v_mov_b32_e32 v215, v214
	s_nop 1
	v_permlane16_swap_b32_e32 v214, v215
	s_nop 0
	v_add_f32_e32 v214, v214, v215
	v_mov_b32_e32 v215, v214
	s_nop 1
	v_permlane32_swap_b32_e32 v214, v215
	s_nop 0
	v_add_f32_e32 v214, v214, v215
	v_fmamk_f32 v214, v214, 0x3a800000, v248
	v_rsq_f32_e32 v216, v214
	s_nop 0
	v_pk_mul_f32 v[12:13], v[12:13], v[216:217] op_sel_hi:[1,0]
	v_pk_mul_f32 v[14:15], v[14:15], v[216:217] op_sel_hi:[1,0]
	v_pk_mul_f32 v[8:9], v[8:9], v[216:217] op_sel_hi:[1,0]
	v_pk_mul_f32 v[10:11], v[10:11], v[216:217] op_sel_hi:[1,0]
	v_pk_mul_f32 v[4:5], v[4:5], v[216:217] op_sel_hi:[1,0]
	v_pk_mul_f32 v[6:7], v[6:7], v[216:217] op_sel_hi:[1,0]
	v_pk_mul_f32 v[0:1], v[0:1], v[216:217] op_sel_hi:[1,0]
	v_pk_mul_f32 v[2:3], v[2:3], v[216:217] op_sel_hi:[1,0]
	v_pk_mul_f32 v[148:149], v[12:13], v[12:13]
	v_pk_fma_f32 v[148:149], v[14:15], v[14:15], v[148:149]
	v_pk_fma_f32 v[148:149], v[8:9], v[8:9], v[148:149]
	v_pk_fma_f32 v[148:149], v[10:11], v[10:11], v[148:149]
	v_pk_fma_f32 v[148:149], v[4:5], v[4:5], v[148:149]
	v_pk_fma_f32 v[148:149], v[6:7], v[6:7], v[148:149]
	v_pk_fma_f32 v[148:149], v[0:1], v[0:1], v[148:149]
	v_pk_fma_f32 v[148:149], v[2:3], v[2:3], v[148:149]
	v_add_f32_e32 v214, v148, v149
	v_mov_b32_e32 v215, v214
	s_nop 1
	v_permlane16_swap_b32_e32 v214, v215
	s_nop 0
	v_add_f32_e32 v214, v214, v215
	v_mov_b32_e32 v215, v214
	s_nop 1
	v_permlane32_swap_b32_e32 v214, v215
	s_nop 0
	v_add_f32_e32 v214, v214, v215
	v_fmamk_f32 v214, v214, 0x3c800000, v248
	v_rsq_f32_e32 v214, v214
	s_nop 0
	v_mul_f32_e32 v218, v155, v214
	v_pk_mul_f32 v[184:185], v[188:189], v[218:219] op_sel_hi:[1,0]
	v_pk_mul_f32 v[12:13], v[12:13], v[184:185]
	v_pk_mul_f32 v[184:185], v[190:191], v[218:219] op_sel_hi:[1,0]
	v_pk_mul_f32 v[14:15], v[14:15], v[184:185]
	v_pk_mul_f32 v[184:185], v[192:193], v[218:219] op_sel_hi:[1,0]
	v_pk_mul_f32 v[8:9], v[8:9], v[184:185]
	v_pk_mul_f32 v[184:185], v[194:195], v[218:219] op_sel_hi:[1,0]
	v_pk_mul_f32 v[10:11], v[10:11], v[184:185]
	v_cvt_pk_bf16_f32 v204, v12, v13
	v_cvt_pk_bf16_f32 v205, v14, v15
	v_cvt_pk_bf16_f32 v206, v8, v9
	v_cvt_pk_bf16_f32 v207, v10, v11
	global_store_dwordx4 v211, v[204:207], s[26:27]
	v_pk_mul_f32 v[184:185], v[196:197], v[218:219] op_sel_hi:[1,0]
	v_pk_mul_f32 v[4:5], v[4:5], v[184:185]
	v_pk_mul_f32 v[184:185], v[198:199], v[218:219] op_sel_hi:[1,0]
	v_pk_mul_f32 v[6:7], v[6:7], v[184:185]
	v_pk_mul_f32 v[184:185], v[200:201], v[218:219] op_sel_hi:[1,0]
	v_pk_mul_f32 v[0:1], v[0:1], v[184:185]
	v_pk_mul_f32 v[184:185], v[202:203], v[218:219] op_sel_hi:[1,0]
	v_pk_mul_f32 v[2:3], v[2:3], v[184:185]
	v_cvt_pk_bf16_f32 v144, v4, v5
	v_cvt_pk_bf16_f32 v145, v6, v7
	v_cvt_pk_bf16_f32 v146, v0, v1
	v_cvt_pk_bf16_f32 v147, v2, v3
	global_store_dwordx4 v211, v[144:147], s[26:27] offset:64
	s_and_b64 vcc, exec, s[4:5]
	s_mov_b64 s[26:27], s[22:23]
	s_cbranch_vccz .LBB0_691
	s_waitcnt vmcnt(0)
	s_cmpk_gt_u32 s54, 0xff
	s_cbranch_scc1 .LBB0_702
	s_barrier

.LBB0_714:
	s_add_u32 s26, s6, 0xfffc0080
	s_addc_u32 s27, s7, -1
	s_add_i32 s63, 0, 0x10000
	v_add_u32_e32 v140, s63, v165
	ds_read_b128 v[128:131], v140
	ds_read_b128 v[132:135], v140 offset:1024
	ds_read_b128 v[136:139], v140 offset:2048
	ds_read_b128 v[140:143], v140 offset:3072
	s_cmp_eq_u32 s51, 12
	s_cselect_b32 s29, s21, s27
	s_cselect_b32 s28, s38, s26
	s_cselect_b32 s27, s11, s50
	s_cselect_b32 s26, s39, s46
	v_lshl_add_u64 v[162:163], s[6:7], 0, v[150:151]
	s_add_i32 m0, s56, 0xc000
	ds_read_b128 v[154:157], v167
	ds_read_b128 v[158:161], v167 offset:1024
	ds_read_b128 v[168:171], v167 offset:2048
	ds_read_b128 v[172:175], v167 offset:3072
	ds_read_b128 v[176:179], v167 offset:4096
	ds_read_b128 v[180:183], v167 offset:5120
	ds_read_b128 v[184:187], v167 offset:6144
	ds_read_b128 v[188:191], v167 offset:7168
	global_load_lds_dwordx4 v[162:163], off
	v_lshl_add_u64 v[162:163], s[6:7], 0, v[152:153]
	s_add_i32 m0, s56, 0xe000
	s_nop 0
	global_load_lds_dwordx4 v[162:163], off
	s_waitcnt lgkmcnt(8)
	s_barrier
	s_waitcnt lgkmcnt(0)
	s_setprio 1
	v_mfma_f32_16x16x32_bf16 v[124:127], v[128:131], v[154:157], v[124:127]
	v_mfma_f32_16x16x32_bf16 v[120:123], v[136:139], v[154:157], v[120:123]
	v_mfma_f32_16x16x32_bf16 v[116:119], v[128:131], v[168:171], v[116:119]
	v_mfma_f32_16x16x32_bf16 v[112:115], v[136:139], v[168:171], v[112:115]
	v_mfma_f32_16x16x32_bf16 v[108:111], v[128:131], v[176:179], v[108:111]
	v_mfma_f32_16x16x32_bf16 v[104:107], v[136:139], v[176:179], v[104:107]
	v_mfma_f32_16x16x32_bf16 v[100:103], v[128:131], v[184:187], v[100:103]
	v_mfma_f32_16x16x32_bf16 v[96:99], v[136:139], v[184:187], v[96:99]
	v_mfma_f32_16x16x32_bf16 v[124:127], v[132:135], v[158:161], v[124:127]
	v_mfma_f32_16x16x32_bf16 v[120:123], v[140:143], v[158:161], v[120:123]
	v_mfma_f32_16x16x32_bf16 v[116:119], v[132:135], v[172:175], v[116:119]
	v_mfma_f32_16x16x32_bf16 v[112:115], v[140:143], v[172:175], v[112:115]
	v_mfma_f32_16x16x32_bf16 v[108:111], v[132:135], v[180:183], v[108:111]
	v_mfma_f32_16x16x32_bf16 v[104:107], v[140:143], v[180:183], v[104:107]
	v_mfma_f32_16x16x32_bf16 v[100:103], v[132:135], v[188:191], v[100:103]
	v_mfma_f32_16x16x32_bf16 v[96:99], v[140:143], v[188:191], v[96:99]
	s_setprio 0
	s_barrier
	s_add_i32 s66, 0, 0x14000
	v_add_u32_e32 v162, s66, v165
	s_add_i32 s63, s63, s55
	ds_read_b128 v[192:195], v162
	ds_read_b128 v[196:199], v162 offset:1024
	ds_read_b128 v[200:203], v162 offset:2048
	ds_read_b128 v[204:207], v162 offset:3072
	v_lshl_add_u64 v[162:163], s[26:27], 0, v[208:209]
	s_mov_b32 m0, s63
	v_lshl_add_u64 v[210:211], s[26:27], 0, v[144:145]
	global_load_lds_dwordx4 v[162:163], off
	s_add_i32 m0, s63, 0x2000
	s_nop 0
	global_load_lds_dwordx4 v[210:211], off
	s_barrier
	s_waitcnt lgkmcnt(0)
	s_setprio 1
	v_mfma_f32_16x16x32_bf16 v[60:63], v[192:195], v[154:157], v[60:63]
	v_mfma_f32_16x16x32_bf16 v[56:59], v[200:203], v[154:157], v[56:59]
	v_mfma_f32_16x16x32_bf16 v[52:55], v[192:195], v[168:171], v[52:55]
	v_mfma_f32_16x16x32_bf16 v[48:51], v[200:203], v[168:171], v[48:51]
	v_mfma_f32_16x16x32_bf16 v[44:47], v[192:195], v[176:179], v[44:47]
	v_mfma_f32_16x16x32_bf16 v[40:43], v[200:203], v[176:179], v[40:43]
	v_mfma_f32_16x16x32_bf16 v[36:39], v[192:195], v[184:187], v[36:39]
	v_mfma_f32_16x16x32_bf16 v[32:35], v[200:203], v[184:187], v[32:35]
	v_mfma_f32_16x16x32_bf16 v[60:63], v[196:199], v[158:161], v[60:63]
	v_mfma_f32_16x16x32_bf16 v[56:59], v[204:207], v[158:161], v[56:59]
	v_mfma_f32_16x16x32_bf16 v[52:55], v[196:199], v[172:175], v[52:55]
	v_mfma_f32_16x16x32_bf16 v[48:51], v[204:207], v[172:175], v[48:51]
	v_mfma_f32_16x16x32_bf16 v[44:47], v[196:199], v[180:183], v[44:47]
	v_mfma_f32_16x16x32_bf16 v[40:43], v[204:207], v[180:183], v[40:43]
	v_mfma_f32_16x16x32_bf16 v[36:39], v[196:199], v[188:191], v[36:39]
	v_mfma_f32_16x16x32_bf16 v[32:35], v[204:207], v[188:191], v[32:35]
	s_setprio 0
	s_mov_b32 m0, s56
	v_lshl_add_u64 v[214:215], s[28:29], 0, v[148:149]
	s_barrier
	ds_read_b128 v[154:157], v167 offset:16384
	ds_read_b128 v[158:161], v167 offset:17408
	ds_read_b128 v[168:171], v167 offset:18432
	ds_read_b128 v[172:175], v167 offset:19456
	ds_read_b128 v[176:179], v167 offset:20480
	ds_read_b128 v[180:183], v167 offset:21504
	ds_read_b128 v[184:187], v167 offset:22528
	ds_read_b128 v[188:191], v167 offset:23552
	global_load_lds_dwordx4 v[214:215], off
	v_lshl_add_u64 v[216:217], s[28:29], 0, v[146:147]
	s_mov_b32 m0, s57
	s_nop 0
	global_load_lds_dwordx4 v[216:217], off
	s_barrier
	s_waitcnt lgkmcnt(0)
	s_setprio 1
	v_mfma_f32_16x16x32_bf16 v[92:95], v[128:131], v[154:157], v[92:95]
	v_mfma_f32_16x16x32_bf16 v[88:91], v[136:139], v[154:157], v[88:91]
	v_mfma_f32_16x16x32_bf16 v[84:87], v[128:131], v[168:171], v[84:87]
	v_mfma_f32_16x16x32_bf16 v[80:83], v[136:139], v[168:171], v[80:83]
	v_mfma_f32_16x16x32_bf16 v[76:79], v[128:131], v[176:179], v[76:79]
	v_mfma_f32_16x16x32_bf16 v[72:75], v[136:139], v[176:179], v[72:75]
	v_mfma_f32_16x16x32_bf16 v[68:71], v[128:131], v[184:187], v[68:71]
	v_mfma_f32_16x16x32_bf16 v[64:67], v[136:139], v[184:187], v[64:67]
	v_mfma_f32_16x16x32_bf16 v[92:95], v[132:135], v[158:161], v[92:95]
	v_mfma_f32_16x16x32_bf16 v[88:91], v[140:143], v[158:161], v[88:91]
	v_mfma_f32_16x16x32_bf16 v[84:87], v[132:135], v[172:175], v[84:87]
	v_mfma_f32_16x16x32_bf16 v[80:83], v[140:143], v[172:175], v[80:83]
	v_mfma_f32_16x16x32_bf16 v[76:79], v[132:135], v[180:183], v[76:79]
	v_mfma_f32_16x16x32_bf16 v[72:75], v[140:143], v[180:183], v[72:75]
	v_mfma_f32_16x16x32_bf16 v[68:71], v[132:135], v[188:191], v[68:71]
	v_mfma_f32_16x16x32_bf16 v[64:67], v[140:143], v[188:191], v[64:67]
	s_setprio 0
	s_barrier
	s_add_u32 s64, s26, 0x40000
	s_addc_u32 s65, s27, 0
	s_add_i32 s63, s66, s55
	v_lshl_add_u64 v[128:129], s[64:65], 0, v[208:209]
	s_mov_b32 m0, s63
	s_nop 0
	global_load_lds_dwordx4 v[128:129], off
	v_lshl_add_u64 v[128:129], s[64:65], 0, v[144:145]
	s_add_i32 m0, s63, 0x2000
	s_nop 0
	global_load_lds_dwordx4 v[128:129], off
	s_waitcnt vmcnt(6)
	s_barrier
	s_setprio 1
	v_mfma_f32_16x16x32_bf16 v[28:31], v[192:195], v[154:157], v[28:31]
	v_mfma_f32_16x16x32_bf16 v[24:27], v[200:203], v[154:157], v[24:27]
	v_mfma_f32_16x16x32_bf16 v[20:23], v[192:195], v[168:171], v[20:23]
	v_mfma_f32_16x16x32_bf16 v[16:19], v[200:203], v[168:171], v[16:19]
	v_mfma_f32_16x16x32_bf16 v[12:15], v[192:195], v[176:179], v[12:15]
	v_mfma_f32_16x16x32_bf16 v[8:11], v[200:203], v[176:179], v[8:11]
	v_mfma_f32_16x16x32_bf16 v[4:7], v[192:195], v[184:187], v[4:7]
	v_mfma_f32_16x16x32_bf16 v[0:3], v[200:203], v[184:187], v[0:3]
	v_mfma_f32_16x16x32_bf16 v[28:31], v[196:199], v[158:161], v[28:31]
	v_mfma_f32_16x16x32_bf16 v[24:27], v[204:207], v[158:161], v[24:27]
	v_mfma_f32_16x16x32_bf16 v[20:23], v[196:199], v[172:175], v[20:23]
	v_mfma_f32_16x16x32_bf16 v[16:19], v[204:207], v[172:175], v[16:19]
	v_mfma_f32_16x16x32_bf16 v[12:15], v[196:199], v[180:183], v[12:15]
	v_mfma_f32_16x16x32_bf16 v[8:11], v[204:207], v[180:183], v[8:11]
	v_mfma_f32_16x16x32_bf16 v[4:7], v[196:199], v[188:191], v[4:7]
	v_mfma_f32_16x16x32_bf16 v[0:3], v[204:207], v[188:191], v[0:3]
	s_setprio 0
	s_add_i32 s63, 0, 0x18000
	v_add_u32_e32 v140, s63, v165
	s_barrier
	ds_read_b128 v[128:131], v140
	ds_read_b128 v[132:135], v140 offset:1024
	ds_read_b128 v[136:139], v140 offset:2048
	ds_read_b128 v[140:143], v140 offset:3072
	s_add_u32 s28, s28, 0x40000
	s_addc_u32 s29, s29, 0
	s_mov_b32 m0, s58
	v_lshl_add_u64 v[192:193], s[28:29], 0, v[148:149]
	ds_read_b128 v[154:157], v167 offset:32768
	ds_read_b128 v[158:161], v167 offset:33792
	ds_read_b128 v[168:171], v167 offset:34816
	ds_read_b128 v[172:175], v167 offset:35840
	ds_read_b128 v[176:179], v167 offset:36864
	ds_read_b128 v[180:183], v167 offset:37888
	ds_read_b128 v[184:187], v167 offset:38912
	ds_read_b128 v[188:191], v167 offset:39936
	global_load_lds_dwordx4 v[192:193], off
	v_lshl_add_u64 v[192:193], s[28:29], 0, v[146:147]
	s_mov_b32 m0, s59
	s_nop 0
	global_load_lds_dwordx4 v[192:193], off
	s_waitcnt lgkmcnt(8)
	s_barrier
	s_waitcnt lgkmcnt(0)
	s_setprio 1
	v_mfma_f32_16x16x32_bf16 v[124:127], v[128:131], v[154:157], v[124:127]
	v_mfma_f32_16x16x32_bf16 v[120:123], v[136:139], v[154:157], v[120:123]
	v_mfma_f32_16x16x32_bf16 v[116:119], v[128:131], v[168:171], v[116:119]
	v_mfma_f32_16x16x32_bf16 v[112:115], v[136:139], v[168:171], v[112:115]
	v_mfma_f32_16x16x32_bf16 v[108:111], v[128:131], v[176:179], v[108:111]
	v_mfma_f32_16x16x32_bf16 v[104:107], v[136:139], v[176:179], v[104:107]
	v_mfma_f32_16x16x32_bf16 v[100:103], v[128:131], v[184:187], v[100:103]
	v_mfma_f32_16x16x32_bf16 v[96:99], v[136:139], v[184:187], v[96:99]
	v_mfma_f32_16x16x32_bf16 v[124:127], v[132:135], v[158:161], v[124:127]
	v_mfma_f32_16x16x32_bf16 v[120:123], v[140:143], v[158:161], v[120:123]
	v_mfma_f32_16x16x32_bf16 v[116:119], v[132:135], v[172:175], v[116:119]
	v_mfma_f32_16x16x32_bf16 v[112:115], v[140:143], v[172:175], v[112:115]
	v_mfma_f32_16x16x32_bf16 v[108:111], v[132:135], v[180:183], v[108:111]
	v_mfma_f32_16x16x32_bf16 v[104:107], v[140:143], v[180:183], v[104:107]
	v_mfma_f32_16x16x32_bf16 v[100:103], v[132:135], v[188:191], v[100:103]
	v_mfma_f32_16x16x32_bf16 v[96:99], v[140:143], v[188:191], v[96:99]
	s_setprio 0
	s_barrier
	s_add_i32 s28, 0, 0x1c000
	s_add_i32 s29, s63, s55
	v_add_u32_e32 v204, s28, v165
	v_lshl_add_u64 v[162:163], v[162:163], 0, s[40:41]
	s_mov_b32 m0, s29
	ds_read_b128 v[192:195], v204
	ds_read_b128 v[196:199], v204 offset:1024
	ds_read_b128 v[200:203], v204 offset:2048
	ds_read_b128 v[204:207], v204 offset:3072
	global_load_lds_dwordx4 v[162:163], off
	v_lshl_add_u64 v[162:163], v[210:211], 0, s[40:41]
	s_add_i32 m0, s29, 0x2000
	s_nop 0
	global_load_lds_dwordx4 v[162:163], off
	s_barrier
	s_waitcnt lgkmcnt(0)
	s_setprio 1
	v_mfma_f32_16x16x32_bf16 v[60:63], v[192:195], v[154:157], v[60:63]
	v_mfma_f32_16x16x32_bf16 v[56:59], v[200:203], v[154:157], v[56:59]
	v_mfma_f32_16x16x32_bf16 v[52:55], v[192:195], v[168:171], v[52:55]
	v_mfma_f32_16x16x32_bf16 v[48:51], v[200:203], v[168:171], v[48:51]
	v_mfma_f32_16x16x32_bf16 v[44:47], v[192:195], v[176:179], v[44:47]
	v_mfma_f32_16x16x32_bf16 v[40:43], v[200:203], v[176:179], v[40:43]
	v_mfma_f32_16x16x32_bf16 v[36:39], v[192:195], v[184:187], v[36:39]
	v_mfma_f32_16x16x32_bf16 v[32:35], v[200:203], v[184:187], v[32:35]
	v_mfma_f32_16x16x32_bf16 v[60:63], v[196:199], v[158:161], v[60:63]
	v_mfma_f32_16x16x32_bf16 v[56:59], v[204:207], v[158:161], v[56:59]
	v_mfma_f32_16x16x32_bf16 v[52:55], v[196:199], v[172:175], v[52:55]
	v_mfma_f32_16x16x32_bf16 v[48:51], v[204:207], v[172:175], v[48:51]
	v_mfma_f32_16x16x32_bf16 v[44:47], v[196:199], v[180:183], v[44:47]
	v_mfma_f32_16x16x32_bf16 v[40:43], v[204:207], v[180:183], v[40:43]
	v_mfma_f32_16x16x32_bf16 v[36:39], v[196:199], v[188:191], v[36:39]
	v_mfma_f32_16x16x32_bf16 v[32:35], v[204:207], v[188:191], v[32:35]
	s_setprio 0
	s_mov_b32 m0, s60
	v_lshl_add_u64 v[162:163], v[214:215], 0, s[40:41]
	s_barrier
	ds_read_b128 v[154:157], v167 offset:49152
	ds_read_b128 v[158:161], v167 offset:50176
	ds_read_b128 v[168:171], v167 offset:51200
	ds_read_b128 v[172:175], v167 offset:52224
	ds_read_b128 v[176:179], v167 offset:53248
	ds_read_b128 v[180:183], v167 offset:54272
	ds_read_b128 v[184:187], v167 offset:55296
	ds_read_b128 v[188:191], v167 offset:56320
	global_load_lds_dwordx4 v[162:163], off
	v_lshl_add_u64 v[162:163], v[216:217], 0, s[40:41]
	s_mov_b32 m0, s61
	s_nop 0
	global_load_lds_dwordx4 v[162:163], off
	s_barrier
	s_waitcnt lgkmcnt(0)
	s_setprio 1
	v_mfma_f32_16x16x32_bf16 v[92:95], v[128:131], v[154:157], v[92:95]
	v_mfma_f32_16x16x32_bf16 v[88:91], v[136:139], v[154:157], v[88:91]
	v_mfma_f32_16x16x32_bf16 v[84:87], v[128:131], v[168:171], v[84:87]
	v_mfma_f32_16x16x32_bf16 v[80:83], v[136:139], v[168:171], v[80:83]
	v_mfma_f32_16x16x32_bf16 v[76:79], v[128:131], v[176:179], v[76:79]
	v_mfma_f32_16x16x32_bf16 v[72:75], v[136:139], v[176:179], v[72:75]
	v_mfma_f32_16x16x32_bf16 v[68:71], v[128:131], v[184:187], v[68:71]
	v_mfma_f32_16x16x32_bf16 v[64:67], v[136:139], v[184:187], v[64:67]
	v_mfma_f32_16x16x32_bf16 v[92:95], v[132:135], v[158:161], v[92:95]
	v_mfma_f32_16x16x32_bf16 v[88:91], v[140:143], v[158:161], v[88:91]
	v_mfma_f32_16x16x32_bf16 v[84:87], v[132:135], v[172:175], v[84:87]
	v_mfma_f32_16x16x32_bf16 v[80:83], v[140:143], v[172:175], v[80:83]
	v_mfma_f32_16x16x32_bf16 v[76:79], v[132:135], v[180:183], v[76:79]
	v_mfma_f32_16x16x32_bf16 v[72:75], v[140:143], v[180:183], v[72:75]
	v_mfma_f32_16x16x32_bf16 v[68:71], v[132:135], v[188:191], v[68:71]
	v_mfma_f32_16x16x32_bf16 v[64:67], v[140:143], v[188:191], v[64:67]
	s_setprio 0
	s_barrier
	s_add_u32 s26, s26, 0x40080
	s_addc_u32 s27, s27, 0
	s_add_i32 s28, s28, s55
	v_lshl_add_u64 v[128:129], s[26:27], 0, v[208:209]
	s_mov_b32 m0, s28
	s_nop 0
	global_load_lds_dwordx4 v[128:129], off
	v_lshl_add_u64 v[128:129], s[26:27], 0, v[144:145]
	s_add_i32 m0, s28, 0x2000
	s_nop 0
	global_load_lds_dwordx4 v[128:129], off
	s_waitcnt vmcnt(6)
	s_barrier
	s_setprio 1
	v_mfma_f32_16x16x32_bf16 v[28:31], v[192:195], v[154:157], v[28:31]
	v_mfma_f32_16x16x32_bf16 v[24:27], v[200:203], v[154:157], v[24:27]
	v_mfma_f32_16x16x32_bf16 v[20:23], v[192:195], v[168:171], v[20:23]
	v_mfma_f32_16x16x32_bf16 v[16:19], v[200:203], v[168:171], v[16:19]
	v_mfma_f32_16x16x32_bf16 v[12:15], v[192:195], v[176:179], v[12:15]
	v_mfma_f32_16x16x32_bf16 v[8:11], v[200:203], v[176:179], v[8:11]
	v_mfma_f32_16x16x32_bf16 v[4:7], v[192:195], v[184:187], v[4:7]
	v_mfma_f32_16x16x32_bf16 v[0:3], v[200:203], v[184:187], v[0:3]
	v_mfma_f32_16x16x32_bf16 v[28:31], v[196:199], v[158:161], v[28:31]
	v_mfma_f32_16x16x32_bf16 v[24:27], v[204:207], v[158:161], v[24:27]
	v_mfma_f32_16x16x32_bf16 v[20:23], v[196:199], v[172:175], v[20:23]
	v_mfma_f32_16x16x32_bf16 v[16:19], v[204:207], v[172:175], v[16:19]
	v_mfma_f32_16x16x32_bf16 v[12:15], v[196:199], v[180:183], v[12:15]
	v_mfma_f32_16x16x32_bf16 v[8:11], v[204:207], v[180:183], v[8:11]
	v_mfma_f32_16x16x32_bf16 v[4:7], v[196:199], v[188:191], v[4:7]
	v_mfma_f32_16x16x32_bf16 v[0:3], v[204:207], v[188:191], v[0:3]
	s_setprio 0
	s_add_i32 s51, s51, 2
	s_add_u32 s6, s6, 0x100
	s_addc_u32 s7, s7, 0
	s_add_u32 s46, s46, 0x100
	s_addc_u32 s50, s50, 0
	s_cmp_gt_u32 s51, 13
	s_barrier
	s_cbranch_scc0 .LBB0_714
	v_lshl_or_b32 v158, s34, 8, v166
	v_lshl_add_u32 v159, s35, 8, v164
	s_mov_b32 s34, s10
	s_mov_b32 s35, s20
	s_mov_b64 s[26:27], s[24:25]
	v_mbcnt_lo_u32_b32 v160, -1, 0
	v_mbcnt_hi_u32_b32 v160, -1, v160
	v_and_b32_e32 v157, 7, v160
	v_and_b32_e32 v160, 8, v160
	v_add_u32_e32 v157, v158, v157
	v_lshlrev_b32_e32 v157, 6, v157
	v_lshl_add_u32 v157, v160, 2, v157
	v_add_u32_e32 v161, 0x2000, v157
	global_load_dwordx4 v[128:131], v157, s[18:19]
	global_load_dwordx4 v[132:135], v157, s[18:19] offset:16
	global_load_dwordx4 v[136:139], v161, s[18:19]
	global_load_dwordx4 v[140:143], v161, s[18:19] offset:16
	v_mov_b32_e32 v155, 0x358637bd
	v_lshlrev_b32_e32 v156, 17, v159
	v_lshl_add_u32 v156, v158, 1, v156
	s_waitcnt vmcnt(0)
	v_pk_add_f32 v[128:129], v[128:129], v[130:131]
	v_pk_add_f32 v[132:133], v[132:133], v[134:135]
	v_pk_add_f32 v[128:129], v[128:129], v[132:133]
	s_nop 0
	v_add_f32_e32 v154, v128, v129
	s_nop 1
	v_add_f32_dpp v154, v154, v154 row_ror:8 row_mask:0xf bank_mask:0xf
	s_nop 0
	v_fmamk_f32 v154, v154, 0x3a800000, v155
	v_rsq_f32_e32 v154, v154
	s_nop 1
	v_mov_b32_dpp v168, v154 row_newbcast:0 row_mask:0xf bank_mask:0xf
	v_mov_b32_dpp v169, v154 row_newbcast:1 row_mask:0xf bank_mask:0xf
	v_mov_b32_dpp v170, v154 row_newbcast:2 row_mask:0xf bank_mask:0xf
	v_mov_b32_dpp v171, v154 row_newbcast:3 row_mask:0xf bank_mask:0xf
	v_mov_b32_dpp v172, v154 row_newbcast:4 row_mask:0xf bank_mask:0xf
	v_mov_b32_dpp v173, v154 row_newbcast:5 row_mask:0xf bank_mask:0xf
	v_mov_b32_dpp v174, v154 row_newbcast:6 row_mask:0xf bank_mask:0xf
	v_mov_b32_dpp v175, v154 row_newbcast:7 row_mask:0xf bank_mask:0xf
	v_pk_add_f32 v[136:137], v[136:137], v[138:139]
	v_pk_add_f32 v[140:141], v[140:141], v[142:143]
	v_pk_add_f32 v[136:137], v[136:137], v[140:141]
	s_nop 0
	v_add_f32_e32 v154, v136, v137
	s_nop 1
	v_add_f32_dpp v154, v154, v154 row_ror:8 row_mask:0xf bank_mask:0xf
	s_nop 0
	v_fmamk_f32 v154, v154, 0x3a800000, v155
	v_rsq_f32_e32 v154, v154
	s_nop 1
	v_mov_b32_dpp v176, v154 row_newbcast:0 row_mask:0xf bank_mask:0xf
	v_mov_b32_dpp v177, v154 row_newbcast:1 row_mask:0xf bank_mask:0xf
	v_mov_b32_dpp v178, v154 row_newbcast:2 row_mask:0xf bank_mask:0xf
	v_mov_b32_dpp v179, v154 row_newbcast:3 row_mask:0xf bank_mask:0xf
	v_mov_b32_dpp v180, v154 row_newbcast:4 row_mask:0xf bank_mask:0xf
	v_mov_b32_dpp v181, v154 row_newbcast:5 row_mask:0xf bank_mask:0xf
	v_mov_b32_dpp v182, v154 row_newbcast:6 row_mask:0xf bank_mask:0xf
	v_mov_b32_dpp v183, v154 row_newbcast:7 row_mask:0xf bank_mask:0xf
	v_pk_mul_f32 v[124:125], v[124:125], v[168:169]
	v_pk_mul_f32 v[126:127], v[126:127], v[170:171]
	v_pk_mul_f32 v[120:121], v[120:121], v[172:173]
	v_pk_mul_f32 v[122:123], v[122:123], v[174:175]
	v_cvt_pk_bf16_f32 v184, v124, v125
	v_cvt_pk_bf16_f32 v185, v126, v127
	v_cvt_pk_bf16_f32 v186, v120, v121
	v_cvt_pk_bf16_f32 v187, v122, v123
	global_store_dwordx4 v156, v[184:187], s[8:9]
	v_pk_mul_f32 v[60:61], v[60:61], v[176:177]
	v_pk_mul_f32 v[62:63], v[62:63], v[178:179]
	v_pk_mul_f32 v[56:57], v[56:57], v[180:181]
	v_pk_mul_f32 v[58:59], v[58:59], v[182:183]
	v_cvt_pk_bf16_f32 v188, v60, v61
	v_cvt_pk_bf16_f32 v189, v62, v63
	v_cvt_pk_bf16_f32 v190, v56, v57
	v_cvt_pk_bf16_f32 v191, v58, v59
	global_store_dwordx4 v156, v[188:191], s[8:9] offset:256
	v_add_u32_e32 v156, 0x200000, v156
	v_pk_mul_f32 v[116:117], v[116:117], v[168:169]
	v_pk_mul_f32 v[118:119], v[118:119], v[170:171]
	v_pk_mul_f32 v[112:113], v[112:113], v[172:173]
	v_pk_mul_f32 v[114:115], v[114:115], v[174:175]
	v_cvt_pk_bf16_f32 v184, v116, v117
	v_cvt_pk_bf16_f32 v185, v118, v119
	v_cvt_pk_bf16_f32 v186, v112, v113
	v_cvt_pk_bf16_f32 v187, v114, v115
	global_store_dwordx4 v156, v[184:187], s[8:9]
	v_pk_mul_f32 v[52:53], v[52:53], v[176:177]
	v_pk_mul_f32 v[54:55], v[54:55], v[178:179]
	v_pk_mul_f32 v[48:49], v[48:49], v[180:181]
	v_pk_mul_f32 v[50:51], v[50:51], v[182:183]
	v_cvt_pk_bf16_f32 v188, v52, v53
	v_cvt_pk_bf16_f32 v189, v54, v55
	v_cvt_pk_bf16_f32 v190, v48, v49
	v_cvt_pk_bf16_f32 v191, v50, v51
	global_store_dwordx4 v156, v[188:191], s[8:9] offset:256
	v_add_u32_e32 v156, 0x200000, v156
	v_pk_mul_f32 v[108:109], v[108:109], v[168:169]
	v_pk_mul_f32 v[110:111], v[110:111], v[170:171]
	v_pk_mul_f32 v[104:105], v[104:105], v[172:173]
	v_pk_mul_f32 v[106:107], v[106:107], v[174:175]
	v_cvt_pk_bf16_f32 v184, v108, v109
	v_cvt_pk_bf16_f32 v185, v110, v111
	v_cvt_pk_bf16_f32 v186, v104, v105
	v_cvt_pk_bf16_f32 v187, v106, v107
	global_store_dwordx4 v156, v[184:187], s[8:9]
	v_pk_mul_f32 v[44:45], v[44:45], v[176:177]
	v_pk_mul_f32 v[46:47], v[46:47], v[178:179]
	v_pk_mul_f32 v[40:41], v[40:41], v[180:181]
	v_pk_mul_f32 v[42:43], v[42:43], v[182:183]
	v_cvt_pk_bf16_f32 v188, v44, v45
	v_cvt_pk_bf16_f32 v189, v46, v47
	v_cvt_pk_bf16_f32 v190, v40, v41
	v_cvt_pk_bf16_f32 v191, v42, v43
	global_store_dwordx4 v156, v[188:191], s[8:9] offset:256
	v_add_u32_e32 v156, 0x200000, v156
	v_pk_mul_f32 v[100:101], v[100:101], v[168:169]
	v_pk_mul_f32 v[102:103], v[102:103], v[170:171]
	v_pk_mul_f32 v[96:97], v[96:97], v[172:173]
	v_pk_mul_f32 v[98:99], v[98:99], v[174:175]
	v_cvt_pk_bf16_f32 v184, v100, v101
	v_cvt_pk_bf16_f32 v185, v102, v103
	v_cvt_pk_bf16_f32 v186, v96, v97
	v_cvt_pk_bf16_f32 v187, v98, v99
	global_store_dwordx4 v156, v[184:187], s[8:9]
	v_pk_mul_f32 v[36:37], v[36:37], v[176:177]
	v_pk_mul_f32 v[38:39], v[38:39], v[178:179]
	v_pk_mul_f32 v[32:33], v[32:33], v[180:181]
	v_pk_mul_f32 v[34:35], v[34:35], v[182:183]
	v_cvt_pk_bf16_f32 v188, v36, v37
	v_cvt_pk_bf16_f32 v189, v38, v39
	v_cvt_pk_bf16_f32 v190, v32, v33
	v_cvt_pk_bf16_f32 v191, v34, v35
	global_store_dwordx4 v156, v[188:191], s[8:9] offset:256
	v_add_u32_e32 v156, 0xa00000, v156
	v_pk_mul_f32 v[92:93], v[92:93], v[168:169]
	v_pk_mul_f32 v[94:95], v[94:95], v[170:171]
	v_pk_mul_f32 v[88:89], v[88:89], v[172:173]
	v_pk_mul_f32 v[90:91], v[90:91], v[174:175]
	v_cvt_pk_bf16_f32 v184, v92, v93
	v_cvt_pk_bf16_f32 v185, v94, v95
	v_cvt_pk_bf16_f32 v186, v88, v89
	v_cvt_pk_bf16_f32 v187, v90, v91
	global_store_dwordx4 v156, v[184:187], s[8:9]
	v_pk_mul_f32 v[28:29], v[28:29], v[176:177]
	v_pk_mul_f32 v[30:31], v[30:31], v[178:179]
	v_pk_mul_f32 v[24:25], v[24:25], v[180:181]
	v_pk_mul_f32 v[26:27], v[26:27], v[182:183]
	v_cvt_pk_bf16_f32 v188, v28, v29
	v_cvt_pk_bf16_f32 v189, v30, v31
	v_cvt_pk_bf16_f32 v190, v24, v25
	v_cvt_pk_bf16_f32 v191, v26, v27
	global_store_dwordx4 v156, v[188:191], s[8:9] offset:256
	v_add_u32_e32 v156, 0x200000, v156
	v_pk_mul_f32 v[84:85], v[84:85], v[168:169]
	v_pk_mul_f32 v[86:87], v[86:87], v[170:171]
	v_pk_mul_f32 v[80:81], v[80:81], v[172:173]
	v_pk_mul_f32 v[82:83], v[82:83], v[174:175]
	v_cvt_pk_bf16_f32 v184, v84, v85
	v_cvt_pk_bf16_f32 v185, v86, v87
	v_cvt_pk_bf16_f32 v186, v80, v81
	v_cvt_pk_bf16_f32 v187, v82, v83
	global_store_dwordx4 v156, v[184:187], s[8:9]
	v_pk_mul_f32 v[20:21], v[20:21], v[176:177]
	v_pk_mul_f32 v[22:23], v[22:23], v[178:179]
	v_pk_mul_f32 v[16:17], v[16:17], v[180:181]
	v_pk_mul_f32 v[18:19], v[18:19], v[182:183]
	v_cvt_pk_bf16_f32 v188, v20, v21
	v_cvt_pk_bf16_f32 v189, v22, v23
	v_cvt_pk_bf16_f32 v190, v16, v17
	v_cvt_pk_bf16_f32 v191, v18, v19
	global_store_dwordx4 v156, v[188:191], s[8:9] offset:256
	v_add_u32_e32 v156, 0x200000, v156
	v_pk_mul_f32 v[76:77], v[76:77], v[168:169]
	v_pk_mul_f32 v[78:79], v[78:79], v[170:171]
	v_pk_mul_f32 v[72:73], v[72:73], v[172:173]
	v_pk_mul_f32 v[74:75], v[74:75], v[174:175]
	v_cvt_pk_bf16_f32 v184, v76, v77
	v_cvt_pk_bf16_f32 v185, v78, v79
	v_cvt_pk_bf16_f32 v186, v72, v73
	v_cvt_pk_bf16_f32 v187, v74, v75
	global_store_dwordx4 v156, v[184:187], s[8:9]
	v_pk_mul_f32 v[12:13], v[12:13], v[176:177]
	v_pk_mul_f32 v[14:15], v[14:15], v[178:179]
	v_pk_mul_f32 v[8:9], v[8:9], v[180:181]
	v_pk_mul_f32 v[10:11], v[10:11], v[182:183]
	v_cvt_pk_bf16_f32 v188, v12, v13
	v_cvt_pk_bf16_f32 v189, v14, v15
	v_cvt_pk_bf16_f32 v190, v8, v9
	v_cvt_pk_bf16_f32 v191, v10, v11
	global_store_dwordx4 v156, v[188:191], s[8:9] offset:256
	v_add_u32_e32 v156, 0x200000, v156
	v_pk_mul_f32 v[68:69], v[68:69], v[168:169]
	v_pk_mul_f32 v[70:71], v[70:71], v[170:171]
	v_pk_mul_f32 v[64:65], v[64:65], v[172:173]
	v_pk_mul_f32 v[66:67], v[66:67], v[174:175]
	v_cvt_pk_bf16_f32 v184, v68, v69
	v_cvt_pk_bf16_f32 v185, v70, v71
	v_cvt_pk_bf16_f32 v186, v64, v65
	v_cvt_pk_bf16_f32 v187, v66, v67
	global_store_dwordx4 v156, v[184:187], s[8:9]
	v_pk_mul_f32 v[4:5], v[4:5], v[176:177]
	v_pk_mul_f32 v[6:7], v[6:7], v[178:179]
	v_pk_mul_f32 v[0:1], v[0:1], v[180:181]
	v_pk_mul_f32 v[2:3], v[2:3], v[182:183]
	v_cvt_pk_bf16_f32 v188, v4, v5
	v_cvt_pk_bf16_f32 v189, v6, v7
	v_cvt_pk_bf16_f32 v190, v0, v1
	v_cvt_pk_bf16_f32 v191, v2, v3
	global_store_dwordx4 v156, v[188:191], s[8:9] offset:256
	s_mov_b64 s[6:7], s[22:23]
	s_and_b64 vcc, exec, s[4:5]
	s_cbranch_vccz .LBB0_707
	s_waitcnt vmcnt(0)
	s_cmpk_gt_u32 s30, 0xff
	s_cbranch_scc1 .LBB0_718
	s_barrier

.LBB0_776:
	s_add_u32 s28, s26, 0xfffc0080
	s_addc_u32 s29, s27, -1
	s_add_i32 s66, 0, 0x10000
	v_add_u32_e32 v154, s66, v143
	ds_read_b128 v[138:141], v154
	ds_read_b128 v[146:149], v154 offset:1024
	ds_read_b128 v[150:153], v154 offset:2048
	ds_read_b128 v[154:157], v154 offset:3072
	s_cmp_eq_u32 s65, 12
	s_cselect_b32 s31, s21, s29
	s_cselect_b32 s30, s39, s28
	s_cselect_b32 s29, s19, s64
	s_cselect_b32 s28, s62, s63
	v_lshl_add_u64 v[190:191], s[26:27], 0, v[134:135]
	s_add_i32 m0, s54, 0xc000
	ds_read_b128 v[158:161], v145
	ds_read_b128 v[162:165], v145 offset:1024
	ds_read_b128 v[166:169], v145 offset:2048
	ds_read_b128 v[170:173], v145 offset:3072
	ds_read_b128 v[174:177], v145 offset:4096
	ds_read_b128 v[178:181], v145 offset:5120
	ds_read_b128 v[182:185], v145 offset:6144
	ds_read_b128 v[186:189], v145 offset:7168
	global_load_lds_dwordx4 v[190:191], off
	v_lshl_add_u64 v[190:191], s[26:27], 0, v[136:137]
	s_add_i32 m0, s54, 0xe000
	s_nop 0
	global_load_lds_dwordx4 v[190:191], off
	s_waitcnt lgkmcnt(8)
	s_barrier
	s_waitcnt lgkmcnt(0)
	s_setprio 1
	v_mfma_f32_16x16x32_bf16 v[124:127], v[138:141], v[158:161], v[124:127]
	v_mfma_f32_16x16x32_bf16 v[120:123], v[150:153], v[158:161], v[120:123]
	v_mfma_f32_16x16x32_bf16 v[108:111], v[138:141], v[166:169], v[108:111]
	v_mfma_f32_16x16x32_bf16 v[104:107], v[150:153], v[166:169], v[104:107]
	v_mfma_f32_16x16x32_bf16 v[92:95], v[138:141], v[174:177], v[92:95]
	v_mfma_f32_16x16x32_bf16 v[88:91], v[150:153], v[174:177], v[88:91]
	v_mfma_f32_16x16x32_bf16 v[76:79], v[138:141], v[182:185], v[76:79]
	v_mfma_f32_16x16x32_bf16 v[72:75], v[150:153], v[182:185], v[72:75]
	v_mfma_f32_16x16x32_bf16 v[124:127], v[146:149], v[162:165], v[124:127]
	v_mfma_f32_16x16x32_bf16 v[120:123], v[154:157], v[162:165], v[120:123]
	v_mfma_f32_16x16x32_bf16 v[108:111], v[146:149], v[170:173], v[108:111]
	v_mfma_f32_16x16x32_bf16 v[104:107], v[154:157], v[170:173], v[104:107]
	v_mfma_f32_16x16x32_bf16 v[92:95], v[146:149], v[178:181], v[92:95]
	v_mfma_f32_16x16x32_bf16 v[88:91], v[154:157], v[178:181], v[88:91]
	v_mfma_f32_16x16x32_bf16 v[76:79], v[146:149], v[186:189], v[76:79]
	v_mfma_f32_16x16x32_bf16 v[72:75], v[154:157], v[186:189], v[72:75]
	s_setprio 0
	s_barrier
	s_add_i32 s68, 0, 0x14000
	s_add_i32 s66, s66, s53
	v_add_u32_e32 v202, s68, v143
	v_lshl_add_u64 v[206:207], s[28:29], 0, v[208:209]
	s_mov_b32 m0, s66
	ds_read_b128 v[190:193], v202
	ds_read_b128 v[194:197], v202 offset:1024
	ds_read_b128 v[198:201], v202 offset:2048
	ds_read_b128 v[202:205], v202 offset:3072
	global_load_lds_dwordx4 v[206:207], off
	v_lshl_add_u64 v[210:211], s[28:29], 0, v[128:129]
	s_add_i32 m0, s66, 0x2000
	s_nop 0
	global_load_lds_dwordx4 v[210:211], off
	s_barrier
	s_waitcnt lgkmcnt(0)
	s_setprio 1
	v_mfma_f32_16x16x32_bf16 v[116:119], v[190:193], v[158:161], v[116:119]
	v_mfma_f32_16x16x32_bf16 v[112:115], v[198:201], v[158:161], v[112:115]
	v_mfma_f32_16x16x32_bf16 v[100:103], v[190:193], v[166:169], v[100:103]
	v_mfma_f32_16x16x32_bf16 v[96:99], v[198:201], v[166:169], v[96:99]
	v_mfma_f32_16x16x32_bf16 v[84:87], v[190:193], v[174:177], v[84:87]
	v_mfma_f32_16x16x32_bf16 v[80:83], v[198:201], v[174:177], v[80:83]
	v_mfma_f32_16x16x32_bf16 v[68:71], v[190:193], v[182:185], v[68:71]
	v_mfma_f32_16x16x32_bf16 v[64:67], v[198:201], v[182:185], v[64:67]
	v_mfma_f32_16x16x32_bf16 v[116:119], v[194:197], v[162:165], v[116:119]
	v_mfma_f32_16x16x32_bf16 v[112:115], v[202:205], v[162:165], v[112:115]
	v_mfma_f32_16x16x32_bf16 v[100:103], v[194:197], v[170:173], v[100:103]
	v_mfma_f32_16x16x32_bf16 v[96:99], v[202:205], v[170:173], v[96:99]
	v_mfma_f32_16x16x32_bf16 v[84:87], v[194:197], v[178:181], v[84:87]
	v_mfma_f32_16x16x32_bf16 v[80:83], v[202:205], v[178:181], v[80:83]
	v_mfma_f32_16x16x32_bf16 v[68:71], v[194:197], v[186:189], v[68:71]
	v_mfma_f32_16x16x32_bf16 v[64:67], v[202:205], v[186:189], v[64:67]
	s_setprio 0
	s_mov_b32 m0, s54
	v_lshl_add_u64 v[214:215], s[30:31], 0, v[132:133]
	s_barrier
	ds_read_b128 v[158:161], v145 offset:16384
	ds_read_b128 v[162:165], v145 offset:17408
	ds_read_b128 v[166:169], v145 offset:18432
	ds_read_b128 v[170:173], v145 offset:19456
	ds_read_b128 v[174:177], v145 offset:20480
	ds_read_b128 v[178:181], v145 offset:21504
	ds_read_b128 v[182:185], v145 offset:22528
	ds_read_b128 v[186:189], v145 offset:23552
	global_load_lds_dwordx4 v[214:215], off
	v_lshl_add_u64 v[216:217], s[30:31], 0, v[130:131]
	s_mov_b32 m0, s55
	s_nop 0
	global_load_lds_dwordx4 v[216:217], off
	s_barrier
	s_waitcnt lgkmcnt(0)
	s_setprio 1
	v_mfma_f32_16x16x32_bf16 v[60:63], v[138:141], v[158:161], v[60:63]
	v_mfma_f32_16x16x32_bf16 v[56:59], v[150:153], v[158:161], v[56:59]
	v_mfma_f32_16x16x32_bf16 v[44:47], v[138:141], v[166:169], v[44:47]
	v_mfma_f32_16x16x32_bf16 v[40:43], v[150:153], v[166:169], v[40:43]
	v_mfma_f32_16x16x32_bf16 v[28:31], v[138:141], v[174:177], v[28:31]
	v_mfma_f32_16x16x32_bf16 v[24:27], v[150:153], v[174:177], v[24:27]
	v_mfma_f32_16x16x32_bf16 v[12:15], v[138:141], v[182:185], v[12:15]
	v_mfma_f32_16x16x32_bf16 v[8:11], v[150:153], v[182:185], v[8:11]
	v_mfma_f32_16x16x32_bf16 v[60:63], v[146:149], v[162:165], v[60:63]
	v_mfma_f32_16x16x32_bf16 v[56:59], v[154:157], v[162:165], v[56:59]
	v_mfma_f32_16x16x32_bf16 v[44:47], v[146:149], v[170:173], v[44:47]
	v_mfma_f32_16x16x32_bf16 v[40:43], v[154:157], v[170:173], v[40:43]
	v_mfma_f32_16x16x32_bf16 v[28:31], v[146:149], v[178:181], v[28:31]
	v_mfma_f32_16x16x32_bf16 v[24:27], v[154:157], v[178:181], v[24:27]
	v_mfma_f32_16x16x32_bf16 v[12:15], v[146:149], v[186:189], v[12:15]
	v_mfma_f32_16x16x32_bf16 v[8:11], v[154:157], v[186:189], v[8:11]
	s_setprio 0
	s_barrier
	s_add_u32 s66, s28, 0x40000
	s_addc_u32 s67, s29, 0
	s_add_i32 s68, s68, s53
	v_lshl_add_u64 v[138:139], s[66:67], 0, v[208:209]
	s_mov_b32 m0, s68
	s_nop 0
	global_load_lds_dwordx4 v[138:139], off
	v_lshl_add_u64 v[138:139], s[66:67], 0, v[128:129]
	s_add_i32 m0, s68, 0x2000
	s_nop 0
	global_load_lds_dwordx4 v[138:139], off
	s_waitcnt vmcnt(6)
	s_barrier
	s_setprio 1
	v_mfma_f32_16x16x32_bf16 v[52:55], v[190:193], v[158:161], v[52:55]
	v_mfma_f32_16x16x32_bf16 v[48:51], v[198:201], v[158:161], v[48:51]
	v_mfma_f32_16x16x32_bf16 v[36:39], v[190:193], v[166:169], v[36:39]
	v_mfma_f32_16x16x32_bf16 v[32:35], v[198:201], v[166:169], v[32:35]
	v_mfma_f32_16x16x32_bf16 v[20:23], v[190:193], v[174:177], v[20:23]
	v_mfma_f32_16x16x32_bf16 v[16:19], v[198:201], v[174:177], v[16:19]
	v_mfma_f32_16x16x32_bf16 v[4:7], v[190:193], v[182:185], v[4:7]
	v_mfma_f32_16x16x32_bf16 v[0:3], v[198:201], v[182:185], v[0:3]
	v_mfma_f32_16x16x32_bf16 v[52:55], v[194:197], v[162:165], v[52:55]
	v_mfma_f32_16x16x32_bf16 v[48:51], v[202:205], v[162:165], v[48:51]
	v_mfma_f32_16x16x32_bf16 v[36:39], v[194:197], v[170:173], v[36:39]
	v_mfma_f32_16x16x32_bf16 v[32:35], v[202:205], v[170:173], v[32:35]
	v_mfma_f32_16x16x32_bf16 v[20:23], v[194:197], v[178:181], v[20:23]
	v_mfma_f32_16x16x32_bf16 v[16:19], v[202:205], v[178:181], v[16:19]
	v_mfma_f32_16x16x32_bf16 v[4:7], v[194:197], v[186:189], v[4:7]
	v_mfma_f32_16x16x32_bf16 v[0:3], v[202:205], v[186:189], v[0:3]
	s_setprio 0
	s_add_i32 s66, 0, 0x18000
	v_add_u32_e32 v154, s66, v143
	s_barrier
	ds_read_b128 v[138:141], v154
	ds_read_b128 v[146:149], v154 offset:1024
	ds_read_b128 v[150:153], v154 offset:2048
	ds_read_b128 v[154:157], v154 offset:3072
	s_add_u32 s30, s30, 0x40000
	s_addc_u32 s31, s31, 0
	s_mov_b32 m0, s56
	v_lshl_add_u64 v[190:191], s[30:31], 0, v[132:133]
	ds_read_b128 v[158:161], v145 offset:32768
	ds_read_b128 v[162:165], v145 offset:33792
	ds_read_b128 v[166:169], v145 offset:34816
	ds_read_b128 v[170:173], v145 offset:35840
	ds_read_b128 v[174:177], v145 offset:36864
	ds_read_b128 v[178:181], v145 offset:37888
	ds_read_b128 v[182:185], v145 offset:38912
	ds_read_b128 v[186:189], v145 offset:39936
	global_load_lds_dwordx4 v[190:191], off
	v_lshl_add_u64 v[190:191], s[30:31], 0, v[130:131]
	s_mov_b32 m0, s57
	s_nop 0
	global_load_lds_dwordx4 v[190:191], off
	s_waitcnt lgkmcnt(8)
	s_barrier
	s_waitcnt lgkmcnt(0)
	s_setprio 1
	v_mfma_f32_16x16x32_bf16 v[124:127], v[138:141], v[158:161], v[124:127]
	v_mfma_f32_16x16x32_bf16 v[120:123], v[150:153], v[158:161], v[120:123]
	v_mfma_f32_16x16x32_bf16 v[108:111], v[138:141], v[166:169], v[108:111]
	v_mfma_f32_16x16x32_bf16 v[104:107], v[150:153], v[166:169], v[104:107]
	v_mfma_f32_16x16x32_bf16 v[92:95], v[138:141], v[174:177], v[92:95]
	v_mfma_f32_16x16x32_bf16 v[88:91], v[150:153], v[174:177], v[88:91]
	v_mfma_f32_16x16x32_bf16 v[76:79], v[138:141], v[182:185], v[76:79]
	v_mfma_f32_16x16x32_bf16 v[72:75], v[150:153], v[182:185], v[72:75]
	v_mfma_f32_16x16x32_bf16 v[124:127], v[146:149], v[162:165], v[124:127]
	v_mfma_f32_16x16x32_bf16 v[120:123], v[154:157], v[162:165], v[120:123]
	v_mfma_f32_16x16x32_bf16 v[108:111], v[146:149], v[170:173], v[108:111]
	v_mfma_f32_16x16x32_bf16 v[104:107], v[154:157], v[170:173], v[104:107]
	v_mfma_f32_16x16x32_bf16 v[92:95], v[146:149], v[178:181], v[92:95]
	v_mfma_f32_16x16x32_bf16 v[88:91], v[154:157], v[178:181], v[88:91]
	v_mfma_f32_16x16x32_bf16 v[76:79], v[146:149], v[186:189], v[76:79]
	v_mfma_f32_16x16x32_bf16 v[72:75], v[154:157], v[186:189], v[72:75]
	s_setprio 0
	s_barrier
	s_add_i32 s30, 0, 0x1c000
	s_add_i32 s31, s66, s53
	v_add_u32_e32 v202, s30, v143
	v_lshl_add_u64 v[206:207], v[206:207], 0, s[40:41]
	s_mov_b32 m0, s31
	ds_read_b128 v[190:193], v202
	ds_read_b128 v[194:197], v202 offset:1024
	ds_read_b128 v[198:201], v202 offset:2048
	ds_read_b128 v[202:205], v202 offset:3072
	global_load_lds_dwordx4 v[206:207], off
	v_lshl_add_u64 v[206:207], v[210:211], 0, s[40:41]
	s_add_i32 m0, s31, 0x2000
	s_nop 0
	global_load_lds_dwordx4 v[206:207], off
	s_barrier
	s_waitcnt lgkmcnt(0)
	s_setprio 1
	v_mfma_f32_16x16x32_bf16 v[116:119], v[190:193], v[158:161], v[116:119]
	v_mfma_f32_16x16x32_bf16 v[112:115], v[198:201], v[158:161], v[112:115]
	v_mfma_f32_16x16x32_bf16 v[100:103], v[190:193], v[166:169], v[100:103]
	v_mfma_f32_16x16x32_bf16 v[96:99], v[198:201], v[166:169], v[96:99]
	v_mfma_f32_16x16x32_bf16 v[84:87], v[190:193], v[174:177], v[84:87]
	v_mfma_f32_16x16x32_bf16 v[80:83], v[198:201], v[174:177], v[80:83]
	v_mfma_f32_16x16x32_bf16 v[68:71], v[190:193], v[182:185], v[68:71]
	v_mfma_f32_16x16x32_bf16 v[64:67], v[198:201], v[182:185], v[64:67]
	v_mfma_f32_16x16x32_bf16 v[116:119], v[194:197], v[162:165], v[116:119]
	v_mfma_f32_16x16x32_bf16 v[112:115], v[202:205], v[162:165], v[112:115]
	v_mfma_f32_16x16x32_bf16 v[100:103], v[194:197], v[170:173], v[100:103]
	v_mfma_f32_16x16x32_bf16 v[96:99], v[202:205], v[170:173], v[96:99]
	v_mfma_f32_16x16x32_bf16 v[84:87], v[194:197], v[178:181], v[84:87]
	v_mfma_f32_16x16x32_bf16 v[80:83], v[202:205], v[178:181], v[80:83]
	v_mfma_f32_16x16x32_bf16 v[68:71], v[194:197], v[186:189], v[68:71]
	v_mfma_f32_16x16x32_bf16 v[64:67], v[202:205], v[186:189], v[64:67]
	s_setprio 0
	s_mov_b32 m0, s59
	v_lshl_add_u64 v[206:207], v[214:215], 0, s[40:41]
	s_barrier
	ds_read_b128 v[158:161], v145 offset:49152
	ds_read_b128 v[162:165], v145 offset:50176
	ds_read_b128 v[166:169], v145 offset:51200
	ds_read_b128 v[170:173], v145 offset:52224
	ds_read_b128 v[174:177], v145 offset:53248
	ds_read_b128 v[178:181], v145 offset:54272
	ds_read_b128 v[182:185], v145 offset:55296
	ds_read_b128 v[186:189], v145 offset:56320
	global_load_lds_dwordx4 v[206:207], off
	v_lshl_add_u64 v[206:207], v[216:217], 0, s[40:41]
	s_mov_b32 m0, s60
	s_nop 0
	global_load_lds_dwordx4 v[206:207], off
	s_barrier
	s_waitcnt lgkmcnt(0)
	s_setprio 1
	v_mfma_f32_16x16x32_bf16 v[60:63], v[138:141], v[158:161], v[60:63]
	v_mfma_f32_16x16x32_bf16 v[56:59], v[150:153], v[158:161], v[56:59]
	v_mfma_f32_16x16x32_bf16 v[44:47], v[138:141], v[166:169], v[44:47]
	v_mfma_f32_16x16x32_bf16 v[40:43], v[150:153], v[166:169], v[40:43]
	v_mfma_f32_16x16x32_bf16 v[28:31], v[138:141], v[174:177], v[28:31]
	v_mfma_f32_16x16x32_bf16 v[24:27], v[150:153], v[174:177], v[24:27]
	v_mfma_f32_16x16x32_bf16 v[12:15], v[138:141], v[182:185], v[12:15]
	v_mfma_f32_16x16x32_bf16 v[8:11], v[150:153], v[182:185], v[8:11]
	v_mfma_f32_16x16x32_bf16 v[60:63], v[146:149], v[162:165], v[60:63]
	v_mfma_f32_16x16x32_bf16 v[56:59], v[154:157], v[162:165], v[56:59]
	v_mfma_f32_16x16x32_bf16 v[44:47], v[146:149], v[170:173], v[44:47]
	v_mfma_f32_16x16x32_bf16 v[40:43], v[154:157], v[170:173], v[40:43]
	v_mfma_f32_16x16x32_bf16 v[28:31], v[146:149], v[178:181], v[28:31]
	v_mfma_f32_16x16x32_bf16 v[24:27], v[154:157], v[178:181], v[24:27]
	v_mfma_f32_16x16x32_bf16 v[12:15], v[146:149], v[186:189], v[12:15]
	v_mfma_f32_16x16x32_bf16 v[8:11], v[154:157], v[186:189], v[8:11]
	s_setprio 0
	s_barrier
	s_add_u32 s28, s28, 0x40080
	s_addc_u32 s29, s29, 0
	s_add_i32 s30, s30, s53
	v_lshl_add_u64 v[138:139], s[28:29], 0, v[208:209]
	s_mov_b32 m0, s30
	s_nop 0
	global_load_lds_dwordx4 v[138:139], off
	v_lshl_add_u64 v[138:139], s[28:29], 0, v[128:129]
	s_add_i32 m0, s30, 0x2000
	s_nop 0
	global_load_lds_dwordx4 v[138:139], off
	s_waitcnt vmcnt(6)
	s_barrier
	s_setprio 1
	v_mfma_f32_16x16x32_bf16 v[52:55], v[190:193], v[158:161], v[52:55]
	v_mfma_f32_16x16x32_bf16 v[48:51], v[198:201], v[158:161], v[48:51]
	v_mfma_f32_16x16x32_bf16 v[36:39], v[190:193], v[166:169], v[36:39]
	v_mfma_f32_16x16x32_bf16 v[32:35], v[198:201], v[166:169], v[32:35]
	v_mfma_f32_16x16x32_bf16 v[20:23], v[190:193], v[174:177], v[20:23]
	v_mfma_f32_16x16x32_bf16 v[16:19], v[198:201], v[174:177], v[16:19]
	v_mfma_f32_16x16x32_bf16 v[4:7], v[190:193], v[182:185], v[4:7]
	v_mfma_f32_16x16x32_bf16 v[0:3], v[198:201], v[182:185], v[0:3]
	v_mfma_f32_16x16x32_bf16 v[52:55], v[194:197], v[162:165], v[52:55]
	v_mfma_f32_16x16x32_bf16 v[48:51], v[202:205], v[162:165], v[48:51]
	v_mfma_f32_16x16x32_bf16 v[36:39], v[194:197], v[170:173], v[36:39]
	v_mfma_f32_16x16x32_bf16 v[32:35], v[202:205], v[170:173], v[32:35]
	v_mfma_f32_16x16x32_bf16 v[20:23], v[194:197], v[178:181], v[20:23]
	v_mfma_f32_16x16x32_bf16 v[16:19], v[202:205], v[178:181], v[16:19]
	v_mfma_f32_16x16x32_bf16 v[4:7], v[194:197], v[186:189], v[4:7]
	v_mfma_f32_16x16x32_bf16 v[0:3], v[202:205], v[186:189], v[0:3]
	s_setprio 0
	s_add_i32 s65, s65, 2
	s_add_u32 s26, s26, 0x100
	s_addc_u32 s27, s27, 0
	s_add_u32 s63, s63, 0x100
	s_addc_u32 s64, s64, 0
	s_cmp_gt_u32 s65, 13
	s_barrier
	s_cbranch_scc0 .LBB0_776
	v_lshl_add_u32 v140, s38, 8, v142
	v_lshl_or_b32 v141, s36, 8, v144
	s_lshl_b32 s26, s36, 2
	s_ashr_i32 s27, s26, 31
	s_lshl_b32 s36, s58, 2
	v_lshlrev_b32_e32 v206, 11, v140
	v_lshl_add_u32 v206, v141, 1, v206
	v_lshl_add_u32 v210, v140, 6, s36
	v_lshl_add_u32 v210, s26, 2, v210
	v_mov_b32_e32 v207, v206
	global_load_dwordx4 v[146:149], v206, s[10:11]
	global_load_dwordx4 v[150:153], v206, s[10:11] offset:256
	v_add_u32_e32 v206, 0x8000, v206
	global_load_dwordx4 v[154:157], v206, s[10:11]
	global_load_dwordx4 v[158:161], v206, s[10:11] offset:256
	v_add_u32_e32 v206, 0x8000, v206
	global_load_dwordx4 v[162:165], v206, s[10:11]
	global_load_dwordx4 v[166:169], v206, s[10:11] offset:256
	v_add_u32_e32 v206, 0x8000, v206
	global_load_dwordx4 v[170:173], v206, s[10:11]
	global_load_dwordx4 v[174:177], v206, s[10:11] offset:256
	v_add_u32_e32 v206, 0x28000, v206
	global_load_dwordx4 v[178:181], v206, s[10:11]
	global_load_dwordx4 v[182:185], v206, s[10:11] offset:256
	v_add_u32_e32 v206, 0x8000, v206
	global_load_dwordx4 v[186:189], v206, s[10:11]
	global_load_dwordx4 v[190:193], v206, s[10:11] offset:256
	v_add_u32_e32 v206, 0x8000, v206
	global_load_dwordx4 v[194:197], v206, s[10:11]
	global_load_dwordx4 v[198:201], v206, s[10:11] offset:256
	v_add_u32_e32 v206, 0x8000, v206
	s_waitcnt vmcnt(12)
	v_lshlrev_b32_e32 v202, 16, v146
	v_and_b32_e32 v203, 0xffff0000, v146
	v_lshlrev_b32_e32 v204, 16, v147
	v_and_b32_e32 v205, 0xffff0000, v147
	v_pk_add_f32 v[124:125], v[124:125], v[202:203]
	v_pk_add_f32 v[126:127], v[126:127], v[204:205]
	v_lshlrev_b32_e32 v202, 16, v148
	v_and_b32_e32 v203, 0xffff0000, v148
	v_lshlrev_b32_e32 v204, 16, v149
	v_and_b32_e32 v205, 0xffff0000, v149
	v_pk_add_f32 v[120:121], v[120:121], v[202:203]
	v_pk_add_f32 v[122:123], v[122:123], v[204:205]
	v_cvt_pk_bf16_f32 v146, v124, v125
	v_cvt_pk_bf16_f32 v147, v126, v127
	v_cvt_pk_bf16_f32 v148, v120, v121
	v_cvt_pk_bf16_f32 v149, v122, v123
	v_pk_mul_f32 v[138:139], v[124:125], v[124:125]
	global_store_dwordx4 v207, v[146:149], s[10:11]
	v_pk_fma_f32 v[138:139], v[126:127], v[126:127], v[138:139]
	v_pk_fma_f32 v[138:139], v[120:121], v[120:121], v[138:139]
	v_pk_fma_f32 v[138:139], v[122:123], v[122:123], v[138:139]
	v_lshlrev_b32_e32 v202, 16, v150
	v_and_b32_e32 v203, 0xffff0000, v150
	v_lshlrev_b32_e32 v204, 16, v151
	v_and_b32_e32 v205, 0xffff0000, v151
	v_pk_add_f32 v[116:117], v[116:117], v[202:203]
	v_pk_add_f32 v[118:119], v[118:119], v[204:205]
	v_lshlrev_b32_e32 v202, 16, v152
	v_and_b32_e32 v203, 0xffff0000, v152
	v_lshlrev_b32_e32 v204, 16, v153
	v_and_b32_e32 v205, 0xffff0000, v153
	v_pk_add_f32 v[112:113], v[112:113], v[202:203]
	v_pk_add_f32 v[114:115], v[114:115], v[204:205]
	v_cvt_pk_bf16_f32 v150, v116, v117
	v_cvt_pk_bf16_f32 v151, v118, v119
	v_cvt_pk_bf16_f32 v152, v112, v113
	v_cvt_pk_bf16_f32 v153, v114, v115
	v_pk_fma_f32 v[138:139], v[116:117], v[116:117], v[138:139]
	global_store_dwordx4 v207, v[150:153], s[10:11] offset:256
	v_pk_fma_f32 v[138:139], v[118:119], v[118:119], v[138:139]
	v_pk_fma_f32 v[138:139], v[112:113], v[112:113], v[138:139]
	v_pk_fma_f32 v[138:139], v[114:115], v[114:115], v[138:139]
	v_add_f32_e32 v214, v138, v139
	v_add_u32_e32 v207, 0x8000, v207
	v_mov_b32_e32 v215, v214
	s_nop 1
	v_permlane16_swap_b32_e32 v214, v215
	s_nop 0
	v_add_f32_e32 v214, v214, v215
	v_mov_b32_e32 v215, v214
	s_nop 1
	v_permlane32_swap_b32_e32 v214, v215
	s_nop 0
	v_add_f32_e32 v214, v214, v215
	s_and_saveexec_b64 s[28:29], s[4:5]
	global_store_dword v210, v214, s[16:17]
	s_mov_b64 exec, s[28:29]
	global_load_dwordx4 v[146:149], v206, s[10:11]
	global_load_dwordx4 v[150:153], v206, s[10:11] offset:256
	s_waitcnt vmcnt(15)
	v_lshlrev_b32_e32 v202, 16, v154
	v_and_b32_e32 v203, 0xffff0000, v154
	v_lshlrev_b32_e32 v204, 16, v155
	v_and_b32_e32 v205, 0xffff0000, v155
	v_pk_add_f32 v[108:109], v[108:109], v[202:203]
	v_pk_add_f32 v[110:111], v[110:111], v[204:205]
	v_lshlrev_b32_e32 v202, 16, v156
	v_and_b32_e32 v203, 0xffff0000, v156
	v_lshlrev_b32_e32 v204, 16, v157
	v_and_b32_e32 v205, 0xffff0000, v157
	v_pk_add_f32 v[104:105], v[104:105], v[202:203]
	v_pk_add_f32 v[106:107], v[106:107], v[204:205]
	v_cvt_pk_bf16_f32 v154, v108, v109
	v_cvt_pk_bf16_f32 v155, v110, v111
	v_cvt_pk_bf16_f32 v156, v104, v105
	v_cvt_pk_bf16_f32 v157, v106, v107
	v_pk_mul_f32 v[138:139], v[108:109], v[108:109]
	global_store_dwordx4 v207, v[154:157], s[10:11]
	v_pk_fma_f32 v[138:139], v[110:111], v[110:111], v[138:139]
	v_pk_fma_f32 v[138:139], v[104:105], v[104:105], v[138:139]
	v_pk_fma_f32 v[138:139], v[106:107], v[106:107], v[138:139]
	v_lshlrev_b32_e32 v202, 16, v158
	v_and_b32_e32 v203, 0xffff0000, v158
	v_lshlrev_b32_e32 v204, 16, v159
	v_and_b32_e32 v205, 0xffff0000, v159
	v_pk_add_f32 v[100:101], v[100:101], v[202:203]
	v_pk_add_f32 v[102:103], v[102:103], v[204:205]
	v_lshlrev_b32_e32 v202, 16, v160
	v_and_b32_e32 v203, 0xffff0000, v160
	v_lshlrev_b32_e32 v204, 16, v161
	v_and_b32_e32 v205, 0xffff0000, v161
	v_pk_add_f32 v[96:97], v[96:97], v[202:203]
	v_pk_add_f32 v[98:99], v[98:99], v[204:205]
	v_cvt_pk_bf16_f32 v158, v100, v101
	v_cvt_pk_bf16_f32 v159, v102, v103
	v_cvt_pk_bf16_f32 v160, v96, v97
	v_cvt_pk_bf16_f32 v161, v98, v99
	v_pk_fma_f32 v[138:139], v[100:101], v[100:101], v[138:139]
	global_store_dwordx4 v207, v[158:161], s[10:11] offset:256
	v_pk_fma_f32 v[138:139], v[102:103], v[102:103], v[138:139]
	v_pk_fma_f32 v[138:139], v[96:97], v[96:97], v[138:139]
	v_pk_fma_f32 v[138:139], v[98:99], v[98:99], v[138:139]
	v_add_f32_e32 v214, v138, v139
	v_add_u32_e32 v207, 0x8000, v207
	v_mov_b32_e32 v215, v214
	s_nop 1
	v_permlane16_swap_b32_e32 v214, v215
	s_nop 0
	v_add_f32_e32 v214, v214, v215
	v_mov_b32_e32 v215, v214
	s_nop 1
	v_permlane32_swap_b32_e32 v214, v215
	s_nop 0
	v_add_f32_e32 v214, v214, v215
	s_and_saveexec_b64 s[28:29], s[4:5]
	global_store_dword v210, v214, s[16:17] offset:1024
	s_mov_b64 exec, s[28:29]
	s_waitcnt vmcnt(16)
	v_lshlrev_b32_e32 v202, 16, v162
	v_and_b32_e32 v203, 0xffff0000, v162
	v_lshlrev_b32_e32 v204, 16, v163
	v_and_b32_e32 v205, 0xffff0000, v163
	v_pk_add_f32 v[92:93], v[92:93], v[202:203]
	v_pk_add_f32 v[94:95], v[94:95], v[204:205]
	v_lshlrev_b32_e32 v202, 16, v164
	v_and_b32_e32 v203, 0xffff0000, v164
	v_lshlrev_b32_e32 v204, 16, v165
	v_and_b32_e32 v205, 0xffff0000, v165
	v_pk_add_f32 v[88:89], v[88:89], v[202:203]
	v_pk_add_f32 v[90:91], v[90:91], v[204:205]
	v_cvt_pk_bf16_f32 v162, v92, v93
	v_cvt_pk_bf16_f32 v163, v94, v95
	v_cvt_pk_bf16_f32 v164, v88, v89
	v_cvt_pk_bf16_f32 v165, v90, v91
	v_pk_mul_f32 v[138:139], v[92:93], v[92:93]
	global_store_dwordx4 v207, v[162:165], s[10:11]
	v_pk_fma_f32 v[138:139], v[94:95], v[94:95], v[138:139]
	v_pk_fma_f32 v[138:139], v[88:89], v[88:89], v[138:139]
	v_pk_fma_f32 v[138:139], v[90:91], v[90:91], v[138:139]
	v_lshlrev_b32_e32 v202, 16, v166
	v_and_b32_e32 v203, 0xffff0000, v166
	v_lshlrev_b32_e32 v204, 16, v167
	v_and_b32_e32 v205, 0xffff0000, v167
	v_pk_add_f32 v[84:85], v[84:85], v[202:203]
	v_pk_add_f32 v[86:87], v[86:87], v[204:205]
	v_lshlrev_b32_e32 v202, 16, v168
	v_and_b32_e32 v203, 0xffff0000, v168
	v_lshlrev_b32_e32 v204, 16, v169
	v_and_b32_e32 v205, 0xffff0000, v169
	v_pk_add_f32 v[80:81], v[80:81], v[202:203]
	v_pk_add_f32 v[82:83], v[82:83], v[204:205]
	v_cvt_pk_bf16_f32 v166, v84, v85
	v_cvt_pk_bf16_f32 v167, v86, v87
	v_cvt_pk_bf16_f32 v168, v80, v81
	v_cvt_pk_bf16_f32 v169, v82, v83
	v_pk_fma_f32 v[138:139], v[84:85], v[84:85], v[138:139]
	global_store_dwordx4 v207, v[166:169], s[10:11] offset:256
	v_pk_fma_f32 v[138:139], v[86:87], v[86:87], v[138:139]
	v_pk_fma_f32 v[138:139], v[80:81], v[80:81], v[138:139]
	v_pk_fma_f32 v[138:139], v[82:83], v[82:83], v[138:139]
	v_add_f32_e32 v214, v138, v139
	v_add_u32_e32 v207, 0x8000, v207
	v_mov_b32_e32 v215, v214
	s_nop 1
	v_permlane16_swap_b32_e32 v214, v215
	s_nop 0
	v_add_f32_e32 v214, v214, v215
	v_mov_b32_e32 v215, v214
	s_nop 1
	v_permlane32_swap_b32_e32 v214, v215
	s_nop 0
	v_add_f32_e32 v214, v214, v215
	s_and_saveexec_b64 s[28:29], s[4:5]
	global_store_dword v210, v214, s[16:17] offset:2048
	s_mov_b64 exec, s[28:29]
	s_waitcnt vmcnt(17)
	v_lshlrev_b32_e32 v202, 16, v170
	v_and_b32_e32 v203, 0xffff0000, v170
	v_lshlrev_b32_e32 v204, 16, v171
	v_and_b32_e32 v205, 0xffff0000, v171
	v_pk_add_f32 v[76:77], v[76:77], v[202:203]
	v_pk_add_f32 v[78:79], v[78:79], v[204:205]
	v_lshlrev_b32_e32 v202, 16, v172
	v_and_b32_e32 v203, 0xffff0000, v172
	v_lshlrev_b32_e32 v204, 16, v173
	v_and_b32_e32 v205, 0xffff0000, v173
	v_pk_add_f32 v[72:73], v[72:73], v[202:203]
	v_pk_add_f32 v[74:75], v[74:75], v[204:205]
	v_cvt_pk_bf16_f32 v170, v76, v77
	v_cvt_pk_bf16_f32 v171, v78, v79
	v_cvt_pk_bf16_f32 v172, v72, v73
	v_cvt_pk_bf16_f32 v173, v74, v75
	v_pk_mul_f32 v[138:139], v[76:77], v[76:77]
	global_store_dwordx4 v207, v[170:173], s[10:11]
	v_pk_fma_f32 v[138:139], v[78:79], v[78:79], v[138:139]
	v_pk_fma_f32 v[138:139], v[72:73], v[72:73], v[138:139]
	v_pk_fma_f32 v[138:139], v[74:75], v[74:75], v[138:139]
	v_lshlrev_b32_e32 v202, 16, v174
	v_and_b32_e32 v203, 0xffff0000, v174
	v_lshlrev_b32_e32 v204, 16, v175
	v_and_b32_e32 v205, 0xffff0000, v175
	v_pk_add_f32 v[68:69], v[68:69], v[202:203]
	v_pk_add_f32 v[70:71], v[70:71], v[204:205]
	v_lshlrev_b32_e32 v202, 16, v176
	v_and_b32_e32 v203, 0xffff0000, v176
	v_lshlrev_b32_e32 v204, 16, v177
	v_and_b32_e32 v205, 0xffff0000, v177
	v_pk_add_f32 v[64:65], v[64:65], v[202:203]
	v_pk_add_f32 v[66:67], v[66:67], v[204:205]
	v_cvt_pk_bf16_f32 v174, v68, v69
	v_cvt_pk_bf16_f32 v175, v70, v71
	v_cvt_pk_bf16_f32 v176, v64, v65
	v_cvt_pk_bf16_f32 v177, v66, v67
	v_pk_fma_f32 v[138:139], v[68:69], v[68:69], v[138:139]
	global_store_dwordx4 v207, v[174:177], s[10:11] offset:256
	v_pk_fma_f32 v[138:139], v[70:71], v[70:71], v[138:139]
	v_pk_fma_f32 v[138:139], v[64:65], v[64:65], v[138:139]
	v_pk_fma_f32 v[138:139], v[66:67], v[66:67], v[138:139]
	v_add_f32_e32 v214, v138, v139
	v_add_u32_e32 v207, 0x28000, v207
	v_mov_b32_e32 v215, v214
	s_nop 1
	v_permlane16_swap_b32_e32 v214, v215
	s_nop 0
	v_add_f32_e32 v214, v214, v215
	v_mov_b32_e32 v215, v214
	s_nop 1
	v_permlane32_swap_b32_e32 v214, v215
	s_nop 0
	v_add_f32_e32 v214, v214, v215
	s_and_saveexec_b64 s[28:29], s[4:5]
	global_store_dword v210, v214, s[16:17] offset:3072
	s_mov_b64 exec, s[28:29]
	v_add_u32_e32 v210, 0x2000, v210
	s_waitcnt vmcnt(18)
	v_lshlrev_b32_e32 v202, 16, v178
	v_and_b32_e32 v203, 0xffff0000, v178
	v_lshlrev_b32_e32 v204, 16, v179
	v_and_b32_e32 v205, 0xffff0000, v179
	v_pk_add_f32 v[60:61], v[60:61], v[202:203]
	v_pk_add_f32 v[62:63], v[62:63], v[204:205]
	v_lshlrev_b32_e32 v202, 16, v180
	v_and_b32_e32 v203, 0xffff0000, v180
	v_lshlrev_b32_e32 v204, 16, v181
	v_and_b32_e32 v205, 0xffff0000, v181
	v_pk_add_f32 v[56:57], v[56:57], v[202:203]
	v_pk_add_f32 v[58:59], v[58:59], v[204:205]
	v_cvt_pk_bf16_f32 v178, v60, v61
	v_cvt_pk_bf16_f32 v179, v62, v63
	v_cvt_pk_bf16_f32 v180, v56, v57
	v_cvt_pk_bf16_f32 v181, v58, v59
	v_pk_mul_f32 v[138:139], v[60:61], v[60:61]
	global_store_dwordx4 v207, v[178:181], s[10:11]
	v_pk_fma_f32 v[138:139], v[62:63], v[62:63], v[138:139]
	v_pk_fma_f32 v[138:139], v[56:57], v[56:57], v[138:139]
	v_pk_fma_f32 v[138:139], v[58:59], v[58:59], v[138:139]
	v_lshlrev_b32_e32 v202, 16, v182
	v_and_b32_e32 v203, 0xffff0000, v182
	v_lshlrev_b32_e32 v204, 16, v183
	v_and_b32_e32 v205, 0xffff0000, v183
	v_pk_add_f32 v[52:53], v[52:53], v[202:203]
	v_pk_add_f32 v[54:55], v[54:55], v[204:205]
	v_lshlrev_b32_e32 v202, 16, v184
	v_and_b32_e32 v203, 0xffff0000, v184
	v_lshlrev_b32_e32 v204, 16, v185
	v_and_b32_e32 v205, 0xffff0000, v185
	v_pk_add_f32 v[48:49], v[48:49], v[202:203]
	v_pk_add_f32 v[50:51], v[50:51], v[204:205]
	v_cvt_pk_bf16_f32 v182, v52, v53
	v_cvt_pk_bf16_f32 v183, v54, v55
	v_cvt_pk_bf16_f32 v184, v48, v49
	v_cvt_pk_bf16_f32 v185, v50, v51
	v_pk_fma_f32 v[138:139], v[52:53], v[52:53], v[138:139]
	global_store_dwordx4 v207, v[182:185], s[10:11] offset:256
	v_pk_fma_f32 v[138:139], v[54:55], v[54:55], v[138:139]
	v_pk_fma_f32 v[138:139], v[48:49], v[48:49], v[138:139]
	v_pk_fma_f32 v[138:139], v[50:51], v[50:51], v[138:139]
	v_add_f32_e32 v214, v138, v139
	v_add_u32_e32 v207, 0x8000, v207
	v_mov_b32_e32 v215, v214
	s_nop 1
	v_permlane16_swap_b32_e32 v214, v215
	s_nop 0
	v_add_f32_e32 v214, v214, v215
	v_mov_b32_e32 v215, v214
	s_nop 1
	v_permlane32_swap_b32_e32 v214, v215
	s_nop 0
	v_add_f32_e32 v214, v214, v215
	s_and_saveexec_b64 s[28:29], s[4:5]
	global_store_dword v210, v214, s[16:17]
	s_mov_b64 exec, s[28:29]
	s_waitcnt vmcnt(19)
	v_lshlrev_b32_e32 v202, 16, v186
	v_and_b32_e32 v203, 0xffff0000, v186
	v_lshlrev_b32_e32 v204, 16, v187
	v_and_b32_e32 v205, 0xffff0000, v187
	v_pk_add_f32 v[44:45], v[44:45], v[202:203]
	v_pk_add_f32 v[46:47], v[46:47], v[204:205]
	v_lshlrev_b32_e32 v202, 16, v188
	v_and_b32_e32 v203, 0xffff0000, v188
	v_lshlrev_b32_e32 v204, 16, v189
	v_and_b32_e32 v205, 0xffff0000, v189
	v_pk_add_f32 v[40:41], v[40:41], v[202:203]
	v_pk_add_f32 v[42:43], v[42:43], v[204:205]
	v_cvt_pk_bf16_f32 v186, v44, v45
	v_cvt_pk_bf16_f32 v187, v46, v47
	v_cvt_pk_bf16_f32 v188, v40, v41
	v_cvt_pk_bf16_f32 v189, v42, v43
	v_pk_mul_f32 v[138:139], v[44:45], v[44:45]
	global_store_dwordx4 v207, v[186:189], s[10:11]
	v_pk_fma_f32 v[138:139], v[46:47], v[46:47], v[138:139]
	v_pk_fma_f32 v[138:139], v[40:41], v[40:41], v[138:139]
	v_pk_fma_f32 v[138:139], v[42:43], v[42:43], v[138:139]
	v_lshlrev_b32_e32 v202, 16, v190
	v_and_b32_e32 v203, 0xffff0000, v190
	v_lshlrev_b32_e32 v204, 16, v191
	v_and_b32_e32 v205, 0xffff0000, v191
	v_pk_add_f32 v[36:37], v[36:37], v[202:203]
	v_pk_add_f32 v[38:39], v[38:39], v[204:205]
	v_lshlrev_b32_e32 v202, 16, v192
	v_and_b32_e32 v203, 0xffff0000, v192
	v_lshlrev_b32_e32 v204, 16, v193
	v_and_b32_e32 v205, 0xffff0000, v193
	v_pk_add_f32 v[32:33], v[32:33], v[202:203]
	v_pk_add_f32 v[34:35], v[34:35], v[204:205]
	v_cvt_pk_bf16_f32 v190, v36, v37
	v_cvt_pk_bf16_f32 v191, v38, v39
	v_cvt_pk_bf16_f32 v192, v32, v33
	v_cvt_pk_bf16_f32 v193, v34, v35
	v_pk_fma_f32 v[138:139], v[36:37], v[36:37], v[138:139]
	global_store_dwordx4 v207, v[190:193], s[10:11] offset:256
	v_pk_fma_f32 v[138:139], v[38:39], v[38:39], v[138:139]
	v_pk_fma_f32 v[138:139], v[32:33], v[32:33], v[138:139]
	v_pk_fma_f32 v[138:139], v[34:35], v[34:35], v[138:139]
	v_add_f32_e32 v214, v138, v139
	v_add_u32_e32 v207, 0x8000, v207
	v_mov_b32_e32 v215, v214
	s_nop 1
	v_permlane16_swap_b32_e32 v214, v215
	s_nop 0
	v_add_f32_e32 v214, v214, v215
	v_mov_b32_e32 v215, v214
	s_nop 1
	v_permlane32_swap_b32_e32 v214, v215
	s_nop 0
	v_add_f32_e32 v214, v214, v215
	s_and_saveexec_b64 s[28:29], s[4:5]
	global_store_dword v210, v214, s[16:17] offset:1024
	s_mov_b64 exec, s[28:29]
	s_waitcnt vmcnt(20)
	v_lshlrev_b32_e32 v202, 16, v194
	v_and_b32_e32 v203, 0xffff0000, v194
	v_lshlrev_b32_e32 v204, 16, v195
	v_and_b32_e32 v205, 0xffff0000, v195
	v_pk_add_f32 v[28:29], v[28:29], v[202:203]
	v_pk_add_f32 v[30:31], v[30:31], v[204:205]
	v_lshlrev_b32_e32 v202, 16, v196
	v_and_b32_e32 v203, 0xffff0000, v196
	v_lshlrev_b32_e32 v204, 16, v197
	v_and_b32_e32 v205, 0xffff0000, v197
	v_pk_add_f32 v[24:25], v[24:25], v[202:203]
	v_pk_add_f32 v[26:27], v[26:27], v[204:205]
	v_cvt_pk_bf16_f32 v194, v28, v29
	v_cvt_pk_bf16_f32 v195, v30, v31
	v_cvt_pk_bf16_f32 v196, v24, v25
	v_cvt_pk_bf16_f32 v197, v26, v27
	v_pk_mul_f32 v[138:139], v[28:29], v[28:29]
	global_store_dwordx4 v207, v[194:197], s[10:11]
	v_pk_fma_f32 v[138:139], v[30:31], v[30:31], v[138:139]
	v_pk_fma_f32 v[138:139], v[24:25], v[24:25], v[138:139]
	v_pk_fma_f32 v[138:139], v[26:27], v[26:27], v[138:139]
	v_lshlrev_b32_e32 v202, 16, v198
	v_and_b32_e32 v203, 0xffff0000, v198
	v_lshlrev_b32_e32 v204, 16, v199
	v_and_b32_e32 v205, 0xffff0000, v199
	v_pk_add_f32 v[20:21], v[20:21], v[202:203]
	v_pk_add_f32 v[22:23], v[22:23], v[204:205]
	v_lshlrev_b32_e32 v202, 16, v200
	v_and_b32_e32 v203, 0xffff0000, v200
	v_lshlrev_b32_e32 v204, 16, v201
	v_and_b32_e32 v205, 0xffff0000, v201
	v_pk_add_f32 v[16:17], v[16:17], v[202:203]
	v_pk_add_f32 v[18:19], v[18:19], v[204:205]
	v_cvt_pk_bf16_f32 v198, v20, v21
	v_cvt_pk_bf16_f32 v199, v22, v23
	v_cvt_pk_bf16_f32 v200, v16, v17
	v_cvt_pk_bf16_f32 v201, v18, v19
	v_pk_fma_f32 v[138:139], v[20:21], v[20:21], v[138:139]
	global_store_dwordx4 v207, v[198:201], s[10:11] offset:256
	v_pk_fma_f32 v[138:139], v[22:23], v[22:23], v[138:139]
	v_pk_fma_f32 v[138:139], v[16:17], v[16:17], v[138:139]
	v_pk_fma_f32 v[138:139], v[18:19], v[18:19], v[138:139]
	v_add_f32_e32 v214, v138, v139
	v_add_u32_e32 v207, 0x8000, v207
	v_mov_b32_e32 v215, v214
	s_nop 1
	v_permlane16_swap_b32_e32 v214, v215
	s_nop 0
	v_add_f32_e32 v214, v214, v215
	v_mov_b32_e32 v215, v214
	s_nop 1
	v_permlane32_swap_b32_e32 v214, v215
	s_nop 0
	v_add_f32_e32 v214, v214, v215
	s_and_saveexec_b64 s[28:29], s[4:5]
	global_store_dword v210, v214, s[16:17] offset:2048
	s_mov_b64 exec, s[28:29]
	s_waitcnt vmcnt(18)
	v_lshlrev_b32_e32 v202, 16, v146
	v_and_b32_e32 v203, 0xffff0000, v146
	v_lshlrev_b32_e32 v204, 16, v147
	v_and_b32_e32 v205, 0xffff0000, v147
	v_pk_add_f32 v[12:13], v[12:13], v[202:203]
	v_pk_add_f32 v[14:15], v[14:15], v[204:205]
	v_lshlrev_b32_e32 v202, 16, v148
	v_and_b32_e32 v203, 0xffff0000, v148
	v_lshlrev_b32_e32 v204, 16, v149
	v_and_b32_e32 v205, 0xffff0000, v149
	v_pk_add_f32 v[8:9], v[8:9], v[202:203]
	v_pk_add_f32 v[10:11], v[10:11], v[204:205]
	v_cvt_pk_bf16_f32 v146, v12, v13
	v_cvt_pk_bf16_f32 v147, v14, v15
	v_cvt_pk_bf16_f32 v148, v8, v9
	v_cvt_pk_bf16_f32 v149, v10, v11
	v_pk_mul_f32 v[138:139], v[12:13], v[12:13]
	global_store_dwordx4 v207, v[146:149], s[10:11]
	v_pk_fma_f32 v[138:139], v[14:15], v[14:15], v[138:139]
	v_pk_fma_f32 v[138:139], v[8:9], v[8:9], v[138:139]
	v_pk_fma_f32 v[138:139], v[10:11], v[10:11], v[138:139]
	v_lshlrev_b32_e32 v202, 16, v150
	v_and_b32_e32 v203, 0xffff0000, v150
	v_lshlrev_b32_e32 v204, 16, v151
	v_and_b32_e32 v205, 0xffff0000, v151
	v_pk_add_f32 v[4:5], v[4:5], v[202:203]
	v_pk_add_f32 v[6:7], v[6:7], v[204:205]
	v_lshlrev_b32_e32 v202, 16, v152
	v_and_b32_e32 v203, 0xffff0000, v152
	v_lshlrev_b32_e32 v204, 16, v153
	v_and_b32_e32 v205, 0xffff0000, v153
	v_pk_add_f32 v[0:1], v[0:1], v[202:203]
	v_pk_add_f32 v[2:3], v[2:3], v[204:205]
	v_cvt_pk_bf16_f32 v150, v4, v5
	v_cvt_pk_bf16_f32 v151, v6, v7
	v_cvt_pk_bf16_f32 v152, v0, v1
	v_cvt_pk_bf16_f32 v153, v2, v3
	v_pk_fma_f32 v[138:139], v[4:5], v[4:5], v[138:139]
	global_store_dwordx4 v207, v[150:153], s[10:11] offset:256
	v_pk_fma_f32 v[138:139], v[6:7], v[6:7], v[138:139]
	v_pk_fma_f32 v[138:139], v[0:1], v[0:1], v[138:139]
	v_pk_fma_f32 v[138:139], v[2:3], v[2:3], v[138:139]
	v_add_f32_e32 v214, v138, v139
	v_add_u32_e32 v207, 0x8000, v207
	v_mov_b32_e32 v215, v214
	s_nop 1
	v_permlane16_swap_b32_e32 v214, v215
	s_nop 0
	v_add_f32_e32 v214, v214, v215
	v_mov_b32_e32 v215, v214
	s_nop 1
	v_permlane32_swap_b32_e32 v214, v215
	s_nop 0
	v_add_f32_e32 v214, v214, v215
	s_and_saveexec_b64 s[28:29], s[4:5]
	global_store_dword v210, v214, s[16:17] offset:3072
	s_mov_b64 exec, s[28:29]
	s_branch .LBB0_768

.LBB0_823:
	s_add_u32 s26, s24, 0xfffc0080
	s_addc_u32 s27, s25, -1
	s_add_i32 s65, 0, 0x10000
	v_add_u32_e32 v154, s65, v143
	ds_read_b128 v[138:141], v154
	ds_read_b128 v[146:149], v154 offset:1024
	ds_read_b128 v[150:153], v154 offset:2048
	ds_read_b128 v[154:157], v154 offset:3072
	s_cmp_eq_u32 s51, 12
	s_cselect_b32 s29, s19, s27
	s_cselect_b32 s28, s38, s26
	s_cselect_b32 s27, s17, s50
	s_cselect_b32 s26, s39, s46
	v_lshl_add_u64 v[190:191], s[24:25], 0, v[134:135]
	s_add_i32 m0, s58, 0xc000
	ds_read_b128 v[158:161], v145
	ds_read_b128 v[162:165], v145 offset:1024
	ds_read_b128 v[166:169], v145 offset:2048
	ds_read_b128 v[170:173], v145 offset:3072
	ds_read_b128 v[174:177], v145 offset:4096
	ds_read_b128 v[178:181], v145 offset:5120
	ds_read_b128 v[182:185], v145 offset:6144
	ds_read_b128 v[186:189], v145 offset:7168
	global_load_lds_dwordx4 v[190:191], off
	v_lshl_add_u64 v[190:191], s[24:25], 0, v[136:137]
	s_add_i32 m0, s58, 0xe000
	s_nop 0
	global_load_lds_dwordx4 v[190:191], off
	s_waitcnt lgkmcnt(8)
	s_barrier
	s_waitcnt lgkmcnt(0)
	s_setprio 1
	v_mfma_f32_16x16x32_bf16 v[124:127], v[138:141], v[158:161], v[124:127]
	v_mfma_f32_16x16x32_bf16 v[120:123], v[150:153], v[158:161], v[120:123]
	v_mfma_f32_16x16x32_bf16 v[108:111], v[138:141], v[166:169], v[108:111]
	v_mfma_f32_16x16x32_bf16 v[104:107], v[150:153], v[166:169], v[104:107]
	v_mfma_f32_16x16x32_bf16 v[92:95], v[138:141], v[174:177], v[92:95]
	v_mfma_f32_16x16x32_bf16 v[88:91], v[150:153], v[174:177], v[88:91]
	v_mfma_f32_16x16x32_bf16 v[76:79], v[138:141], v[182:185], v[76:79]
	v_mfma_f32_16x16x32_bf16 v[72:75], v[150:153], v[182:185], v[72:75]
	v_mfma_f32_16x16x32_bf16 v[124:127], v[146:149], v[162:165], v[124:127]
	v_mfma_f32_16x16x32_bf16 v[120:123], v[154:157], v[162:165], v[120:123]
	v_mfma_f32_16x16x32_bf16 v[108:111], v[146:149], v[170:173], v[108:111]
	v_mfma_f32_16x16x32_bf16 v[104:107], v[154:157], v[170:173], v[104:107]
	v_mfma_f32_16x16x32_bf16 v[92:95], v[146:149], v[178:181], v[92:95]
	v_mfma_f32_16x16x32_bf16 v[88:91], v[154:157], v[178:181], v[88:91]
	v_mfma_f32_16x16x32_bf16 v[76:79], v[146:149], v[186:189], v[76:79]
	v_mfma_f32_16x16x32_bf16 v[72:75], v[154:157], v[186:189], v[72:75]
	s_setprio 0
	s_barrier
	s_add_i32 s68, 0, 0x14000
	s_add_i32 s65, s65, s57
	v_add_u32_e32 v202, s68, v143
	v_lshl_add_u64 v[206:207], s[26:27], 0, v[208:209]
	s_mov_b32 m0, s65
	ds_read_b128 v[190:193], v202
	ds_read_b128 v[194:197], v202 offset:1024
	ds_read_b128 v[198:201], v202 offset:2048
	ds_read_b128 v[202:205], v202 offset:3072
	global_load_lds_dwordx4 v[206:207], off
	v_lshl_add_u64 v[210:211], s[26:27], 0, v[128:129]
	s_add_i32 m0, s65, 0x2000
	s_nop 0
	global_load_lds_dwordx4 v[210:211], off
	s_barrier
	s_waitcnt lgkmcnt(0)
	s_setprio 1
	v_mfma_f32_16x16x32_bf16 v[116:119], v[190:193], v[158:161], v[116:119]
	v_mfma_f32_16x16x32_bf16 v[112:115], v[198:201], v[158:161], v[112:115]
	v_mfma_f32_16x16x32_bf16 v[100:103], v[190:193], v[166:169], v[100:103]
	v_mfma_f32_16x16x32_bf16 v[96:99], v[198:201], v[166:169], v[96:99]
	v_mfma_f32_16x16x32_bf16 v[84:87], v[190:193], v[174:177], v[84:87]
	v_mfma_f32_16x16x32_bf16 v[80:83], v[198:201], v[174:177], v[80:83]
	v_mfma_f32_16x16x32_bf16 v[68:71], v[190:193], v[182:185], v[68:71]
	v_mfma_f32_16x16x32_bf16 v[64:67], v[198:201], v[182:185], v[64:67]
	v_mfma_f32_16x16x32_bf16 v[116:119], v[194:197], v[162:165], v[116:119]
	v_mfma_f32_16x16x32_bf16 v[112:115], v[202:205], v[162:165], v[112:115]
	v_mfma_f32_16x16x32_bf16 v[100:103], v[194:197], v[170:173], v[100:103]
	v_mfma_f32_16x16x32_bf16 v[96:99], v[202:205], v[170:173], v[96:99]
	v_mfma_f32_16x16x32_bf16 v[84:87], v[194:197], v[178:181], v[84:87]
	v_mfma_f32_16x16x32_bf16 v[80:83], v[202:205], v[178:181], v[80:83]
	v_mfma_f32_16x16x32_bf16 v[68:71], v[194:197], v[186:189], v[68:71]
	v_mfma_f32_16x16x32_bf16 v[64:67], v[202:205], v[186:189], v[64:67]
	s_setprio 0
	s_mov_b32 m0, s58
	v_lshl_add_u64 v[214:215], s[28:29], 0, v[132:133]
	s_barrier
	ds_read_b128 v[158:161], v145 offset:16384
	ds_read_b128 v[162:165], v145 offset:17408
	ds_read_b128 v[166:169], v145 offset:18432
	ds_read_b128 v[170:173], v145 offset:19456
	ds_read_b128 v[174:177], v145 offset:20480
	ds_read_b128 v[178:181], v145 offset:21504
	ds_read_b128 v[182:185], v145 offset:22528
	ds_read_b128 v[186:189], v145 offset:23552
	global_load_lds_dwordx4 v[214:215], off
	v_lshl_add_u64 v[216:217], s[28:29], 0, v[130:131]
	s_mov_b32 m0, s59
	s_nop 0
	global_load_lds_dwordx4 v[216:217], off
	s_barrier
	s_waitcnt lgkmcnt(0)
	s_setprio 1
	v_mfma_f32_16x16x32_bf16 v[60:63], v[138:141], v[158:161], v[60:63]
	v_mfma_f32_16x16x32_bf16 v[56:59], v[150:153], v[158:161], v[56:59]
	v_mfma_f32_16x16x32_bf16 v[44:47], v[138:141], v[166:169], v[44:47]
	v_mfma_f32_16x16x32_bf16 v[40:43], v[150:153], v[166:169], v[40:43]
	v_mfma_f32_16x16x32_bf16 v[28:31], v[138:141], v[174:177], v[28:31]
	v_mfma_f32_16x16x32_bf16 v[24:27], v[150:153], v[174:177], v[24:27]
	v_mfma_f32_16x16x32_bf16 v[12:15], v[138:141], v[182:185], v[12:15]
	v_mfma_f32_16x16x32_bf16 v[8:11], v[150:153], v[182:185], v[8:11]
	v_mfma_f32_16x16x32_bf16 v[60:63], v[146:149], v[162:165], v[60:63]
	v_mfma_f32_16x16x32_bf16 v[56:59], v[154:157], v[162:165], v[56:59]
	v_mfma_f32_16x16x32_bf16 v[44:47], v[146:149], v[170:173], v[44:47]
	v_mfma_f32_16x16x32_bf16 v[40:43], v[154:157], v[170:173], v[40:43]
	v_mfma_f32_16x16x32_bf16 v[28:31], v[146:149], v[178:181], v[28:31]
	v_mfma_f32_16x16x32_bf16 v[24:27], v[154:157], v[178:181], v[24:27]
	v_mfma_f32_16x16x32_bf16 v[12:15], v[146:149], v[186:189], v[12:15]
	v_mfma_f32_16x16x32_bf16 v[8:11], v[154:157], v[186:189], v[8:11]
	s_setprio 0
	s_barrier
	s_add_u32 s66, s26, 0x40000
	s_addc_u32 s67, s27, 0
	s_add_i32 s65, s68, s57
	v_lshl_add_u64 v[138:139], s[66:67], 0, v[208:209]
	s_mov_b32 m0, s65
	s_nop 0
	global_load_lds_dwordx4 v[138:139], off
	v_lshl_add_u64 v[138:139], s[66:67], 0, v[128:129]
	s_add_i32 m0, s65, 0x2000
	s_nop 0
	global_load_lds_dwordx4 v[138:139], off
	s_waitcnt vmcnt(6)
	s_barrier
	s_setprio 1
	v_mfma_f32_16x16x32_bf16 v[52:55], v[190:193], v[158:161], v[52:55]
	v_mfma_f32_16x16x32_bf16 v[48:51], v[198:201], v[158:161], v[48:51]
	v_mfma_f32_16x16x32_bf16 v[36:39], v[190:193], v[166:169], v[36:39]
	v_mfma_f32_16x16x32_bf16 v[32:35], v[198:201], v[166:169], v[32:35]
	v_mfma_f32_16x16x32_bf16 v[20:23], v[190:193], v[174:177], v[20:23]
	v_mfma_f32_16x16x32_bf16 v[16:19], v[198:201], v[174:177], v[16:19]
	v_mfma_f32_16x16x32_bf16 v[4:7], v[190:193], v[182:185], v[4:7]
	v_mfma_f32_16x16x32_bf16 v[0:3], v[198:201], v[182:185], v[0:3]
	v_mfma_f32_16x16x32_bf16 v[52:55], v[194:197], v[162:165], v[52:55]
	v_mfma_f32_16x16x32_bf16 v[48:51], v[202:205], v[162:165], v[48:51]
	v_mfma_f32_16x16x32_bf16 v[36:39], v[194:197], v[170:173], v[36:39]
	v_mfma_f32_16x16x32_bf16 v[32:35], v[202:205], v[170:173], v[32:35]
	v_mfma_f32_16x16x32_bf16 v[20:23], v[194:197], v[178:181], v[20:23]
	v_mfma_f32_16x16x32_bf16 v[16:19], v[202:205], v[178:181], v[16:19]
	v_mfma_f32_16x16x32_bf16 v[4:7], v[194:197], v[186:189], v[4:7]
	v_mfma_f32_16x16x32_bf16 v[0:3], v[202:205], v[186:189], v[0:3]
	s_setprio 0
	s_add_i32 s65, 0, 0x18000
	v_add_u32_e32 v154, s65, v143
	s_barrier
	ds_read_b128 v[138:141], v154
	ds_read_b128 v[146:149], v154 offset:1024
	ds_read_b128 v[150:153], v154 offset:2048
	ds_read_b128 v[154:157], v154 offset:3072
	s_add_u32 s28, s28, 0x40000
	s_addc_u32 s29, s29, 0
	s_mov_b32 m0, s60
	v_lshl_add_u64 v[190:191], s[28:29], 0, v[132:133]
	ds_read_b128 v[158:161], v145 offset:32768
	ds_read_b128 v[162:165], v145 offset:33792
	ds_read_b128 v[166:169], v145 offset:34816
	ds_read_b128 v[170:173], v145 offset:35840
	ds_read_b128 v[174:177], v145 offset:36864
	ds_read_b128 v[178:181], v145 offset:37888
	ds_read_b128 v[182:185], v145 offset:38912
	ds_read_b128 v[186:189], v145 offset:39936
	global_load_lds_dwordx4 v[190:191], off
	v_lshl_add_u64 v[190:191], s[28:29], 0, v[130:131]
	s_mov_b32 m0, s61
	s_nop 0
	global_load_lds_dwordx4 v[190:191], off
	s_waitcnt lgkmcnt(8)
	s_barrier
	s_waitcnt lgkmcnt(0)
	s_setprio 1
	v_mfma_f32_16x16x32_bf16 v[124:127], v[138:141], v[158:161], v[124:127]
	v_mfma_f32_16x16x32_bf16 v[120:123], v[150:153], v[158:161], v[120:123]
	v_mfma_f32_16x16x32_bf16 v[108:111], v[138:141], v[166:169], v[108:111]
	v_mfma_f32_16x16x32_bf16 v[104:107], v[150:153], v[166:169], v[104:107]
	v_mfma_f32_16x16x32_bf16 v[92:95], v[138:141], v[174:177], v[92:95]
	v_mfma_f32_16x16x32_bf16 v[88:91], v[150:153], v[174:177], v[88:91]
	v_mfma_f32_16x16x32_bf16 v[76:79], v[138:141], v[182:185], v[76:79]
	v_mfma_f32_16x16x32_bf16 v[72:75], v[150:153], v[182:185], v[72:75]
	v_mfma_f32_16x16x32_bf16 v[124:127], v[146:149], v[162:165], v[124:127]
	v_mfma_f32_16x16x32_bf16 v[120:123], v[154:157], v[162:165], v[120:123]
	v_mfma_f32_16x16x32_bf16 v[108:111], v[146:149], v[170:173], v[108:111]
	v_mfma_f32_16x16x32_bf16 v[104:107], v[154:157], v[170:173], v[104:107]
	v_mfma_f32_16x16x32_bf16 v[92:95], v[146:149], v[178:181], v[92:95]
	v_mfma_f32_16x16x32_bf16 v[88:91], v[154:157], v[178:181], v[88:91]
	v_mfma_f32_16x16x32_bf16 v[76:79], v[146:149], v[186:189], v[76:79]
	v_mfma_f32_16x16x32_bf16 v[72:75], v[154:157], v[186:189], v[72:75]
	s_setprio 0
	s_barrier
	s_add_i32 s28, 0, 0x1c000
	s_add_i32 s29, s65, s57
	v_add_u32_e32 v202, s28, v143
	v_lshl_add_u64 v[206:207], v[206:207], 0, s[40:41]
	s_mov_b32 m0, s29
	ds_read_b128 v[190:193], v202
	ds_read_b128 v[194:197], v202 offset:1024
	ds_read_b128 v[198:201], v202 offset:2048
	ds_read_b128 v[202:205], v202 offset:3072
	global_load_lds_dwordx4 v[206:207], off
	v_lshl_add_u64 v[206:207], v[210:211], 0, s[40:41]
	s_add_i32 m0, s29, 0x2000
	s_nop 0
	global_load_lds_dwordx4 v[206:207], off
	s_barrier
	s_waitcnt lgkmcnt(0)
	s_setprio 1
	v_mfma_f32_16x16x32_bf16 v[116:119], v[190:193], v[158:161], v[116:119]
	v_mfma_f32_16x16x32_bf16 v[112:115], v[198:201], v[158:161], v[112:115]
	v_mfma_f32_16x16x32_bf16 v[100:103], v[190:193], v[166:169], v[100:103]
	v_mfma_f32_16x16x32_bf16 v[96:99], v[198:201], v[166:169], v[96:99]
	v_mfma_f32_16x16x32_bf16 v[84:87], v[190:193], v[174:177], v[84:87]
	v_mfma_f32_16x16x32_bf16 v[80:83], v[198:201], v[174:177], v[80:83]
	v_mfma_f32_16x16x32_bf16 v[68:71], v[190:193], v[182:185], v[68:71]
	v_mfma_f32_16x16x32_bf16 v[64:67], v[198:201], v[182:185], v[64:67]
	v_mfma_f32_16x16x32_bf16 v[116:119], v[194:197], v[162:165], v[116:119]
	v_mfma_f32_16x16x32_bf16 v[112:115], v[202:205], v[162:165], v[112:115]
	v_mfma_f32_16x16x32_bf16 v[100:103], v[194:197], v[170:173], v[100:103]
	v_mfma_f32_16x16x32_bf16 v[96:99], v[202:205], v[170:173], v[96:99]
	v_mfma_f32_16x16x32_bf16 v[84:87], v[194:197], v[178:181], v[84:87]
	v_mfma_f32_16x16x32_bf16 v[80:83], v[202:205], v[178:181], v[80:83]
	v_mfma_f32_16x16x32_bf16 v[68:71], v[194:197], v[186:189], v[68:71]
	v_mfma_f32_16x16x32_bf16 v[64:67], v[202:205], v[186:189], v[64:67]
	s_setprio 0
	s_mov_b32 m0, s62
	v_lshl_add_u64 v[206:207], v[214:215], 0, s[40:41]
	s_barrier
	ds_read_b128 v[158:161], v145 offset:49152
	ds_read_b128 v[162:165], v145 offset:50176
	ds_read_b128 v[166:169], v145 offset:51200
	ds_read_b128 v[170:173], v145 offset:52224
	ds_read_b128 v[174:177], v145 offset:53248
	ds_read_b128 v[178:181], v145 offset:54272
	ds_read_b128 v[182:185], v145 offset:55296
	ds_read_b128 v[186:189], v145 offset:56320
	global_load_lds_dwordx4 v[206:207], off
	v_lshl_add_u64 v[206:207], v[216:217], 0, s[40:41]
	s_mov_b32 m0, s63
	s_nop 0
	global_load_lds_dwordx4 v[206:207], off
	s_barrier
	s_waitcnt lgkmcnt(0)
	s_setprio 1
	v_mfma_f32_16x16x32_bf16 v[60:63], v[138:141], v[158:161], v[60:63]
	v_mfma_f32_16x16x32_bf16 v[56:59], v[150:153], v[158:161], v[56:59]
	v_mfma_f32_16x16x32_bf16 v[44:47], v[138:141], v[166:169], v[44:47]
	v_mfma_f32_16x16x32_bf16 v[40:43], v[150:153], v[166:169], v[40:43]
	v_mfma_f32_16x16x32_bf16 v[28:31], v[138:141], v[174:177], v[28:31]
	v_mfma_f32_16x16x32_bf16 v[24:27], v[150:153], v[174:177], v[24:27]
	v_mfma_f32_16x16x32_bf16 v[12:15], v[138:141], v[182:185], v[12:15]
	v_mfma_f32_16x16x32_bf16 v[8:11], v[150:153], v[182:185], v[8:11]
	v_mfma_f32_16x16x32_bf16 v[60:63], v[146:149], v[162:165], v[60:63]
	v_mfma_f32_16x16x32_bf16 v[56:59], v[154:157], v[162:165], v[56:59]
	v_mfma_f32_16x16x32_bf16 v[44:47], v[146:149], v[170:173], v[44:47]
	v_mfma_f32_16x16x32_bf16 v[40:43], v[154:157], v[170:173], v[40:43]
	v_mfma_f32_16x16x32_bf16 v[28:31], v[146:149], v[178:181], v[28:31]
	v_mfma_f32_16x16x32_bf16 v[24:27], v[154:157], v[178:181], v[24:27]
	v_mfma_f32_16x16x32_bf16 v[12:15], v[146:149], v[186:189], v[12:15]
	v_mfma_f32_16x16x32_bf16 v[8:11], v[154:157], v[186:189], v[8:11]
	s_setprio 0
	s_barrier
	s_add_u32 s26, s26, 0x40080
	s_addc_u32 s27, s27, 0
	s_add_i32 s28, s28, s57
	v_lshl_add_u64 v[138:139], s[26:27], 0, v[208:209]
	s_mov_b32 m0, s28
	s_nop 0
	global_load_lds_dwordx4 v[138:139], off
	v_lshl_add_u64 v[138:139], s[26:27], 0, v[128:129]
	s_add_i32 m0, s28, 0x2000
	s_nop 0
	global_load_lds_dwordx4 v[138:139], off
	s_waitcnt vmcnt(6)
	s_barrier
	s_setprio 1
	v_mfma_f32_16x16x32_bf16 v[52:55], v[190:193], v[158:161], v[52:55]
	v_mfma_f32_16x16x32_bf16 v[48:51], v[198:201], v[158:161], v[48:51]
	v_mfma_f32_16x16x32_bf16 v[36:39], v[190:193], v[166:169], v[36:39]
	v_mfma_f32_16x16x32_bf16 v[32:35], v[198:201], v[166:169], v[32:35]
	v_mfma_f32_16x16x32_bf16 v[20:23], v[190:193], v[174:177], v[20:23]
	v_mfma_f32_16x16x32_bf16 v[16:19], v[198:201], v[174:177], v[16:19]
	v_mfma_f32_16x16x32_bf16 v[4:7], v[190:193], v[182:185], v[4:7]
	v_mfma_f32_16x16x32_bf16 v[0:3], v[198:201], v[182:185], v[0:3]
	v_mfma_f32_16x16x32_bf16 v[52:55], v[194:197], v[162:165], v[52:55]
	v_mfma_f32_16x16x32_bf16 v[48:51], v[202:205], v[162:165], v[48:51]
	v_mfma_f32_16x16x32_bf16 v[36:39], v[194:197], v[170:173], v[36:39]
	v_mfma_f32_16x16x32_bf16 v[32:35], v[202:205], v[170:173], v[32:35]
	v_mfma_f32_16x16x32_bf16 v[20:23], v[194:197], v[178:181], v[20:23]
	v_mfma_f32_16x16x32_bf16 v[16:19], v[202:205], v[178:181], v[16:19]
	v_mfma_f32_16x16x32_bf16 v[4:7], v[194:197], v[186:189], v[4:7]
	v_mfma_f32_16x16x32_bf16 v[0:3], v[202:205], v[186:189], v[0:3]
	s_setprio 0
	s_add_i32 s51, s51, 2
	s_add_u32 s24, s24, 0x100
	s_addc_u32 s25, s25, 0
	s_add_u32 s46, s46, 0x100
	s_addc_u32 s50, s50, 0
	s_cmp_gt_u32 s51, 13
	s_barrier
	s_cbranch_scc0 .LBB0_823
	v_lshl_add_u32 v140, s35, 8, v142
	v_lshl_or_b32 v141, s34, 8, v144
	s_mov_b32 s34, s16
	s_mov_b32 s35, s18
	s_mov_b64 s[26:27], s[22:23]
	s_mov_b64 s[24:25], s[20:21]
	v_mbcnt_lo_u32_b32 v206, -1, 0
	v_mbcnt_hi_u32_b32 v206, -1, v206
	v_and_b32_e32 v206, 48, v206
	v_lshl_add_u32 v206, v140, 6, v206
	v_lshlrev_b32_e32 v207, 11, v140
	v_lshl_add_u32 v207, v141, 1, v207
	global_load_dwordx4 v[146:149], v206, s[14:15]
	global_load_dwordx4 v[150:153], v206, s[14:15] offset:1024
	global_load_dwordx4 v[154:157], v206, s[14:15] offset:2048
	global_load_dwordx4 v[158:161], v206, s[14:15] offset:3072
	v_add_u32_e32 v206, 0x2000, v206
	global_load_dwordx4 v[162:165], v206, s[14:15]
	global_load_dwordx4 v[166:169], v206, s[14:15] offset:1024
	global_load_dwordx4 v[170:173], v206, s[14:15] offset:2048
	global_load_dwordx4 v[174:177], v206, s[14:15] offset:3072
	s_waitcnt vmcnt(7)
	v_pk_add_f32 v[146:147], v[146:147], v[148:149]
	s_nop 0
	v_add_f32_e32 v214, v146, v147
	v_mov_b32_e32 v215, v214
	s_nop 1
	v_permlane16_swap_b32_e32 v214, v215
	s_nop 0
	v_add_f32_e32 v214, v214, v215
	v_mov_b32_e32 v215, v214
	s_nop 1
	v_permlane32_swap_b32_e32 v214, v215
	s_nop 0
	v_add_f32_e32 v214, v214, v215
	v_fmamk_f32 v214, v214, 0x3a800000, v248
	v_rsq_f32_e32 v178, v214
	s_nop 0
	v_pk_mul_f32 v[124:125], v[124:125], v[178:179] op_sel_hi:[1,0]
	v_pk_mul_f32 v[126:127], v[126:127], v[178:179] op_sel_hi:[1,0]
	v_pk_mul_f32 v[120:121], v[120:121], v[178:179] op_sel_hi:[1,0]
	v_pk_mul_f32 v[122:123], v[122:123], v[178:179] op_sel_hi:[1,0]
	v_cvt_pk_bf16_f32 v198, v124, v125
	v_cvt_pk_bf16_f32 v199, v126, v127
	v_cvt_pk_bf16_f32 v200, v120, v121
	v_cvt_pk_bf16_f32 v201, v122, v123
	global_store_dwordx4 v207, v[198:201], s[10:11]
	v_pk_mul_f32 v[116:117], v[116:117], v[178:179] op_sel_hi:[1,0]
	v_pk_mul_f32 v[118:119], v[118:119], v[178:179] op_sel_hi:[1,0]
	v_pk_mul_f32 v[112:113], v[112:113], v[178:179] op_sel_hi:[1,0]
	v_pk_mul_f32 v[114:115], v[114:115], v[178:179] op_sel_hi:[1,0]
	v_cvt_pk_bf16_f32 v202, v116, v117
	v_cvt_pk_bf16_f32 v203, v118, v119
	v_cvt_pk_bf16_f32 v204, v112, v113
	v_cvt_pk_bf16_f32 v205, v114, v115
	global_store_dwordx4 v207, v[202:205], s[10:11] offset:256
	v_add_u32_e32 v207, 0x8000, v207
	s_waitcnt vmcnt(8)
	v_pk_add_f32 v[150:151], v[150:151], v[152:153]
	s_nop 0
	v_add_f32_e32 v214, v150, v151
	v_mov_b32_e32 v215, v214
	s_nop 1
	v_permlane16_swap_b32_e32 v214, v215
	s_nop 0
	v_add_f32_e32 v214, v214, v215
	v_mov_b32_e32 v215, v214
	s_nop 1
	v_permlane32_swap_b32_e32 v214, v215
	s_nop 0
	v_add_f32_e32 v214, v214, v215
	v_fmamk_f32 v214, v214, 0x3a800000, v248
	v_rsq_f32_e32 v180, v214
	s_nop 0
	v_pk_mul_f32 v[108:109], v[108:109], v[180:181] op_sel_hi:[1,0]
	v_pk_mul_f32 v[110:111], v[110:111], v[180:181] op_sel_hi:[1,0]
	v_pk_mul_f32 v[104:105], v[104:105], v[180:181] op_sel_hi:[1,0]
	v_pk_mul_f32 v[106:107], v[106:107], v[180:181] op_sel_hi:[1,0]
	v_cvt_pk_bf16_f32 v198, v108, v109
	v_cvt_pk_bf16_f32 v199, v110, v111
	v_cvt_pk_bf16_f32 v200, v104, v105
	v_cvt_pk_bf16_f32 v201, v106, v107
	global_store_dwordx4 v207, v[198:201], s[10:11]
	v_pk_mul_f32 v[100:101], v[100:101], v[180:181] op_sel_hi:[1,0]
	v_pk_mul_f32 v[102:103], v[102:103], v[180:181] op_sel_hi:[1,0]
	v_pk_mul_f32 v[96:97], v[96:97], v[180:181] op_sel_hi:[1,0]
	v_pk_mul_f32 v[98:99], v[98:99], v[180:181] op_sel_hi:[1,0]
	v_cvt_pk_bf16_f32 v202, v100, v101
	v_cvt_pk_bf16_f32 v203, v102, v103
	v_cvt_pk_bf16_f32 v204, v96, v97
	v_cvt_pk_bf16_f32 v205, v98, v99
	global_store_dwordx4 v207, v[202:205], s[10:11] offset:256
	v_add_u32_e32 v207, 0x8000, v207
	s_waitcnt vmcnt(9)
	v_pk_add_f32 v[154:155], v[154:155], v[156:157]
	s_nop 0
	v_add_f32_e32 v214, v154, v155
	v_mov_b32_e32 v215, v214
	s_nop 1
	v_permlane16_swap_b32_e32 v214, v215
	s_nop 0
	v_add_f32_e32 v214, v214, v215
	v_mov_b32_e32 v215, v214
	s_nop 1
	v_permlane32_swap_b32_e32 v214, v215
	s_nop 0
	v_add_f32_e32 v214, v214, v215
	v_fmamk_f32 v214, v214, 0x3a800000, v248
	v_rsq_f32_e32 v182, v214
	s_nop 0
	v_pk_mul_f32 v[92:93], v[92:93], v[182:183] op_sel_hi:[1,0]
	v_pk_mul_f32 v[94:95], v[94:95], v[182:183] op_sel_hi:[1,0]
	v_pk_mul_f32 v[88:89], v[88:89], v[182:183] op_sel_hi:[1,0]
	v_pk_mul_f32 v[90:91], v[90:91], v[182:183] op_sel_hi:[1,0]
	v_cvt_pk_bf16_f32 v198, v92, v93
	v_cvt_pk_bf16_f32 v199, v94, v95
	v_cvt_pk_bf16_f32 v200, v88, v89
	v_cvt_pk_bf16_f32 v201, v90, v91
	global_store_dwordx4 v207, v[198:201], s[10:11]
	v_pk_mul_f32 v[84:85], v[84:85], v[182:183] op_sel_hi:[1,0]
	v_pk_mul_f32 v[86:87], v[86:87], v[182:183] op_sel_hi:[1,0]
	v_pk_mul_f32 v[80:81], v[80:81], v[182:183] op_sel_hi:[1,0]
	v_pk_mul_f32 v[82:83], v[82:83], v[182:183] op_sel_hi:[1,0]
	v_cvt_pk_bf16_f32 v202, v84, v85
	v_cvt_pk_bf16_f32 v203, v86, v87
	v_cvt_pk_bf16_f32 v204, v80, v81
	v_cvt_pk_bf16_f32 v205, v82, v83
	global_store_dwordx4 v207, v[202:205], s[10:11] offset:256
	v_add_u32_e32 v207, 0x8000, v207
	s_waitcnt vmcnt(10)
	v_pk_add_f32 v[158:159], v[158:159], v[160:161]
	s_nop 0
	v_add_f32_e32 v214, v158, v159
	v_mov_b32_e32 v215, v214
	s_nop 1
	v_permlane16_swap_b32_e32 v214, v215
	s_nop 0
	v_add_f32_e32 v214, v214, v215
	v_mov_b32_e32 v215, v214
	s_nop 1
	v_permlane32_swap_b32_e32 v214, v215
	s_nop 0
	v_add_f32_e32 v214, v214, v215
	v_fmamk_f32 v214, v214, 0x3a800000, v248
	v_rsq_f32_e32 v184, v214
	s_nop 0
	v_pk_mul_f32 v[76:77], v[76:77], v[184:185] op_sel_hi:[1,0]
	v_pk_mul_f32 v[78:79], v[78:79], v[184:185] op_sel_hi:[1,0]
	v_pk_mul_f32 v[72:73], v[72:73], v[184:185] op_sel_hi:[1,0]
	v_pk_mul_f32 v[74:75], v[74:75], v[184:185] op_sel_hi:[1,0]
	v_cvt_pk_bf16_f32 v198, v76, v77
	v_cvt_pk_bf16_f32 v199, v78, v79
	v_cvt_pk_bf16_f32 v200, v72, v73
	v_cvt_pk_bf16_f32 v201, v74, v75
	global_store_dwordx4 v207, v[198:201], s[10:11]
	v_pk_mul_f32 v[68:69], v[68:69], v[184:185] op_sel_hi:[1,0]
	v_pk_mul_f32 v[70:71], v[70:71], v[184:185] op_sel_hi:[1,0]
	v_pk_mul_f32 v[64:65], v[64:65], v[184:185] op_sel_hi:[1,0]
	v_pk_mul_f32 v[66:67], v[66:67], v[184:185] op_sel_hi:[1,0]
	v_cvt_pk_bf16_f32 v202, v68, v69
	v_cvt_pk_bf16_f32 v203, v70, v71
	v_cvt_pk_bf16_f32 v204, v64, v65
	v_cvt_pk_bf16_f32 v205, v66, v67
	global_store_dwordx4 v207, v[202:205], s[10:11] offset:256
	v_add_u32_e32 v207, 0x28000, v207
	s_waitcnt vmcnt(11)
	v_pk_add_f32 v[162:163], v[162:163], v[164:165]
	s_nop 0
	v_add_f32_e32 v214, v162, v163
	v_mov_b32_e32 v215, v214
	s_nop 1
	v_permlane16_swap_b32_e32 v214, v215
	s_nop 0
	v_add_f32_e32 v214, v214, v215
	v_mov_b32_e32 v215, v214
	s_nop 1
	v_permlane32_swap_b32_e32 v214, v215
	s_nop 0
	v_add_f32_e32 v214, v214, v215
	v_fmamk_f32 v214, v214, 0x3a800000, v248
	v_rsq_f32_e32 v186, v214
	s_nop 0
	v_pk_mul_f32 v[60:61], v[60:61], v[186:187] op_sel_hi:[1,0]
	v_pk_mul_f32 v[62:63], v[62:63], v[186:187] op_sel_hi:[1,0]
	v_pk_mul_f32 v[56:57], v[56:57], v[186:187] op_sel_hi:[1,0]
	v_pk_mul_f32 v[58:59], v[58:59], v[186:187] op_sel_hi:[1,0]
	v_cvt_pk_bf16_f32 v198, v60, v61
	v_cvt_pk_bf16_f32 v199, v62, v63
	v_cvt_pk_bf16_f32 v200, v56, v57
	v_cvt_pk_bf16_f32 v201, v58, v59
	global_store_dwordx4 v207, v[198:201], s[10:11]
	v_pk_mul_f32 v[52:53], v[52:53], v[186:187] op_sel_hi:[1,0]
	v_pk_mul_f32 v[54:55], v[54:55], v[186:187] op_sel_hi:[1,0]
	v_pk_mul_f32 v[48:49], v[48:49], v[186:187] op_sel_hi:[1,0]
	v_pk_mul_f32 v[50:51], v[50:51], v[186:187] op_sel_hi:[1,0]
	v_cvt_pk_bf16_f32 v202, v52, v53
	v_cvt_pk_bf16_f32 v203, v54, v55
	v_cvt_pk_bf16_f32 v204, v48, v49
	v_cvt_pk_bf16_f32 v205, v50, v51
	global_store_dwordx4 v207, v[202:205], s[10:11] offset:256
	v_add_u32_e32 v207, 0x8000, v207
	s_waitcnt vmcnt(12)
	v_pk_add_f32 v[166:167], v[166:167], v[168:169]
	s_nop 0
	v_add_f32_e32 v214, v166, v167
	v_mov_b32_e32 v215, v214
	s_nop 1
	v_permlane16_swap_b32_e32 v214, v215
	s_nop 0
	v_add_f32_e32 v214, v214, v215
	v_mov_b32_e32 v215, v214
	s_nop 1
	v_permlane32_swap_b32_e32 v214, v215
	s_nop 0
	v_add_f32_e32 v214, v214, v215
	v_fmamk_f32 v214, v214, 0x3a800000, v248
	v_rsq_f32_e32 v188, v214
	s_nop 0
	v_pk_mul_f32 v[44:45], v[44:45], v[188:189] op_sel_hi:[1,0]
	v_pk_mul_f32 v[46:47], v[46:47], v[188:189] op_sel_hi:[1,0]
	v_pk_mul_f32 v[40:41], v[40:41], v[188:189] op_sel_hi:[1,0]
	v_pk_mul_f32 v[42:43], v[42:43], v[188:189] op_sel_hi:[1,0]
	v_cvt_pk_bf16_f32 v198, v44, v45
	v_cvt_pk_bf16_f32 v199, v46, v47
	v_cvt_pk_bf16_f32 v200, v40, v41
	v_cvt_pk_bf16_f32 v201, v42, v43
	global_store_dwordx4 v207, v[198:201], s[10:11]
	v_pk_mul_f32 v[36:37], v[36:37], v[188:189] op_sel_hi:[1,0]
	v_pk_mul_f32 v[38:39], v[38:39], v[188:189] op_sel_hi:[1,0]
	v_pk_mul_f32 v[32:33], v[32:33], v[188:189] op_sel_hi:[1,0]
	v_pk_mul_f32 v[34:35], v[34:35], v[188:189] op_sel_hi:[1,0]
	v_cvt_pk_bf16_f32 v202, v36, v37
	v_cvt_pk_bf16_f32 v203, v38, v39
	v_cvt_pk_bf16_f32 v204, v32, v33
	v_cvt_pk_bf16_f32 v205, v34, v35
	global_store_dwordx4 v207, v[202:205], s[10:11] offset:256
	v_add_u32_e32 v207, 0x8000, v207
	s_waitcnt vmcnt(13)
	v_pk_add_f32 v[170:171], v[170:171], v[172:173]
	s_nop 0
	v_add_f32_e32 v214, v170, v171
	v_mov_b32_e32 v215, v214
	s_nop 1
	v_permlane16_swap_b32_e32 v214, v215
	s_nop 0
	v_add_f32_e32 v214, v214, v215
	v_mov_b32_e32 v215, v214
	s_nop 1
	v_permlane32_swap_b32_e32 v214, v215
	s_nop 0
	v_add_f32_e32 v214, v214, v215
	v_fmamk_f32 v214, v214, 0x3a800000, v248
	v_rsq_f32_e32 v190, v214
	s_nop 0
	v_pk_mul_f32 v[28:29], v[28:29], v[190:191] op_sel_hi:[1,0]
	v_pk_mul_f32 v[30:31], v[30:31], v[190:191] op_sel_hi:[1,0]
	v_pk_mul_f32 v[24:25], v[24:25], v[190:191] op_sel_hi:[1,0]
	v_pk_mul_f32 v[26:27], v[26:27], v[190:191] op_sel_hi:[1,0]
	v_cvt_pk_bf16_f32 v198, v28, v29
	v_cvt_pk_bf16_f32 v199, v30, v31
	v_cvt_pk_bf16_f32 v200, v24, v25
	v_cvt_pk_bf16_f32 v201, v26, v27
	global_store_dwordx4 v207, v[198:201], s[10:11]
	v_pk_mul_f32 v[20:21], v[20:21], v[190:191] op_sel_hi:[1,0]
	v_pk_mul_f32 v[22:23], v[22:23], v[190:191] op_sel_hi:[1,0]
	v_pk_mul_f32 v[16:17], v[16:17], v[190:191] op_sel_hi:[1,0]
	v_pk_mul_f32 v[18:19], v[18:19], v[190:191] op_sel_hi:[1,0]
	v_cvt_pk_bf16_f32 v202, v20, v21
	v_cvt_pk_bf16_f32 v203, v22, v23
	v_cvt_pk_bf16_f32 v204, v16, v17
	v_cvt_pk_bf16_f32 v205, v18, v19
	global_store_dwordx4 v207, v[202:205], s[10:11] offset:256
	v_add_u32_e32 v207, 0x8000, v207
	s_waitcnt vmcnt(14)
	v_pk_add_f32 v[174:175], v[174:175], v[176:177]
	s_nop 0
	v_add_f32_e32 v214, v174, v175
	v_mov_b32_e32 v215, v214
	s_nop 1
	v_permlane16_swap_b32_e32 v214, v215
	s_nop 0
	v_add_f32_e32 v214, v214, v215
	v_mov_b32_e32 v215, v214
	s_nop 1
	v_permlane32_swap_b32_e32 v214, v215
	s_nop 0
	v_add_f32_e32 v214, v214, v215
	v_fmamk_f32 v214, v214, 0x3a800000, v248
	v_rsq_f32_e32 v192, v214
	s_nop 0
	v_pk_mul_f32 v[12:13], v[12:13], v[192:193] op_sel_hi:[1,0]
	v_pk_mul_f32 v[14:15], v[14:15], v[192:193] op_sel_hi:[1,0]
	v_pk_mul_f32 v[8:9], v[8:9], v[192:193] op_sel_hi:[1,0]
	v_pk_mul_f32 v[10:11], v[10:11], v[192:193] op_sel_hi:[1,0]
	v_cvt_pk_bf16_f32 v198, v12, v13
	v_cvt_pk_bf16_f32 v199, v14, v15
	v_cvt_pk_bf16_f32 v200, v8, v9
	v_cvt_pk_bf16_f32 v201, v10, v11
	global_store_dwordx4 v207, v[198:201], s[10:11]
	v_pk_mul_f32 v[4:5], v[4:5], v[192:193] op_sel_hi:[1,0]
	v_pk_mul_f32 v[6:7], v[6:7], v[192:193] op_sel_hi:[1,0]
	v_pk_mul_f32 v[0:1], v[0:1], v[192:193] op_sel_hi:[1,0]
	v_pk_mul_f32 v[2:3], v[2:3], v[192:193] op_sel_hi:[1,0]
	v_cvt_pk_bf16_f32 v202, v4, v5
	v_cvt_pk_bf16_f32 v203, v6, v7
	v_cvt_pk_bf16_f32 v204, v0, v1
	v_cvt_pk_bf16_f32 v205, v2, v3
	global_store_dwordx4 v207, v[202:205], s[10:11] offset:256
	s_and_b64 vcc, exec, s[4:5]
	s_cbranch_vccz .LBB0_816
	s_waitcnt vmcnt(0)
	s_cmpk_gt_u32 s30, 0xff
	s_cbranch_scc1 .LBB0_827
	s_barrier

.LBB0_878:
	s_add_u32 s26, s24, 0xfffc0080
	s_addc_u32 s27, s25, -1
	s_add_i32 s65, 0, 0x10000
	v_add_u32_e32 v154, s65, v143
	ds_read_b128 v[138:141], v154
	ds_read_b128 v[146:149], v154 offset:1024
	ds_read_b128 v[150:153], v154 offset:2048
	ds_read_b128 v[154:157], v154 offset:3072
	s_cmp_eq_u32 s64, 12
	s_cselect_b32 s29, s19, s27
	s_cselect_b32 s28, s39, s26
	s_cselect_b32 s27, s17, s63
	s_cselect_b32 s26, s61, s62
	v_lshl_add_u64 v[190:191], s[24:25], 0, v[134:135]
	s_add_i32 m0, s50, 0xc000
	ds_read_b128 v[158:161], v145
	ds_read_b128 v[162:165], v145 offset:1024
	ds_read_b128 v[166:169], v145 offset:2048
	ds_read_b128 v[170:173], v145 offset:3072
	ds_read_b128 v[174:177], v145 offset:4096
	ds_read_b128 v[178:181], v145 offset:5120
	ds_read_b128 v[182:185], v145 offset:6144
	ds_read_b128 v[186:189], v145 offset:7168
	global_load_lds_dwordx4 v[190:191], off
	v_lshl_add_u64 v[190:191], s[24:25], 0, v[136:137]
	s_add_i32 m0, s50, 0xe000
	s_nop 0
	global_load_lds_dwordx4 v[190:191], off
	s_waitcnt lgkmcnt(8)
	s_barrier
	s_waitcnt lgkmcnt(0)
	s_setprio 1
	v_mfma_f32_16x16x32_bf16 v[124:127], v[138:141], v[158:161], v[124:127]
	v_mfma_f32_16x16x32_bf16 v[120:123], v[150:153], v[158:161], v[120:123]
	v_mfma_f32_16x16x32_bf16 v[108:111], v[138:141], v[166:169], v[108:111]
	v_mfma_f32_16x16x32_bf16 v[104:107], v[150:153], v[166:169], v[104:107]
	v_mfma_f32_16x16x32_bf16 v[92:95], v[138:141], v[174:177], v[92:95]
	v_mfma_f32_16x16x32_bf16 v[88:91], v[150:153], v[174:177], v[88:91]
	v_mfma_f32_16x16x32_bf16 v[76:79], v[138:141], v[182:185], v[76:79]
	v_mfma_f32_16x16x32_bf16 v[72:75], v[150:153], v[182:185], v[72:75]
	v_mfma_f32_16x16x32_bf16 v[124:127], v[146:149], v[162:165], v[124:127]
	v_mfma_f32_16x16x32_bf16 v[120:123], v[154:157], v[162:165], v[120:123]
	v_mfma_f32_16x16x32_bf16 v[108:111], v[146:149], v[170:173], v[108:111]
	v_mfma_f32_16x16x32_bf16 v[104:107], v[154:157], v[170:173], v[104:107]
	v_mfma_f32_16x16x32_bf16 v[92:95], v[146:149], v[178:181], v[92:95]
	v_mfma_f32_16x16x32_bf16 v[88:91], v[154:157], v[178:181], v[88:91]
	v_mfma_f32_16x16x32_bf16 v[76:79], v[146:149], v[186:189], v[76:79]
	v_mfma_f32_16x16x32_bf16 v[72:75], v[154:157], v[186:189], v[72:75]
	s_setprio 0
	s_barrier
	s_add_i32 s68, 0, 0x14000
	s_add_i32 s65, s65, s47
	v_add_u32_e32 v202, s68, v143
	v_lshl_add_u64 v[206:207], s[26:27], 0, v[208:209]
	s_mov_b32 m0, s65
	ds_read_b128 v[190:193], v202
	ds_read_b128 v[194:197], v202 offset:1024
	ds_read_b128 v[198:201], v202 offset:2048
	ds_read_b128 v[202:205], v202 offset:3072
	global_load_lds_dwordx4 v[206:207], off
	v_lshl_add_u64 v[210:211], s[26:27], 0, v[128:129]
	s_add_i32 m0, s65, 0x2000
	s_nop 0
	global_load_lds_dwordx4 v[210:211], off
	s_barrier
	s_waitcnt lgkmcnt(0)
	s_setprio 1
	v_mfma_f32_16x16x32_bf16 v[116:119], v[190:193], v[158:161], v[116:119]
	v_mfma_f32_16x16x32_bf16 v[112:115], v[198:201], v[158:161], v[112:115]
	v_mfma_f32_16x16x32_bf16 v[100:103], v[190:193], v[166:169], v[100:103]
	v_mfma_f32_16x16x32_bf16 v[96:99], v[198:201], v[166:169], v[96:99]
	v_mfma_f32_16x16x32_bf16 v[84:87], v[190:193], v[174:177], v[84:87]
	v_mfma_f32_16x16x32_bf16 v[80:83], v[198:201], v[174:177], v[80:83]
	v_mfma_f32_16x16x32_bf16 v[68:71], v[190:193], v[182:185], v[68:71]
	v_mfma_f32_16x16x32_bf16 v[64:67], v[198:201], v[182:185], v[64:67]
	v_mfma_f32_16x16x32_bf16 v[116:119], v[194:197], v[162:165], v[116:119]
	v_mfma_f32_16x16x32_bf16 v[112:115], v[202:205], v[162:165], v[112:115]
	v_mfma_f32_16x16x32_bf16 v[100:103], v[194:197], v[170:173], v[100:103]
	v_mfma_f32_16x16x32_bf16 v[96:99], v[202:205], v[170:173], v[96:99]
	v_mfma_f32_16x16x32_bf16 v[84:87], v[194:197], v[178:181], v[84:87]
	v_mfma_f32_16x16x32_bf16 v[80:83], v[202:205], v[178:181], v[80:83]
	v_mfma_f32_16x16x32_bf16 v[68:71], v[194:197], v[186:189], v[68:71]
	v_mfma_f32_16x16x32_bf16 v[64:67], v[202:205], v[186:189], v[64:67]
	s_setprio 0
	s_mov_b32 m0, s50
	v_lshl_add_u64 v[214:215], s[28:29], 0, v[132:133]
	s_barrier
	ds_read_b128 v[158:161], v145 offset:16384
	ds_read_b128 v[162:165], v145 offset:17408
	ds_read_b128 v[166:169], v145 offset:18432
	ds_read_b128 v[170:173], v145 offset:19456
	ds_read_b128 v[174:177], v145 offset:20480
	ds_read_b128 v[178:181], v145 offset:21504
	ds_read_b128 v[182:185], v145 offset:22528
	ds_read_b128 v[186:189], v145 offset:23552
	global_load_lds_dwordx4 v[214:215], off
	v_lshl_add_u64 v[216:217], s[28:29], 0, v[130:131]
	s_mov_b32 m0, s51
	s_nop 0
	global_load_lds_dwordx4 v[216:217], off
	s_barrier
	s_waitcnt lgkmcnt(0)
	s_setprio 1
	v_mfma_f32_16x16x32_bf16 v[60:63], v[138:141], v[158:161], v[60:63]
	v_mfma_f32_16x16x32_bf16 v[56:59], v[150:153], v[158:161], v[56:59]
	v_mfma_f32_16x16x32_bf16 v[44:47], v[138:141], v[166:169], v[44:47]
	v_mfma_f32_16x16x32_bf16 v[40:43], v[150:153], v[166:169], v[40:43]
	v_mfma_f32_16x16x32_bf16 v[28:31], v[138:141], v[174:177], v[28:31]
	v_mfma_f32_16x16x32_bf16 v[24:27], v[150:153], v[174:177], v[24:27]
	v_mfma_f32_16x16x32_bf16 v[12:15], v[138:141], v[182:185], v[12:15]
	v_mfma_f32_16x16x32_bf16 v[8:11], v[150:153], v[182:185], v[8:11]
	v_mfma_f32_16x16x32_bf16 v[60:63], v[146:149], v[162:165], v[60:63]
	v_mfma_f32_16x16x32_bf16 v[56:59], v[154:157], v[162:165], v[56:59]
	v_mfma_f32_16x16x32_bf16 v[44:47], v[146:149], v[170:173], v[44:47]
	v_mfma_f32_16x16x32_bf16 v[40:43], v[154:157], v[170:173], v[40:43]
	v_mfma_f32_16x16x32_bf16 v[28:31], v[146:149], v[178:181], v[28:31]
	v_mfma_f32_16x16x32_bf16 v[24:27], v[154:157], v[178:181], v[24:27]
	v_mfma_f32_16x16x32_bf16 v[12:15], v[146:149], v[186:189], v[12:15]
	v_mfma_f32_16x16x32_bf16 v[8:11], v[154:157], v[186:189], v[8:11]
	s_setprio 0
	s_barrier
	s_add_u32 s66, s26, 0x40000
	s_addc_u32 s67, s27, 0
	s_add_i32 s65, s68, s47
	v_lshl_add_u64 v[138:139], s[66:67], 0, v[208:209]
	s_mov_b32 m0, s65
	s_nop 0
	global_load_lds_dwordx4 v[138:139], off
	v_lshl_add_u64 v[138:139], s[66:67], 0, v[128:129]
	s_add_i32 m0, s65, 0x2000
	s_nop 0
	global_load_lds_dwordx4 v[138:139], off
	s_waitcnt vmcnt(6)
	s_barrier
	s_setprio 1
	v_mfma_f32_16x16x32_bf16 v[52:55], v[190:193], v[158:161], v[52:55]
	v_mfma_f32_16x16x32_bf16 v[48:51], v[198:201], v[158:161], v[48:51]
	v_mfma_f32_16x16x32_bf16 v[36:39], v[190:193], v[166:169], v[36:39]
	v_mfma_f32_16x16x32_bf16 v[32:35], v[198:201], v[166:169], v[32:35]
	v_mfma_f32_16x16x32_bf16 v[20:23], v[190:193], v[174:177], v[20:23]
	v_mfma_f32_16x16x32_bf16 v[16:19], v[198:201], v[174:177], v[16:19]
	v_mfma_f32_16x16x32_bf16 v[4:7], v[190:193], v[182:185], v[4:7]
	v_mfma_f32_16x16x32_bf16 v[0:3], v[198:201], v[182:185], v[0:3]
	v_mfma_f32_16x16x32_bf16 v[52:55], v[194:197], v[162:165], v[52:55]
	v_mfma_f32_16x16x32_bf16 v[48:51], v[202:205], v[162:165], v[48:51]
	v_mfma_f32_16x16x32_bf16 v[36:39], v[194:197], v[170:173], v[36:39]
	v_mfma_f32_16x16x32_bf16 v[32:35], v[202:205], v[170:173], v[32:35]
	v_mfma_f32_16x16x32_bf16 v[20:23], v[194:197], v[178:181], v[20:23]
	v_mfma_f32_16x16x32_bf16 v[16:19], v[202:205], v[178:181], v[16:19]
	v_mfma_f32_16x16x32_bf16 v[4:7], v[194:197], v[186:189], v[4:7]
	v_mfma_f32_16x16x32_bf16 v[0:3], v[202:205], v[186:189], v[0:3]
	s_setprio 0
	s_add_i32 s65, 0, 0x18000
	v_add_u32_e32 v154, s65, v143
	s_barrier
	ds_read_b128 v[138:141], v154
	ds_read_b128 v[146:149], v154 offset:1024
	ds_read_b128 v[150:153], v154 offset:2048
	ds_read_b128 v[154:157], v154 offset:3072
	s_add_u32 s28, s28, 0x40000
	s_addc_u32 s29, s29, 0
	s_mov_b32 m0, s53
	v_lshl_add_u64 v[190:191], s[28:29], 0, v[132:133]
	ds_read_b128 v[158:161], v145 offset:32768
	ds_read_b128 v[162:165], v145 offset:33792
	ds_read_b128 v[166:169], v145 offset:34816
	ds_read_b128 v[170:173], v145 offset:35840
	ds_read_b128 v[174:177], v145 offset:36864
	ds_read_b128 v[178:181], v145 offset:37888
	ds_read_b128 v[182:185], v145 offset:38912
	ds_read_b128 v[186:189], v145 offset:39936
	global_load_lds_dwordx4 v[190:191], off
	v_lshl_add_u64 v[190:191], s[28:29], 0, v[130:131]
	s_mov_b32 m0, s56
	s_nop 0
	global_load_lds_dwordx4 v[190:191], off
	s_waitcnt lgkmcnt(8)
	s_barrier
	s_waitcnt lgkmcnt(0)
	s_setprio 1
	v_mfma_f32_16x16x32_bf16 v[124:127], v[138:141], v[158:161], v[124:127]
	v_mfma_f32_16x16x32_bf16 v[120:123], v[150:153], v[158:161], v[120:123]
	v_mfma_f32_16x16x32_bf16 v[108:111], v[138:141], v[166:169], v[108:111]
	v_mfma_f32_16x16x32_bf16 v[104:107], v[150:153], v[166:169], v[104:107]
	v_mfma_f32_16x16x32_bf16 v[92:95], v[138:141], v[174:177], v[92:95]
	v_mfma_f32_16x16x32_bf16 v[88:91], v[150:153], v[174:177], v[88:91]
	v_mfma_f32_16x16x32_bf16 v[76:79], v[138:141], v[182:185], v[76:79]
	v_mfma_f32_16x16x32_bf16 v[72:75], v[150:153], v[182:185], v[72:75]
	v_mfma_f32_16x16x32_bf16 v[124:127], v[146:149], v[162:165], v[124:127]
	v_mfma_f32_16x16x32_bf16 v[120:123], v[154:157], v[162:165], v[120:123]
	v_mfma_f32_16x16x32_bf16 v[108:111], v[146:149], v[170:173], v[108:111]
	v_mfma_f32_16x16x32_bf16 v[104:107], v[154:157], v[170:173], v[104:107]
	v_mfma_f32_16x16x32_bf16 v[92:95], v[146:149], v[178:181], v[92:95]
	v_mfma_f32_16x16x32_bf16 v[88:91], v[154:157], v[178:181], v[88:91]
	v_mfma_f32_16x16x32_bf16 v[76:79], v[146:149], v[186:189], v[76:79]
	v_mfma_f32_16x16x32_bf16 v[72:75], v[154:157], v[186:189], v[72:75]
	s_setprio 0
	s_barrier
	s_add_i32 s28, 0, 0x1c000
	s_add_i32 s29, s65, s47
	v_add_u32_e32 v202, s28, v143
	v_lshl_add_u64 v[206:207], v[206:207], 0, s[40:41]
	s_mov_b32 m0, s29
	ds_read_b128 v[190:193], v202
	ds_read_b128 v[194:197], v202 offset:1024
	ds_read_b128 v[198:201], v202 offset:2048
	ds_read_b128 v[202:205], v202 offset:3072
	global_load_lds_dwordx4 v[206:207], off
	v_lshl_add_u64 v[206:207], v[210:211], 0, s[40:41]
	s_add_i32 m0, s29, 0x2000
	s_nop 0
	global_load_lds_dwordx4 v[206:207], off
	s_barrier
	s_waitcnt lgkmcnt(0)
	s_setprio 1
	v_mfma_f32_16x16x32_bf16 v[116:119], v[190:193], v[158:161], v[116:119]
	v_mfma_f32_16x16x32_bf16 v[112:115], v[198:201], v[158:161], v[112:115]
	v_mfma_f32_16x16x32_bf16 v[100:103], v[190:193], v[166:169], v[100:103]
	v_mfma_f32_16x16x32_bf16 v[96:99], v[198:201], v[166:169], v[96:99]
	v_mfma_f32_16x16x32_bf16 v[84:87], v[190:193], v[174:177], v[84:87]
	v_mfma_f32_16x16x32_bf16 v[80:83], v[198:201], v[174:177], v[80:83]
	v_mfma_f32_16x16x32_bf16 v[68:71], v[190:193], v[182:185], v[68:71]
	v_mfma_f32_16x16x32_bf16 v[64:67], v[198:201], v[182:185], v[64:67]
	v_mfma_f32_16x16x32_bf16 v[116:119], v[194:197], v[162:165], v[116:119]
	v_mfma_f32_16x16x32_bf16 v[112:115], v[202:205], v[162:165], v[112:115]
	v_mfma_f32_16x16x32_bf16 v[100:103], v[194:197], v[170:173], v[100:103]
	v_mfma_f32_16x16x32_bf16 v[96:99], v[202:205], v[170:173], v[96:99]
	v_mfma_f32_16x16x32_bf16 v[84:87], v[194:197], v[178:181], v[84:87]
	v_mfma_f32_16x16x32_bf16 v[80:83], v[202:205], v[178:181], v[80:83]
	v_mfma_f32_16x16x32_bf16 v[68:71], v[194:197], v[186:189], v[68:71]
	v_mfma_f32_16x16x32_bf16 v[64:67], v[202:205], v[186:189], v[64:67]
	s_setprio 0
	s_mov_b32 m0, s58
	v_lshl_add_u64 v[206:207], v[214:215], 0, s[40:41]
	s_barrier
	ds_read_b128 v[158:161], v145 offset:49152
	ds_read_b128 v[162:165], v145 offset:50176
	ds_read_b128 v[166:169], v145 offset:51200
	ds_read_b128 v[170:173], v145 offset:52224
	ds_read_b128 v[174:177], v145 offset:53248
	ds_read_b128 v[178:181], v145 offset:54272
	ds_read_b128 v[182:185], v145 offset:55296
	ds_read_b128 v[186:189], v145 offset:56320
	global_load_lds_dwordx4 v[206:207], off
	v_lshl_add_u64 v[206:207], v[216:217], 0, s[40:41]
	s_mov_b32 m0, s59
	s_nop 0
	global_load_lds_dwordx4 v[206:207], off
	s_barrier
	s_waitcnt lgkmcnt(0)
	s_setprio 1
	v_mfma_f32_16x16x32_bf16 v[60:63], v[138:141], v[158:161], v[60:63]
	v_mfma_f32_16x16x32_bf16 v[56:59], v[150:153], v[158:161], v[56:59]
	v_mfma_f32_16x16x32_bf16 v[44:47], v[138:141], v[166:169], v[44:47]
	v_mfma_f32_16x16x32_bf16 v[40:43], v[150:153], v[166:169], v[40:43]
	v_mfma_f32_16x16x32_bf16 v[28:31], v[138:141], v[174:177], v[28:31]
	v_mfma_f32_16x16x32_bf16 v[24:27], v[150:153], v[174:177], v[24:27]
	v_mfma_f32_16x16x32_bf16 v[12:15], v[138:141], v[182:185], v[12:15]
	v_mfma_f32_16x16x32_bf16 v[8:11], v[150:153], v[182:185], v[8:11]
	v_mfma_f32_16x16x32_bf16 v[60:63], v[146:149], v[162:165], v[60:63]
	v_mfma_f32_16x16x32_bf16 v[56:59], v[154:157], v[162:165], v[56:59]
	v_mfma_f32_16x16x32_bf16 v[44:47], v[146:149], v[170:173], v[44:47]
	v_mfma_f32_16x16x32_bf16 v[40:43], v[154:157], v[170:173], v[40:43]
	v_mfma_f32_16x16x32_bf16 v[28:31], v[146:149], v[178:181], v[28:31]
	v_mfma_f32_16x16x32_bf16 v[24:27], v[154:157], v[178:181], v[24:27]
	v_mfma_f32_16x16x32_bf16 v[12:15], v[146:149], v[186:189], v[12:15]
	v_mfma_f32_16x16x32_bf16 v[8:11], v[154:157], v[186:189], v[8:11]
	s_setprio 0
	s_barrier
	s_add_u32 s26, s26, 0x40080
	s_addc_u32 s27, s27, 0
	s_add_i32 s28, s28, s47
	v_lshl_add_u64 v[138:139], s[26:27], 0, v[208:209]
	s_mov_b32 m0, s28
	s_nop 0
	global_load_lds_dwordx4 v[138:139], off
	v_lshl_add_u64 v[138:139], s[26:27], 0, v[128:129]
	s_add_i32 m0, s28, 0x2000
	s_nop 0
	global_load_lds_dwordx4 v[138:139], off
	s_waitcnt vmcnt(6)
	s_barrier
	s_setprio 1
	v_mfma_f32_16x16x32_bf16 v[52:55], v[190:193], v[158:161], v[52:55]
	v_mfma_f32_16x16x32_bf16 v[48:51], v[198:201], v[158:161], v[48:51]
	v_mfma_f32_16x16x32_bf16 v[36:39], v[190:193], v[166:169], v[36:39]
	v_mfma_f32_16x16x32_bf16 v[32:35], v[198:201], v[166:169], v[32:35]
	v_mfma_f32_16x16x32_bf16 v[20:23], v[190:193], v[174:177], v[20:23]
	v_mfma_f32_16x16x32_bf16 v[16:19], v[198:201], v[174:177], v[16:19]
	v_mfma_f32_16x16x32_bf16 v[4:7], v[190:193], v[182:185], v[4:7]
	v_mfma_f32_16x16x32_bf16 v[0:3], v[198:201], v[182:185], v[0:3]
	v_mfma_f32_16x16x32_bf16 v[52:55], v[194:197], v[162:165], v[52:55]
	v_mfma_f32_16x16x32_bf16 v[48:51], v[202:205], v[162:165], v[48:51]
	v_mfma_f32_16x16x32_bf16 v[36:39], v[194:197], v[170:173], v[36:39]
	v_mfma_f32_16x16x32_bf16 v[32:35], v[202:205], v[170:173], v[32:35]
	v_mfma_f32_16x16x32_bf16 v[20:23], v[194:197], v[178:181], v[20:23]
	v_mfma_f32_16x16x32_bf16 v[16:19], v[202:205], v[178:181], v[16:19]
	v_mfma_f32_16x16x32_bf16 v[4:7], v[194:197], v[186:189], v[4:7]
	v_mfma_f32_16x16x32_bf16 v[0:3], v[202:205], v[186:189], v[0:3]
	s_setprio 0
	s_add_i32 s64, s64, 2
	s_add_u32 s24, s24, 0x100
	s_addc_u32 s25, s25, 0
	s_add_u32 s62, s62, 0x100
	s_addc_u32 s63, s63, 0
	s_cmp_gt_u32 s64, 13
	s_barrier
	s_cbranch_scc0 .LBB0_878
	v_lshl_add_u32 v140, s38, 8, v142
	v_lshl_or_b32 v141, s36, 8, v144
	s_lshl_b32 s24, s36, 2
	s_ashr_i32 s25, s24, 31
	s_lshl_b32 s36, s57, 2
	v_lshlrev_b32_e32 v206, 11, v140
	v_lshl_add_u32 v206, v141, 1, v206
	v_lshl_add_u32 v210, v140, 6, s36
	v_lshl_add_u32 v210, s24, 2, v210
	v_mov_b32_e32 v207, v206
	global_load_dwordx4 v[146:149], v206, s[8:9]
	global_load_dwordx4 v[150:153], v206, s[8:9] offset:256
	v_add_u32_e32 v206, 0x8000, v206
	global_load_dwordx4 v[154:157], v206, s[8:9]
	global_load_dwordx4 v[158:161], v206, s[8:9] offset:256
	v_add_u32_e32 v206, 0x8000, v206
	global_load_dwordx4 v[162:165], v206, s[8:9]
	global_load_dwordx4 v[166:169], v206, s[8:9] offset:256
	v_add_u32_e32 v206, 0x8000, v206
	global_load_dwordx4 v[170:173], v206, s[8:9]
	global_load_dwordx4 v[174:177], v206, s[8:9] offset:256
	v_add_u32_e32 v206, 0x28000, v206
	global_load_dwordx4 v[178:181], v206, s[8:9]
	global_load_dwordx4 v[182:185], v206, s[8:9] offset:256
	v_add_u32_e32 v206, 0x8000, v206
	global_load_dwordx4 v[186:189], v206, s[8:9]
	global_load_dwordx4 v[190:193], v206, s[8:9] offset:256
	v_add_u32_e32 v206, 0x8000, v206
	global_load_dwordx4 v[194:197], v206, s[8:9]
	global_load_dwordx4 v[198:201], v206, s[8:9] offset:256
	v_add_u32_e32 v206, 0x8000, v206
	s_waitcnt vmcnt(12)
	v_lshlrev_b32_e32 v202, 16, v146
	v_and_b32_e32 v203, 0xffff0000, v146
	v_lshlrev_b32_e32 v204, 16, v147
	v_and_b32_e32 v205, 0xffff0000, v147
	v_pk_add_f32 v[124:125], v[124:125], v[202:203]
	v_pk_add_f32 v[126:127], v[126:127], v[204:205]
	v_lshlrev_b32_e32 v202, 16, v148
	v_and_b32_e32 v203, 0xffff0000, v148
	v_lshlrev_b32_e32 v204, 16, v149
	v_and_b32_e32 v205, 0xffff0000, v149
	v_pk_add_f32 v[120:121], v[120:121], v[202:203]
	v_pk_add_f32 v[122:123], v[122:123], v[204:205]
	v_cvt_pk_bf16_f32 v146, v124, v125
	v_cvt_pk_bf16_f32 v147, v126, v127
	v_cvt_pk_bf16_f32 v148, v120, v121
	v_cvt_pk_bf16_f32 v149, v122, v123
	v_pk_mul_f32 v[138:139], v[124:125], v[124:125]
	global_store_dwordx4 v207, v[146:149], s[8:9]
	v_pk_fma_f32 v[138:139], v[126:127], v[126:127], v[138:139]
	v_pk_fma_f32 v[138:139], v[120:121], v[120:121], v[138:139]
	v_pk_fma_f32 v[138:139], v[122:123], v[122:123], v[138:139]
	v_lshlrev_b32_e32 v202, 16, v150
	v_and_b32_e32 v203, 0xffff0000, v150
	v_lshlrev_b32_e32 v204, 16, v151
	v_and_b32_e32 v205, 0xffff0000, v151
	v_pk_add_f32 v[116:117], v[116:117], v[202:203]
	v_pk_add_f32 v[118:119], v[118:119], v[204:205]
	v_lshlrev_b32_e32 v202, 16, v152
	v_and_b32_e32 v203, 0xffff0000, v152
	v_lshlrev_b32_e32 v204, 16, v153
	v_and_b32_e32 v205, 0xffff0000, v153
	v_pk_add_f32 v[112:113], v[112:113], v[202:203]
	v_pk_add_f32 v[114:115], v[114:115], v[204:205]
	v_cvt_pk_bf16_f32 v150, v116, v117
	v_cvt_pk_bf16_f32 v151, v118, v119
	v_cvt_pk_bf16_f32 v152, v112, v113
	v_cvt_pk_bf16_f32 v153, v114, v115
	v_pk_fma_f32 v[138:139], v[116:117], v[116:117], v[138:139]
	global_store_dwordx4 v207, v[150:153], s[8:9] offset:256
	v_pk_fma_f32 v[138:139], v[118:119], v[118:119], v[138:139]
	v_pk_fma_f32 v[138:139], v[112:113], v[112:113], v[138:139]
	v_pk_fma_f32 v[138:139], v[114:115], v[114:115], v[138:139]
	v_add_f32_e32 v214, v138, v139
	v_add_u32_e32 v207, 0x8000, v207
	v_mov_b32_e32 v215, v214
	s_nop 1
	v_permlane16_swap_b32_e32 v214, v215
	s_nop 0
	v_add_f32_e32 v214, v214, v215
	v_mov_b32_e32 v215, v214
	s_nop 1
	v_permlane32_swap_b32_e32 v214, v215
	s_nop 0
	v_add_f32_e32 v214, v214, v215
	s_and_saveexec_b64 s[26:27], s[4:5]
	global_store_dword v210, v214, s[14:15]
	s_mov_b64 exec, s[26:27]
	global_load_dwordx4 v[146:149], v206, s[8:9]
	global_load_dwordx4 v[150:153], v206, s[8:9] offset:256
	s_waitcnt vmcnt(15)
	v_lshlrev_b32_e32 v202, 16, v154
	v_and_b32_e32 v203, 0xffff0000, v154
	v_lshlrev_b32_e32 v204, 16, v155
	v_and_b32_e32 v205, 0xffff0000, v155
	v_pk_add_f32 v[108:109], v[108:109], v[202:203]
	v_pk_add_f32 v[110:111], v[110:111], v[204:205]
	v_lshlrev_b32_e32 v202, 16, v156
	v_and_b32_e32 v203, 0xffff0000, v156
	v_lshlrev_b32_e32 v204, 16, v157
	v_and_b32_e32 v205, 0xffff0000, v157
	v_pk_add_f32 v[104:105], v[104:105], v[202:203]
	v_pk_add_f32 v[106:107], v[106:107], v[204:205]
	v_cvt_pk_bf16_f32 v154, v108, v109
	v_cvt_pk_bf16_f32 v155, v110, v111
	v_cvt_pk_bf16_f32 v156, v104, v105
	v_cvt_pk_bf16_f32 v157, v106, v107
	v_pk_mul_f32 v[138:139], v[108:109], v[108:109]
	global_store_dwordx4 v207, v[154:157], s[8:9]
	v_pk_fma_f32 v[138:139], v[110:111], v[110:111], v[138:139]
	v_pk_fma_f32 v[138:139], v[104:105], v[104:105], v[138:139]
	v_pk_fma_f32 v[138:139], v[106:107], v[106:107], v[138:139]
	v_lshlrev_b32_e32 v202, 16, v158
	v_and_b32_e32 v203, 0xffff0000, v158
	v_lshlrev_b32_e32 v204, 16, v159
	v_and_b32_e32 v205, 0xffff0000, v159
	v_pk_add_f32 v[100:101], v[100:101], v[202:203]
	v_pk_add_f32 v[102:103], v[102:103], v[204:205]
	v_lshlrev_b32_e32 v202, 16, v160
	v_and_b32_e32 v203, 0xffff0000, v160
	v_lshlrev_b32_e32 v204, 16, v161
	v_and_b32_e32 v205, 0xffff0000, v161
	v_pk_add_f32 v[96:97], v[96:97], v[202:203]
	v_pk_add_f32 v[98:99], v[98:99], v[204:205]
	v_cvt_pk_bf16_f32 v158, v100, v101
	v_cvt_pk_bf16_f32 v159, v102, v103
	v_cvt_pk_bf16_f32 v160, v96, v97
	v_cvt_pk_bf16_f32 v161, v98, v99
	v_pk_fma_f32 v[138:139], v[100:101], v[100:101], v[138:139]
	global_store_dwordx4 v207, v[158:161], s[8:9] offset:256
	v_pk_fma_f32 v[138:139], v[102:103], v[102:103], v[138:139]
	v_pk_fma_f32 v[138:139], v[96:97], v[96:97], v[138:139]
	v_pk_fma_f32 v[138:139], v[98:99], v[98:99], v[138:139]
	v_add_f32_e32 v214, v138, v139
	v_add_u32_e32 v207, 0x8000, v207
	v_mov_b32_e32 v215, v214
	s_nop 1
	v_permlane16_swap_b32_e32 v214, v215
	s_nop 0
	v_add_f32_e32 v214, v214, v215
	v_mov_b32_e32 v215, v214
	s_nop 1
	v_permlane32_swap_b32_e32 v214, v215
	s_nop 0
	v_add_f32_e32 v214, v214, v215
	s_and_saveexec_b64 s[26:27], s[4:5]
	global_store_dword v210, v214, s[14:15] offset:1024
	s_mov_b64 exec, s[26:27]
	s_waitcnt vmcnt(16)
	v_lshlrev_b32_e32 v202, 16, v162
	v_and_b32_e32 v203, 0xffff0000, v162
	v_lshlrev_b32_e32 v204, 16, v163
	v_and_b32_e32 v205, 0xffff0000, v163
	v_pk_add_f32 v[92:93], v[92:93], v[202:203]
	v_pk_add_f32 v[94:95], v[94:95], v[204:205]
	v_lshlrev_b32_e32 v202, 16, v164
	v_and_b32_e32 v203, 0xffff0000, v164
	v_lshlrev_b32_e32 v204, 16, v165
	v_and_b32_e32 v205, 0xffff0000, v165
	v_pk_add_f32 v[88:89], v[88:89], v[202:203]
	v_pk_add_f32 v[90:91], v[90:91], v[204:205]
	v_cvt_pk_bf16_f32 v162, v92, v93
	v_cvt_pk_bf16_f32 v163, v94, v95
	v_cvt_pk_bf16_f32 v164, v88, v89
	v_cvt_pk_bf16_f32 v165, v90, v91
	v_pk_mul_f32 v[138:139], v[92:93], v[92:93]
	global_store_dwordx4 v207, v[162:165], s[8:9]
	v_pk_fma_f32 v[138:139], v[94:95], v[94:95], v[138:139]
	v_pk_fma_f32 v[138:139], v[88:89], v[88:89], v[138:139]
	v_pk_fma_f32 v[138:139], v[90:91], v[90:91], v[138:139]
	v_lshlrev_b32_e32 v202, 16, v166
	v_and_b32_e32 v203, 0xffff0000, v166
	v_lshlrev_b32_e32 v204, 16, v167
	v_and_b32_e32 v205, 0xffff0000, v167
	v_pk_add_f32 v[84:85], v[84:85], v[202:203]
	v_pk_add_f32 v[86:87], v[86:87], v[204:205]
	v_lshlrev_b32_e32 v202, 16, v168
	v_and_b32_e32 v203, 0xffff0000, v168
	v_lshlrev_b32_e32 v204, 16, v169
	v_and_b32_e32 v205, 0xffff0000, v169
	v_pk_add_f32 v[80:81], v[80:81], v[202:203]
	v_pk_add_f32 v[82:83], v[82:83], v[204:205]
	v_cvt_pk_bf16_f32 v166, v84, v85
	v_cvt_pk_bf16_f32 v167, v86, v87
	v_cvt_pk_bf16_f32 v168, v80, v81
	v_cvt_pk_bf16_f32 v169, v82, v83
	v_pk_fma_f32 v[138:139], v[84:85], v[84:85], v[138:139]
	global_store_dwordx4 v207, v[166:169], s[8:9] offset:256
	v_pk_fma_f32 v[138:139], v[86:87], v[86:87], v[138:139]
	v_pk_fma_f32 v[138:139], v[80:81], v[80:81], v[138:139]
	v_pk_fma_f32 v[138:139], v[82:83], v[82:83], v[138:139]
	v_add_f32_e32 v214, v138, v139
	v_add_u32_e32 v207, 0x8000, v207
	v_mov_b32_e32 v215, v214
	s_nop 1
	v_permlane16_swap_b32_e32 v214, v215
	s_nop 0
	v_add_f32_e32 v214, v214, v215
	v_mov_b32_e32 v215, v214
	s_nop 1
	v_permlane32_swap_b32_e32 v214, v215
	s_nop 0
	v_add_f32_e32 v214, v214, v215
	s_and_saveexec_b64 s[26:27], s[4:5]
	global_store_dword v210, v214, s[14:15] offset:2048
	s_mov_b64 exec, s[26:27]
	s_waitcnt vmcnt(17)
	v_lshlrev_b32_e32 v202, 16, v170
	v_and_b32_e32 v203, 0xffff0000, v170
	v_lshlrev_b32_e32 v204, 16, v171
	v_and_b32_e32 v205, 0xffff0000, v171
	v_pk_add_f32 v[76:77], v[76:77], v[202:203]
	v_pk_add_f32 v[78:79], v[78:79], v[204:205]
	v_lshlrev_b32_e32 v202, 16, v172
	v_and_b32_e32 v203, 0xffff0000, v172
	v_lshlrev_b32_e32 v204, 16, v173
	v_and_b32_e32 v205, 0xffff0000, v173
	v_pk_add_f32 v[72:73], v[72:73], v[202:203]
	v_pk_add_f32 v[74:75], v[74:75], v[204:205]
	v_cvt_pk_bf16_f32 v170, v76, v77
	v_cvt_pk_bf16_f32 v171, v78, v79
	v_cvt_pk_bf16_f32 v172, v72, v73
	v_cvt_pk_bf16_f32 v173, v74, v75
	v_pk_mul_f32 v[138:139], v[76:77], v[76:77]
	global_store_dwordx4 v207, v[170:173], s[8:9]
	v_pk_fma_f32 v[138:139], v[78:79], v[78:79], v[138:139]
	v_pk_fma_f32 v[138:139], v[72:73], v[72:73], v[138:139]
	v_pk_fma_f32 v[138:139], v[74:75], v[74:75], v[138:139]
	v_lshlrev_b32_e32 v202, 16, v174
	v_and_b32_e32 v203, 0xffff0000, v174
	v_lshlrev_b32_e32 v204, 16, v175
	v_and_b32_e32 v205, 0xffff0000, v175
	v_pk_add_f32 v[68:69], v[68:69], v[202:203]
	v_pk_add_f32 v[70:71], v[70:71], v[204:205]
	v_lshlrev_b32_e32 v202, 16, v176
	v_and_b32_e32 v203, 0xffff0000, v176
	v_lshlrev_b32_e32 v204, 16, v177
	v_and_b32_e32 v205, 0xffff0000, v177
	v_pk_add_f32 v[64:65], v[64:65], v[202:203]
	v_pk_add_f32 v[66:67], v[66:67], v[204:205]
	v_cvt_pk_bf16_f32 v174, v68, v69
	v_cvt_pk_bf16_f32 v175, v70, v71
	v_cvt_pk_bf16_f32 v176, v64, v65
	v_cvt_pk_bf16_f32 v177, v66, v67
	v_pk_fma_f32 v[138:139], v[68:69], v[68:69], v[138:139]
	global_store_dwordx4 v207, v[174:177], s[8:9] offset:256
	v_pk_fma_f32 v[138:139], v[70:71], v[70:71], v[138:139]
	v_pk_fma_f32 v[138:139], v[64:65], v[64:65], v[138:139]
	v_pk_fma_f32 v[138:139], v[66:67], v[66:67], v[138:139]
	v_add_f32_e32 v214, v138, v139
	v_add_u32_e32 v207, 0x28000, v207
	v_mov_b32_e32 v215, v214
	s_nop 1
	v_permlane16_swap_b32_e32 v214, v215
	s_nop 0
	v_add_f32_e32 v214, v214, v215
	v_mov_b32_e32 v215, v214
	s_nop 1
	v_permlane32_swap_b32_e32 v214, v215
	s_nop 0
	v_add_f32_e32 v214, v214, v215
	s_and_saveexec_b64 s[26:27], s[4:5]
	global_store_dword v210, v214, s[14:15] offset:3072
	s_mov_b64 exec, s[26:27]
	v_add_u32_e32 v210, 0x2000, v210
	s_waitcnt vmcnt(18)
	v_lshlrev_b32_e32 v202, 16, v178
	v_and_b32_e32 v203, 0xffff0000, v178
	v_lshlrev_b32_e32 v204, 16, v179
	v_and_b32_e32 v205, 0xffff0000, v179
	v_pk_add_f32 v[60:61], v[60:61], v[202:203]
	v_pk_add_f32 v[62:63], v[62:63], v[204:205]
	v_lshlrev_b32_e32 v202, 16, v180
	v_and_b32_e32 v203, 0xffff0000, v180
	v_lshlrev_b32_e32 v204, 16, v181
	v_and_b32_e32 v205, 0xffff0000, v181
	v_pk_add_f32 v[56:57], v[56:57], v[202:203]
	v_pk_add_f32 v[58:59], v[58:59], v[204:205]
	v_cvt_pk_bf16_f32 v178, v60, v61
	v_cvt_pk_bf16_f32 v179, v62, v63
	v_cvt_pk_bf16_f32 v180, v56, v57
	v_cvt_pk_bf16_f32 v181, v58, v59
	v_pk_mul_f32 v[138:139], v[60:61], v[60:61]
	global_store_dwordx4 v207, v[178:181], s[8:9]
	v_pk_fma_f32 v[138:139], v[62:63], v[62:63], v[138:139]
	v_pk_fma_f32 v[138:139], v[56:57], v[56:57], v[138:139]
	v_pk_fma_f32 v[138:139], v[58:59], v[58:59], v[138:139]
	v_lshlrev_b32_e32 v202, 16, v182
	v_and_b32_e32 v203, 0xffff0000, v182
	v_lshlrev_b32_e32 v204, 16, v183
	v_and_b32_e32 v205, 0xffff0000, v183
	v_pk_add_f32 v[52:53], v[52:53], v[202:203]
	v_pk_add_f32 v[54:55], v[54:55], v[204:205]
	v_lshlrev_b32_e32 v202, 16, v184
	v_and_b32_e32 v203, 0xffff0000, v184
	v_lshlrev_b32_e32 v204, 16, v185
	v_and_b32_e32 v205, 0xffff0000, v185
	v_pk_add_f32 v[48:49], v[48:49], v[202:203]
	v_pk_add_f32 v[50:51], v[50:51], v[204:205]
	v_cvt_pk_bf16_f32 v182, v52, v53
	v_cvt_pk_bf16_f32 v183, v54, v55
	v_cvt_pk_bf16_f32 v184, v48, v49
	v_cvt_pk_bf16_f32 v185, v50, v51
	v_pk_fma_f32 v[138:139], v[52:53], v[52:53], v[138:139]
	global_store_dwordx4 v207, v[182:185], s[8:9] offset:256
	v_pk_fma_f32 v[138:139], v[54:55], v[54:55], v[138:139]
	v_pk_fma_f32 v[138:139], v[48:49], v[48:49], v[138:139]
	v_pk_fma_f32 v[138:139], v[50:51], v[50:51], v[138:139]
	v_add_f32_e32 v214, v138, v139
	v_add_u32_e32 v207, 0x8000, v207
	v_mov_b32_e32 v215, v214
	s_nop 1
	v_permlane16_swap_b32_e32 v214, v215
	s_nop 0
	v_add_f32_e32 v214, v214, v215
	v_mov_b32_e32 v215, v214
	s_nop 1
	v_permlane32_swap_b32_e32 v214, v215
	s_nop 0
	v_add_f32_e32 v214, v214, v215
	s_and_saveexec_b64 s[26:27], s[4:5]
	global_store_dword v210, v214, s[14:15]
	s_mov_b64 exec, s[26:27]
	s_waitcnt vmcnt(19)
	v_lshlrev_b32_e32 v202, 16, v186
	v_and_b32_e32 v203, 0xffff0000, v186
	v_lshlrev_b32_e32 v204, 16, v187
	v_and_b32_e32 v205, 0xffff0000, v187
	v_pk_add_f32 v[44:45], v[44:45], v[202:203]
	v_pk_add_f32 v[46:47], v[46:47], v[204:205]
	v_lshlrev_b32_e32 v202, 16, v188
	v_and_b32_e32 v203, 0xffff0000, v188
	v_lshlrev_b32_e32 v204, 16, v189
	v_and_b32_e32 v205, 0xffff0000, v189
	v_pk_add_f32 v[40:41], v[40:41], v[202:203]
	v_pk_add_f32 v[42:43], v[42:43], v[204:205]
	v_cvt_pk_bf16_f32 v186, v44, v45
	v_cvt_pk_bf16_f32 v187, v46, v47
	v_cvt_pk_bf16_f32 v188, v40, v41
	v_cvt_pk_bf16_f32 v189, v42, v43
	v_pk_mul_f32 v[138:139], v[44:45], v[44:45]
	global_store_dwordx4 v207, v[186:189], s[8:9]
	v_pk_fma_f32 v[138:139], v[46:47], v[46:47], v[138:139]
	v_pk_fma_f32 v[138:139], v[40:41], v[40:41], v[138:139]
	v_pk_fma_f32 v[138:139], v[42:43], v[42:43], v[138:139]
	v_lshlrev_b32_e32 v202, 16, v190
	v_and_b32_e32 v203, 0xffff0000, v190
	v_lshlrev_b32_e32 v204, 16, v191
	v_and_b32_e32 v205, 0xffff0000, v191
	v_pk_add_f32 v[36:37], v[36:37], v[202:203]
	v_pk_add_f32 v[38:39], v[38:39], v[204:205]
	v_lshlrev_b32_e32 v202, 16, v192
	v_and_b32_e32 v203, 0xffff0000, v192
	v_lshlrev_b32_e32 v204, 16, v193
	v_and_b32_e32 v205, 0xffff0000, v193
	v_pk_add_f32 v[32:33], v[32:33], v[202:203]
	v_pk_add_f32 v[34:35], v[34:35], v[204:205]
	v_cvt_pk_bf16_f32 v190, v36, v37
	v_cvt_pk_bf16_f32 v191, v38, v39
	v_cvt_pk_bf16_f32 v192, v32, v33
	v_cvt_pk_bf16_f32 v193, v34, v35
	v_pk_fma_f32 v[138:139], v[36:37], v[36:37], v[138:139]
	global_store_dwordx4 v207, v[190:193], s[8:9] offset:256
	v_pk_fma_f32 v[138:139], v[38:39], v[38:39], v[138:139]
	v_pk_fma_f32 v[138:139], v[32:33], v[32:33], v[138:139]
	v_pk_fma_f32 v[138:139], v[34:35], v[34:35], v[138:139]
	v_add_f32_e32 v214, v138, v139
	v_add_u32_e32 v207, 0x8000, v207
	v_mov_b32_e32 v215, v214
	s_nop 1
	v_permlane16_swap_b32_e32 v214, v215
	s_nop 0
	v_add_f32_e32 v214, v214, v215
	v_mov_b32_e32 v215, v214
	s_nop 1
	v_permlane32_swap_b32_e32 v214, v215
	s_nop 0
	v_add_f32_e32 v214, v214, v215
	s_and_saveexec_b64 s[26:27], s[4:5]
	global_store_dword v210, v214, s[14:15] offset:1024
	s_mov_b64 exec, s[26:27]
	s_waitcnt vmcnt(20)
	v_lshlrev_b32_e32 v202, 16, v194
	v_and_b32_e32 v203, 0xffff0000, v194
	v_lshlrev_b32_e32 v204, 16, v195
	v_and_b32_e32 v205, 0xffff0000, v195
	v_pk_add_f32 v[28:29], v[28:29], v[202:203]
	v_pk_add_f32 v[30:31], v[30:31], v[204:205]
	v_lshlrev_b32_e32 v202, 16, v196
	v_and_b32_e32 v203, 0xffff0000, v196
	v_lshlrev_b32_e32 v204, 16, v197
	v_and_b32_e32 v205, 0xffff0000, v197
	v_pk_add_f32 v[24:25], v[24:25], v[202:203]
	v_pk_add_f32 v[26:27], v[26:27], v[204:205]
	v_cvt_pk_bf16_f32 v194, v28, v29
	v_cvt_pk_bf16_f32 v195, v30, v31
	v_cvt_pk_bf16_f32 v196, v24, v25
	v_cvt_pk_bf16_f32 v197, v26, v27
	v_pk_mul_f32 v[138:139], v[28:29], v[28:29]
	global_store_dwordx4 v207, v[194:197], s[8:9]
	v_pk_fma_f32 v[138:139], v[30:31], v[30:31], v[138:139]
	v_pk_fma_f32 v[138:139], v[24:25], v[24:25], v[138:139]
	v_pk_fma_f32 v[138:139], v[26:27], v[26:27], v[138:139]
	v_lshlrev_b32_e32 v202, 16, v198
	v_and_b32_e32 v203, 0xffff0000, v198
	v_lshlrev_b32_e32 v204, 16, v199
	v_and_b32_e32 v205, 0xffff0000, v199
	v_pk_add_f32 v[20:21], v[20:21], v[202:203]
	v_pk_add_f32 v[22:23], v[22:23], v[204:205]
	v_lshlrev_b32_e32 v202, 16, v200
	v_and_b32_e32 v203, 0xffff0000, v200
	v_lshlrev_b32_e32 v204, 16, v201
	v_and_b32_e32 v205, 0xffff0000, v201
	v_pk_add_f32 v[16:17], v[16:17], v[202:203]
	v_pk_add_f32 v[18:19], v[18:19], v[204:205]
	v_cvt_pk_bf16_f32 v198, v20, v21
	v_cvt_pk_bf16_f32 v199, v22, v23
	v_cvt_pk_bf16_f32 v200, v16, v17
	v_cvt_pk_bf16_f32 v201, v18, v19
	v_pk_fma_f32 v[138:139], v[20:21], v[20:21], v[138:139]
	global_store_dwordx4 v207, v[198:201], s[8:9] offset:256
	v_pk_fma_f32 v[138:139], v[22:23], v[22:23], v[138:139]
	v_pk_fma_f32 v[138:139], v[16:17], v[16:17], v[138:139]
	v_pk_fma_f32 v[138:139], v[18:19], v[18:19], v[138:139]
	v_add_f32_e32 v214, v138, v139
	v_add_u32_e32 v207, 0x8000, v207
	v_mov_b32_e32 v215, v214
	s_nop 1
	v_permlane16_swap_b32_e32 v214, v215
	s_nop 0
	v_add_f32_e32 v214, v214, v215
	v_mov_b32_e32 v215, v214
	s_nop 1
	v_permlane32_swap_b32_e32 v214, v215
	s_nop 0
	v_add_f32_e32 v214, v214, v215
	s_and_saveexec_b64 s[26:27], s[4:5]
	global_store_dword v210, v214, s[14:15] offset:2048
	s_mov_b64 exec, s[26:27]
	s_waitcnt vmcnt(18)
	v_lshlrev_b32_e32 v202, 16, v146
	v_and_b32_e32 v203, 0xffff0000, v146
	v_lshlrev_b32_e32 v204, 16, v147
	v_and_b32_e32 v205, 0xffff0000, v147
	v_pk_add_f32 v[12:13], v[12:13], v[202:203]
	v_pk_add_f32 v[14:15], v[14:15], v[204:205]
	v_lshlrev_b32_e32 v202, 16, v148
	v_and_b32_e32 v203, 0xffff0000, v148
	v_lshlrev_b32_e32 v204, 16, v149
	v_and_b32_e32 v205, 0xffff0000, v149
	v_pk_add_f32 v[8:9], v[8:9], v[202:203]
	v_pk_add_f32 v[10:11], v[10:11], v[204:205]
	v_cvt_pk_bf16_f32 v146, v12, v13
	v_cvt_pk_bf16_f32 v147, v14, v15
	v_cvt_pk_bf16_f32 v148, v8, v9
	v_cvt_pk_bf16_f32 v149, v10, v11
	v_pk_mul_f32 v[138:139], v[12:13], v[12:13]
	global_store_dwordx4 v207, v[146:149], s[8:9]
	v_pk_fma_f32 v[138:139], v[14:15], v[14:15], v[138:139]
	v_pk_fma_f32 v[138:139], v[8:9], v[8:9], v[138:139]
	v_pk_fma_f32 v[138:139], v[10:11], v[10:11], v[138:139]
	v_lshlrev_b32_e32 v202, 16, v150
	v_and_b32_e32 v203, 0xffff0000, v150
	v_lshlrev_b32_e32 v204, 16, v151
	v_and_b32_e32 v205, 0xffff0000, v151
	v_pk_add_f32 v[4:5], v[4:5], v[202:203]
	v_pk_add_f32 v[6:7], v[6:7], v[204:205]
	v_lshlrev_b32_e32 v202, 16, v152
	v_and_b32_e32 v203, 0xffff0000, v152
	v_lshlrev_b32_e32 v204, 16, v153
	v_and_b32_e32 v205, 0xffff0000, v153
	v_pk_add_f32 v[0:1], v[0:1], v[202:203]
	v_pk_add_f32 v[2:3], v[2:3], v[204:205]
	v_cvt_pk_bf16_f32 v150, v4, v5
	v_cvt_pk_bf16_f32 v151, v6, v7
	v_cvt_pk_bf16_f32 v152, v0, v1
	v_cvt_pk_bf16_f32 v153, v2, v3
	v_pk_fma_f32 v[138:139], v[4:5], v[4:5], v[138:139]
	global_store_dwordx4 v207, v[150:153], s[8:9] offset:256
	v_pk_fma_f32 v[138:139], v[6:7], v[6:7], v[138:139]
	v_pk_fma_f32 v[138:139], v[0:1], v[0:1], v[138:139]
	v_pk_fma_f32 v[138:139], v[2:3], v[2:3], v[138:139]
	v_add_f32_e32 v214, v138, v139
	v_add_u32_e32 v207, 0x8000, v207
	v_mov_b32_e32 v215, v214
	s_nop 1
	v_permlane16_swap_b32_e32 v214, v215
	s_nop 0
	v_add_f32_e32 v214, v214, v215
	v_mov_b32_e32 v215, v214
	s_nop 1
	v_permlane32_swap_b32_e32 v214, v215
	s_nop 0
	v_add_f32_e32 v214, v214, v215
	s_and_saveexec_b64 s[26:27], s[4:5]
	global_store_dword v210, v214, s[14:15] offset:3072
	s_mov_b64 exec, s[26:27]
	s_branch .LBB0_870

.LBB0_921:
	s_add_u32 s8, s6, 0xfffe0080
	s_addc_u32 s9, s7, -1
	s_add_i32 s84, 0, 0x10000
	v_add_u32_e32 v140, s84, v253
	ds_read_b128 v[128:131], v140
	ds_read_b128 v[132:135], v140 offset:1024
	ds_read_b128 v[136:139], v140 offset:2048
	ds_read_b128 v[140:143], v140 offset:3072
	s_cmp_eq_u32 s73, 12
	s_cselect_b32 s11, s15, s9
	s_cselect_b32 s10, s39, s8
	s_cselect_b32 s9, s65, vcc_hi
	s_cselect_b32 s8, s67, vcc_lo
	v_lshl_add_u64 v[176:177], s[6:7], 0, v[220:221]
	s_add_i32 m0, s46, 0xc000
	ds_read_b128 v[144:147], v251
	ds_read_b128 v[148:151], v251 offset:1024
	ds_read_b128 v[152:155], v251 offset:2048
	ds_read_b128 v[156:159], v251 offset:3072
	ds_read_b128 v[160:163], v251 offset:4096
	ds_read_b128 v[164:167], v251 offset:5120
	ds_read_b128 v[168:171], v251 offset:6144
	ds_read_b128 v[172:175], v251 offset:7168
	global_load_lds_dwordx4 v[176:177], off
	v_lshl_add_u64 v[176:177], s[6:7], 0, v[222:223]
	s_add_i32 m0, s46, 0xe000
	s_nop 0
	global_load_lds_dwordx4 v[176:177], off
	s_waitcnt lgkmcnt(8)
	s_barrier
	s_waitcnt lgkmcnt(0)
	s_setprio 1
	v_mfma_f32_16x16x32_bf16 v[124:127], v[128:131], v[144:147], v[124:127]
	v_mfma_f32_16x16x32_bf16 v[120:123], v[136:139], v[144:147], v[120:123]
	v_mfma_f32_16x16x32_bf16 v[92:95], v[128:131], v[152:155], v[92:95]
	v_mfma_f32_16x16x32_bf16 v[44:47], v[136:139], v[152:155], v[44:47]
	v_mfma_f32_16x16x32_bf16 v[84:87], v[128:131], v[160:163], v[84:87]
	v_mfma_f32_16x16x32_bf16 v[40:43], v[136:139], v[160:163], v[40:43]
	v_mfma_f32_16x16x32_bf16 v[76:79], v[128:131], v[168:171], v[76:79]
	v_mfma_f32_16x16x32_bf16 v[36:39], v[136:139], v[168:171], v[36:39]
	v_mfma_f32_16x16x32_bf16 v[124:127], v[132:135], v[148:151], v[124:127]
	v_mfma_f32_16x16x32_bf16 v[120:123], v[140:143], v[148:151], v[120:123]
	v_mfma_f32_16x16x32_bf16 v[92:95], v[132:135], v[156:159], v[92:95]
	v_mfma_f32_16x16x32_bf16 v[44:47], v[140:143], v[156:159], v[44:47]
	v_mfma_f32_16x16x32_bf16 v[84:87], v[132:135], v[164:167], v[84:87]
	v_mfma_f32_16x16x32_bf16 v[40:43], v[140:143], v[164:167], v[40:43]
	v_mfma_f32_16x16x32_bf16 v[76:79], v[132:135], v[172:175], v[76:79]
	v_mfma_f32_16x16x32_bf16 v[36:39], v[140:143], v[172:175], v[36:39]
	s_setprio 0
	s_barrier
	s_add_i32 s86, 0, 0x14000
	s_add_i32 s84, s84, s88
	v_add_u32_e32 v188, s86, v253
	v_lshl_add_u64 v[192:193], s[8:9], 0, v[208:209]
	s_mov_b32 m0, s84
	ds_read_b128 v[176:179], v188
	ds_read_b128 v[180:183], v188 offset:1024
	ds_read_b128 v[184:187], v188 offset:2048
	ds_read_b128 v[188:191], v188 offset:3072
	global_load_lds_dwordx4 v[192:193], off
	v_lshl_add_u64 v[194:195], s[8:9], 0, v[214:215]
	s_add_i32 m0, s84, 0x2000
	s_nop 0
	global_load_lds_dwordx4 v[194:195], off
	s_barrier
	s_waitcnt lgkmcnt(0)
	s_setprio 1
	v_mfma_f32_16x16x32_bf16 v[116:119], v[176:179], v[144:147], v[116:119]
	v_mfma_f32_16x16x32_bf16 v[112:115], v[184:187], v[144:147], v[112:115]
	v_mfma_f32_16x16x32_bf16 v[88:91], v[176:179], v[152:155], v[88:91]
	v_mfma_f32_16x16x32_bf16 v[32:35], v[184:187], v[152:155], v[32:35]
	v_mfma_f32_16x16x32_bf16 v[80:83], v[176:179], v[160:163], v[80:83]
	v_mfma_f32_16x16x32_bf16 v[28:31], v[184:187], v[160:163], v[28:31]
	v_mfma_f32_16x16x32_bf16 v[72:75], v[176:179], v[168:171], v[72:75]
	v_mfma_f32_16x16x32_bf16 v[24:27], v[184:187], v[168:171], v[24:27]
	v_mfma_f32_16x16x32_bf16 v[116:119], v[180:183], v[148:151], v[116:119]
	v_mfma_f32_16x16x32_bf16 v[112:115], v[188:191], v[148:151], v[112:115]
	v_mfma_f32_16x16x32_bf16 v[88:91], v[180:183], v[156:159], v[88:91]
	v_mfma_f32_16x16x32_bf16 v[32:35], v[188:191], v[156:159], v[32:35]
	v_mfma_f32_16x16x32_bf16 v[80:83], v[180:183], v[164:167], v[80:83]
	v_mfma_f32_16x16x32_bf16 v[28:31], v[188:191], v[164:167], v[28:31]
	v_mfma_f32_16x16x32_bf16 v[72:75], v[180:183], v[172:175], v[72:75]
	v_mfma_f32_16x16x32_bf16 v[24:27], v[188:191], v[172:175], v[24:27]
	s_setprio 0
	s_mov_b32 m0, s46
	v_lshl_add_u64 v[196:197], s[10:11], 0, v[218:219]
	s_barrier
	ds_read_b128 v[144:147], v251 offset:16384
	ds_read_b128 v[148:151], v251 offset:17408
	ds_read_b128 v[152:155], v251 offset:18432
	ds_read_b128 v[156:159], v251 offset:19456
	ds_read_b128 v[160:163], v251 offset:20480
	ds_read_b128 v[164:167], v251 offset:21504
	ds_read_b128 v[168:171], v251 offset:22528
	ds_read_b128 v[172:175], v251 offset:23552
	global_load_lds_dwordx4 v[196:197], off
	v_lshl_add_u64 v[198:199], s[10:11], 0, v[216:217]
	s_mov_b32 m0, s50
	s_nop 0
	global_load_lds_dwordx4 v[198:199], off
	s_barrier
	s_waitcnt lgkmcnt(0)
	s_setprio 1
	v_mfma_f32_16x16x32_bf16 v[68:71], v[128:131], v[144:147], v[68:71]
	v_mfma_f32_16x16x32_bf16 v[20:23], v[136:139], v[144:147], v[20:23]
	v_mfma_f32_16x16x32_bf16 v[64:67], v[128:131], v[152:155], v[64:67]
	v_mfma_f32_16x16x32_bf16 v[16:19], v[136:139], v[152:155], v[16:19]
	v_mfma_f32_16x16x32_bf16 v[60:63], v[128:131], v[160:163], v[60:63]
	v_mfma_f32_16x16x32_bf16 v[12:15], v[136:139], v[160:163], v[12:15]
	v_mfma_f32_16x16x32_bf16 v[108:111], v[128:131], v[168:171], v[108:111]
	v_mfma_f32_16x16x32_bf16 v[104:107], v[136:139], v[168:171], v[104:107]
	v_mfma_f32_16x16x32_bf16 v[68:71], v[132:135], v[148:151], v[68:71]
	v_mfma_f32_16x16x32_bf16 v[20:23], v[140:143], v[148:151], v[20:23]
	v_mfma_f32_16x16x32_bf16 v[64:67], v[132:135], v[156:159], v[64:67]
	v_mfma_f32_16x16x32_bf16 v[16:19], v[140:143], v[156:159], v[16:19]
	v_mfma_f32_16x16x32_bf16 v[60:63], v[132:135], v[164:167], v[60:63]
	v_mfma_f32_16x16x32_bf16 v[12:15], v[140:143], v[164:167], v[12:15]
	v_mfma_f32_16x16x32_bf16 v[108:111], v[132:135], v[172:175], v[108:111]
	v_mfma_f32_16x16x32_bf16 v[104:107], v[140:143], v[172:175], v[104:107]
	s_setprio 0
	s_barrier
	s_add_u32 s84, s8, 0x40000
	s_addc_u32 s85, s9, 0
	s_add_i32 s86, s86, s88
	v_lshl_add_u64 v[128:129], s[84:85], 0, v[208:209]
	s_mov_b32 m0, s86
	s_nop 0
	global_load_lds_dwordx4 v[128:129], off
	v_lshl_add_u64 v[128:129], s[84:85], 0, v[214:215]
	s_add_i32 m0, s86, 0x2000
	s_nop 0
	global_load_lds_dwordx4 v[128:129], off
	s_waitcnt vmcnt(6)
	s_barrier
	s_setprio 1
	v_mfma_f32_16x16x32_bf16 v[56:59], v[176:179], v[144:147], v[56:59]
	v_mfma_f32_16x16x32_bf16 v[8:11], v[184:187], v[144:147], v[8:11]
	v_mfma_f32_16x16x32_bf16 v[52:55], v[176:179], v[152:155], v[52:55]
	v_mfma_f32_16x16x32_bf16 v[4:7], v[184:187], v[152:155], v[4:7]
	v_mfma_f32_16x16x32_bf16 v[48:51], v[176:179], v[160:163], v[48:51]
	v_mfma_f32_16x16x32_bf16 v[0:3], v[184:187], v[160:163], v[0:3]
	v_mfma_f32_16x16x32_bf16 v[100:103], v[176:179], v[168:171], v[100:103]
	v_mfma_f32_16x16x32_bf16 v[96:99], v[184:187], v[168:171], v[96:99]
	v_mfma_f32_16x16x32_bf16 v[56:59], v[180:183], v[148:151], v[56:59]
	v_mfma_f32_16x16x32_bf16 v[8:11], v[188:191], v[148:151], v[8:11]
	v_mfma_f32_16x16x32_bf16 v[52:55], v[180:183], v[156:159], v[52:55]
	v_mfma_f32_16x16x32_bf16 v[4:7], v[188:191], v[156:159], v[4:7]
	v_mfma_f32_16x16x32_bf16 v[48:51], v[180:183], v[164:167], v[48:51]
	v_mfma_f32_16x16x32_bf16 v[0:3], v[188:191], v[164:167], v[0:3]
	v_mfma_f32_16x16x32_bf16 v[100:103], v[180:183], v[172:175], v[100:103]
	v_mfma_f32_16x16x32_bf16 v[96:99], v[188:191], v[172:175], v[96:99]
	s_setprio 0
	s_add_i32 s84, 0, 0x18000
	v_add_u32_e32 v140, s84, v253
	s_barrier
	ds_read_b128 v[128:131], v140
	ds_read_b128 v[132:135], v140 offset:1024
	ds_read_b128 v[136:139], v140 offset:2048
	ds_read_b128 v[140:143], v140 offset:3072
	s_add_u32 s10, s10, 0x20000
	s_addc_u32 s11, s11, 0
	s_mov_b32 m0, s51
	v_lshl_add_u64 v[176:177], s[10:11], 0, v[218:219]
	ds_read_b128 v[144:147], v251 offset:32768
	ds_read_b128 v[148:151], v251 offset:33792
	ds_read_b128 v[152:155], v251 offset:34816
	ds_read_b128 v[156:159], v251 offset:35840
	ds_read_b128 v[160:163], v251 offset:36864
	ds_read_b128 v[164:167], v251 offset:37888
	ds_read_b128 v[168:171], v251 offset:38912
	ds_read_b128 v[172:175], v251 offset:39936
	global_load_lds_dwordx4 v[176:177], off
	v_lshl_add_u64 v[176:177], s[10:11], 0, v[216:217]
	s_mov_b32 m0, s34
	s_nop 0
	global_load_lds_dwordx4 v[176:177], off
	s_waitcnt lgkmcnt(8)
	s_barrier
	s_waitcnt lgkmcnt(0)
	s_setprio 1
	v_mfma_f32_16x16x32_bf16 v[124:127], v[128:131], v[144:147], v[124:127]
	v_mfma_f32_16x16x32_bf16 v[120:123], v[136:139], v[144:147], v[120:123]
	v_mfma_f32_16x16x32_bf16 v[92:95], v[128:131], v[152:155], v[92:95]
	v_mfma_f32_16x16x32_bf16 v[44:47], v[136:139], v[152:155], v[44:47]
	v_mfma_f32_16x16x32_bf16 v[84:87], v[128:131], v[160:163], v[84:87]
	v_mfma_f32_16x16x32_bf16 v[40:43], v[136:139], v[160:163], v[40:43]
	v_mfma_f32_16x16x32_bf16 v[76:79], v[128:131], v[168:171], v[76:79]
	v_mfma_f32_16x16x32_bf16 v[36:39], v[136:139], v[168:171], v[36:39]
	v_mfma_f32_16x16x32_bf16 v[124:127], v[132:135], v[148:151], v[124:127]
	v_mfma_f32_16x16x32_bf16 v[120:123], v[140:143], v[148:151], v[120:123]
	v_mfma_f32_16x16x32_bf16 v[92:95], v[132:135], v[156:159], v[92:95]
	v_mfma_f32_16x16x32_bf16 v[44:47], v[140:143], v[156:159], v[44:47]
	v_mfma_f32_16x16x32_bf16 v[84:87], v[132:135], v[164:167], v[84:87]
	v_mfma_f32_16x16x32_bf16 v[40:43], v[140:143], v[164:167], v[40:43]
	v_mfma_f32_16x16x32_bf16 v[76:79], v[132:135], v[172:175], v[76:79]
	v_mfma_f32_16x16x32_bf16 v[36:39], v[140:143], v[172:175], v[36:39]
	s_setprio 0
	s_barrier
	s_add_i32 s10, 0, 0x1c000
	s_add_i32 s11, s84, s88
	v_add_u32_e32 v188, s10, v253
	v_lshl_add_u64 v[192:193], v[192:193], 0, s[40:41]
	s_mov_b32 m0, s11
	ds_read_b128 v[176:179], v188
	ds_read_b128 v[180:183], v188 offset:1024
	ds_read_b128 v[184:187], v188 offset:2048
	ds_read_b128 v[188:191], v188 offset:3072
	global_load_lds_dwordx4 v[192:193], off
	v_lshl_add_u64 v[192:193], v[194:195], 0, s[40:41]
	s_add_i32 m0, s11, 0x2000
	s_nop 0
	global_load_lds_dwordx4 v[192:193], off
	s_barrier
	s_waitcnt lgkmcnt(0)
	s_setprio 1
	v_mfma_f32_16x16x32_bf16 v[116:119], v[176:179], v[144:147], v[116:119]
	v_mfma_f32_16x16x32_bf16 v[112:115], v[184:187], v[144:147], v[112:115]
	v_mfma_f32_16x16x32_bf16 v[88:91], v[176:179], v[152:155], v[88:91]
	v_mfma_f32_16x16x32_bf16 v[32:35], v[184:187], v[152:155], v[32:35]
	v_mfma_f32_16x16x32_bf16 v[80:83], v[176:179], v[160:163], v[80:83]
	v_mfma_f32_16x16x32_bf16 v[28:31], v[184:187], v[160:163], v[28:31]
	v_mfma_f32_16x16x32_bf16 v[72:75], v[176:179], v[168:171], v[72:75]
	v_mfma_f32_16x16x32_bf16 v[24:27], v[184:187], v[168:171], v[24:27]
	v_mfma_f32_16x16x32_bf16 v[116:119], v[180:183], v[148:151], v[116:119]
	v_mfma_f32_16x16x32_bf16 v[112:115], v[188:191], v[148:151], v[112:115]
	v_mfma_f32_16x16x32_bf16 v[88:91], v[180:183], v[156:159], v[88:91]
	v_mfma_f32_16x16x32_bf16 v[32:35], v[188:191], v[156:159], v[32:35]
	v_mfma_f32_16x16x32_bf16 v[80:83], v[180:183], v[164:167], v[80:83]
	v_mfma_f32_16x16x32_bf16 v[28:31], v[188:191], v[164:167], v[28:31]
	v_mfma_f32_16x16x32_bf16 v[72:75], v[180:183], v[172:175], v[72:75]
	v_mfma_f32_16x16x32_bf16 v[24:27], v[188:191], v[172:175], v[24:27]
	s_setprio 0
	s_mov_b32 m0, s92
	v_lshl_add_u64 v[192:193], v[196:197], 0, s[40:41]
	s_barrier
	ds_read_b128 v[144:147], v251 offset:49152
	ds_read_b128 v[148:151], v251 offset:50176
	ds_read_b128 v[152:155], v251 offset:51200
	ds_read_b128 v[156:159], v251 offset:52224
	ds_read_b128 v[160:163], v251 offset:53248
	ds_read_b128 v[164:167], v251 offset:54272
	ds_read_b128 v[168:171], v251 offset:55296
	ds_read_b128 v[172:175], v251 offset:56320
	global_load_lds_dwordx4 v[192:193], off
	v_lshl_add_u64 v[192:193], v[198:199], 0, s[40:41]
	s_mov_b32 m0, s93
	s_nop 0
	global_load_lds_dwordx4 v[192:193], off
	s_barrier
	s_waitcnt lgkmcnt(0)
	s_setprio 1
	v_mfma_f32_16x16x32_bf16 v[68:71], v[128:131], v[144:147], v[68:71]
	v_mfma_f32_16x16x32_bf16 v[20:23], v[136:139], v[144:147], v[20:23]
	v_mfma_f32_16x16x32_bf16 v[64:67], v[128:131], v[152:155], v[64:67]
	v_mfma_f32_16x16x32_bf16 v[16:19], v[136:139], v[152:155], v[16:19]
	v_mfma_f32_16x16x32_bf16 v[60:63], v[128:131], v[160:163], v[60:63]
	v_mfma_f32_16x16x32_bf16 v[12:15], v[136:139], v[160:163], v[12:15]
	v_mfma_f32_16x16x32_bf16 v[108:111], v[128:131], v[168:171], v[108:111]
	v_mfma_f32_16x16x32_bf16 v[104:107], v[136:139], v[168:171], v[104:107]
	v_mfma_f32_16x16x32_bf16 v[68:71], v[132:135], v[148:151], v[68:71]
	v_mfma_f32_16x16x32_bf16 v[20:23], v[140:143], v[148:151], v[20:23]
	v_mfma_f32_16x16x32_bf16 v[64:67], v[132:135], v[156:159], v[64:67]
	v_mfma_f32_16x16x32_bf16 v[16:19], v[140:143], v[156:159], v[16:19]
	v_mfma_f32_16x16x32_bf16 v[60:63], v[132:135], v[164:167], v[60:63]
	v_mfma_f32_16x16x32_bf16 v[12:15], v[140:143], v[164:167], v[12:15]
	v_mfma_f32_16x16x32_bf16 v[108:111], v[132:135], v[172:175], v[108:111]
	v_mfma_f32_16x16x32_bf16 v[104:107], v[140:143], v[172:175], v[104:107]
	s_setprio 0
	s_barrier
	s_add_u32 s8, s8, 0x40080
	s_addc_u32 s9, s9, 0
	s_add_i32 s10, s10, s88
	v_lshl_add_u64 v[128:129], s[8:9], 0, v[208:209]
	s_mov_b32 m0, s10
	s_nop 0
	global_load_lds_dwordx4 v[128:129], off
	v_lshl_add_u64 v[128:129], s[8:9], 0, v[214:215]
	s_add_i32 m0, s10, 0x2000
	s_nop 0
	global_load_lds_dwordx4 v[128:129], off
	s_waitcnt vmcnt(6)
	s_barrier
	s_setprio 1
	v_mfma_f32_16x16x32_bf16 v[56:59], v[176:179], v[144:147], v[56:59]
	v_mfma_f32_16x16x32_bf16 v[8:11], v[184:187], v[144:147], v[8:11]
	v_mfma_f32_16x16x32_bf16 v[52:55], v[176:179], v[152:155], v[52:55]
	v_mfma_f32_16x16x32_bf16 v[4:7], v[184:187], v[152:155], v[4:7]
	v_mfma_f32_16x16x32_bf16 v[48:51], v[176:179], v[160:163], v[48:51]
	v_mfma_f32_16x16x32_bf16 v[0:3], v[184:187], v[160:163], v[0:3]
	v_mfma_f32_16x16x32_bf16 v[100:103], v[176:179], v[168:171], v[100:103]
	v_mfma_f32_16x16x32_bf16 v[96:99], v[184:187], v[168:171], v[96:99]
	v_mfma_f32_16x16x32_bf16 v[56:59], v[180:183], v[148:151], v[56:59]
	v_mfma_f32_16x16x32_bf16 v[8:11], v[188:191], v[148:151], v[8:11]
	v_mfma_f32_16x16x32_bf16 v[52:55], v[180:183], v[156:159], v[52:55]
	v_mfma_f32_16x16x32_bf16 v[4:7], v[188:191], v[156:159], v[4:7]
	v_mfma_f32_16x16x32_bf16 v[48:51], v[180:183], v[164:167], v[48:51]
	v_mfma_f32_16x16x32_bf16 v[0:3], v[188:191], v[164:167], v[0:3]
	v_mfma_f32_16x16x32_bf16 v[100:103], v[180:183], v[172:175], v[100:103]
	v_mfma_f32_16x16x32_bf16 v[96:99], v[188:191], v[172:175], v[96:99]
	s_setprio 0
	s_add_i32 s73, s73, 2
	s_add_u32 s6, s6, 0x100
	s_addc_u32 s7, s7, 0
	s_add_u32 vcc_lo, vcc_lo, 0x100
	s_addc_u32 vcc_hi, vcc_hi, 0
	s_cmp_gt_u32 s73, 13
	s_barrier
	s_cbranch_scc0 .LBB0_921
	s_lshl_b32 s6, s38, 8
	v_mov_b32_e32 v250, v210
	v_mov_b32_e32 v254, v249
	s_add_i32 s6, s6, s90
	v_mov_b64_e32 v[242:243], s[44:45]
	v_add_u32_e32 v234, s6, v254
	v_ashrrev_i32_e32 v235, 31, v234
	v_mbcnt_lo_u32_b32 v212, -1, 0
	v_mbcnt_hi_u32_b32 v212, -1, v212
	v_lshlrev_b32_e32 v244, 6, v234
	v_and_b32_e32 v212, 48, v212
	v_add_u32_e32 v212, v244, v212
	v_add_u32_e32 v213, 0x1000, v212
	v_add_u32_e32 v245, 0x1000, v244
	global_load_dwordx4 v[192:195], v212, s[20:21]
	global_load_dwordx4 v[196:199], v212, s[20:21] offset:1024
	global_load_dwordx4 v[200:203], v213, s[20:21] offset:2048
	global_load_dwordx4 v[204:207], v213, s[20:21] offset:3072
	global_load_dwordx4 v[160:163], v244, s[20:21] offset:2096
	global_load_dwordx4 v[164:167], v244, s[20:21] offset:2080
	global_load_dwordx4 v[176:179], v244, s[20:21] offset:2064
	global_load_dwordx4 v[180:183], v244, s[20:21] offset:2048
	global_load_dwordx4 v[168:171], v244, s[20:21] offset:3120
	global_load_dwordx4 v[172:175], v244, s[20:21] offset:3104
	global_load_dwordx4 v[184:187], v244, s[20:21] offset:3088
	global_load_dwordx4 v[188:191], v244, s[20:21] offset:3072
	global_load_dwordx4 v[144:147], v245, s[20:21] offset:48
	global_load_dwordx4 v[148:151], v245, s[20:21] offset:32
	global_load_dwordx4 v[152:155], v245, s[20:21] offset:16
	global_load_dwordx4 v[156:159], v245, s[20:21]
	global_load_dwordx4 v[128:131], v245, s[20:21] offset:1072
	global_load_dwordx4 v[132:135], v245, s[20:21] offset:1056
	global_load_dwordx4 v[136:139], v245, s[20:21] offset:1040
	global_load_dwordx4 v[140:143], v245, s[20:21] offset:1024
	v_add_u32_e32 v236, 16, v234
	v_ashrrev_i32_e32 v237, 31, v236
	v_add_u32_e32 v238, 32, v234
	v_ashrrev_i32_e32 v239, 31, v238
	v_add_u32_e32 v232, 48, v234
	v_ashrrev_i32_e32 v233, 31, v232
	v_add_u32_e32 v230, 64, v234
	v_ashrrev_i32_e32 v231, 31, v230
	v_add_u32_e32 v228, 0x50, v234
	v_ashrrev_i32_e32 v229, 31, v228
	v_add_u32_e32 v224, 0x60, v234
	v_ashrrev_i32_e32 v225, 31, v224
	v_add_u32_e32 v226, 0x70, v234
	v_ashrrev_i32_e32 v227, 31, v226
	s_lshl_b32 s14, s14, 7
	s_or_b32 s14, s14, s35
	s_waitcnt vmcnt(16)
	v_pk_add_f32 v[192:193], v[192:193], v[194:195]
	s_nop 0
	v_add_f32_e32 v246, v192, v193
	v_mov_b32_e32 v247, v246
	s_nop 1
	v_permlane16_swap_b32_e32 v246, v247
	s_nop 0
	v_add_f32_e32 v246, v246, v247
	v_mov_b32_e32 v247, v246
	s_nop 1
	v_permlane32_swap_b32_e32 v246, v247
	s_nop 0
	v_add_f32_e32 v193, v246, v247
	v_pk_add_f32 v[196:197], v[196:197], v[198:199]
	s_nop 0
	v_add_f32_e32 v246, v196, v197
	v_mov_b32_e32 v247, v246
	s_nop 1
	v_permlane16_swap_b32_e32 v246, v247
	s_nop 0
	v_add_f32_e32 v246, v246, v247
	v_mov_b32_e32 v247, v246
	s_nop 1
	v_permlane32_swap_b32_e32 v246, v247
	s_nop 0
	v_add_f32_e32 v192, v246, v247
	v_pk_add_f32 v[200:201], v[200:201], v[202:203]
	s_nop 0
	v_add_f32_e32 v246, v200, v201
	v_mov_b32_e32 v247, v246
	s_nop 1
	v_permlane16_swap_b32_e32 v246, v247
	s_nop 0
	v_add_f32_e32 v246, v246, v247
	v_mov_b32_e32 v247, v246
	s_nop 1
	v_permlane32_swap_b32_e32 v246, v247
	s_nop 0
	v_add_f32_e32 v197, v246, v247
	v_pk_add_f32 v[204:205], v[204:205], v[206:207]
	s_nop 0
	v_add_f32_e32 v246, v204, v205
	v_mov_b32_e32 v247, v246
	s_nop 1
	v_permlane16_swap_b32_e32 v246, v247
	s_nop 0
	v_add_f32_e32 v246, v246, v247
	v_mov_b32_e32 v247, v246
	s_nop 1
	v_permlane32_swap_b32_e32 v246, v247
	s_nop 0
	v_add_f32_e32 v196, v246, v247
	s_nop 0
	v_pk_fma_f32 v[240:241], v[192:193], s[42:43], v[242:243] op_sel_hi:[1,0,0]
	v_pk_fma_f32 v[202:203], v[196:197], s[42:43], v[242:243] op_sel_hi:[1,0,0]
	v_cmp_gt_f32_e64 s[6:7], s97, v240
	v_cmp_gt_f32_e32 vcc, s97, v241
	s_waitcnt vmcnt(0)
	v_lshl_add_u32 v192, v250, 3, s14
	v_add_u32_e32 v193, -14, v254
	v_cmp_gt_f32_e64 s[8:9], s97, v203
	v_cmp_gt_f32_e64 s[10:11], s97, v202
	v_cmp_lt_u32_e64 s[14:15], -13, v193
	v_ashrrev_i32_e32 v193, 31, v192
	s_and_saveexec_b64 s[86:87], s[14:15]
	s_xor_b64 s[14:15], exec, s[86:87]
	s_or_saveexec_b64 s[14:15], s[14:15]
	v_mul_f32_e32 v194, 0x4b800000, v241
	v_cndmask_b32_e32 v194, v241, v194, vcc
	v_rsq_f32_e32 v194, v194
	s_nop 0
	v_mul_f32_e32 v195, 0x45800000, v194
	v_cndmask_b32_e32 v204, v194, v195, vcc
	v_pk_mul_f32 v[196:197], v[118:119], v[204:205] op_sel_hi:[1,0]
	v_mul_f32_e32 v118, 0x4b800000, v202
	v_cndmask_b32_e64 v118, v202, v118, s[10:11]
	v_rsq_f32_e32 v118, v118
	v_pk_mul_f32 v[200:201], v[116:117], v[204:205] op_sel_hi:[1,0]
	v_pk_mul_f32 v[194:195], v[126:127], v[204:205] op_sel_hi:[1,0]
	v_pk_mul_f32 v[198:199], v[124:125], v[204:205] op_sel_hi:[1,0]
	v_mul_f32_e32 v116, 0x45800000, v118
	v_cndmask_b32_e64 v116, v118, v116, s[10:11]
	v_pk_mul_f32 v[122:123], v[122:123], v[204:205] op_sel_hi:[1,0]
	v_pk_mul_f32 v[120:121], v[120:121], v[204:205] op_sel_hi:[1,0]
	v_pk_mul_f32 v[114:115], v[114:115], v[204:205] op_sel_hi:[1,0]
	v_pk_mul_f32 v[112:113], v[112:113], v[204:205] op_sel_hi:[1,0]
	v_pk_mul_f32 v[110:111], v[110:111], v[116:117] op_sel_hi:[1,0]
	v_pk_mul_f32 v[108:109], v[108:109], v[116:117] op_sel_hi:[1,0]
	v_pk_mul_f32 v[106:107], v[106:107], v[116:117] op_sel_hi:[1,0]
	v_pk_mul_f32 v[104:105], v[104:105], v[116:117] op_sel_hi:[1,0]
	v_pk_mul_f32 v[102:103], v[102:103], v[116:117] op_sel_hi:[1,0]
	v_pk_mul_f32 v[100:101], v[100:101], v[116:117] op_sel_hi:[1,0]
	v_pk_mul_f32 v[98:99], v[98:99], v[116:117] op_sel_hi:[1,0]
	v_pk_mul_f32 v[96:97], v[96:97], v[116:117] op_sel_hi:[1,0]
	s_xor_b64 exec, exec, s[14:15]
	s_cbranch_execz .LBB0_917
	v_add_u32_e32 v116, -12, v254
	v_cmp_gt_i32_e64 s[10:11], 2, v254
	s_lshl_b32 s38, s38, 3
	s_add_i32 s38, s38, s91
	v_cndmask_b32_e64 v116, v116, v254, s[10:11]
	v_add_u32_e32 v126, s38, v116
	v_mov_b64_e32 v[124:125], s[22:23]
	s_movk_i32 s38, 0x5800
	v_mad_i64_i32 v[124:125], s[38:39], v126, s38, v[124:125]
	v_cndmask_b32_e64 v119, v111, v195, s[10:11]
	v_cndmask_b32_e64 v118, v110, v194, s[10:11]
	v_cndmask_b32_e64 v117, v109, v199, s[10:11]
	v_cndmask_b32_e64 v116, v108, v198, s[10:11]
	v_lshl_add_u64 v[124:125], v[192:193], 2, v[124:125]
	s_mov_b64 s[38:39], 0x2c00
	global_store_dwordx4 v[124:125], v[116:119], off
	v_lshl_add_u64 v[126:127], v[124:125], 0, s[38:39]
	s_movk_i32 s38, 0x2000
	v_cndmask_b32_e64 v119, v107, v123, s[10:11]
	v_cndmask_b32_e64 v118, v106, v122, s[10:11]
	v_cndmask_b32_e64 v117, v105, v121, s[10:11]
	v_cndmask_b32_e64 v116, v104, v120, s[10:11]
	global_store_dwordx4 v[124:125], v[116:119], off offset:16
	v_add_co_u32_e32 v124, vcc, s38, v124
	s_nop 0
	v_cndmask_b32_e64 v119, v103, v197, s[10:11]
	v_cndmask_b32_e64 v118, v102, v196, s[10:11]
	v_cndmask_b32_e64 v117, v101, v201, s[10:11]
	v_cndmask_b32_e64 v116, v100, v200, s[10:11]
	v_addc_co_u32_e32 v125, vcc, 0, v125, vcc
	global_store_dwordx4 v[124:125], v[116:119], off offset:3072
	s_nop 1
	v_cndmask_b32_e64 v119, v99, v115, s[10:11]
	v_cndmask_b32_e64 v118, v98, v114, s[10:11]
	v_cndmask_b32_e64 v117, v97, v113, s[10:11]
	v_cndmask_b32_e64 v116, v96, v112, s[10:11]
	global_store_dwordx4 v[126:127], v[116:119], off offset:16
	s_branch .LBB0_917

.LBB0_998:
	s_add_u32 s20, s10, 0x100
	s_addc_u32 s21, s11, 0
	s_add_i32 s60, 0, 0x10000
	v_add_u32_e32 v142, s60, v145
	ds_read_b128 v[138:141], v142
	ds_read_b128 v[148:151], v142 offset:1024
	ds_read_b128 v[152:155], v142 offset:2048
	ds_read_b128 v[156:159], v142 offset:3072
	s_cmp_eq_u32 s59, 40
	s_cselect_b32 s25, s7, s21
	s_cselect_b32 s24, s6, s20
	s_cselect_b32 s23, s9, s58
	s_cselect_b32 s22, s8, s57
	v_lshl_add_u64 v[142:143], s[10:11], 0, v[134:135]
	s_add_i32 m0, s34, 0xc000
	ds_read_b128 v[160:163], v147
	ds_read_b128 v[164:167], v147 offset:1024
	ds_read_b128 v[168:171], v147 offset:2048
	ds_read_b128 v[172:175], v147 offset:3072
	ds_read_b128 v[176:179], v147 offset:4096
	ds_read_b128 v[180:183], v147 offset:5120
	ds_read_b128 v[184:187], v147 offset:6144
	ds_read_b128 v[188:191], v147 offset:7168
	global_load_lds_dwordx4 v[142:143], off
	v_lshl_add_u64 v[142:143], s[10:11], 0, v[136:137]
	s_add_i32 m0, s34, 0xe000
	s_nop 0
	global_load_lds_dwordx4 v[142:143], off
	s_waitcnt lgkmcnt(8)
	s_barrier
	s_waitcnt lgkmcnt(0)
	s_setprio 1
	v_mfma_f32_16x16x32_bf16 v[124:127], v[138:141], v[160:163], v[124:127]
	v_mfma_f32_16x16x32_bf16 v[120:123], v[152:155], v[160:163], v[120:123]
	v_mfma_f32_16x16x32_bf16 v[108:111], v[138:141], v[168:171], v[108:111]
	v_mfma_f32_16x16x32_bf16 v[104:107], v[152:155], v[168:171], v[104:107]
	v_mfma_f32_16x16x32_bf16 v[92:95], v[138:141], v[176:179], v[92:95]
	v_mfma_f32_16x16x32_bf16 v[88:91], v[152:155], v[176:179], v[88:91]
	v_mfma_f32_16x16x32_bf16 v[76:79], v[138:141], v[184:187], v[76:79]
	v_mfma_f32_16x16x32_bf16 v[72:75], v[152:155], v[184:187], v[72:75]
	v_mfma_f32_16x16x32_bf16 v[124:127], v[148:151], v[164:167], v[124:127]
	v_mfma_f32_16x16x32_bf16 v[120:123], v[156:159], v[164:167], v[120:123]
	v_mfma_f32_16x16x32_bf16 v[108:111], v[148:151], v[172:175], v[108:111]
	v_mfma_f32_16x16x32_bf16 v[104:107], v[156:159], v[172:175], v[104:107]
	v_mfma_f32_16x16x32_bf16 v[92:95], v[148:151], v[180:183], v[92:95]
	v_mfma_f32_16x16x32_bf16 v[88:91], v[156:159], v[180:183], v[88:91]
	v_mfma_f32_16x16x32_bf16 v[76:79], v[148:151], v[188:191], v[76:79]
	v_mfma_f32_16x16x32_bf16 v[72:75], v[156:159], v[188:191], v[72:75]
	s_setprio 0
	s_barrier
	s_add_i32 s61, 0, 0x14000
	v_add_u32_e32 v142, s61, v145
	s_add_i32 s10, s60, s27
	ds_read_b128 v[192:195], v142
	ds_read_b128 v[196:199], v142 offset:1024
	ds_read_b128 v[200:203], v142 offset:2048
	ds_read_b128 v[204:207], v142 offset:3072
	v_lshl_add_u64 v[142:143], s[22:23], 0, v[208:209]
	s_mov_b32 m0, s10
	v_lshl_add_u64 v[210:211], s[22:23], 0, v[128:129]
	global_load_lds_dwordx4 v[142:143], off
	s_add_i32 m0, s10, 0x2000
	s_nop 0
	global_load_lds_dwordx4 v[210:211], off
	s_barrier
	s_waitcnt lgkmcnt(0)
	s_setprio 1
	v_mfma_f32_16x16x32_bf16 v[116:119], v[192:195], v[160:163], v[116:119]
	v_mfma_f32_16x16x32_bf16 v[112:115], v[200:203], v[160:163], v[112:115]
	v_mfma_f32_16x16x32_bf16 v[100:103], v[192:195], v[168:171], v[100:103]
	v_mfma_f32_16x16x32_bf16 v[96:99], v[200:203], v[168:171], v[96:99]
	v_mfma_f32_16x16x32_bf16 v[84:87], v[192:195], v[176:179], v[84:87]
	v_mfma_f32_16x16x32_bf16 v[80:83], v[200:203], v[176:179], v[80:83]
	v_mfma_f32_16x16x32_bf16 v[68:71], v[192:195], v[184:187], v[68:71]
	v_mfma_f32_16x16x32_bf16 v[64:67], v[200:203], v[184:187], v[64:67]
	v_mfma_f32_16x16x32_bf16 v[116:119], v[196:199], v[164:167], v[116:119]
	v_mfma_f32_16x16x32_bf16 v[112:115], v[204:207], v[164:167], v[112:115]
	v_mfma_f32_16x16x32_bf16 v[100:103], v[196:199], v[172:175], v[100:103]
	v_mfma_f32_16x16x32_bf16 v[96:99], v[204:207], v[172:175], v[96:99]
	v_mfma_f32_16x16x32_bf16 v[84:87], v[196:199], v[180:183], v[84:87]
	v_mfma_f32_16x16x32_bf16 v[80:83], v[204:207], v[180:183], v[80:83]
	v_mfma_f32_16x16x32_bf16 v[68:71], v[196:199], v[188:191], v[68:71]
	v_mfma_f32_16x16x32_bf16 v[64:67], v[204:207], v[188:191], v[64:67]
	s_setprio 0
	s_mov_b32 m0, s34
	v_lshl_add_u64 v[212:213], s[24:25], 0, v[132:133]
	s_barrier
	ds_read_b128 v[160:163], v147 offset:16384
	ds_read_b128 v[164:167], v147 offset:17408
	ds_read_b128 v[168:171], v147 offset:18432
	ds_read_b128 v[172:175], v147 offset:19456
	ds_read_b128 v[176:179], v147 offset:20480
	ds_read_b128 v[180:183], v147 offset:21504
	ds_read_b128 v[184:187], v147 offset:22528
	ds_read_b128 v[188:191], v147 offset:23552
	global_load_lds_dwordx4 v[212:213], off
	v_lshl_add_u64 v[214:215], s[24:25], 0, v[130:131]
	s_mov_b32 m0, s35
	s_nop 0
	global_load_lds_dwordx4 v[214:215], off
	s_barrier
	s_waitcnt lgkmcnt(0)
	s_setprio 1
	v_mfma_f32_16x16x32_bf16 v[60:63], v[138:141], v[160:163], v[60:63]
	v_mfma_f32_16x16x32_bf16 v[56:59], v[152:155], v[160:163], v[56:59]
	v_mfma_f32_16x16x32_bf16 v[44:47], v[138:141], v[168:171], v[44:47]
	v_mfma_f32_16x16x32_bf16 v[40:43], v[152:155], v[168:171], v[40:43]
	v_mfma_f32_16x16x32_bf16 v[28:31], v[138:141], v[176:179], v[28:31]
	v_mfma_f32_16x16x32_bf16 v[24:27], v[152:155], v[176:179], v[24:27]
	v_mfma_f32_16x16x32_bf16 v[12:15], v[138:141], v[184:187], v[12:15]
	v_mfma_f32_16x16x32_bf16 v[8:11], v[152:155], v[184:187], v[8:11]
	v_mfma_f32_16x16x32_bf16 v[60:63], v[148:151], v[164:167], v[60:63]
	v_mfma_f32_16x16x32_bf16 v[56:59], v[156:159], v[164:167], v[56:59]
	v_mfma_f32_16x16x32_bf16 v[44:47], v[148:151], v[172:175], v[44:47]
	v_mfma_f32_16x16x32_bf16 v[40:43], v[156:159], v[172:175], v[40:43]
	v_mfma_f32_16x16x32_bf16 v[28:31], v[148:151], v[180:183], v[28:31]
	v_mfma_f32_16x16x32_bf16 v[24:27], v[156:159], v[180:183], v[24:27]
	v_mfma_f32_16x16x32_bf16 v[12:15], v[148:151], v[188:191], v[12:15]
	v_mfma_f32_16x16x32_bf16 v[8:11], v[156:159], v[188:191], v[8:11]
	s_setprio 0
	s_barrier
	s_add_u32 s10, s22, 0xb0000
	s_addc_u32 s11, s23, 0
	s_add_i32 s60, s61, s27
	v_lshl_add_u64 v[138:139], s[10:11], 0, v[208:209]
	s_mov_b32 m0, s60
	s_nop 0
	global_load_lds_dwordx4 v[138:139], off
	v_lshl_add_u64 v[138:139], s[10:11], 0, v[128:129]
	s_add_i32 m0, s60, 0x2000
	s_nop 0
	global_load_lds_dwordx4 v[138:139], off
	s_waitcnt vmcnt(6)
	s_barrier
	s_setprio 1
	v_mfma_f32_16x16x32_bf16 v[52:55], v[192:195], v[160:163], v[52:55]
	v_mfma_f32_16x16x32_bf16 v[48:51], v[200:203], v[160:163], v[48:51]
	v_mfma_f32_16x16x32_bf16 v[36:39], v[192:195], v[168:171], v[36:39]
	v_mfma_f32_16x16x32_bf16 v[32:35], v[200:203], v[168:171], v[32:35]
	v_mfma_f32_16x16x32_bf16 v[20:23], v[192:195], v[176:179], v[20:23]
	v_mfma_f32_16x16x32_bf16 v[16:19], v[200:203], v[176:179], v[16:19]
	v_mfma_f32_16x16x32_bf16 v[4:7], v[192:195], v[184:187], v[4:7]
	v_mfma_f32_16x16x32_bf16 v[0:3], v[200:203], v[184:187], v[0:3]
	v_mfma_f32_16x16x32_bf16 v[52:55], v[196:199], v[164:167], v[52:55]
	v_mfma_f32_16x16x32_bf16 v[48:51], v[204:207], v[164:167], v[48:51]
	v_mfma_f32_16x16x32_bf16 v[36:39], v[196:199], v[172:175], v[36:39]
	v_mfma_f32_16x16x32_bf16 v[32:35], v[204:207], v[172:175], v[32:35]
	v_mfma_f32_16x16x32_bf16 v[20:23], v[196:199], v[180:183], v[20:23]
	v_mfma_f32_16x16x32_bf16 v[16:19], v[204:207], v[180:183], v[16:19]
	v_mfma_f32_16x16x32_bf16 v[4:7], v[196:199], v[188:191], v[4:7]
	v_mfma_f32_16x16x32_bf16 v[0:3], v[204:207], v[188:191], v[0:3]
	s_setprio 0
	s_add_i32 s60, 0, 0x18000
	v_add_u32_e32 v156, s60, v145
	s_barrier
	ds_read_b128 v[138:141], v156
	ds_read_b128 v[148:151], v156 offset:1024
	ds_read_b128 v[152:155], v156 offset:2048
	ds_read_b128 v[156:159], v156 offset:3072
	s_add_u32 s10, s24, 0xb0000
	s_addc_u32 s11, s25, 0
	s_mov_b32 m0, s36
	v_lshl_add_u64 v[192:193], s[10:11], 0, v[132:133]
	ds_read_b128 v[160:163], v147 offset:32768
	ds_read_b128 v[164:167], v147 offset:33792
	ds_read_b128 v[168:171], v147 offset:34816
	ds_read_b128 v[172:175], v147 offset:35840
	ds_read_b128 v[176:179], v147 offset:36864
	ds_read_b128 v[180:183], v147 offset:37888
	ds_read_b128 v[184:187], v147 offset:38912
	ds_read_b128 v[188:191], v147 offset:39936
	global_load_lds_dwordx4 v[192:193], off
	v_lshl_add_u64 v[192:193], s[10:11], 0, v[130:131]
	s_mov_b32 m0, s46
	s_nop 0
	global_load_lds_dwordx4 v[192:193], off
	s_waitcnt lgkmcnt(8)
	s_barrier
	s_waitcnt lgkmcnt(0)
	s_setprio 1
	v_mfma_f32_16x16x32_bf16 v[124:127], v[138:141], v[160:163], v[124:127]
	v_mfma_f32_16x16x32_bf16 v[120:123], v[152:155], v[160:163], v[120:123]
	v_mfma_f32_16x16x32_bf16 v[108:111], v[138:141], v[168:171], v[108:111]
	v_mfma_f32_16x16x32_bf16 v[104:107], v[152:155], v[168:171], v[104:107]
	v_mfma_f32_16x16x32_bf16 v[92:95], v[138:141], v[176:179], v[92:95]
	v_mfma_f32_16x16x32_bf16 v[88:91], v[152:155], v[176:179], v[88:91]
	v_mfma_f32_16x16x32_bf16 v[76:79], v[138:141], v[184:187], v[76:79]
	v_mfma_f32_16x16x32_bf16 v[72:75], v[152:155], v[184:187], v[72:75]
	v_mfma_f32_16x16x32_bf16 v[124:127], v[148:151], v[164:167], v[124:127]
	v_mfma_f32_16x16x32_bf16 v[120:123], v[156:159], v[164:167], v[120:123]
	v_mfma_f32_16x16x32_bf16 v[108:111], v[148:151], v[172:175], v[108:111]
	v_mfma_f32_16x16x32_bf16 v[104:107], v[156:159], v[172:175], v[104:107]
	v_mfma_f32_16x16x32_bf16 v[92:95], v[148:151], v[180:183], v[92:95]
	v_mfma_f32_16x16x32_bf16 v[88:91], v[156:159], v[180:183], v[88:91]
	v_mfma_f32_16x16x32_bf16 v[76:79], v[148:151], v[188:191], v[76:79]
	v_mfma_f32_16x16x32_bf16 v[72:75], v[156:159], v[188:191], v[72:75]
	s_setprio 0
	s_barrier
	s_add_i32 s24, 0, 0x1c000
	s_add_i32 s10, s60, s27
	v_add_u32_e32 v204, s24, v145
	v_lshl_add_u64 v[142:143], v[142:143], 0, s[40:41]
	s_mov_b32 m0, s10
	ds_read_b128 v[192:195], v204
	ds_read_b128 v[196:199], v204 offset:1024
	ds_read_b128 v[200:203], v204 offset:2048
	ds_read_b128 v[204:207], v204 offset:3072
	global_load_lds_dwordx4 v[142:143], off
	v_lshl_add_u64 v[142:143], v[210:211], 0, s[40:41]
	s_add_i32 m0, s10, 0x2000
	s_nop 0
	global_load_lds_dwordx4 v[142:143], off
	s_barrier
	s_waitcnt lgkmcnt(0)
	s_setprio 1
	v_mfma_f32_16x16x32_bf16 v[116:119], v[192:195], v[160:163], v[116:119]
	v_mfma_f32_16x16x32_bf16 v[112:115], v[200:203], v[160:163], v[112:115]
	v_mfma_f32_16x16x32_bf16 v[100:103], v[192:195], v[168:171], v[100:103]
	v_mfma_f32_16x16x32_bf16 v[96:99], v[200:203], v[168:171], v[96:99]
	v_mfma_f32_16x16x32_bf16 v[84:87], v[192:195], v[176:179], v[84:87]
	v_mfma_f32_16x16x32_bf16 v[80:83], v[200:203], v[176:179], v[80:83]
	v_mfma_f32_16x16x32_bf16 v[68:71], v[192:195], v[184:187], v[68:71]
	v_mfma_f32_16x16x32_bf16 v[64:67], v[200:203], v[184:187], v[64:67]
	v_mfma_f32_16x16x32_bf16 v[116:119], v[196:199], v[164:167], v[116:119]
	v_mfma_f32_16x16x32_bf16 v[112:115], v[204:207], v[164:167], v[112:115]
	v_mfma_f32_16x16x32_bf16 v[100:103], v[196:199], v[172:175], v[100:103]
	v_mfma_f32_16x16x32_bf16 v[96:99], v[204:207], v[172:175], v[96:99]
	v_mfma_f32_16x16x32_bf16 v[84:87], v[196:199], v[180:183], v[84:87]
	v_mfma_f32_16x16x32_bf16 v[80:83], v[204:207], v[180:183], v[80:83]
	v_mfma_f32_16x16x32_bf16 v[68:71], v[196:199], v[188:191], v[68:71]
	v_mfma_f32_16x16x32_bf16 v[64:67], v[204:207], v[188:191], v[64:67]
	s_setprio 0
	s_mov_b32 m0, s50
	v_lshl_add_u64 v[142:143], v[212:213], 0, s[40:41]
	s_barrier
	ds_read_b128 v[160:163], v147 offset:49152
	ds_read_b128 v[164:167], v147 offset:50176
	ds_read_b128 v[168:171], v147 offset:51200
	ds_read_b128 v[172:175], v147 offset:52224
	ds_read_b128 v[176:179], v147 offset:53248
	ds_read_b128 v[180:183], v147 offset:54272
	ds_read_b128 v[184:187], v147 offset:55296
	ds_read_b128 v[188:191], v147 offset:56320
	global_load_lds_dwordx4 v[142:143], off
	v_lshl_add_u64 v[142:143], v[214:215], 0, s[40:41]
	s_mov_b32 m0, s51
	s_nop 0
	global_load_lds_dwordx4 v[142:143], off
	s_barrier
	s_waitcnt lgkmcnt(0)
	s_setprio 1
	v_mfma_f32_16x16x32_bf16 v[60:63], v[138:141], v[160:163], v[60:63]
	v_mfma_f32_16x16x32_bf16 v[56:59], v[152:155], v[160:163], v[56:59]
	v_mfma_f32_16x16x32_bf16 v[44:47], v[138:141], v[168:171], v[44:47]
	v_mfma_f32_16x16x32_bf16 v[40:43], v[152:155], v[168:171], v[40:43]
	v_mfma_f32_16x16x32_bf16 v[28:31], v[138:141], v[176:179], v[28:31]
	v_mfma_f32_16x16x32_bf16 v[24:27], v[152:155], v[176:179], v[24:27]
	v_mfma_f32_16x16x32_bf16 v[12:15], v[138:141], v[184:187], v[12:15]
	v_mfma_f32_16x16x32_bf16 v[8:11], v[152:155], v[184:187], v[8:11]
	v_mfma_f32_16x16x32_bf16 v[60:63], v[148:151], v[164:167], v[60:63]
	v_mfma_f32_16x16x32_bf16 v[56:59], v[156:159], v[164:167], v[56:59]
	v_mfma_f32_16x16x32_bf16 v[44:47], v[148:151], v[172:175], v[44:47]
	v_mfma_f32_16x16x32_bf16 v[40:43], v[156:159], v[172:175], v[40:43]
	v_mfma_f32_16x16x32_bf16 v[28:31], v[148:151], v[180:183], v[28:31]
	v_mfma_f32_16x16x32_bf16 v[24:27], v[156:159], v[180:183], v[24:27]
	v_mfma_f32_16x16x32_bf16 v[12:15], v[148:151], v[188:191], v[12:15]
	v_mfma_f32_16x16x32_bf16 v[8:11], v[156:159], v[188:191], v[8:11]
	s_setprio 0
	s_barrier
	s_add_u32 s10, s22, 0xb0080
	s_addc_u32 s11, s23, 0
	s_add_i32 s22, s24, s27
	v_lshl_add_u64 v[138:139], s[10:11], 0, v[208:209]
	s_mov_b32 m0, s22
	s_nop 0
	global_load_lds_dwordx4 v[138:139], off
	v_lshl_add_u64 v[138:139], s[10:11], 0, v[128:129]
	s_add_i32 m0, s22, 0x2000
	s_nop 0
	global_load_lds_dwordx4 v[138:139], off
	s_waitcnt vmcnt(6)
	s_barrier
	s_setprio 1
	v_mfma_f32_16x16x32_bf16 v[52:55], v[192:195], v[160:163], v[52:55]
	v_mfma_f32_16x16x32_bf16 v[48:51], v[200:203], v[160:163], v[48:51]
	v_mfma_f32_16x16x32_bf16 v[36:39], v[192:195], v[168:171], v[36:39]
	v_mfma_f32_16x16x32_bf16 v[32:35], v[200:203], v[168:171], v[32:35]
	v_mfma_f32_16x16x32_bf16 v[20:23], v[192:195], v[176:179], v[20:23]
	v_mfma_f32_16x16x32_bf16 v[16:19], v[200:203], v[176:179], v[16:19]
	v_mfma_f32_16x16x32_bf16 v[4:7], v[192:195], v[184:187], v[4:7]
	v_mfma_f32_16x16x32_bf16 v[0:3], v[200:203], v[184:187], v[0:3]
	v_mfma_f32_16x16x32_bf16 v[52:55], v[196:199], v[164:167], v[52:55]
	v_mfma_f32_16x16x32_bf16 v[48:51], v[204:207], v[164:167], v[48:51]
	v_mfma_f32_16x16x32_bf16 v[36:39], v[196:199], v[172:175], v[36:39]
	v_mfma_f32_16x16x32_bf16 v[32:35], v[204:207], v[172:175], v[32:35]
	v_mfma_f32_16x16x32_bf16 v[20:23], v[196:199], v[180:183], v[20:23]
	v_mfma_f32_16x16x32_bf16 v[16:19], v[204:207], v[180:183], v[16:19]
	v_mfma_f32_16x16x32_bf16 v[4:7], v[196:199], v[188:191], v[4:7]
	v_mfma_f32_16x16x32_bf16 v[0:3], v[204:207], v[188:191], v[0:3]
	s_setprio 0
	s_add_i32 s59, s59, 2
	s_add_u32 s57, s57, 0x100
	s_addc_u32 s58, s58, 0
	s_cmp_gt_u32 s59, 41
	s_mov_b64 s[10:11], s[20:21]
	s_barrier
	s_cbranch_scc0 .LBB0_998
	v_lshl_add_u32 v142, s39, 8, v144
	v_lshl_or_b32 v143, s38, 8, v146
	s_and_b64 vcc, exec, s[4:5]
	s_mov_b32 s38, s53
	s_mov_b32 s39, s56
	s_mov_b64 s[20:21], s[8:9]
	s_mov_b64 s[10:11], s[6:7]
	v_lshl_add_u32 v210, v142, 10, v143
	v_lshlrev_b32_e32 v211, 2, v210
	v_lshlrev_b32_e32 v210, 1, v210
	global_load_dwordx4 v[148:151], v210, s[14:15]
	global_load_dwordx4 v[152:155], v210, s[14:15] offset:256
	v_add_u32_e32 v210, 0x8000, v210
	global_load_dwordx4 v[156:159], v210, s[14:15]
	global_load_dwordx4 v[160:163], v210, s[14:15] offset:256
	v_add_u32_e32 v210, 0x8000, v210
	global_load_dwordx4 v[164:167], v210, s[14:15]
	global_load_dwordx4 v[168:171], v210, s[14:15] offset:256
	v_add_u32_e32 v210, 0x8000, v210
	global_load_dwordx4 v[172:175], v210, s[14:15]
	global_load_dwordx4 v[176:179], v210, s[14:15] offset:256
	v_add_u32_e32 v210, 0x28000, v210
	global_load_dwordx4 v[180:183], v210, s[14:15]
	global_load_dwordx4 v[184:187], v210, s[14:15] offset:256
	v_add_u32_e32 v210, 0x8000, v210
	global_load_dwordx4 v[188:191], v210, s[14:15]
	global_load_dwordx4 v[192:195], v210, s[14:15] offset:256
	v_add_u32_e32 v210, 0x8000, v210
	global_load_dwordx4 v[196:199], v210, s[14:15]
	global_load_dwordx4 v[200:203], v210, s[14:15] offset:256
	v_add_u32_e32 v210, 0x8000, v210
	s_waitcnt vmcnt(12)
	v_lshlrev_b32_e32 v204, 16, v148
	v_and_b32_e32 v205, 0xffff0000, v148
	v_lshlrev_b32_e32 v206, 16, v149
	v_and_b32_e32 v207, 0xffff0000, v149
	v_pk_add_f32 v[124:125], v[124:125], v[204:205]
	v_pk_add_f32 v[126:127], v[126:127], v[206:207]
	v_lshlrev_b32_e32 v204, 16, v150
	v_and_b32_e32 v205, 0xffff0000, v150
	v_lshlrev_b32_e32 v206, 16, v151
	v_and_b32_e32 v207, 0xffff0000, v151
	v_pk_add_f32 v[120:121], v[120:121], v[204:205]
	v_pk_add_f32 v[122:123], v[122:123], v[206:207]
	global_store_dwordx4 v211, v[124:127], s[16:17]
	global_store_dwordx4 v211, v[120:123], s[16:17] offset:16
	v_lshlrev_b32_e32 v204, 16, v152
	v_and_b32_e32 v205, 0xffff0000, v152
	v_lshlrev_b32_e32 v206, 16, v153
	v_and_b32_e32 v207, 0xffff0000, v153
	v_pk_add_f32 v[116:117], v[116:117], v[204:205]
	v_pk_add_f32 v[118:119], v[118:119], v[206:207]
	v_lshlrev_b32_e32 v204, 16, v154
	v_and_b32_e32 v205, 0xffff0000, v154
	v_lshlrev_b32_e32 v206, 16, v155
	v_and_b32_e32 v207, 0xffff0000, v155
	v_pk_add_f32 v[112:113], v[112:113], v[204:205]
	v_pk_add_f32 v[114:115], v[114:115], v[206:207]
	global_store_dwordx4 v211, v[116:119], s[16:17] offset:512
	global_store_dwordx4 v211, v[112:115], s[16:17] offset:528
	v_add_u32_e32 v211, 0x10000, v211
	global_load_dwordx4 v[148:151], v210, s[14:15]
	global_load_dwordx4 v[152:155], v210, s[14:15] offset:256
	s_waitcnt vmcnt(16)
	v_lshlrev_b32_e32 v204, 16, v156
	v_and_b32_e32 v205, 0xffff0000, v156
	v_lshlrev_b32_e32 v206, 16, v157
	v_and_b32_e32 v207, 0xffff0000, v157
	v_pk_add_f32 v[108:109], v[108:109], v[204:205]
	v_pk_add_f32 v[110:111], v[110:111], v[206:207]
	v_lshlrev_b32_e32 v204, 16, v158
	v_and_b32_e32 v205, 0xffff0000, v158
	v_lshlrev_b32_e32 v206, 16, v159
	v_and_b32_e32 v207, 0xffff0000, v159
	v_pk_add_f32 v[104:105], v[104:105], v[204:205]
	v_pk_add_f32 v[106:107], v[106:107], v[206:207]
	global_store_dwordx4 v211, v[108:111], s[16:17]
	global_store_dwordx4 v211, v[104:107], s[16:17] offset:16
	v_lshlrev_b32_e32 v204, 16, v160
	v_and_b32_e32 v205, 0xffff0000, v160
	v_lshlrev_b32_e32 v206, 16, v161
	v_and_b32_e32 v207, 0xffff0000, v161
	v_pk_add_f32 v[100:101], v[100:101], v[204:205]
	v_pk_add_f32 v[102:103], v[102:103], v[206:207]
	v_lshlrev_b32_e32 v204, 16, v162
	v_and_b32_e32 v205, 0xffff0000, v162
	v_lshlrev_b32_e32 v206, 16, v163
	v_and_b32_e32 v207, 0xffff0000, v163
	v_pk_add_f32 v[96:97], v[96:97], v[204:205]
	v_pk_add_f32 v[98:99], v[98:99], v[206:207]
	global_store_dwordx4 v211, v[100:103], s[16:17] offset:512
	global_store_dwordx4 v211, v[96:99], s[16:17] offset:528
	v_add_u32_e32 v211, 0x10000, v211
	s_waitcnt vmcnt(18)
	v_lshlrev_b32_e32 v204, 16, v164
	v_and_b32_e32 v205, 0xffff0000, v164
	v_lshlrev_b32_e32 v206, 16, v165
	v_and_b32_e32 v207, 0xffff0000, v165
	v_pk_add_f32 v[92:93], v[92:93], v[204:205]
	v_pk_add_f32 v[94:95], v[94:95], v[206:207]
	v_lshlrev_b32_e32 v204, 16, v166
	v_and_b32_e32 v205, 0xffff0000, v166
	v_lshlrev_b32_e32 v206, 16, v167
	v_and_b32_e32 v207, 0xffff0000, v167
	v_pk_add_f32 v[88:89], v[88:89], v[204:205]
	v_pk_add_f32 v[90:91], v[90:91], v[206:207]
	global_store_dwordx4 v211, v[92:95], s[16:17]
	global_store_dwordx4 v211, v[88:91], s[16:17] offset:16
	v_lshlrev_b32_e32 v204, 16, v168
	v_and_b32_e32 v205, 0xffff0000, v168
	v_lshlrev_b32_e32 v206, 16, v169
	v_and_b32_e32 v207, 0xffff0000, v169
	v_pk_add_f32 v[84:85], v[84:85], v[204:205]
	v_pk_add_f32 v[86:87], v[86:87], v[206:207]
	v_lshlrev_b32_e32 v204, 16, v170
	v_and_b32_e32 v205, 0xffff0000, v170
	v_lshlrev_b32_e32 v206, 16, v171
	v_and_b32_e32 v207, 0xffff0000, v171
	v_pk_add_f32 v[80:81], v[80:81], v[204:205]
	v_pk_add_f32 v[82:83], v[82:83], v[206:207]
	global_store_dwordx4 v211, v[84:87], s[16:17] offset:512
	global_store_dwordx4 v211, v[80:83], s[16:17] offset:528
	v_add_u32_e32 v211, 0x10000, v211
	s_waitcnt vmcnt(20)
	v_lshlrev_b32_e32 v204, 16, v172
	v_and_b32_e32 v205, 0xffff0000, v172
	v_lshlrev_b32_e32 v206, 16, v173
	v_and_b32_e32 v207, 0xffff0000, v173
	v_pk_add_f32 v[76:77], v[76:77], v[204:205]
	v_pk_add_f32 v[78:79], v[78:79], v[206:207]
	v_lshlrev_b32_e32 v204, 16, v174
	v_and_b32_e32 v205, 0xffff0000, v174
	v_lshlrev_b32_e32 v206, 16, v175
	v_and_b32_e32 v207, 0xffff0000, v175
	v_pk_add_f32 v[72:73], v[72:73], v[204:205]
	v_pk_add_f32 v[74:75], v[74:75], v[206:207]
	global_store_dwordx4 v211, v[76:79], s[16:17]
	global_store_dwordx4 v211, v[72:75], s[16:17] offset:16
	v_lshlrev_b32_e32 v204, 16, v176
	v_and_b32_e32 v205, 0xffff0000, v176
	v_lshlrev_b32_e32 v206, 16, v177
	v_and_b32_e32 v207, 0xffff0000, v177
	v_pk_add_f32 v[68:69], v[68:69], v[204:205]
	v_pk_add_f32 v[70:71], v[70:71], v[206:207]
	v_lshlrev_b32_e32 v204, 16, v178
	v_and_b32_e32 v205, 0xffff0000, v178
	v_lshlrev_b32_e32 v206, 16, v179
	v_and_b32_e32 v207, 0xffff0000, v179
	v_pk_add_f32 v[64:65], v[64:65], v[204:205]
	v_pk_add_f32 v[66:67], v[66:67], v[206:207]
	global_store_dwordx4 v211, v[68:71], s[16:17] offset:512
	global_store_dwordx4 v211, v[64:67], s[16:17] offset:528
	v_add_u32_e32 v211, 0x50000, v211
	s_waitcnt vmcnt(22)
	v_lshlrev_b32_e32 v204, 16, v180
	v_and_b32_e32 v205, 0xffff0000, v180
	v_lshlrev_b32_e32 v206, 16, v181
	v_and_b32_e32 v207, 0xffff0000, v181
	v_pk_add_f32 v[60:61], v[60:61], v[204:205]
	v_pk_add_f32 v[62:63], v[62:63], v[206:207]
	v_lshlrev_b32_e32 v204, 16, v182
	v_and_b32_e32 v205, 0xffff0000, v182
	v_lshlrev_b32_e32 v206, 16, v183
	v_and_b32_e32 v207, 0xffff0000, v183
	v_pk_add_f32 v[56:57], v[56:57], v[204:205]
	v_pk_add_f32 v[58:59], v[58:59], v[206:207]
	global_store_dwordx4 v211, v[60:63], s[16:17]
	global_store_dwordx4 v211, v[56:59], s[16:17] offset:16
	v_lshlrev_b32_e32 v204, 16, v184
	v_and_b32_e32 v205, 0xffff0000, v184
	v_lshlrev_b32_e32 v206, 16, v185
	v_and_b32_e32 v207, 0xffff0000, v185
	v_pk_add_f32 v[52:53], v[52:53], v[204:205]
	v_pk_add_f32 v[54:55], v[54:55], v[206:207]
	v_lshlrev_b32_e32 v204, 16, v186
	v_and_b32_e32 v205, 0xffff0000, v186
	v_lshlrev_b32_e32 v206, 16, v187
	v_and_b32_e32 v207, 0xffff0000, v187
	v_pk_add_f32 v[48:49], v[48:49], v[204:205]
	v_pk_add_f32 v[50:51], v[50:51], v[206:207]
	global_store_dwordx4 v211, v[52:55], s[16:17] offset:512
	global_store_dwordx4 v211, v[48:51], s[16:17] offset:528
	v_add_u32_e32 v211, 0x10000, v211
	s_waitcnt vmcnt(24)
	v_lshlrev_b32_e32 v204, 16, v188
	v_and_b32_e32 v205, 0xffff0000, v188
	v_lshlrev_b32_e32 v206, 16, v189
	v_and_b32_e32 v207, 0xffff0000, v189
	v_pk_add_f32 v[44:45], v[44:45], v[204:205]
	v_pk_add_f32 v[46:47], v[46:47], v[206:207]
	v_lshlrev_b32_e32 v204, 16, v190
	v_and_b32_e32 v205, 0xffff0000, v190
	v_lshlrev_b32_e32 v206, 16, v191
	v_and_b32_e32 v207, 0xffff0000, v191
	v_pk_add_f32 v[40:41], v[40:41], v[204:205]
	v_pk_add_f32 v[42:43], v[42:43], v[206:207]
	global_store_dwordx4 v211, v[44:47], s[16:17]
	global_store_dwordx4 v211, v[40:43], s[16:17] offset:16
	v_lshlrev_b32_e32 v204, 16, v192
	v_and_b32_e32 v205, 0xffff0000, v192
	v_lshlrev_b32_e32 v206, 16, v193
	v_and_b32_e32 v207, 0xffff0000, v193
	v_pk_add_f32 v[36:37], v[36:37], v[204:205]
	v_pk_add_f32 v[38:39], v[38:39], v[206:207]
	v_lshlrev_b32_e32 v204, 16, v194
	v_and_b32_e32 v205, 0xffff0000, v194
	v_lshlrev_b32_e32 v206, 16, v195
	v_and_b32_e32 v207, 0xffff0000, v195
	v_pk_add_f32 v[32:33], v[32:33], v[204:205]
	v_pk_add_f32 v[34:35], v[34:35], v[206:207]
	global_store_dwordx4 v211, v[36:39], s[16:17] offset:512
	global_store_dwordx4 v211, v[32:35], s[16:17] offset:528
	v_add_u32_e32 v211, 0x10000, v211
	s_waitcnt vmcnt(26)
	v_lshlrev_b32_e32 v204, 16, v196
	v_and_b32_e32 v205, 0xffff0000, v196
	v_lshlrev_b32_e32 v206, 16, v197
	v_and_b32_e32 v207, 0xffff0000, v197
	v_pk_add_f32 v[28:29], v[28:29], v[204:205]
	v_pk_add_f32 v[30:31], v[30:31], v[206:207]
	v_lshlrev_b32_e32 v204, 16, v198
	v_and_b32_e32 v205, 0xffff0000, v198
	v_lshlrev_b32_e32 v206, 16, v199
	v_and_b32_e32 v207, 0xffff0000, v199
	v_pk_add_f32 v[24:25], v[24:25], v[204:205]
	v_pk_add_f32 v[26:27], v[26:27], v[206:207]
	global_store_dwordx4 v211, v[28:31], s[16:17]
	global_store_dwordx4 v211, v[24:27], s[16:17] offset:16
	v_lshlrev_b32_e32 v204, 16, v200
	v_and_b32_e32 v205, 0xffff0000, v200
	v_lshlrev_b32_e32 v206, 16, v201
	v_and_b32_e32 v207, 0xffff0000, v201
	v_pk_add_f32 v[20:21], v[20:21], v[204:205]
	v_pk_add_f32 v[22:23], v[22:23], v[206:207]
	v_lshlrev_b32_e32 v204, 16, v202
	v_and_b32_e32 v205, 0xffff0000, v202
	v_lshlrev_b32_e32 v206, 16, v203
	v_and_b32_e32 v207, 0xffff0000, v203
	v_pk_add_f32 v[16:17], v[16:17], v[204:205]
	v_pk_add_f32 v[18:19], v[18:19], v[206:207]
	global_store_dwordx4 v211, v[20:23], s[16:17] offset:512
	global_store_dwordx4 v211, v[16:19], s[16:17] offset:528
	v_add_u32_e32 v211, 0x10000, v211
	s_waitcnt vmcnt(24)
	v_lshlrev_b32_e32 v204, 16, v148
	v_and_b32_e32 v205, 0xffff0000, v148
	v_lshlrev_b32_e32 v206, 16, v149
	v_and_b32_e32 v207, 0xffff0000, v149
	v_pk_add_f32 v[12:13], v[12:13], v[204:205]
	v_pk_add_f32 v[14:15], v[14:15], v[206:207]
	v_lshlrev_b32_e32 v204, 16, v150
	v_and_b32_e32 v205, 0xffff0000, v150
	v_lshlrev_b32_e32 v206, 16, v151
	v_and_b32_e32 v207, 0xffff0000, v151
	v_pk_add_f32 v[8:9], v[8:9], v[204:205]
	v_pk_add_f32 v[10:11], v[10:11], v[206:207]
	global_store_dwordx4 v211, v[12:15], s[16:17]
	global_store_dwordx4 v211, v[8:11], s[16:17] offset:16
	v_lshlrev_b32_e32 v204, 16, v152
	v_and_b32_e32 v205, 0xffff0000, v152
	v_lshlrev_b32_e32 v206, 16, v153
	v_and_b32_e32 v207, 0xffff0000, v153
	v_pk_add_f32 v[4:5], v[4:5], v[204:205]
	v_pk_add_f32 v[6:7], v[6:7], v[206:207]
	v_lshlrev_b32_e32 v204, 16, v154
	v_and_b32_e32 v205, 0xffff0000, v154
	v_lshlrev_b32_e32 v206, 16, v155
	v_and_b32_e32 v207, 0xffff0000, v155
	v_pk_add_f32 v[0:1], v[0:1], v[204:205]
	v_pk_add_f32 v[2:3], v[2:3], v[206:207]
	global_store_dwordx4 v211, v[4:7], s[16:17] offset:512
	global_store_dwordx4 v211, v[0:3], s[16:17] offset:528
	v_add_u32_e32 v211, 0x10000, v211
	s_cbranch_vccz .LBB0_987
	s_waitcnt vmcnt(0)
	s_cmpk_gt_u32 s26, 0xff
	s_cbranch_scc1 .LBB0_1002
	s_barrier

.LBB0_1021:
	s_add_u32 s22, s20, 0x100
	s_addc_u32 s23, s21, 0
	s_add_i32 s62, 0, 0x10000
	v_add_u32_e32 v154, s62, v143
	ds_read_b128 v[138:141], v154
	ds_read_b128 v[146:149], v154 offset:1024
	ds_read_b128 v[150:153], v154 offset:2048
	ds_read_b128 v[154:157], v154 offset:3072
	s_cmp_eq_u32 s61, 40
	s_cselect_b32 s27, s9, s23
	s_cselect_b32 s26, s8, s22
	s_cselect_b32 s25, s11, s60
	s_cselect_b32 s24, s10, s39
	v_lshl_add_u64 v[190:191], s[20:21], 0, v[134:135]
	s_add_i32 m0, s46, 0xc000
	ds_read_b128 v[158:161], v145
	ds_read_b128 v[162:165], v145 offset:1024
	ds_read_b128 v[166:169], v145 offset:2048
	ds_read_b128 v[170:173], v145 offset:3072
	ds_read_b128 v[174:177], v145 offset:4096
	ds_read_b128 v[178:181], v145 offset:5120
	ds_read_b128 v[182:185], v145 offset:6144
	ds_read_b128 v[186:189], v145 offset:7168
	global_load_lds_dwordx4 v[190:191], off
	v_lshl_add_u64 v[190:191], s[20:21], 0, v[136:137]
	s_add_i32 m0, s46, 0xe000
	s_nop 0
	global_load_lds_dwordx4 v[190:191], off
	s_waitcnt lgkmcnt(8)
	s_barrier
	s_waitcnt lgkmcnt(0)
	s_setprio 1
	v_mfma_f32_16x16x32_bf16 v[124:127], v[138:141], v[158:161], v[124:127]
	v_mfma_f32_16x16x32_bf16 v[120:123], v[150:153], v[158:161], v[120:123]
	v_mfma_f32_16x16x32_bf16 v[108:111], v[138:141], v[166:169], v[108:111]
	v_mfma_f32_16x16x32_bf16 v[104:107], v[150:153], v[166:169], v[104:107]
	v_mfma_f32_16x16x32_bf16 v[92:95], v[138:141], v[174:177], v[92:95]
	v_mfma_f32_16x16x32_bf16 v[88:91], v[150:153], v[174:177], v[88:91]
	v_mfma_f32_16x16x32_bf16 v[76:79], v[138:141], v[182:185], v[76:79]
	v_mfma_f32_16x16x32_bf16 v[72:75], v[150:153], v[182:185], v[72:75]
	v_mfma_f32_16x16x32_bf16 v[124:127], v[146:149], v[162:165], v[124:127]
	v_mfma_f32_16x16x32_bf16 v[120:123], v[154:157], v[162:165], v[120:123]
	v_mfma_f32_16x16x32_bf16 v[108:111], v[146:149], v[170:173], v[108:111]
	v_mfma_f32_16x16x32_bf16 v[104:107], v[154:157], v[170:173], v[104:107]
	v_mfma_f32_16x16x32_bf16 v[92:95], v[146:149], v[178:181], v[92:95]
	v_mfma_f32_16x16x32_bf16 v[88:91], v[154:157], v[178:181], v[88:91]
	v_mfma_f32_16x16x32_bf16 v[76:79], v[146:149], v[186:189], v[76:79]
	v_mfma_f32_16x16x32_bf16 v[72:75], v[154:157], v[186:189], v[72:75]
	s_setprio 0
	s_barrier
	s_add_i32 s63, 0, 0x14000
	s_add_i32 s20, s62, s35
	v_add_u32_e32 v202, s63, v143
	v_lshl_add_u64 v[206:207], s[24:25], 0, v[208:209]
	s_mov_b32 m0, s20
	ds_read_b128 v[190:193], v202
	ds_read_b128 v[194:197], v202 offset:1024
	ds_read_b128 v[198:201], v202 offset:2048
	ds_read_b128 v[202:205], v202 offset:3072
	global_load_lds_dwordx4 v[206:207], off
	v_lshl_add_u64 v[210:211], s[24:25], 0, v[128:129]
	s_add_i32 m0, s20, 0x2000
	s_nop 0
	global_load_lds_dwordx4 v[210:211], off
	s_barrier
	s_waitcnt lgkmcnt(0)
	s_setprio 1
	v_mfma_f32_16x16x32_bf16 v[116:119], v[190:193], v[158:161], v[116:119]
	v_mfma_f32_16x16x32_bf16 v[112:115], v[198:201], v[158:161], v[112:115]
	v_mfma_f32_16x16x32_bf16 v[100:103], v[190:193], v[166:169], v[100:103]
	v_mfma_f32_16x16x32_bf16 v[96:99], v[198:201], v[166:169], v[96:99]
	v_mfma_f32_16x16x32_bf16 v[84:87], v[190:193], v[174:177], v[84:87]
	v_mfma_f32_16x16x32_bf16 v[80:83], v[198:201], v[174:177], v[80:83]
	v_mfma_f32_16x16x32_bf16 v[68:71], v[190:193], v[182:185], v[68:71]
	v_mfma_f32_16x16x32_bf16 v[64:67], v[198:201], v[182:185], v[64:67]
	v_mfma_f32_16x16x32_bf16 v[116:119], v[194:197], v[162:165], v[116:119]
	v_mfma_f32_16x16x32_bf16 v[112:115], v[202:205], v[162:165], v[112:115]
	v_mfma_f32_16x16x32_bf16 v[100:103], v[194:197], v[170:173], v[100:103]
	v_mfma_f32_16x16x32_bf16 v[96:99], v[202:205], v[170:173], v[96:99]
	v_mfma_f32_16x16x32_bf16 v[84:87], v[194:197], v[178:181], v[84:87]
	v_mfma_f32_16x16x32_bf16 v[80:83], v[202:205], v[178:181], v[80:83]
	v_mfma_f32_16x16x32_bf16 v[68:71], v[194:197], v[186:189], v[68:71]
	v_mfma_f32_16x16x32_bf16 v[64:67], v[202:205], v[186:189], v[64:67]
	s_setprio 0
	s_mov_b32 m0, s46
	v_lshl_add_u64 v[212:213], s[26:27], 0, v[132:133]
	s_barrier
	ds_read_b128 v[158:161], v145 offset:16384
	ds_read_b128 v[162:165], v145 offset:17408
	ds_read_b128 v[166:169], v145 offset:18432
	ds_read_b128 v[170:173], v145 offset:19456
	ds_read_b128 v[174:177], v145 offset:20480
	ds_read_b128 v[178:181], v145 offset:21504
	ds_read_b128 v[182:185], v145 offset:22528
	ds_read_b128 v[186:189], v145 offset:23552
	global_load_lds_dwordx4 v[212:213], off
	v_lshl_add_u64 v[214:215], s[26:27], 0, v[130:131]
	s_mov_b32 m0, s47
	s_nop 0
	global_load_lds_dwordx4 v[214:215], off
	s_barrier
	s_waitcnt lgkmcnt(0)
	s_setprio 1
	v_mfma_f32_16x16x32_bf16 v[60:63], v[138:141], v[158:161], v[60:63]
	v_mfma_f32_16x16x32_bf16 v[56:59], v[150:153], v[158:161], v[56:59]
	v_mfma_f32_16x16x32_bf16 v[44:47], v[138:141], v[166:169], v[44:47]
	v_mfma_f32_16x16x32_bf16 v[40:43], v[150:153], v[166:169], v[40:43]
	v_mfma_f32_16x16x32_bf16 v[28:31], v[138:141], v[174:177], v[28:31]
	v_mfma_f32_16x16x32_bf16 v[24:27], v[150:153], v[174:177], v[24:27]
	v_mfma_f32_16x16x32_bf16 v[12:15], v[138:141], v[182:185], v[12:15]
	v_mfma_f32_16x16x32_bf16 v[8:11], v[150:153], v[182:185], v[8:11]
	v_mfma_f32_16x16x32_bf16 v[60:63], v[146:149], v[162:165], v[60:63]
	v_mfma_f32_16x16x32_bf16 v[56:59], v[154:157], v[162:165], v[56:59]
	v_mfma_f32_16x16x32_bf16 v[44:47], v[146:149], v[170:173], v[44:47]
	v_mfma_f32_16x16x32_bf16 v[40:43], v[154:157], v[170:173], v[40:43]
	v_mfma_f32_16x16x32_bf16 v[28:31], v[146:149], v[178:181], v[28:31]
	v_mfma_f32_16x16x32_bf16 v[24:27], v[154:157], v[178:181], v[24:27]
	v_mfma_f32_16x16x32_bf16 v[12:15], v[146:149], v[186:189], v[12:15]
	v_mfma_f32_16x16x32_bf16 v[8:11], v[154:157], v[186:189], v[8:11]
	s_setprio 0
	s_barrier
	s_add_u32 s20, s24, 0xb0000
	s_addc_u32 s21, s25, 0
	s_add_i32 s62, s63, s35
	v_lshl_add_u64 v[138:139], s[20:21], 0, v[208:209]
	s_mov_b32 m0, s62
	s_nop 0
	global_load_lds_dwordx4 v[138:139], off
	v_lshl_add_u64 v[138:139], s[20:21], 0, v[128:129]
	s_add_i32 m0, s62, 0x2000
	s_nop 0
	global_load_lds_dwordx4 v[138:139], off
	s_waitcnt vmcnt(6)
	s_barrier
	s_setprio 1
	v_mfma_f32_16x16x32_bf16 v[52:55], v[190:193], v[158:161], v[52:55]
	v_mfma_f32_16x16x32_bf16 v[48:51], v[198:201], v[158:161], v[48:51]
	v_mfma_f32_16x16x32_bf16 v[36:39], v[190:193], v[166:169], v[36:39]
	v_mfma_f32_16x16x32_bf16 v[32:35], v[198:201], v[166:169], v[32:35]
	v_mfma_f32_16x16x32_bf16 v[20:23], v[190:193], v[174:177], v[20:23]
	v_mfma_f32_16x16x32_bf16 v[16:19], v[198:201], v[174:177], v[16:19]
	v_mfma_f32_16x16x32_bf16 v[4:7], v[190:193], v[182:185], v[4:7]
	v_mfma_f32_16x16x32_bf16 v[0:3], v[198:201], v[182:185], v[0:3]
	v_mfma_f32_16x16x32_bf16 v[52:55], v[194:197], v[162:165], v[52:55]
	v_mfma_f32_16x16x32_bf16 v[48:51], v[202:205], v[162:165], v[48:51]
	v_mfma_f32_16x16x32_bf16 v[36:39], v[194:197], v[170:173], v[36:39]
	v_mfma_f32_16x16x32_bf16 v[32:35], v[202:205], v[170:173], v[32:35]
	v_mfma_f32_16x16x32_bf16 v[20:23], v[194:197], v[178:181], v[20:23]
	v_mfma_f32_16x16x32_bf16 v[16:19], v[202:205], v[178:181], v[16:19]
	v_mfma_f32_16x16x32_bf16 v[4:7], v[194:197], v[186:189], v[4:7]
	v_mfma_f32_16x16x32_bf16 v[0:3], v[202:205], v[186:189], v[0:3]
	s_setprio 0
	s_add_i32 s62, 0, 0x18000
	v_add_u32_e32 v154, s62, v143
	s_barrier
	ds_read_b128 v[138:141], v154
	ds_read_b128 v[146:149], v154 offset:1024
	ds_read_b128 v[150:153], v154 offset:2048
	ds_read_b128 v[154:157], v154 offset:3072
	s_add_u32 s20, s26, 0xb0000
	s_addc_u32 s21, s27, 0
	s_mov_b32 m0, s50
	v_lshl_add_u64 v[190:191], s[20:21], 0, v[132:133]
	ds_read_b128 v[158:161], v145 offset:32768
	ds_read_b128 v[162:165], v145 offset:33792
	ds_read_b128 v[166:169], v145 offset:34816
	ds_read_b128 v[170:173], v145 offset:35840
	ds_read_b128 v[174:177], v145 offset:36864
	ds_read_b128 v[178:181], v145 offset:37888
	ds_read_b128 v[182:185], v145 offset:38912
	ds_read_b128 v[186:189], v145 offset:39936
	global_load_lds_dwordx4 v[190:191], off
	v_lshl_add_u64 v[190:191], s[20:21], 0, v[130:131]
	s_mov_b32 m0, s51
	s_nop 0
	global_load_lds_dwordx4 v[190:191], off
	s_waitcnt lgkmcnt(8)
	s_barrier
	s_waitcnt lgkmcnt(0)
	s_setprio 1
	v_mfma_f32_16x16x32_bf16 v[124:127], v[138:141], v[158:161], v[124:127]
	v_mfma_f32_16x16x32_bf16 v[120:123], v[150:153], v[158:161], v[120:123]
	v_mfma_f32_16x16x32_bf16 v[108:111], v[138:141], v[166:169], v[108:111]
	v_mfma_f32_16x16x32_bf16 v[104:107], v[150:153], v[166:169], v[104:107]
	v_mfma_f32_16x16x32_bf16 v[92:95], v[138:141], v[174:177], v[92:95]
	v_mfma_f32_16x16x32_bf16 v[88:91], v[150:153], v[174:177], v[88:91]
	v_mfma_f32_16x16x32_bf16 v[76:79], v[138:141], v[182:185], v[76:79]
	v_mfma_f32_16x16x32_bf16 v[72:75], v[150:153], v[182:185], v[72:75]
	v_mfma_f32_16x16x32_bf16 v[124:127], v[146:149], v[162:165], v[124:127]
	v_mfma_f32_16x16x32_bf16 v[120:123], v[154:157], v[162:165], v[120:123]
	v_mfma_f32_16x16x32_bf16 v[108:111], v[146:149], v[170:173], v[108:111]
	v_mfma_f32_16x16x32_bf16 v[104:107], v[154:157], v[170:173], v[104:107]
	v_mfma_f32_16x16x32_bf16 v[92:95], v[146:149], v[178:181], v[92:95]
	v_mfma_f32_16x16x32_bf16 v[88:91], v[154:157], v[178:181], v[88:91]
	v_mfma_f32_16x16x32_bf16 v[76:79], v[146:149], v[186:189], v[76:79]
	v_mfma_f32_16x16x32_bf16 v[72:75], v[154:157], v[186:189], v[72:75]
	s_setprio 0
	s_barrier
	s_add_i32 s26, 0, 0x1c000
	s_add_i32 s20, s62, s35
	v_add_u32_e32 v202, s26, v143
	v_lshl_add_u64 v[206:207], v[206:207], 0, s[40:41]
	s_mov_b32 m0, s20
	ds_read_b128 v[190:193], v202
	ds_read_b128 v[194:197], v202 offset:1024
	ds_read_b128 v[198:201], v202 offset:2048
	ds_read_b128 v[202:205], v202 offset:3072
	global_load_lds_dwordx4 v[206:207], off
	v_lshl_add_u64 v[206:207], v[210:211], 0, s[40:41]
	s_add_i32 m0, s20, 0x2000
	s_nop 0
	global_load_lds_dwordx4 v[206:207], off
	s_barrier
	s_waitcnt lgkmcnt(0)
	s_setprio 1
	v_mfma_f32_16x16x32_bf16 v[116:119], v[190:193], v[158:161], v[116:119]
	v_mfma_f32_16x16x32_bf16 v[112:115], v[198:201], v[158:161], v[112:115]
	v_mfma_f32_16x16x32_bf16 v[100:103], v[190:193], v[166:169], v[100:103]
	v_mfma_f32_16x16x32_bf16 v[96:99], v[198:201], v[166:169], v[96:99]
	v_mfma_f32_16x16x32_bf16 v[84:87], v[190:193], v[174:177], v[84:87]
	v_mfma_f32_16x16x32_bf16 v[80:83], v[198:201], v[174:177], v[80:83]
	v_mfma_f32_16x16x32_bf16 v[68:71], v[190:193], v[182:185], v[68:71]
	v_mfma_f32_16x16x32_bf16 v[64:67], v[198:201], v[182:185], v[64:67]
	v_mfma_f32_16x16x32_bf16 v[116:119], v[194:197], v[162:165], v[116:119]
	v_mfma_f32_16x16x32_bf16 v[112:115], v[202:205], v[162:165], v[112:115]
	v_mfma_f32_16x16x32_bf16 v[100:103], v[194:197], v[170:173], v[100:103]
	v_mfma_f32_16x16x32_bf16 v[96:99], v[202:205], v[170:173], v[96:99]
	v_mfma_f32_16x16x32_bf16 v[84:87], v[194:197], v[178:181], v[84:87]
	v_mfma_f32_16x16x32_bf16 v[80:83], v[202:205], v[178:181], v[80:83]
	v_mfma_f32_16x16x32_bf16 v[68:71], v[194:197], v[186:189], v[68:71]
	v_mfma_f32_16x16x32_bf16 v[64:67], v[202:205], v[186:189], v[64:67]
	s_setprio 0
	s_mov_b32 m0, s53
	v_lshl_add_u64 v[206:207], v[212:213], 0, s[40:41]
	s_barrier
	ds_read_b128 v[158:161], v145 offset:49152
	ds_read_b128 v[162:165], v145 offset:50176
	ds_read_b128 v[166:169], v145 offset:51200
	ds_read_b128 v[170:173], v145 offset:52224
	ds_read_b128 v[174:177], v145 offset:53248
	ds_read_b128 v[178:181], v145 offset:54272
	ds_read_b128 v[182:185], v145 offset:55296
	ds_read_b128 v[186:189], v145 offset:56320
	global_load_lds_dwordx4 v[206:207], off
	v_lshl_add_u64 v[206:207], v[214:215], 0, s[40:41]
	s_mov_b32 m0, s56
	s_nop 0
	global_load_lds_dwordx4 v[206:207], off
	s_barrier
	s_waitcnt lgkmcnt(0)
	s_setprio 1
	v_mfma_f32_16x16x32_bf16 v[60:63], v[138:141], v[158:161], v[60:63]
	v_mfma_f32_16x16x32_bf16 v[56:59], v[150:153], v[158:161], v[56:59]
	v_mfma_f32_16x16x32_bf16 v[44:47], v[138:141], v[166:169], v[44:47]
	v_mfma_f32_16x16x32_bf16 v[40:43], v[150:153], v[166:169], v[40:43]
	v_mfma_f32_16x16x32_bf16 v[28:31], v[138:141], v[174:177], v[28:31]
	v_mfma_f32_16x16x32_bf16 v[24:27], v[150:153], v[174:177], v[24:27]
	v_mfma_f32_16x16x32_bf16 v[12:15], v[138:141], v[182:185], v[12:15]
	v_mfma_f32_16x16x32_bf16 v[8:11], v[150:153], v[182:185], v[8:11]
	v_mfma_f32_16x16x32_bf16 v[60:63], v[146:149], v[162:165], v[60:63]
	v_mfma_f32_16x16x32_bf16 v[56:59], v[154:157], v[162:165], v[56:59]
	v_mfma_f32_16x16x32_bf16 v[44:47], v[146:149], v[170:173], v[44:47]
	v_mfma_f32_16x16x32_bf16 v[40:43], v[154:157], v[170:173], v[40:43]
	v_mfma_f32_16x16x32_bf16 v[28:31], v[146:149], v[178:181], v[28:31]
	v_mfma_f32_16x16x32_bf16 v[24:27], v[154:157], v[178:181], v[24:27]
	v_mfma_f32_16x16x32_bf16 v[12:15], v[146:149], v[186:189], v[12:15]
	v_mfma_f32_16x16x32_bf16 v[8:11], v[154:157], v[186:189], v[8:11]
	s_setprio 0
	s_barrier
	s_add_u32 s20, s24, 0xb0080
	s_addc_u32 s21, s25, 0
	s_add_i32 s24, s26, s35
	v_lshl_add_u64 v[138:139], s[20:21], 0, v[208:209]
	s_mov_b32 m0, s24
	s_nop 0
	global_load_lds_dwordx4 v[138:139], off
	v_lshl_add_u64 v[138:139], s[20:21], 0, v[128:129]
	s_add_i32 m0, s24, 0x2000
	s_nop 0
	global_load_lds_dwordx4 v[138:139], off
	s_waitcnt vmcnt(6)
	s_barrier
	s_setprio 1
	v_mfma_f32_16x16x32_bf16 v[52:55], v[190:193], v[158:161], v[52:55]
	v_mfma_f32_16x16x32_bf16 v[48:51], v[198:201], v[158:161], v[48:51]
	v_mfma_f32_16x16x32_bf16 v[36:39], v[190:193], v[166:169], v[36:39]
	v_mfma_f32_16x16x32_bf16 v[32:35], v[198:201], v[166:169], v[32:35]
	v_mfma_f32_16x16x32_bf16 v[20:23], v[190:193], v[174:177], v[20:23]
	v_mfma_f32_16x16x32_bf16 v[16:19], v[198:201], v[174:177], v[16:19]
	v_mfma_f32_16x16x32_bf16 v[4:7], v[190:193], v[182:185], v[4:7]
	v_mfma_f32_16x16x32_bf16 v[0:3], v[198:201], v[182:185], v[0:3]
	v_mfma_f32_16x16x32_bf16 v[52:55], v[194:197], v[162:165], v[52:55]
	v_mfma_f32_16x16x32_bf16 v[48:51], v[202:205], v[162:165], v[48:51]
	v_mfma_f32_16x16x32_bf16 v[36:39], v[194:197], v[170:173], v[36:39]
	v_mfma_f32_16x16x32_bf16 v[32:35], v[202:205], v[170:173], v[32:35]
	v_mfma_f32_16x16x32_bf16 v[20:23], v[194:197], v[178:181], v[20:23]
	v_mfma_f32_16x16x32_bf16 v[16:19], v[202:205], v[178:181], v[16:19]
	v_mfma_f32_16x16x32_bf16 v[4:7], v[194:197], v[186:189], v[4:7]
	v_mfma_f32_16x16x32_bf16 v[0:3], v[202:205], v[186:189], v[0:3]
	s_setprio 0
	s_add_i32 s61, s61, 2
	s_add_u32 s39, s39, 0x100
	s_addc_u32 s60, s60, 0
	s_cmp_gt_u32 s61, 41
	s_mov_b64 s[20:21], s[22:23]
	s_barrier
	s_cbranch_scc0 .LBB0_1021
	v_lshl_add_u32 v140, s38, 8, v142
	v_lshl_or_b32 v141, s36, 8, v144
	s_lshl_b32 s20, s36, 2
	s_ashr_i32 s21, s20, 31
	s_lshl_b32 s36, s52, 2
	v_lshlrev_b32_e32 v206, 11, v140
	v_lshl_add_u32 v206, v141, 1, v206
	v_lshl_add_u32 v210, v140, 6, s36
	v_lshl_add_u32 v210, s20, 2, v210
	v_mov_b32_e32 v207, v206
	global_load_dwordx4 v[146:149], v206, s[14:15]
	global_load_dwordx4 v[150:153], v206, s[14:15] offset:256
	v_add_u32_e32 v206, 0x8000, v206
	global_load_dwordx4 v[154:157], v206, s[14:15]
	global_load_dwordx4 v[158:161], v206, s[14:15] offset:256
	v_add_u32_e32 v206, 0x8000, v206
	global_load_dwordx4 v[162:165], v206, s[14:15]
	global_load_dwordx4 v[166:169], v206, s[14:15] offset:256
	v_add_u32_e32 v206, 0x8000, v206
	global_load_dwordx4 v[170:173], v206, s[14:15]
	global_load_dwordx4 v[174:177], v206, s[14:15] offset:256
	v_add_u32_e32 v206, 0x28000, v206
	global_load_dwordx4 v[178:181], v206, s[14:15]
	global_load_dwordx4 v[182:185], v206, s[14:15] offset:256
	v_add_u32_e32 v206, 0x8000, v206
	global_load_dwordx4 v[186:189], v206, s[14:15]
	global_load_dwordx4 v[190:193], v206, s[14:15] offset:256
	v_add_u32_e32 v206, 0x8000, v206
	global_load_dwordx4 v[194:197], v206, s[14:15]
	global_load_dwordx4 v[198:201], v206, s[14:15] offset:256
	v_add_u32_e32 v206, 0x8000, v206
	s_waitcnt vmcnt(12)
	v_lshlrev_b32_e32 v202, 16, v146
	v_and_b32_e32 v203, 0xffff0000, v146
	v_lshlrev_b32_e32 v204, 16, v147
	v_and_b32_e32 v205, 0xffff0000, v147
	v_pk_add_f32 v[124:125], v[124:125], v[202:203]
	v_pk_add_f32 v[126:127], v[126:127], v[204:205]
	v_lshlrev_b32_e32 v202, 16, v148
	v_and_b32_e32 v203, 0xffff0000, v148
	v_lshlrev_b32_e32 v204, 16, v149
	v_and_b32_e32 v205, 0xffff0000, v149
	v_pk_add_f32 v[120:121], v[120:121], v[202:203]
	v_pk_add_f32 v[122:123], v[122:123], v[204:205]
	v_cvt_pk_bf16_f32 v146, v124, v125
	v_cvt_pk_bf16_f32 v147, v126, v127
	v_cvt_pk_bf16_f32 v148, v120, v121
	v_cvt_pk_bf16_f32 v149, v122, v123
	v_pk_mul_f32 v[138:139], v[124:125], v[124:125]
	global_store_dwordx4 v207, v[146:149], s[14:15]
	v_pk_fma_f32 v[138:139], v[126:127], v[126:127], v[138:139]
	v_pk_fma_f32 v[138:139], v[120:121], v[120:121], v[138:139]
	v_pk_fma_f32 v[138:139], v[122:123], v[122:123], v[138:139]
	v_lshlrev_b32_e32 v202, 16, v150
	v_and_b32_e32 v203, 0xffff0000, v150
	v_lshlrev_b32_e32 v204, 16, v151
	v_and_b32_e32 v205, 0xffff0000, v151
	v_pk_add_f32 v[116:117], v[116:117], v[202:203]
	v_pk_add_f32 v[118:119], v[118:119], v[204:205]
	v_lshlrev_b32_e32 v202, 16, v152
	v_and_b32_e32 v203, 0xffff0000, v152
	v_lshlrev_b32_e32 v204, 16, v153
	v_and_b32_e32 v205, 0xffff0000, v153
	v_pk_add_f32 v[112:113], v[112:113], v[202:203]
	v_pk_add_f32 v[114:115], v[114:115], v[204:205]
	v_cvt_pk_bf16_f32 v150, v116, v117
	v_cvt_pk_bf16_f32 v151, v118, v119
	v_cvt_pk_bf16_f32 v152, v112, v113
	v_cvt_pk_bf16_f32 v153, v114, v115
	v_pk_fma_f32 v[138:139], v[116:117], v[116:117], v[138:139]
	global_store_dwordx4 v207, v[150:153], s[14:15] offset:256
	v_pk_fma_f32 v[138:139], v[118:119], v[118:119], v[138:139]
	v_pk_fma_f32 v[138:139], v[112:113], v[112:113], v[138:139]
	v_pk_fma_f32 v[138:139], v[114:115], v[114:115], v[138:139]
	v_add_f32_e32 v214, v138, v139
	v_add_u32_e32 v207, 0x8000, v207
	v_mov_b32_e32 v215, v214
	s_nop 1
	v_permlane16_swap_b32_e32 v214, v215
	s_nop 0
	v_add_f32_e32 v214, v214, v215
	v_mov_b32_e32 v215, v214
	s_nop 1
	v_permlane32_swap_b32_e32 v214, v215
	s_nop 0
	v_add_f32_e32 v214, v214, v215
	s_and_saveexec_b64 s[22:23], s[4:5]
	global_store_dword v210, v214, s[16:17]
	s_mov_b64 exec, s[22:23]
	global_load_dwordx4 v[146:149], v206, s[14:15]
	global_load_dwordx4 v[150:153], v206, s[14:15] offset:256
	s_waitcnt vmcnt(15)
	v_lshlrev_b32_e32 v202, 16, v154
	v_and_b32_e32 v203, 0xffff0000, v154
	v_lshlrev_b32_e32 v204, 16, v155
	v_and_b32_e32 v205, 0xffff0000, v155
	v_pk_add_f32 v[108:109], v[108:109], v[202:203]
	v_pk_add_f32 v[110:111], v[110:111], v[204:205]
	v_lshlrev_b32_e32 v202, 16, v156
	v_and_b32_e32 v203, 0xffff0000, v156
	v_lshlrev_b32_e32 v204, 16, v157
	v_and_b32_e32 v205, 0xffff0000, v157
	v_pk_add_f32 v[104:105], v[104:105], v[202:203]
	v_pk_add_f32 v[106:107], v[106:107], v[204:205]
	v_cvt_pk_bf16_f32 v154, v108, v109
	v_cvt_pk_bf16_f32 v155, v110, v111
	v_cvt_pk_bf16_f32 v156, v104, v105
	v_cvt_pk_bf16_f32 v157, v106, v107
	v_pk_mul_f32 v[138:139], v[108:109], v[108:109]
	global_store_dwordx4 v207, v[154:157], s[14:15]
	v_pk_fma_f32 v[138:139], v[110:111], v[110:111], v[138:139]
	v_pk_fma_f32 v[138:139], v[104:105], v[104:105], v[138:139]
	v_pk_fma_f32 v[138:139], v[106:107], v[106:107], v[138:139]
	v_lshlrev_b32_e32 v202, 16, v158
	v_and_b32_e32 v203, 0xffff0000, v158
	v_lshlrev_b32_e32 v204, 16, v159
	v_and_b32_e32 v205, 0xffff0000, v159
	v_pk_add_f32 v[100:101], v[100:101], v[202:203]
	v_pk_add_f32 v[102:103], v[102:103], v[204:205]
	v_lshlrev_b32_e32 v202, 16, v160
	v_and_b32_e32 v203, 0xffff0000, v160
	v_lshlrev_b32_e32 v204, 16, v161
	v_and_b32_e32 v205, 0xffff0000, v161
	v_pk_add_f32 v[96:97], v[96:97], v[202:203]
	v_pk_add_f32 v[98:99], v[98:99], v[204:205]
	v_cvt_pk_bf16_f32 v158, v100, v101
	v_cvt_pk_bf16_f32 v159, v102, v103
	v_cvt_pk_bf16_f32 v160, v96, v97
	v_cvt_pk_bf16_f32 v161, v98, v99
	v_pk_fma_f32 v[138:139], v[100:101], v[100:101], v[138:139]
	global_store_dwordx4 v207, v[158:161], s[14:15] offset:256
	v_pk_fma_f32 v[138:139], v[102:103], v[102:103], v[138:139]
	v_pk_fma_f32 v[138:139], v[96:97], v[96:97], v[138:139]
	v_pk_fma_f32 v[138:139], v[98:99], v[98:99], v[138:139]
	v_add_f32_e32 v214, v138, v139
	v_add_u32_e32 v207, 0x8000, v207
	v_mov_b32_e32 v215, v214
	s_nop 1
	v_permlane16_swap_b32_e32 v214, v215
	s_nop 0
	v_add_f32_e32 v214, v214, v215
	v_mov_b32_e32 v215, v214
	s_nop 1
	v_permlane32_swap_b32_e32 v214, v215
	s_nop 0
	v_add_f32_e32 v214, v214, v215
	s_and_saveexec_b64 s[22:23], s[4:5]
	global_store_dword v210, v214, s[16:17] offset:1024
	s_mov_b64 exec, s[22:23]
	s_waitcnt vmcnt(16)
	v_lshlrev_b32_e32 v202, 16, v162
	v_and_b32_e32 v203, 0xffff0000, v162
	v_lshlrev_b32_e32 v204, 16, v163
	v_and_b32_e32 v205, 0xffff0000, v163
	v_pk_add_f32 v[92:93], v[92:93], v[202:203]
	v_pk_add_f32 v[94:95], v[94:95], v[204:205]
	v_lshlrev_b32_e32 v202, 16, v164
	v_and_b32_e32 v203, 0xffff0000, v164
	v_lshlrev_b32_e32 v204, 16, v165
	v_and_b32_e32 v205, 0xffff0000, v165
	v_pk_add_f32 v[88:89], v[88:89], v[202:203]
	v_pk_add_f32 v[90:91], v[90:91], v[204:205]
	v_cvt_pk_bf16_f32 v162, v92, v93
	v_cvt_pk_bf16_f32 v163, v94, v95
	v_cvt_pk_bf16_f32 v164, v88, v89
	v_cvt_pk_bf16_f32 v165, v90, v91
	v_pk_mul_f32 v[138:139], v[92:93], v[92:93]
	global_store_dwordx4 v207, v[162:165], s[14:15]
	v_pk_fma_f32 v[138:139], v[94:95], v[94:95], v[138:139]
	v_pk_fma_f32 v[138:139], v[88:89], v[88:89], v[138:139]
	v_pk_fma_f32 v[138:139], v[90:91], v[90:91], v[138:139]
	v_lshlrev_b32_e32 v202, 16, v166
	v_and_b32_e32 v203, 0xffff0000, v166
	v_lshlrev_b32_e32 v204, 16, v167
	v_and_b32_e32 v205, 0xffff0000, v167
	v_pk_add_f32 v[84:85], v[84:85], v[202:203]
	v_pk_add_f32 v[86:87], v[86:87], v[204:205]
	v_lshlrev_b32_e32 v202, 16, v168
	v_and_b32_e32 v203, 0xffff0000, v168
	v_lshlrev_b32_e32 v204, 16, v169
	v_and_b32_e32 v205, 0xffff0000, v169
	v_pk_add_f32 v[80:81], v[80:81], v[202:203]
	v_pk_add_f32 v[82:83], v[82:83], v[204:205]
	v_cvt_pk_bf16_f32 v166, v84, v85
	v_cvt_pk_bf16_f32 v167, v86, v87
	v_cvt_pk_bf16_f32 v168, v80, v81
	v_cvt_pk_bf16_f32 v169, v82, v83
	v_pk_fma_f32 v[138:139], v[84:85], v[84:85], v[138:139]
	global_store_dwordx4 v207, v[166:169], s[14:15] offset:256
	v_pk_fma_f32 v[138:139], v[86:87], v[86:87], v[138:139]
	v_pk_fma_f32 v[138:139], v[80:81], v[80:81], v[138:139]
	v_pk_fma_f32 v[138:139], v[82:83], v[82:83], v[138:139]
	v_add_f32_e32 v214, v138, v139
	v_add_u32_e32 v207, 0x8000, v207
	v_mov_b32_e32 v215, v214
	s_nop 1
	v_permlane16_swap_b32_e32 v214, v215
	s_nop 0
	v_add_f32_e32 v214, v214, v215
	v_mov_b32_e32 v215, v214
	s_nop 1
	v_permlane32_swap_b32_e32 v214, v215
	s_nop 0
	v_add_f32_e32 v214, v214, v215
	s_and_saveexec_b64 s[22:23], s[4:5]
	global_store_dword v210, v214, s[16:17] offset:2048
	s_mov_b64 exec, s[22:23]
	s_waitcnt vmcnt(17)
	v_lshlrev_b32_e32 v202, 16, v170
	v_and_b32_e32 v203, 0xffff0000, v170
	v_lshlrev_b32_e32 v204, 16, v171
	v_and_b32_e32 v205, 0xffff0000, v171
	v_pk_add_f32 v[76:77], v[76:77], v[202:203]
	v_pk_add_f32 v[78:79], v[78:79], v[204:205]
	v_lshlrev_b32_e32 v202, 16, v172
	v_and_b32_e32 v203, 0xffff0000, v172
	v_lshlrev_b32_e32 v204, 16, v173
	v_and_b32_e32 v205, 0xffff0000, v173
	v_pk_add_f32 v[72:73], v[72:73], v[202:203]
	v_pk_add_f32 v[74:75], v[74:75], v[204:205]
	v_cvt_pk_bf16_f32 v170, v76, v77
	v_cvt_pk_bf16_f32 v171, v78, v79
	v_cvt_pk_bf16_f32 v172, v72, v73
	v_cvt_pk_bf16_f32 v173, v74, v75
	v_pk_mul_f32 v[138:139], v[76:77], v[76:77]
	global_store_dwordx4 v207, v[170:173], s[14:15]
	v_pk_fma_f32 v[138:139], v[78:79], v[78:79], v[138:139]
	v_pk_fma_f32 v[138:139], v[72:73], v[72:73], v[138:139]
	v_pk_fma_f32 v[138:139], v[74:75], v[74:75], v[138:139]
	v_lshlrev_b32_e32 v202, 16, v174
	v_and_b32_e32 v203, 0xffff0000, v174
	v_lshlrev_b32_e32 v204, 16, v175
	v_and_b32_e32 v205, 0xffff0000, v175
	v_pk_add_f32 v[68:69], v[68:69], v[202:203]
	v_pk_add_f32 v[70:71], v[70:71], v[204:205]
	v_lshlrev_b32_e32 v202, 16, v176
	v_and_b32_e32 v203, 0xffff0000, v176
	v_lshlrev_b32_e32 v204, 16, v177
	v_and_b32_e32 v205, 0xffff0000, v177
	v_pk_add_f32 v[64:65], v[64:65], v[202:203]
	v_pk_add_f32 v[66:67], v[66:67], v[204:205]
	v_cvt_pk_bf16_f32 v174, v68, v69
	v_cvt_pk_bf16_f32 v175, v70, v71
	v_cvt_pk_bf16_f32 v176, v64, v65
	v_cvt_pk_bf16_f32 v177, v66, v67
	v_pk_fma_f32 v[138:139], v[68:69], v[68:69], v[138:139]
	global_store_dwordx4 v207, v[174:177], s[14:15] offset:256
	v_pk_fma_f32 v[138:139], v[70:71], v[70:71], v[138:139]
	v_pk_fma_f32 v[138:139], v[64:65], v[64:65], v[138:139]
	v_pk_fma_f32 v[138:139], v[66:67], v[66:67], v[138:139]
	v_add_f32_e32 v214, v138, v139
	v_add_u32_e32 v207, 0x28000, v207
	v_mov_b32_e32 v215, v214
	s_nop 1
	v_permlane16_swap_b32_e32 v214, v215
	s_nop 0
	v_add_f32_e32 v214, v214, v215
	v_mov_b32_e32 v215, v214
	s_nop 1
	v_permlane32_swap_b32_e32 v214, v215
	s_nop 0
	v_add_f32_e32 v214, v214, v215
	s_and_saveexec_b64 s[22:23], s[4:5]
	global_store_dword v210, v214, s[16:17] offset:3072
	s_mov_b64 exec, s[22:23]
	v_add_u32_e32 v210, 0x2000, v210
	s_waitcnt vmcnt(18)
	v_lshlrev_b32_e32 v202, 16, v178
	v_and_b32_e32 v203, 0xffff0000, v178
	v_lshlrev_b32_e32 v204, 16, v179
	v_and_b32_e32 v205, 0xffff0000, v179
	v_pk_add_f32 v[60:61], v[60:61], v[202:203]
	v_pk_add_f32 v[62:63], v[62:63], v[204:205]
	v_lshlrev_b32_e32 v202, 16, v180
	v_and_b32_e32 v203, 0xffff0000, v180
	v_lshlrev_b32_e32 v204, 16, v181
	v_and_b32_e32 v205, 0xffff0000, v181
	v_pk_add_f32 v[56:57], v[56:57], v[202:203]
	v_pk_add_f32 v[58:59], v[58:59], v[204:205]
	v_cvt_pk_bf16_f32 v178, v60, v61
	v_cvt_pk_bf16_f32 v179, v62, v63
	v_cvt_pk_bf16_f32 v180, v56, v57
	v_cvt_pk_bf16_f32 v181, v58, v59
	v_pk_mul_f32 v[138:139], v[60:61], v[60:61]
	global_store_dwordx4 v207, v[178:181], s[14:15]
	v_pk_fma_f32 v[138:139], v[62:63], v[62:63], v[138:139]
	v_pk_fma_f32 v[138:139], v[56:57], v[56:57], v[138:139]
	v_pk_fma_f32 v[138:139], v[58:59], v[58:59], v[138:139]
	v_lshlrev_b32_e32 v202, 16, v182
	v_and_b32_e32 v203, 0xffff0000, v182
	v_lshlrev_b32_e32 v204, 16, v183
	v_and_b32_e32 v205, 0xffff0000, v183
	v_pk_add_f32 v[52:53], v[52:53], v[202:203]
	v_pk_add_f32 v[54:55], v[54:55], v[204:205]
	v_lshlrev_b32_e32 v202, 16, v184
	v_and_b32_e32 v203, 0xffff0000, v184
	v_lshlrev_b32_e32 v204, 16, v185
	v_and_b32_e32 v205, 0xffff0000, v185
	v_pk_add_f32 v[48:49], v[48:49], v[202:203]
	v_pk_add_f32 v[50:51], v[50:51], v[204:205]
	v_cvt_pk_bf16_f32 v182, v52, v53
	v_cvt_pk_bf16_f32 v183, v54, v55
	v_cvt_pk_bf16_f32 v184, v48, v49
	v_cvt_pk_bf16_f32 v185, v50, v51
	v_pk_fma_f32 v[138:139], v[52:53], v[52:53], v[138:139]
	global_store_dwordx4 v207, v[182:185], s[14:15] offset:256
	v_pk_fma_f32 v[138:139], v[54:55], v[54:55], v[138:139]
	v_pk_fma_f32 v[138:139], v[48:49], v[48:49], v[138:139]
	v_pk_fma_f32 v[138:139], v[50:51], v[50:51], v[138:139]
	v_add_f32_e32 v214, v138, v139
	v_add_u32_e32 v207, 0x8000, v207
	v_mov_b32_e32 v215, v214
	s_nop 1
	v_permlane16_swap_b32_e32 v214, v215
	s_nop 0
	v_add_f32_e32 v214, v214, v215
	v_mov_b32_e32 v215, v214
	s_nop 1
	v_permlane32_swap_b32_e32 v214, v215
	s_nop 0
	v_add_f32_e32 v214, v214, v215
	s_and_saveexec_b64 s[22:23], s[4:5]
	global_store_dword v210, v214, s[16:17]
	s_mov_b64 exec, s[22:23]
	s_waitcnt vmcnt(19)
	v_lshlrev_b32_e32 v202, 16, v186
	v_and_b32_e32 v203, 0xffff0000, v186
	v_lshlrev_b32_e32 v204, 16, v187
	v_and_b32_e32 v205, 0xffff0000, v187
	v_pk_add_f32 v[44:45], v[44:45], v[202:203]
	v_pk_add_f32 v[46:47], v[46:47], v[204:205]
	v_lshlrev_b32_e32 v202, 16, v188
	v_and_b32_e32 v203, 0xffff0000, v188
	v_lshlrev_b32_e32 v204, 16, v189
	v_and_b32_e32 v205, 0xffff0000, v189
	v_pk_add_f32 v[40:41], v[40:41], v[202:203]
	v_pk_add_f32 v[42:43], v[42:43], v[204:205]
	v_cvt_pk_bf16_f32 v186, v44, v45
	v_cvt_pk_bf16_f32 v187, v46, v47
	v_cvt_pk_bf16_f32 v188, v40, v41
	v_cvt_pk_bf16_f32 v189, v42, v43
	v_pk_mul_f32 v[138:139], v[44:45], v[44:45]
	global_store_dwordx4 v207, v[186:189], s[14:15]
	v_pk_fma_f32 v[138:139], v[46:47], v[46:47], v[138:139]
	v_pk_fma_f32 v[138:139], v[40:41], v[40:41], v[138:139]
	v_pk_fma_f32 v[138:139], v[42:43], v[42:43], v[138:139]
	v_lshlrev_b32_e32 v202, 16, v190
	v_and_b32_e32 v203, 0xffff0000, v190
	v_lshlrev_b32_e32 v204, 16, v191
	v_and_b32_e32 v205, 0xffff0000, v191
	v_pk_add_f32 v[36:37], v[36:37], v[202:203]
	v_pk_add_f32 v[38:39], v[38:39], v[204:205]
	v_lshlrev_b32_e32 v202, 16, v192
	v_and_b32_e32 v203, 0xffff0000, v192
	v_lshlrev_b32_e32 v204, 16, v193
	v_and_b32_e32 v205, 0xffff0000, v193
	v_pk_add_f32 v[32:33], v[32:33], v[202:203]
	v_pk_add_f32 v[34:35], v[34:35], v[204:205]
	v_cvt_pk_bf16_f32 v190, v36, v37
	v_cvt_pk_bf16_f32 v191, v38, v39
	v_cvt_pk_bf16_f32 v192, v32, v33
	v_cvt_pk_bf16_f32 v193, v34, v35
	v_pk_fma_f32 v[138:139], v[36:37], v[36:37], v[138:139]
	global_store_dwordx4 v207, v[190:193], s[14:15] offset:256
	v_pk_fma_f32 v[138:139], v[38:39], v[38:39], v[138:139]
	v_pk_fma_f32 v[138:139], v[32:33], v[32:33], v[138:139]
	v_pk_fma_f32 v[138:139], v[34:35], v[34:35], v[138:139]
	v_add_f32_e32 v214, v138, v139
	v_add_u32_e32 v207, 0x8000, v207
	v_mov_b32_e32 v215, v214
	s_nop 1
	v_permlane16_swap_b32_e32 v214, v215
	s_nop 0
	v_add_f32_e32 v214, v214, v215
	v_mov_b32_e32 v215, v214
	s_nop 1
	v_permlane32_swap_b32_e32 v214, v215
	s_nop 0
	v_add_f32_e32 v214, v214, v215
	s_and_saveexec_b64 s[22:23], s[4:5]
	global_store_dword v210, v214, s[16:17] offset:1024
	s_mov_b64 exec, s[22:23]
	s_waitcnt vmcnt(20)
	v_lshlrev_b32_e32 v202, 16, v194
	v_and_b32_e32 v203, 0xffff0000, v194
	v_lshlrev_b32_e32 v204, 16, v195
	v_and_b32_e32 v205, 0xffff0000, v195
	v_pk_add_f32 v[28:29], v[28:29], v[202:203]
	v_pk_add_f32 v[30:31], v[30:31], v[204:205]
	v_lshlrev_b32_e32 v202, 16, v196
	v_and_b32_e32 v203, 0xffff0000, v196
	v_lshlrev_b32_e32 v204, 16, v197
	v_and_b32_e32 v205, 0xffff0000, v197
	v_pk_add_f32 v[24:25], v[24:25], v[202:203]
	v_pk_add_f32 v[26:27], v[26:27], v[204:205]
	v_cvt_pk_bf16_f32 v194, v28, v29
	v_cvt_pk_bf16_f32 v195, v30, v31
	v_cvt_pk_bf16_f32 v196, v24, v25
	v_cvt_pk_bf16_f32 v197, v26, v27
	v_pk_mul_f32 v[138:139], v[28:29], v[28:29]
	global_store_dwordx4 v207, v[194:197], s[14:15]
	v_pk_fma_f32 v[138:139], v[30:31], v[30:31], v[138:139]
	v_pk_fma_f32 v[138:139], v[24:25], v[24:25], v[138:139]
	v_pk_fma_f32 v[138:139], v[26:27], v[26:27], v[138:139]
	v_lshlrev_b32_e32 v202, 16, v198
	v_and_b32_e32 v203, 0xffff0000, v198
	v_lshlrev_b32_e32 v204, 16, v199
	v_and_b32_e32 v205, 0xffff0000, v199
	v_pk_add_f32 v[20:21], v[20:21], v[202:203]
	v_pk_add_f32 v[22:23], v[22:23], v[204:205]
	v_lshlrev_b32_e32 v202, 16, v200
	v_and_b32_e32 v203, 0xffff0000, v200
	v_lshlrev_b32_e32 v204, 16, v201
	v_and_b32_e32 v205, 0xffff0000, v201
	v_pk_add_f32 v[16:17], v[16:17], v[202:203]
	v_pk_add_f32 v[18:19], v[18:19], v[204:205]
	v_cvt_pk_bf16_f32 v198, v20, v21
	v_cvt_pk_bf16_f32 v199, v22, v23
	v_cvt_pk_bf16_f32 v200, v16, v17
	v_cvt_pk_bf16_f32 v201, v18, v19
	v_pk_fma_f32 v[138:139], v[20:21], v[20:21], v[138:139]
	global_store_dwordx4 v207, v[198:201], s[14:15] offset:256
	v_pk_fma_f32 v[138:139], v[22:23], v[22:23], v[138:139]
	v_pk_fma_f32 v[138:139], v[16:17], v[16:17], v[138:139]
	v_pk_fma_f32 v[138:139], v[18:19], v[18:19], v[138:139]
	v_add_f32_e32 v214, v138, v139
	v_add_u32_e32 v207, 0x8000, v207
	v_mov_b32_e32 v215, v214
	s_nop 1
	v_permlane16_swap_b32_e32 v214, v215
	s_nop 0
	v_add_f32_e32 v214, v214, v215
	v_mov_b32_e32 v215, v214
	s_nop 1
	v_permlane32_swap_b32_e32 v214, v215
	s_nop 0
	v_add_f32_e32 v214, v214, v215
	s_and_saveexec_b64 s[22:23], s[4:5]
	global_store_dword v210, v214, s[16:17] offset:2048
	s_mov_b64 exec, s[22:23]
	s_waitcnt vmcnt(18)
	v_lshlrev_b32_e32 v202, 16, v146
	v_and_b32_e32 v203, 0xffff0000, v146
	v_lshlrev_b32_e32 v204, 16, v147
	v_and_b32_e32 v205, 0xffff0000, v147
	v_pk_add_f32 v[12:13], v[12:13], v[202:203]
	v_pk_add_f32 v[14:15], v[14:15], v[204:205]
	v_lshlrev_b32_e32 v202, 16, v148
	v_and_b32_e32 v203, 0xffff0000, v148
	v_lshlrev_b32_e32 v204, 16, v149
	v_and_b32_e32 v205, 0xffff0000, v149
	v_pk_add_f32 v[8:9], v[8:9], v[202:203]
	v_pk_add_f32 v[10:11], v[10:11], v[204:205]
	v_cvt_pk_bf16_f32 v146, v12, v13
	v_cvt_pk_bf16_f32 v147, v14, v15
	v_cvt_pk_bf16_f32 v148, v8, v9
	v_cvt_pk_bf16_f32 v149, v10, v11
	v_pk_mul_f32 v[138:139], v[12:13], v[12:13]
	global_store_dwordx4 v207, v[146:149], s[14:15]
	v_pk_fma_f32 v[138:139], v[14:15], v[14:15], v[138:139]
	v_pk_fma_f32 v[138:139], v[8:9], v[8:9], v[138:139]
	v_pk_fma_f32 v[138:139], v[10:11], v[10:11], v[138:139]
	v_lshlrev_b32_e32 v202, 16, v150
	v_and_b32_e32 v203, 0xffff0000, v150
	v_lshlrev_b32_e32 v204, 16, v151
	v_and_b32_e32 v205, 0xffff0000, v151
	v_pk_add_f32 v[4:5], v[4:5], v[202:203]
	v_pk_add_f32 v[6:7], v[6:7], v[204:205]
	v_lshlrev_b32_e32 v202, 16, v152
	v_and_b32_e32 v203, 0xffff0000, v152
	v_lshlrev_b32_e32 v204, 16, v153
	v_and_b32_e32 v205, 0xffff0000, v153
	v_pk_add_f32 v[0:1], v[0:1], v[202:203]
	v_pk_add_f32 v[2:3], v[2:3], v[204:205]
	v_cvt_pk_bf16_f32 v150, v4, v5
	v_cvt_pk_bf16_f32 v151, v6, v7
	v_cvt_pk_bf16_f32 v152, v0, v1
	v_cvt_pk_bf16_f32 v153, v2, v3
	v_pk_fma_f32 v[138:139], v[4:5], v[4:5], v[138:139]
	global_store_dwordx4 v207, v[150:153], s[14:15] offset:256
	v_pk_fma_f32 v[138:139], v[6:7], v[6:7], v[138:139]
	v_pk_fma_f32 v[138:139], v[0:1], v[0:1], v[138:139]
	v_pk_fma_f32 v[138:139], v[2:3], v[2:3], v[138:139]
	v_add_f32_e32 v214, v138, v139
	v_add_u32_e32 v207, 0x8000, v207
	v_mov_b32_e32 v215, v214
	s_nop 1
	v_permlane16_swap_b32_e32 v214, v215
	s_nop 0
	v_add_f32_e32 v214, v214, v215
	v_mov_b32_e32 v215, v214
	s_nop 1
	v_permlane32_swap_b32_e32 v214, v215
	s_nop 0
	v_add_f32_e32 v214, v214, v215
	s_and_saveexec_b64 s[22:23], s[4:5]
	global_store_dword v210, v214, s[16:17] offset:3072
	s_mov_b64 exec, s[22:23]
	s_branch .LBB0_1009
